# K-loops: s_setprio 1 issued before the barrier that precedes each MFMA segment and s_setprio 0 after the barrier that follows it (one SALU less on each barrier-to-MFMA and MFMA-to-barrier path)
# speedup vs baseline: 1.0112x; 1.0037x over previous
.LBB0_175:
	s_ashr_i32 s57, s56, 31
	s_lshl_b64 s[52:53], s[56:57], 20
	v_readlane_b32 s66, v254, 17
	v_readlane_b32 s67, v254, 18
	s_add_u32 s66, s66, s52
	s_addc_u32 s67, s67, s53
	s_and_b64 s[52:53], s[6:7], exec
	s_cselect_b32 s11, s67, s9
	s_cselect_b32 s13, s66, s8
	s_ashr_i32 s61, s60, 31
	s_lshl_b64 s[52:53], s[60:61], 20
	v_readlane_b32 s68, v254, 21
	v_readlane_b32 s69, v254, 22
	s_add_u32 s88, s68, s52
	s_addc_u32 s89, s69, s53
	s_and_b64 s[52:53], s[6:7], exec
	s_cselect_b32 s57, s89, s15
	s_cselect_b32 s61, s88, s14
	s_add_u32 s8, s8, 0x80080
	s_addc_u32 s9, s9, 0
	s_add_u32 s68, s14, 0x100
	s_addc_u32 s69, s15, 0
	s_mov_b32 s90, -2
	s_add_u32 s14, s8, 0xfff80080
	s_addc_u32 s15, s9, -1
	s_add_i32 s91, 0, 0x10000
	s_cmp_eq_u32 s90, 28
	s_cselect_b32 s53, s11, s15
	s_cselect_b32 s52, s13, s14
	v_add_u32_e32 v14, s91, v188
	s_cselect_b32 s15, s57, s69
	s_cselect_b32 s14, s61, s68
	s_add_i32 s96, 0, 0x14000
	ds_read_b128 v[6:9], v14
	ds_read_b128 v[10:13], v14 offset:1024
	ds_read_b128 v[140:143], v14 offset:2048
	ds_read_b128 v[144:147], v14 offset:3072
	v_add_u32_e32 v14, s96, v188
	ds_read_b128 v[148:151], v14
	ds_read_b128 v[152:155], v14 offset:1024
	ds_read_b128 v[180:183], v14 offset:2048
	ds_read_b128 v[208:211], v14 offset:3072
	v_lshl_add_u64 v[14:15], s[8:9], 0, v[176:177]
	s_add_i32 m0, s40, 0xc000
	ds_read_b128 v[212:215], v206
	ds_read_b128 v[216:219], v206 offset:1024
	ds_read_b128 v[220:223], v206 offset:2048
	ds_read_b128 v[224:227], v206 offset:3072
	ds_read_b128 v[238:241], v206 offset:4096
	ds_read_b128 v[242:245], v206 offset:5120
	ds_read_b128 v[246:249], v206 offset:6144
	ds_read_b128 v[250:253], v206 offset:7168
	global_load_lds_dwordx4 v[14:15], off
	s_add_i32 m0, s40, 0xe000
	v_lshl_add_u64 v[14:15], s[8:9], 0, v[178:179]
	global_load_lds_dwordx4 v[14:15], off
	s_waitcnt vmcnt(8) lgkmcnt(0)
	s_setprio 1
	s_barrier
	v_mfma_f32_16x16x32_bf16 v[136:139], v[6:9], v[212:215], 0
	v_mfma_f32_16x16x32_bf16 v[104:107], v[140:143], v[212:215], 0
	v_mfma_f32_16x16x32_bf16 v[132:135], v[6:9], v[220:223], 0
	v_mfma_f32_16x16x32_bf16 v[100:103], v[140:143], v[220:223], 0
	v_mfma_f32_16x16x32_bf16 v[128:131], v[6:9], v[238:241], 0
	v_mfma_f32_16x16x32_bf16 v[96:99], v[140:143], v[238:241], 0
	v_mfma_f32_16x16x32_bf16 v[124:127], v[6:9], v[246:249], 0
	v_mfma_f32_16x16x32_bf16 v[92:95], v[140:143], v[246:249], 0
	v_mfma_f32_16x16x32_bf16 v[136:139], v[10:13], v[216:219], v[136:139]
	v_mfma_f32_16x16x32_bf16 v[104:107], v[144:147], v[216:219], v[104:107]
	v_mfma_f32_16x16x32_bf16 v[132:135], v[10:13], v[224:227], v[132:135]
	v_mfma_f32_16x16x32_bf16 v[100:103], v[144:147], v[224:227], v[100:103]
	v_mfma_f32_16x16x32_bf16 v[128:131], v[10:13], v[242:245], v[128:131]
	v_mfma_f32_16x16x32_bf16 v[96:99], v[144:147], v[242:245], v[96:99]
	v_mfma_f32_16x16x32_bf16 v[124:127], v[10:13], v[250:253], v[124:127]
	v_mfma_f32_16x16x32_bf16 v[92:95], v[144:147], v[250:253], v[92:95]
	s_setprio 0
	s_setprio 1
	v_mfma_f32_16x16x32_bf16 v[72:75], v[148:151], v[212:215], 0
	v_mfma_f32_16x16x32_bf16 v[40:43], v[180:183], v[212:215], 0
	v_mfma_f32_16x16x32_bf16 v[68:71], v[148:151], v[220:223], 0
	v_mfma_f32_16x16x32_bf16 v[36:39], v[180:183], v[220:223], 0
	v_mfma_f32_16x16x32_bf16 v[64:67], v[148:151], v[238:241], 0
	v_mfma_f32_16x16x32_bf16 v[32:35], v[180:183], v[238:241], 0
	v_mfma_f32_16x16x32_bf16 v[60:63], v[148:151], v[246:249], 0
	v_mfma_f32_16x16x32_bf16 v[28:31], v[180:183], v[246:249], 0
	v_mfma_f32_16x16x32_bf16 v[72:75], v[152:155], v[216:219], v[72:75]
	v_mfma_f32_16x16x32_bf16 v[40:43], v[208:211], v[216:219], v[40:43]
	v_mfma_f32_16x16x32_bf16 v[68:71], v[152:155], v[224:227], v[68:71]
	v_mfma_f32_16x16x32_bf16 v[36:39], v[208:211], v[224:227], v[36:39]
	v_mfma_f32_16x16x32_bf16 v[64:67], v[152:155], v[242:245], v[64:67]
	v_mfma_f32_16x16x32_bf16 v[32:35], v[208:211], v[242:245], v[32:35]
	v_mfma_f32_16x16x32_bf16 v[60:63], v[152:155], v[250:253], v[60:63]
	v_mfma_f32_16x16x32_bf16 v[28:31], v[208:211], v[250:253], v[28:31]
	s_barrier
	s_setprio 0
	s_add_i32 s91, s91, s33
	v_lshl_add_u64 v[156:157], s[14:15], 0, v[160:161]
	s_mov_b32 m0, s91
	ds_read_b128 v[212:215], v206 offset:16384
	ds_read_b128 v[216:219], v206 offset:17408
	ds_read_b128 v[220:223], v206 offset:18432
	ds_read_b128 v[224:227], v206 offset:19456
	ds_read_b128 v[238:241], v206 offset:20480
	ds_read_b128 v[242:245], v206 offset:21504
	ds_read_b128 v[246:249], v206 offset:22528
	ds_read_b128 v[250:253], v206 offset:23552
	global_load_lds_dwordx4 v[156:157], off
	s_add_i32 m0, s91, 0x2000
	s_add_u32 vcc_lo, s14, 0x80000
	v_lshl_add_u64 v[184:185], s[14:15], 0, v[164:165]
	s_addc_u32 vcc_hi, s15, 0
	s_add_i32 s91, s96, s33
	global_load_lds_dwordx4 v[184:185], off
	v_lshl_add_u64 v[14:15], vcc, 0, v[160:161]
	s_mov_b32 m0, s91
	v_lshl_add_u64 v[196:197], s[52:53], 0, v[158:159]
	global_load_lds_dwordx4 v[14:15], off
	v_lshl_add_u64 v[14:15], vcc, 0, v[164:165]
	s_add_i32 m0, s91, 0x2000
	v_lshl_add_u64 v[198:199], s[52:53], 0, v[162:163]
	global_load_lds_dwordx4 v[14:15], off
	s_mov_b32 m0, s40
	s_nop 0
	global_load_lds_dwordx4 v[196:197], off
	s_mov_b32 m0, s41
	s_nop 0
	global_load_lds_dwordx4 v[198:199], off
	s_waitcnt vmcnt(8) lgkmcnt(0)
	s_setprio 1
	s_barrier
	v_mfma_f32_16x16x32_bf16 v[120:123], v[6:9], v[212:215], 0
	v_mfma_f32_16x16x32_bf16 v[88:91], v[140:143], v[212:215], 0
	v_mfma_f32_16x16x32_bf16 v[116:119], v[6:9], v[220:223], 0
	v_mfma_f32_16x16x32_bf16 v[84:87], v[140:143], v[220:223], 0
	v_mfma_f32_16x16x32_bf16 v[112:115], v[6:9], v[238:241], 0
	v_mfma_f32_16x16x32_bf16 v[80:83], v[140:143], v[238:241], 0
	v_mfma_f32_16x16x32_bf16 v[6:9], v[6:9], v[246:249], 0
	v_mfma_f32_16x16x32_bf16 v[120:123], v[10:13], v[216:219], v[120:123]
	v_mfma_f32_16x16x32_bf16 v[88:91], v[144:147], v[216:219], v[88:91]
	v_mfma_f32_16x16x32_bf16 v[116:119], v[10:13], v[224:227], v[116:119]
	v_mfma_f32_16x16x32_bf16 v[84:87], v[144:147], v[224:227], v[84:87]
	v_mfma_f32_16x16x32_bf16 v[112:115], v[10:13], v[242:245], v[112:115]
	v_mfma_f32_16x16x32_bf16 v[80:83], v[144:147], v[242:245], v[80:83]
	v_mfma_f32_16x16x32_bf16 v[6:9], v[10:13], v[250:253], v[6:9]
	v_mfma_f32_16x16x32_bf16 v[10:13], v[140:143], v[246:249], 0
	v_mfma_f32_16x16x32_bf16 v[10:13], v[144:147], v[250:253], v[10:13]
	s_setprio 0
	s_setprio 1
	v_mfma_f32_16x16x32_bf16 v[56:59], v[148:151], v[212:215], 0
	v_mfma_f32_16x16x32_bf16 v[24:27], v[180:183], v[212:215], 0
	v_mfma_f32_16x16x32_bf16 v[52:55], v[148:151], v[220:223], 0
	v_mfma_f32_16x16x32_bf16 v[20:23], v[180:183], v[220:223], 0
	v_mfma_f32_16x16x32_bf16 v[48:51], v[148:151], v[238:241], 0
	v_mfma_f32_16x16x32_bf16 v[14:17], v[180:183], v[238:241], 0
	v_mfma_f32_16x16x32_bf16 v[44:47], v[148:151], v[246:249], 0
	v_mfma_f32_16x16x32_bf16 v[2:5], v[180:183], v[246:249], 0
	v_mfma_f32_16x16x32_bf16 v[56:59], v[152:155], v[216:219], v[56:59]
	v_mfma_f32_16x16x32_bf16 v[24:27], v[208:211], v[216:219], v[24:27]
	v_mfma_f32_16x16x32_bf16 v[52:55], v[152:155], v[224:227], v[52:55]
	v_mfma_f32_16x16x32_bf16 v[20:23], v[208:211], v[224:227], v[20:23]
	v_mfma_f32_16x16x32_bf16 v[48:51], v[152:155], v[242:245], v[48:51]
	v_mfma_f32_16x16x32_bf16 v[14:17], v[208:211], v[242:245], v[14:17]
	v_mfma_f32_16x16x32_bf16 v[44:47], v[152:155], v[250:253], v[44:47]
	v_mfma_f32_16x16x32_bf16 v[2:5], v[208:211], v[250:253], v[2:5]
	s_barrier
	s_setprio 0
	s_add_i32 s91, 0, 0x18000
	v_add_u32_e32 v18, s91, v188
	s_add_i32 s96, 0, 0x1c000
	ds_read_b128 v[76:79], v18
	ds_read_b128 v[108:111], v18 offset:1024
	ds_read_b128 v[140:143], v18 offset:2048
	ds_read_b128 v[144:147], v18 offset:3072
	v_add_u32_e32 v18, s96, v188
	ds_read_b128 v[148:151], v18
	ds_read_b128 v[152:155], v18 offset:1024
	ds_read_b128 v[180:183], v18 offset:2048
	ds_read_b128 v[208:211], v18 offset:3072
	s_add_u32 s52, s52, 0x80000
	s_addc_u32 s53, s53, 0
	s_mov_b32 m0, s42
	v_lshl_add_u64 v[18:19], s[52:53], 0, v[158:159]
	ds_read_b128 v[212:215], v206 offset:32768
	ds_read_b128 v[216:219], v206 offset:33792
	ds_read_b128 v[220:223], v206 offset:34816
	ds_read_b128 v[224:227], v206 offset:35840
	ds_read_b128 v[238:241], v206 offset:36864
	ds_read_b128 v[242:245], v206 offset:37888
	ds_read_b128 v[246:249], v206 offset:38912
	ds_read_b128 v[250:253], v206 offset:39936
	global_load_lds_dwordx4 v[18:19], off
	s_mov_b32 m0, s43
	v_lshl_add_u64 v[18:19], s[52:53], 0, v[162:163]
	global_load_lds_dwordx4 v[18:19], off
	s_waitcnt vmcnt(8) lgkmcnt(0)
	s_setprio 1
	s_barrier
	v_mfma_f32_16x16x32_bf16 v[136:139], v[76:79], v[212:215], v[136:139]
	v_mfma_f32_16x16x32_bf16 v[104:107], v[140:143], v[212:215], v[104:107]
	v_mfma_f32_16x16x32_bf16 v[132:135], v[76:79], v[220:223], v[132:135]
	v_mfma_f32_16x16x32_bf16 v[100:103], v[140:143], v[220:223], v[100:103]
	v_mfma_f32_16x16x32_bf16 v[128:131], v[76:79], v[238:241], v[128:131]
	v_mfma_f32_16x16x32_bf16 v[96:99], v[140:143], v[238:241], v[96:99]
	v_mfma_f32_16x16x32_bf16 v[124:127], v[76:79], v[246:249], v[124:127]
	v_mfma_f32_16x16x32_bf16 v[92:95], v[140:143], v[246:249], v[92:95]
	v_mfma_f32_16x16x32_bf16 v[136:139], v[108:111], v[216:219], v[136:139]
	v_mfma_f32_16x16x32_bf16 v[104:107], v[144:147], v[216:219], v[104:107]
	v_mfma_f32_16x16x32_bf16 v[132:135], v[108:111], v[224:227], v[132:135]
	v_mfma_f32_16x16x32_bf16 v[100:103], v[144:147], v[224:227], v[100:103]
	v_mfma_f32_16x16x32_bf16 v[128:131], v[108:111], v[242:245], v[128:131]
	v_mfma_f32_16x16x32_bf16 v[96:99], v[144:147], v[242:245], v[96:99]
	v_mfma_f32_16x16x32_bf16 v[124:127], v[108:111], v[250:253], v[124:127]
	v_mfma_f32_16x16x32_bf16 v[92:95], v[144:147], v[250:253], v[92:95]
	s_setprio 0
	s_setprio 1
	v_mfma_f32_16x16x32_bf16 v[72:75], v[148:151], v[212:215], v[72:75]
	v_mfma_f32_16x16x32_bf16 v[40:43], v[180:183], v[212:215], v[40:43]
	v_mfma_f32_16x16x32_bf16 v[68:71], v[148:151], v[220:223], v[68:71]
	v_mfma_f32_16x16x32_bf16 v[36:39], v[180:183], v[220:223], v[36:39]
	v_mfma_f32_16x16x32_bf16 v[64:67], v[148:151], v[238:241], v[64:67]
	v_mfma_f32_16x16x32_bf16 v[32:35], v[180:183], v[238:241], v[32:35]
	v_mfma_f32_16x16x32_bf16 v[60:63], v[148:151], v[246:249], v[60:63]
	v_mfma_f32_16x16x32_bf16 v[28:31], v[180:183], v[246:249], v[28:31]
	v_mfma_f32_16x16x32_bf16 v[72:75], v[152:155], v[216:219], v[72:75]
	v_mfma_f32_16x16x32_bf16 v[40:43], v[208:211], v[216:219], v[40:43]
	v_mfma_f32_16x16x32_bf16 v[68:71], v[152:155], v[224:227], v[68:71]
	v_mfma_f32_16x16x32_bf16 v[36:39], v[208:211], v[224:227], v[36:39]
	v_mfma_f32_16x16x32_bf16 v[64:67], v[152:155], v[242:245], v[64:67]
	v_mfma_f32_16x16x32_bf16 v[32:35], v[208:211], v[242:245], v[32:35]
	v_mfma_f32_16x16x32_bf16 v[60:63], v[152:155], v[250:253], v[60:63]
	v_mfma_f32_16x16x32_bf16 v[28:31], v[208:211], v[250:253], v[28:31]
	s_barrier
	s_setprio 0
	s_add_i32 s52, s91, s33
	v_lshl_add_u64 v[18:19], v[156:157], 0, s[58:59]
	s_mov_b32 m0, s52
	ds_read_b128 v[212:215], v206 offset:49152
	ds_read_b128 v[216:219], v206 offset:50176
	ds_read_b128 v[220:223], v206 offset:51200
	ds_read_b128 v[224:227], v206 offset:52224
	ds_read_b128 v[238:241], v206 offset:53248
	ds_read_b128 v[242:245], v206 offset:54272
	ds_read_b128 v[246:249], v206 offset:55296
	ds_read_b128 v[250:253], v206 offset:56320
	global_load_lds_dwordx4 v[18:19], off
	s_add_i32 m0, s52, 0x2000
	s_add_u32 s14, s14, 0x80080
	v_lshl_add_u64 v[18:19], v[184:185], 0, s[58:59]
	s_addc_u32 s15, s15, 0
	s_add_i32 s52, s96, s33
	global_load_lds_dwordx4 v[18:19], off
	s_mov_b32 m0, s52
	v_lshl_add_u64 v[18:19], s[14:15], 0, v[160:161]
	global_load_lds_dwordx4 v[18:19], off
	s_add_i32 m0, s52, 0x2000
	v_lshl_add_u64 v[18:19], s[14:15], 0, v[164:165]
	global_load_lds_dwordx4 v[18:19], off
	s_mov_b32 m0, s55
	v_lshl_add_u64 v[18:19], v[196:197], 0, s[58:59]
	global_load_lds_dwordx4 v[18:19], off
	s_mov_b32 m0, s77
	v_lshl_add_u64 v[18:19], v[198:199], 0, s[58:59]
	global_load_lds_dwordx4 v[18:19], off
	s_waitcnt vmcnt(8) lgkmcnt(0)
	s_setprio 1
	s_barrier
	v_mfma_f32_16x16x32_bf16 v[120:123], v[76:79], v[212:215], v[120:123]
	v_mfma_f32_16x16x32_bf16 v[116:119], v[76:79], v[220:223], v[116:119]
	v_mfma_f32_16x16x32_bf16 v[112:115], v[76:79], v[238:241], v[112:115]
	v_mfma_f32_16x16x32_bf16 v[6:9], v[76:79], v[246:249], v[6:9]
	v_mfma_f32_16x16x32_bf16 v[120:123], v[108:111], v[216:219], v[120:123]
	v_mfma_f32_16x16x32_bf16 v[88:91], v[140:143], v[212:215], v[88:91]
	v_mfma_f32_16x16x32_bf16 v[116:119], v[108:111], v[224:227], v[116:119]
	v_mfma_f32_16x16x32_bf16 v[84:87], v[140:143], v[220:223], v[84:87]
	v_mfma_f32_16x16x32_bf16 v[112:115], v[108:111], v[242:245], v[112:115]
	v_mfma_f32_16x16x32_bf16 v[80:83], v[140:143], v[238:241], v[80:83]
	v_mfma_f32_16x16x32_bf16 v[108:111], v[108:111], v[250:253], v[6:9]
	v_mfma_f32_16x16x32_bf16 v[6:9], v[140:143], v[246:249], v[10:13]
	v_mfma_f32_16x16x32_bf16 v[88:91], v[144:147], v[216:219], v[88:91]
	v_mfma_f32_16x16x32_bf16 v[84:87], v[144:147], v[224:227], v[84:87]
	v_mfma_f32_16x16x32_bf16 v[80:83], v[144:147], v[242:245], v[80:83]
	v_mfma_f32_16x16x32_bf16 v[76:79], v[144:147], v[250:253], v[6:9]
	s_setprio 0
	s_setprio 1
	v_mfma_f32_16x16x32_bf16 v[6:9], v[148:151], v[212:215], v[56:59]
	v_mfma_f32_16x16x32_bf16 v[56:59], v[152:155], v[216:219], v[6:9]
	v_mfma_f32_16x16x32_bf16 v[6:9], v[180:183], v[212:215], v[24:27]
	v_mfma_f32_16x16x32_bf16 v[24:27], v[208:211], v[216:219], v[6:9]
	v_mfma_f32_16x16x32_bf16 v[6:9], v[148:151], v[220:223], v[52:55]
	v_mfma_f32_16x16x32_bf16 v[52:55], v[152:155], v[224:227], v[6:9]
	v_mfma_f32_16x16x32_bf16 v[6:9], v[180:183], v[220:223], v[20:23]
	v_mfma_f32_16x16x32_bf16 v[20:23], v[208:211], v[224:227], v[6:9]
	v_mfma_f32_16x16x32_bf16 v[6:9], v[148:151], v[238:241], v[48:51]
	v_mfma_f32_16x16x32_bf16 v[48:51], v[152:155], v[242:245], v[6:9]
	v_mfma_f32_16x16x32_bf16 v[6:9], v[180:183], v[238:241], v[14:17]
	v_mfma_f32_16x16x32_bf16 v[16:19], v[208:211], v[242:245], v[6:9]
	v_mfma_f32_16x16x32_bf16 v[6:9], v[148:151], v[246:249], v[44:47]
	v_mfma_f32_16x16x32_bf16 v[2:5], v[180:183], v[246:249], v[2:5]
	v_mfma_f32_16x16x32_bf16 v[44:47], v[152:155], v[250:253], v[6:9]
	v_mfma_f32_16x16x32_bf16 v[2:5], v[208:211], v[250:253], v[2:5]
	s_barrier
	s_setprio 0
	s_add_i32 s90, s90, 2
	s_add_u32 s8, s8, 0x100
	s_addc_u32 s9, s9, 0
	s_add_u32 s68, s68, 0x100
	s_addc_u32 s69, s69, 0
	s_cmp_gt_u32 s90, 29
	s_cbranch_scc1 .Lpeel_done_0
.LBB0_176:
	s_add_u32 s14, s8, 0xfff80080
	s_addc_u32 s15, s9, -1
	s_add_i32 s91, 0, 0x10000
	s_cmp_eq_u32 s90, 28
	s_cselect_b32 s53, s11, s15
	s_cselect_b32 s52, s13, s14
	v_add_u32_e32 v14, s91, v188
	s_cselect_b32 s15, s57, s69
	s_cselect_b32 s14, s61, s68
	s_add_i32 s96, 0, 0x14000
	ds_read_b128 v[6:9], v14
	ds_read_b128 v[10:13], v14 offset:1024
	ds_read_b128 v[140:143], v14 offset:2048
	ds_read_b128 v[144:147], v14 offset:3072
	v_add_u32_e32 v14, s96, v188
	ds_read_b128 v[148:151], v14
	ds_read_b128 v[152:155], v14 offset:1024
	ds_read_b128 v[180:183], v14 offset:2048
	ds_read_b128 v[208:211], v14 offset:3072
	v_lshl_add_u64 v[14:15], s[8:9], 0, v[176:177]
	s_add_i32 m0, s40, 0xc000
	ds_read_b128 v[212:215], v206
	ds_read_b128 v[216:219], v206 offset:1024
	ds_read_b128 v[220:223], v206 offset:2048
	ds_read_b128 v[224:227], v206 offset:3072
	ds_read_b128 v[238:241], v206 offset:4096
	ds_read_b128 v[242:245], v206 offset:5120
	ds_read_b128 v[246:249], v206 offset:6144
	ds_read_b128 v[250:253], v206 offset:7168
	global_load_lds_dwordx4 v[14:15], off
	s_add_i32 m0, s40, 0xe000
	v_lshl_add_u64 v[14:15], s[8:9], 0, v[178:179]
	global_load_lds_dwordx4 v[14:15], off
	s_waitcnt vmcnt(8) lgkmcnt(0)
	s_setprio 1
	s_barrier
	v_mfma_f32_16x16x32_bf16 v[136:139], v[6:9], v[212:215], v[136:139]
	v_mfma_f32_16x16x32_bf16 v[104:107], v[140:143], v[212:215], v[104:107]
	v_mfma_f32_16x16x32_bf16 v[132:135], v[6:9], v[220:223], v[132:135]
	v_mfma_f32_16x16x32_bf16 v[100:103], v[140:143], v[220:223], v[100:103]
	v_mfma_f32_16x16x32_bf16 v[128:131], v[6:9], v[238:241], v[128:131]
	v_mfma_f32_16x16x32_bf16 v[96:99], v[140:143], v[238:241], v[96:99]
	v_mfma_f32_16x16x32_bf16 v[124:127], v[6:9], v[246:249], v[124:127]
	v_mfma_f32_16x16x32_bf16 v[92:95], v[140:143], v[246:249], v[92:95]
	v_mfma_f32_16x16x32_bf16 v[136:139], v[10:13], v[216:219], v[136:139]
	v_mfma_f32_16x16x32_bf16 v[104:107], v[144:147], v[216:219], v[104:107]
	v_mfma_f32_16x16x32_bf16 v[132:135], v[10:13], v[224:227], v[132:135]
	v_mfma_f32_16x16x32_bf16 v[100:103], v[144:147], v[224:227], v[100:103]
	v_mfma_f32_16x16x32_bf16 v[128:131], v[10:13], v[242:245], v[128:131]
	v_mfma_f32_16x16x32_bf16 v[96:99], v[144:147], v[242:245], v[96:99]
	v_mfma_f32_16x16x32_bf16 v[124:127], v[10:13], v[250:253], v[124:127]
	v_mfma_f32_16x16x32_bf16 v[92:95], v[144:147], v[250:253], v[92:95]
	s_setprio 0
	s_setprio 1
	v_mfma_f32_16x16x32_bf16 v[72:75], v[148:151], v[212:215], v[72:75]
	v_mfma_f32_16x16x32_bf16 v[40:43], v[180:183], v[212:215], v[40:43]
	v_mfma_f32_16x16x32_bf16 v[68:71], v[148:151], v[220:223], v[68:71]
	v_mfma_f32_16x16x32_bf16 v[36:39], v[180:183], v[220:223], v[36:39]
	v_mfma_f32_16x16x32_bf16 v[64:67], v[148:151], v[238:241], v[64:67]
	v_mfma_f32_16x16x32_bf16 v[32:35], v[180:183], v[238:241], v[32:35]
	v_mfma_f32_16x16x32_bf16 v[60:63], v[148:151], v[246:249], v[60:63]
	v_mfma_f32_16x16x32_bf16 v[28:31], v[180:183], v[246:249], v[28:31]
	v_mfma_f32_16x16x32_bf16 v[72:75], v[152:155], v[216:219], v[72:75]
	v_mfma_f32_16x16x32_bf16 v[40:43], v[208:211], v[216:219], v[40:43]
	v_mfma_f32_16x16x32_bf16 v[68:71], v[152:155], v[224:227], v[68:71]
	v_mfma_f32_16x16x32_bf16 v[36:39], v[208:211], v[224:227], v[36:39]
	v_mfma_f32_16x16x32_bf16 v[64:67], v[152:155], v[242:245], v[64:67]
	v_mfma_f32_16x16x32_bf16 v[32:35], v[208:211], v[242:245], v[32:35]
	v_mfma_f32_16x16x32_bf16 v[60:63], v[152:155], v[250:253], v[60:63]
	v_mfma_f32_16x16x32_bf16 v[28:31], v[208:211], v[250:253], v[28:31]
	s_setprio 0
	s_barrier
	s_add_i32 s91, s91, s33
	v_lshl_add_u64 v[156:157], s[14:15], 0, v[160:161]
	s_mov_b32 m0, s91
	ds_read_b128 v[212:215], v206 offset:16384
	ds_read_b128 v[216:219], v206 offset:17408
	ds_read_b128 v[220:223], v206 offset:18432
	ds_read_b128 v[224:227], v206 offset:19456
	ds_read_b128 v[238:241], v206 offset:20480
	ds_read_b128 v[242:245], v206 offset:21504
	ds_read_b128 v[246:249], v206 offset:22528
	ds_read_b128 v[250:253], v206 offset:23552
	global_load_lds_dwordx4 v[156:157], off
	s_add_i32 m0, s91, 0x2000
	s_add_u32 vcc_lo, s14, 0x80000
	v_lshl_add_u64 v[184:185], s[14:15], 0, v[164:165]
	s_addc_u32 vcc_hi, s15, 0
	s_add_i32 s91, s96, s33
	global_load_lds_dwordx4 v[184:185], off
	v_lshl_add_u64 v[14:15], vcc, 0, v[160:161]
	s_mov_b32 m0, s91
	v_lshl_add_u64 v[196:197], s[52:53], 0, v[158:159]
	global_load_lds_dwordx4 v[14:15], off
	v_lshl_add_u64 v[14:15], vcc, 0, v[164:165]
	s_add_i32 m0, s91, 0x2000
	v_lshl_add_u64 v[198:199], s[52:53], 0, v[162:163]
	global_load_lds_dwordx4 v[14:15], off
	s_mov_b32 m0, s40
	s_nop 0
	global_load_lds_dwordx4 v[196:197], off
	s_mov_b32 m0, s41
	s_nop 0
	global_load_lds_dwordx4 v[198:199], off
	s_waitcnt vmcnt(8) lgkmcnt(0)
	s_setprio 1
	s_barrier
	v_mfma_f32_16x16x32_bf16 v[120:123], v[6:9], v[212:215], v[120:123]
	v_mfma_f32_16x16x32_bf16 v[88:91], v[140:143], v[212:215], v[88:91]
	v_mfma_f32_16x16x32_bf16 v[116:119], v[6:9], v[220:223], v[116:119]
	v_mfma_f32_16x16x32_bf16 v[84:87], v[140:143], v[220:223], v[84:87]
	v_mfma_f32_16x16x32_bf16 v[112:115], v[6:9], v[238:241], v[112:115]
	v_mfma_f32_16x16x32_bf16 v[80:83], v[140:143], v[238:241], v[80:83]
	v_mfma_f32_16x16x32_bf16 v[6:9], v[6:9], v[246:249], v[108:111]
	v_mfma_f32_16x16x32_bf16 v[120:123], v[10:13], v[216:219], v[120:123]
	v_mfma_f32_16x16x32_bf16 v[88:91], v[144:147], v[216:219], v[88:91]
	v_mfma_f32_16x16x32_bf16 v[116:119], v[10:13], v[224:227], v[116:119]
	v_mfma_f32_16x16x32_bf16 v[84:87], v[144:147], v[224:227], v[84:87]
	v_mfma_f32_16x16x32_bf16 v[112:115], v[10:13], v[242:245], v[112:115]
	v_mfma_f32_16x16x32_bf16 v[80:83], v[144:147], v[242:245], v[80:83]
	v_mfma_f32_16x16x32_bf16 v[6:9], v[10:13], v[250:253], v[6:9]
	v_mfma_f32_16x16x32_bf16 v[10:13], v[140:143], v[246:249], v[76:79]
	v_mfma_f32_16x16x32_bf16 v[10:13], v[144:147], v[250:253], v[10:13]
	s_setprio 0
	s_setprio 1
	v_mfma_f32_16x16x32_bf16 v[56:59], v[148:151], v[212:215], v[56:59]
	v_mfma_f32_16x16x32_bf16 v[24:27], v[180:183], v[212:215], v[24:27]
	v_mfma_f32_16x16x32_bf16 v[52:55], v[148:151], v[220:223], v[52:55]
	v_mfma_f32_16x16x32_bf16 v[20:23], v[180:183], v[220:223], v[20:23]
	v_mfma_f32_16x16x32_bf16 v[48:51], v[148:151], v[238:241], v[48:51]
	v_mfma_f32_16x16x32_bf16 v[14:17], v[180:183], v[238:241], v[16:19]
	v_mfma_f32_16x16x32_bf16 v[44:47], v[148:151], v[246:249], v[44:47]
	v_mfma_f32_16x16x32_bf16 v[2:5], v[180:183], v[246:249], v[2:5]
	v_mfma_f32_16x16x32_bf16 v[56:59], v[152:155], v[216:219], v[56:59]
	v_mfma_f32_16x16x32_bf16 v[24:27], v[208:211], v[216:219], v[24:27]
	v_mfma_f32_16x16x32_bf16 v[52:55], v[152:155], v[224:227], v[52:55]
	v_mfma_f32_16x16x32_bf16 v[20:23], v[208:211], v[224:227], v[20:23]
	v_mfma_f32_16x16x32_bf16 v[48:51], v[152:155], v[242:245], v[48:51]
	v_mfma_f32_16x16x32_bf16 v[14:17], v[208:211], v[242:245], v[14:17]
	v_mfma_f32_16x16x32_bf16 v[44:47], v[152:155], v[250:253], v[44:47]
	v_mfma_f32_16x16x32_bf16 v[2:5], v[208:211], v[250:253], v[2:5]
	s_setprio 0
	s_barrier
	s_add_i32 s91, 0, 0x18000
	v_add_u32_e32 v18, s91, v188
	s_add_i32 s96, 0, 0x1c000
	ds_read_b128 v[76:79], v18
	ds_read_b128 v[108:111], v18 offset:1024
	ds_read_b128 v[140:143], v18 offset:2048
	ds_read_b128 v[144:147], v18 offset:3072
	v_add_u32_e32 v18, s96, v188
	ds_read_b128 v[148:151], v18
	ds_read_b128 v[152:155], v18 offset:1024
	ds_read_b128 v[180:183], v18 offset:2048
	ds_read_b128 v[208:211], v18 offset:3072
	s_add_u32 s52, s52, 0x80000
	s_addc_u32 s53, s53, 0
	s_mov_b32 m0, s42
	v_lshl_add_u64 v[18:19], s[52:53], 0, v[158:159]
	ds_read_b128 v[212:215], v206 offset:32768
	ds_read_b128 v[216:219], v206 offset:33792
	ds_read_b128 v[220:223], v206 offset:34816
	ds_read_b128 v[224:227], v206 offset:35840
	ds_read_b128 v[238:241], v206 offset:36864
	ds_read_b128 v[242:245], v206 offset:37888
	ds_read_b128 v[246:249], v206 offset:38912
	ds_read_b128 v[250:253], v206 offset:39936
	global_load_lds_dwordx4 v[18:19], off
	s_mov_b32 m0, s43
	v_lshl_add_u64 v[18:19], s[52:53], 0, v[162:163]
	global_load_lds_dwordx4 v[18:19], off
	s_waitcnt vmcnt(8) lgkmcnt(0)
	s_setprio 1
	s_barrier
	v_mfma_f32_16x16x32_bf16 v[136:139], v[76:79], v[212:215], v[136:139]
	v_mfma_f32_16x16x32_bf16 v[104:107], v[140:143], v[212:215], v[104:107]
	v_mfma_f32_16x16x32_bf16 v[132:135], v[76:79], v[220:223], v[132:135]
	v_mfma_f32_16x16x32_bf16 v[100:103], v[140:143], v[220:223], v[100:103]
	v_mfma_f32_16x16x32_bf16 v[128:131], v[76:79], v[238:241], v[128:131]
	v_mfma_f32_16x16x32_bf16 v[96:99], v[140:143], v[238:241], v[96:99]
	v_mfma_f32_16x16x32_bf16 v[124:127], v[76:79], v[246:249], v[124:127]
	v_mfma_f32_16x16x32_bf16 v[92:95], v[140:143], v[246:249], v[92:95]
	v_mfma_f32_16x16x32_bf16 v[136:139], v[108:111], v[216:219], v[136:139]
	v_mfma_f32_16x16x32_bf16 v[104:107], v[144:147], v[216:219], v[104:107]
	v_mfma_f32_16x16x32_bf16 v[132:135], v[108:111], v[224:227], v[132:135]
	v_mfma_f32_16x16x32_bf16 v[100:103], v[144:147], v[224:227], v[100:103]
	v_mfma_f32_16x16x32_bf16 v[128:131], v[108:111], v[242:245], v[128:131]
	v_mfma_f32_16x16x32_bf16 v[96:99], v[144:147], v[242:245], v[96:99]
	v_mfma_f32_16x16x32_bf16 v[124:127], v[108:111], v[250:253], v[124:127]
	v_mfma_f32_16x16x32_bf16 v[92:95], v[144:147], v[250:253], v[92:95]
	s_setprio 0
	s_setprio 1
	v_mfma_f32_16x16x32_bf16 v[72:75], v[148:151], v[212:215], v[72:75]
	v_mfma_f32_16x16x32_bf16 v[40:43], v[180:183], v[212:215], v[40:43]
	v_mfma_f32_16x16x32_bf16 v[68:71], v[148:151], v[220:223], v[68:71]
	v_mfma_f32_16x16x32_bf16 v[36:39], v[180:183], v[220:223], v[36:39]
	v_mfma_f32_16x16x32_bf16 v[64:67], v[148:151], v[238:241], v[64:67]
	v_mfma_f32_16x16x32_bf16 v[32:35], v[180:183], v[238:241], v[32:35]
	v_mfma_f32_16x16x32_bf16 v[60:63], v[148:151], v[246:249], v[60:63]
	v_mfma_f32_16x16x32_bf16 v[28:31], v[180:183], v[246:249], v[28:31]
	v_mfma_f32_16x16x32_bf16 v[72:75], v[152:155], v[216:219], v[72:75]
	v_mfma_f32_16x16x32_bf16 v[40:43], v[208:211], v[216:219], v[40:43]
	v_mfma_f32_16x16x32_bf16 v[68:71], v[152:155], v[224:227], v[68:71]
	v_mfma_f32_16x16x32_bf16 v[36:39], v[208:211], v[224:227], v[36:39]
	v_mfma_f32_16x16x32_bf16 v[64:67], v[152:155], v[242:245], v[64:67]
	v_mfma_f32_16x16x32_bf16 v[32:35], v[208:211], v[242:245], v[32:35]
	v_mfma_f32_16x16x32_bf16 v[60:63], v[152:155], v[250:253], v[60:63]
	v_mfma_f32_16x16x32_bf16 v[28:31], v[208:211], v[250:253], v[28:31]
	s_setprio 0
	s_barrier
	s_add_i32 s52, s91, s33
	v_lshl_add_u64 v[18:19], v[156:157], 0, s[58:59]
	s_mov_b32 m0, s52
	ds_read_b128 v[212:215], v206 offset:49152
	ds_read_b128 v[216:219], v206 offset:50176
	ds_read_b128 v[220:223], v206 offset:51200
	ds_read_b128 v[224:227], v206 offset:52224
	ds_read_b128 v[238:241], v206 offset:53248
	ds_read_b128 v[242:245], v206 offset:54272
	ds_read_b128 v[246:249], v206 offset:55296
	ds_read_b128 v[250:253], v206 offset:56320
	global_load_lds_dwordx4 v[18:19], off
	s_add_i32 m0, s52, 0x2000
	s_add_u32 s14, s14, 0x80080
	v_lshl_add_u64 v[18:19], v[184:185], 0, s[58:59]
	s_addc_u32 s15, s15, 0
	s_add_i32 s52, s96, s33
	global_load_lds_dwordx4 v[18:19], off
	s_mov_b32 m0, s52
	v_lshl_add_u64 v[18:19], s[14:15], 0, v[160:161]
	global_load_lds_dwordx4 v[18:19], off
	s_add_i32 m0, s52, 0x2000
	v_lshl_add_u64 v[18:19], s[14:15], 0, v[164:165]
	global_load_lds_dwordx4 v[18:19], off
	s_mov_b32 m0, s55
	v_lshl_add_u64 v[18:19], v[196:197], 0, s[58:59]
	global_load_lds_dwordx4 v[18:19], off
	s_mov_b32 m0, s77
	v_lshl_add_u64 v[18:19], v[198:199], 0, s[58:59]
	global_load_lds_dwordx4 v[18:19], off
	s_waitcnt vmcnt(8) lgkmcnt(0)
	s_setprio 1
	s_barrier
	v_mfma_f32_16x16x32_bf16 v[120:123], v[76:79], v[212:215], v[120:123]
	v_mfma_f32_16x16x32_bf16 v[116:119], v[76:79], v[220:223], v[116:119]
	v_mfma_f32_16x16x32_bf16 v[112:115], v[76:79], v[238:241], v[112:115]
	v_mfma_f32_16x16x32_bf16 v[6:9], v[76:79], v[246:249], v[6:9]
	v_mfma_f32_16x16x32_bf16 v[120:123], v[108:111], v[216:219], v[120:123]
	v_mfma_f32_16x16x32_bf16 v[88:91], v[140:143], v[212:215], v[88:91]
	v_mfma_f32_16x16x32_bf16 v[116:119], v[108:111], v[224:227], v[116:119]
	v_mfma_f32_16x16x32_bf16 v[84:87], v[140:143], v[220:223], v[84:87]
	v_mfma_f32_16x16x32_bf16 v[112:115], v[108:111], v[242:245], v[112:115]
	v_mfma_f32_16x16x32_bf16 v[80:83], v[140:143], v[238:241], v[80:83]
	v_mfma_f32_16x16x32_bf16 v[108:111], v[108:111], v[250:253], v[6:9]
	v_mfma_f32_16x16x32_bf16 v[6:9], v[140:143], v[246:249], v[10:13]
	v_mfma_f32_16x16x32_bf16 v[88:91], v[144:147], v[216:219], v[88:91]
	v_mfma_f32_16x16x32_bf16 v[84:87], v[144:147], v[224:227], v[84:87]
	v_mfma_f32_16x16x32_bf16 v[80:83], v[144:147], v[242:245], v[80:83]
	v_mfma_f32_16x16x32_bf16 v[76:79], v[144:147], v[250:253], v[6:9]
	s_setprio 0
	s_setprio 1
	v_mfma_f32_16x16x32_bf16 v[6:9], v[148:151], v[212:215], v[56:59]
	v_mfma_f32_16x16x32_bf16 v[56:59], v[152:155], v[216:219], v[6:9]
	v_mfma_f32_16x16x32_bf16 v[6:9], v[180:183], v[212:215], v[24:27]
	v_mfma_f32_16x16x32_bf16 v[24:27], v[208:211], v[216:219], v[6:9]
	v_mfma_f32_16x16x32_bf16 v[6:9], v[148:151], v[220:223], v[52:55]
	v_mfma_f32_16x16x32_bf16 v[52:55], v[152:155], v[224:227], v[6:9]
	v_mfma_f32_16x16x32_bf16 v[6:9], v[180:183], v[220:223], v[20:23]
	v_mfma_f32_16x16x32_bf16 v[20:23], v[208:211], v[224:227], v[6:9]
	v_mfma_f32_16x16x32_bf16 v[6:9], v[148:151], v[238:241], v[48:51]
	v_mfma_f32_16x16x32_bf16 v[48:51], v[152:155], v[242:245], v[6:9]
	v_mfma_f32_16x16x32_bf16 v[6:9], v[180:183], v[238:241], v[14:17]
	v_mfma_f32_16x16x32_bf16 v[16:19], v[208:211], v[242:245], v[6:9]
	v_mfma_f32_16x16x32_bf16 v[6:9], v[148:151], v[246:249], v[44:47]
	v_mfma_f32_16x16x32_bf16 v[2:5], v[180:183], v[246:249], v[2:5]
	v_mfma_f32_16x16x32_bf16 v[44:47], v[152:155], v[250:253], v[6:9]
	v_mfma_f32_16x16x32_bf16 v[2:5], v[208:211], v[250:253], v[2:5]
	s_setprio 0
	s_barrier
	s_add_i32 s90, s90, 2
	s_add_u32 s8, s8, 0x100
	s_addc_u32 s9, s9, 0
	s_add_u32 s68, s68, 0x100
	s_addc_u32 s69, s69, 0
	s_cmp_gt_u32 s90, 29
	s_cbranch_scc0 .LBB0_176

.LBB0_671:
	s_ashr_i32 s11, s10, 31
	s_lshl_b64 s[12:13], s[10:11], 20
	v_readlane_b32 s14, v254, 17
	v_readlane_b32 s15, v254, 18
	s_add_u32 s12, s14, s12
	s_addc_u32 s13, s15, s13
	s_and_b64 s[14:15], s[4:5], exec
	s_cselect_b32 s11, s13, s23
	s_cselect_b32 s18, s12, s22
	s_ashr_i32 s9, s8, 31
	s_lshl_b64 s[14:15], s[8:9], 20
	v_readlane_b32 s26, v254, 44
	v_readlane_b32 s27, v254, 45
	s_add_u32 s14, s26, s14
	s_addc_u32 s15, s27, s15
	s_and_b64 s[26:27], s[4:5], exec
	s_cselect_b32 s9, s15, s25
	s_cselect_b32 s19, s14, s24
	s_add_u32 s22, s22, 0x80080
	s_addc_u32 s23, s23, 0
	s_add_u32 s21, s24, 0x100
	s_addc_u32 s33, s25, 0
	s_mov_b32 s40, -2
	v_readlane_b32 s41, v255, 49
	s_nop 3
	s_cmp_eq_u32 s41, 2
	v_writelane_b32 v255, 2, 49
	s_cbranch_scc0 .Ltrip0_strict_1
	s_add_u32 s24, s22, 0xfff80080
	s_addc_u32 s25, s23, -1
	s_add_i32 s41, 0, 0x10000
	s_cmp_eq_u32 s40, 28
	s_cselect_b32 s27, s11, s25
	s_cselect_b32 s26, s18, s24
	s_cselect_b32 s25, s9, s33
	s_cselect_b32 s24, s19, s21
	s_add_i32 s46, 0, 0x14000
	v_add_u32_e32 v142, s41, v214
	v_add_u32_e32 v158, s46, v214
	ds_read_b128 v[130:133], v142
	ds_read_b128 v[134:137], v142 offset:1024
	ds_read_b128 v[138:141], v142 offset:2048
	ds_read_b128 v[142:145], v142 offset:3072
	ds_read_b128 v[146:149], v158
	ds_read_b128 v[150:153], v158 offset:1024
	ds_read_b128 v[154:157], v158 offset:2048
	ds_read_b128 v[158:161], v158 offset:3072
	v_lshl_add_u64 v[212:213], s[22:23], 0, v[182:183]
	s_add_i32 m0, s17, 0xc000
	ds_read_b128 v[162:165], v216
	ds_read_b128 v[166:169], v216 offset:1024
	ds_read_b128 v[170:173], v216 offset:2048
	ds_read_b128 v[186:189], v216 offset:3072
	ds_read_b128 v[196:199], v216 offset:4096
	ds_read_b128 v[200:203], v216 offset:5120
	ds_read_b128 v[204:207], v216 offset:6144
	ds_read_b128 v[208:211], v216 offset:7168
	global_load_lds_dwordx4 v[212:213], off
	s_add_i32 m0, s17, 0xe000
	v_lshl_add_u64 v[212:213], s[22:23], 0, v[184:185]
	global_load_lds_dwordx4 v[212:213], off
	s_waitcnt vmcnt(24) lgkmcnt(0)
	s_setprio 1
	s_barrier
	v_mfma_f32_16x16x32_bf16 v[126:129], v[130:133], v[162:165], 0
	v_mfma_f32_16x16x32_bf16 v[122:125], v[138:141], v[162:165], 0
	v_mfma_f32_16x16x32_bf16 v[110:113], v[130:133], v[170:173], 0
	v_mfma_f32_16x16x32_bf16 v[106:109], v[138:141], v[170:173], 0
	v_mfma_f32_16x16x32_bf16 v[94:97], v[130:133], v[196:199], 0
	v_mfma_f32_16x16x32_bf16 v[90:93], v[138:141], v[196:199], 0
	v_mfma_f32_16x16x32_bf16 v[78:81], v[130:133], v[204:207], 0
	v_mfma_f32_16x16x32_bf16 v[74:77], v[138:141], v[204:207], 0
	v_mfma_f32_16x16x32_bf16 v[126:129], v[134:137], v[166:169], v[126:129]
	v_mfma_f32_16x16x32_bf16 v[122:125], v[142:145], v[166:169], v[122:125]
	v_mfma_f32_16x16x32_bf16 v[110:113], v[134:137], v[186:189], v[110:113]
	v_mfma_f32_16x16x32_bf16 v[106:109], v[142:145], v[186:189], v[106:109]
	v_mfma_f32_16x16x32_bf16 v[94:97], v[134:137], v[200:203], v[94:97]
	v_mfma_f32_16x16x32_bf16 v[90:93], v[142:145], v[200:203], v[90:93]
	v_mfma_f32_16x16x32_bf16 v[78:81], v[134:137], v[208:211], v[78:81]
	v_mfma_f32_16x16x32_bf16 v[74:77], v[142:145], v[208:211], v[74:77]
	s_setprio 0
	s_setprio 1
	v_mfma_f32_16x16x32_bf16 v[118:121], v[146:149], v[162:165], 0
	v_mfma_f32_16x16x32_bf16 v[114:117], v[154:157], v[162:165], 0
	v_mfma_f32_16x16x32_bf16 v[102:105], v[146:149], v[170:173], 0
	v_mfma_f32_16x16x32_bf16 v[98:101], v[154:157], v[170:173], 0
	v_mfma_f32_16x16x32_bf16 v[86:89], v[146:149], v[196:199], 0
	v_mfma_f32_16x16x32_bf16 v[82:85], v[154:157], v[196:199], 0
	v_mfma_f32_16x16x32_bf16 v[70:73], v[146:149], v[204:207], 0
	v_mfma_f32_16x16x32_bf16 v[66:69], v[154:157], v[204:207], 0
	v_mfma_f32_16x16x32_bf16 v[118:121], v[150:153], v[166:169], v[118:121]
	v_mfma_f32_16x16x32_bf16 v[114:117], v[158:161], v[166:169], v[114:117]
	v_mfma_f32_16x16x32_bf16 v[102:105], v[150:153], v[186:189], v[102:105]
	v_mfma_f32_16x16x32_bf16 v[98:101], v[158:161], v[186:189], v[98:101]
	v_mfma_f32_16x16x32_bf16 v[86:89], v[150:153], v[200:203], v[86:89]
	v_mfma_f32_16x16x32_bf16 v[82:85], v[158:161], v[200:203], v[82:85]
	v_mfma_f32_16x16x32_bf16 v[70:73], v[150:153], v[208:211], v[70:73]
	v_mfma_f32_16x16x32_bf16 v[66:69], v[158:161], v[208:211], v[66:69]
	s_barrier
	s_setprio 0
	s_add_i32 s41, s41, s29
	v_lshl_add_u64 v[212:213], s[24:25], 0, v[178:179]
	s_mov_b32 m0, s41
	ds_read_b128 v[162:165], v216 offset:16384
	ds_read_b128 v[166:169], v216 offset:17408
	ds_read_b128 v[170:173], v216 offset:18432
	ds_read_b128 v[186:189], v216 offset:19456
	ds_read_b128 v[196:199], v216 offset:20480
	ds_read_b128 v[200:203], v216 offset:21504
	ds_read_b128 v[204:207], v216 offset:22528
	ds_read_b128 v[208:211], v216 offset:23552
	global_load_lds_dwordx4 v[212:213], off
	s_add_i32 m0, s41, 0x2000
	s_add_u32 s42, s24, 0x80000
	v_lshl_add_u64 v[218:219], s[24:25], 0, v[174:175]
	s_addc_u32 s43, s25, 0
	s_add_i32 s41, s46, s29
	global_load_lds_dwordx4 v[218:219], off
	v_lshl_add_u64 v[220:221], s[42:43], 0, v[178:179]
	s_mov_b32 m0, s41
	v_lshl_add_u64 v[222:223], s[26:27], 0, v[176:177]
	global_load_lds_dwordx4 v[220:221], off
	s_add_i32 m0, s41, 0x2000
	v_lshl_add_u64 v[220:221], s[42:43], 0, v[174:175]
	global_load_lds_dwordx4 v[220:221], off
	s_mov_b32 m0, s17
	v_lshl_add_u64 v[220:221], s[26:27], 0, v[180:181]
	global_load_lds_dwordx4 v[220:221], off
	s_mov_b32 m0, s31
	s_nop 0
	global_load_lds_dwordx4 v[222:223], off
	s_waitcnt vmcnt(24) lgkmcnt(0)
	s_setprio 1
	s_barrier
	v_mfma_f32_16x16x32_bf16 v[62:65], v[130:133], v[162:165], 0
	v_mfma_f32_16x16x32_bf16 v[58:61], v[138:141], v[162:165], 0
	v_mfma_f32_16x16x32_bf16 v[46:49], v[130:133], v[170:173], 0
	v_mfma_f32_16x16x32_bf16 v[42:45], v[138:141], v[170:173], 0
	v_mfma_f32_16x16x32_bf16 v[30:33], v[130:133], v[196:199], 0
	v_mfma_f32_16x16x32_bf16 v[26:29], v[138:141], v[196:199], 0
	v_mfma_f32_16x16x32_bf16 v[14:17], v[130:133], v[204:207], 0
	v_mfma_f32_16x16x32_bf16 v[10:13], v[138:141], v[204:207], 0
	v_mfma_f32_16x16x32_bf16 v[62:65], v[134:137], v[166:169], v[62:65]
	v_mfma_f32_16x16x32_bf16 v[58:61], v[142:145], v[166:169], v[58:61]
	v_mfma_f32_16x16x32_bf16 v[46:49], v[134:137], v[186:189], v[46:49]
	v_mfma_f32_16x16x32_bf16 v[42:45], v[142:145], v[186:189], v[42:45]
	v_mfma_f32_16x16x32_bf16 v[30:33], v[134:137], v[200:203], v[30:33]
	v_mfma_f32_16x16x32_bf16 v[26:29], v[142:145], v[200:203], v[26:29]
	v_mfma_f32_16x16x32_bf16 v[14:17], v[134:137], v[208:211], v[14:17]
	v_mfma_f32_16x16x32_bf16 v[10:13], v[142:145], v[208:211], v[10:13]
	s_setprio 0
	s_setprio 1
	v_mfma_f32_16x16x32_bf16 v[54:57], v[146:149], v[162:165], 0
	v_mfma_f32_16x16x32_bf16 v[50:53], v[154:157], v[162:165], 0
	v_mfma_f32_16x16x32_bf16 v[38:41], v[146:149], v[170:173], 0
	v_mfma_f32_16x16x32_bf16 v[34:37], v[154:157], v[170:173], 0
	v_mfma_f32_16x16x32_bf16 v[22:25], v[146:149], v[196:199], 0
	v_mfma_f32_16x16x32_bf16 v[18:21], v[154:157], v[196:199], 0
	v_mfma_f32_16x16x32_bf16 v[6:9], v[146:149], v[204:207], 0
	v_mfma_f32_16x16x32_bf16 v[2:5], v[154:157], v[204:207], 0
	v_mfma_f32_16x16x32_bf16 v[54:57], v[150:153], v[166:169], v[54:57]
	v_mfma_f32_16x16x32_bf16 v[50:53], v[158:161], v[166:169], v[50:53]
	v_mfma_f32_16x16x32_bf16 v[38:41], v[150:153], v[186:189], v[38:41]
	v_mfma_f32_16x16x32_bf16 v[34:37], v[158:161], v[186:189], v[34:37]
	v_mfma_f32_16x16x32_bf16 v[22:25], v[150:153], v[200:203], v[22:25]
	v_mfma_f32_16x16x32_bf16 v[18:21], v[158:161], v[200:203], v[18:21]
	v_mfma_f32_16x16x32_bf16 v[6:9], v[150:153], v[208:211], v[6:9]
	v_mfma_f32_16x16x32_bf16 v[2:5], v[158:161], v[208:211], v[2:5]
	s_barrier
	s_setprio 0
	s_add_i32 s41, 0, 0x18000
	s_add_i32 s42, 0, 0x1c000
	v_add_u32_e32 v142, s41, v214
	v_add_u32_e32 v158, s42, v214
	ds_read_b128 v[130:133], v142
	ds_read_b128 v[134:137], v142 offset:1024
	ds_read_b128 v[138:141], v142 offset:2048
	ds_read_b128 v[142:145], v142 offset:3072
	ds_read_b128 v[146:149], v158
	ds_read_b128 v[150:153], v158 offset:1024
	ds_read_b128 v[154:157], v158 offset:2048
	ds_read_b128 v[158:161], v158 offset:3072
	s_add_u32 s26, s26, 0x80000
	s_addc_u32 s27, s27, 0
	s_mov_b32 m0, s34
	v_lshl_add_u64 v[224:225], s[26:27], 0, v[180:181]
	ds_read_b128 v[162:165], v216 offset:32768
	ds_read_b128 v[166:169], v216 offset:33792
	ds_read_b128 v[170:173], v216 offset:34816
	ds_read_b128 v[186:189], v216 offset:35840
	ds_read_b128 v[196:199], v216 offset:36864
	ds_read_b128 v[200:203], v216 offset:37888
	ds_read_b128 v[204:207], v216 offset:38912
	ds_read_b128 v[208:211], v216 offset:39936
	global_load_lds_dwordx4 v[224:225], off
	s_mov_b32 m0, s35
	v_lshl_add_u64 v[224:225], s[26:27], 0, v[176:177]
	global_load_lds_dwordx4 v[224:225], off
	s_waitcnt vmcnt(8) lgkmcnt(0)
	s_setprio 1
	s_barrier
	v_mfma_f32_16x16x32_bf16 v[126:129], v[130:133], v[162:165], v[126:129]
	v_mfma_f32_16x16x32_bf16 v[122:125], v[138:141], v[162:165], v[122:125]
	v_mfma_f32_16x16x32_bf16 v[110:113], v[130:133], v[170:173], v[110:113]
	v_mfma_f32_16x16x32_bf16 v[106:109], v[138:141], v[170:173], v[106:109]
	v_mfma_f32_16x16x32_bf16 v[94:97], v[130:133], v[196:199], v[94:97]
	v_mfma_f32_16x16x32_bf16 v[90:93], v[138:141], v[196:199], v[90:93]
	v_mfma_f32_16x16x32_bf16 v[78:81], v[130:133], v[204:207], v[78:81]
	v_mfma_f32_16x16x32_bf16 v[74:77], v[138:141], v[204:207], v[74:77]
	v_mfma_f32_16x16x32_bf16 v[126:129], v[134:137], v[166:169], v[126:129]
	v_mfma_f32_16x16x32_bf16 v[122:125], v[142:145], v[166:169], v[122:125]
	v_mfma_f32_16x16x32_bf16 v[110:113], v[134:137], v[186:189], v[110:113]
	v_mfma_f32_16x16x32_bf16 v[106:109], v[142:145], v[186:189], v[106:109]
	v_mfma_f32_16x16x32_bf16 v[94:97], v[134:137], v[200:203], v[94:97]
	v_mfma_f32_16x16x32_bf16 v[90:93], v[142:145], v[200:203], v[90:93]
	v_mfma_f32_16x16x32_bf16 v[78:81], v[134:137], v[208:211], v[78:81]
	v_mfma_f32_16x16x32_bf16 v[74:77], v[142:145], v[208:211], v[74:77]
	s_setprio 0
	s_setprio 1
	v_mfma_f32_16x16x32_bf16 v[118:121], v[146:149], v[162:165], v[118:121]
	v_mfma_f32_16x16x32_bf16 v[114:117], v[154:157], v[162:165], v[114:117]
	v_mfma_f32_16x16x32_bf16 v[102:105], v[146:149], v[170:173], v[102:105]
	v_mfma_f32_16x16x32_bf16 v[98:101], v[154:157], v[170:173], v[98:101]
	v_mfma_f32_16x16x32_bf16 v[86:89], v[146:149], v[196:199], v[86:89]
	v_mfma_f32_16x16x32_bf16 v[82:85], v[154:157], v[196:199], v[82:85]
	v_mfma_f32_16x16x32_bf16 v[70:73], v[146:149], v[204:207], v[70:73]
	v_mfma_f32_16x16x32_bf16 v[66:69], v[154:157], v[204:207], v[66:69]
	v_mfma_f32_16x16x32_bf16 v[118:121], v[150:153], v[166:169], v[118:121]
	v_mfma_f32_16x16x32_bf16 v[114:117], v[158:161], v[166:169], v[114:117]
	v_mfma_f32_16x16x32_bf16 v[102:105], v[150:153], v[186:189], v[102:105]
	v_mfma_f32_16x16x32_bf16 v[98:101], v[158:161], v[186:189], v[98:101]
	v_mfma_f32_16x16x32_bf16 v[86:89], v[150:153], v[200:203], v[86:89]
	v_mfma_f32_16x16x32_bf16 v[82:85], v[158:161], v[200:203], v[82:85]
	v_mfma_f32_16x16x32_bf16 v[70:73], v[150:153], v[208:211], v[70:73]
	v_mfma_f32_16x16x32_bf16 v[66:69], v[158:161], v[208:211], v[66:69]
	s_barrier
	s_setprio 0
	s_add_i32 s26, s41, s29
	v_lshl_add_u64 v[212:213], v[212:213], 0, s[58:59]
	s_mov_b32 m0, s26
	ds_read_b128 v[162:165], v216 offset:49152
	ds_read_b128 v[166:169], v216 offset:50176
	ds_read_b128 v[170:173], v216 offset:51200
	ds_read_b128 v[186:189], v216 offset:52224
	ds_read_b128 v[196:199], v216 offset:53248
	ds_read_b128 v[200:203], v216 offset:54272
	ds_read_b128 v[204:207], v216 offset:55296
	ds_read_b128 v[208:211], v216 offset:56320
	global_load_lds_dwordx4 v[212:213], off
	s_add_i32 m0, s26, 0x2000
	s_add_u32 s24, s24, 0x80080
	v_lshl_add_u64 v[212:213], v[218:219], 0, s[58:59]
	s_addc_u32 s25, s25, 0
	s_add_i32 s26, s42, s29
	global_load_lds_dwordx4 v[212:213], off
	s_mov_b32 m0, s26
	v_lshl_add_u64 v[212:213], s[24:25], 0, v[178:179]
	global_load_lds_dwordx4 v[212:213], off
	s_add_i32 m0, s26, 0x2000
	v_lshl_add_u64 v[212:213], s[24:25], 0, v[174:175]
	global_load_lds_dwordx4 v[212:213], off
	s_mov_b32 m0, s38
	v_lshl_add_u64 v[212:213], v[220:221], 0, s[58:59]
	global_load_lds_dwordx4 v[212:213], off
	s_mov_b32 m0, s39
	v_lshl_add_u64 v[212:213], v[222:223], 0, s[58:59]
	global_load_lds_dwordx4 v[212:213], off
	s_waitcnt vmcnt(8) lgkmcnt(0)
	s_setprio 1
	s_barrier
	v_mfma_f32_16x16x32_bf16 v[62:65], v[130:133], v[162:165], v[62:65]
	v_mfma_f32_16x16x32_bf16 v[58:61], v[138:141], v[162:165], v[58:61]
	v_mfma_f32_16x16x32_bf16 v[46:49], v[130:133], v[170:173], v[46:49]
	v_mfma_f32_16x16x32_bf16 v[42:45], v[138:141], v[170:173], v[42:45]
	v_mfma_f32_16x16x32_bf16 v[30:33], v[130:133], v[196:199], v[30:33]
	v_mfma_f32_16x16x32_bf16 v[26:29], v[138:141], v[196:199], v[26:29]
	v_mfma_f32_16x16x32_bf16 v[14:17], v[130:133], v[204:207], v[14:17]
	v_mfma_f32_16x16x32_bf16 v[10:13], v[138:141], v[204:207], v[10:13]
	v_mfma_f32_16x16x32_bf16 v[62:65], v[134:137], v[166:169], v[62:65]
	v_mfma_f32_16x16x32_bf16 v[58:61], v[142:145], v[166:169], v[58:61]
	v_mfma_f32_16x16x32_bf16 v[46:49], v[134:137], v[186:189], v[46:49]
	v_mfma_f32_16x16x32_bf16 v[42:45], v[142:145], v[186:189], v[42:45]
	v_mfma_f32_16x16x32_bf16 v[30:33], v[134:137], v[200:203], v[30:33]
	v_mfma_f32_16x16x32_bf16 v[26:29], v[142:145], v[200:203], v[26:29]
	v_mfma_f32_16x16x32_bf16 v[14:17], v[134:137], v[208:211], v[14:17]
	v_mfma_f32_16x16x32_bf16 v[10:13], v[142:145], v[208:211], v[10:13]
	s_setprio 0
	s_setprio 1
	v_mfma_f32_16x16x32_bf16 v[54:57], v[146:149], v[162:165], v[54:57]
	v_mfma_f32_16x16x32_bf16 v[50:53], v[154:157], v[162:165], v[50:53]
	v_mfma_f32_16x16x32_bf16 v[38:41], v[146:149], v[170:173], v[38:41]
	v_mfma_f32_16x16x32_bf16 v[34:37], v[154:157], v[170:173], v[34:37]
	v_mfma_f32_16x16x32_bf16 v[22:25], v[146:149], v[196:199], v[22:25]
	v_mfma_f32_16x16x32_bf16 v[18:21], v[154:157], v[196:199], v[18:21]
	v_mfma_f32_16x16x32_bf16 v[6:9], v[146:149], v[204:207], v[6:9]
	v_mfma_f32_16x16x32_bf16 v[2:5], v[154:157], v[204:207], v[2:5]
	v_mfma_f32_16x16x32_bf16 v[54:57], v[150:153], v[166:169], v[54:57]
	v_mfma_f32_16x16x32_bf16 v[50:53], v[158:161], v[166:169], v[50:53]
	v_mfma_f32_16x16x32_bf16 v[38:41], v[150:153], v[186:189], v[38:41]
	v_mfma_f32_16x16x32_bf16 v[34:37], v[158:161], v[186:189], v[34:37]
	v_mfma_f32_16x16x32_bf16 v[22:25], v[150:153], v[200:203], v[22:25]
	v_mfma_f32_16x16x32_bf16 v[18:21], v[158:161], v[200:203], v[18:21]
	v_mfma_f32_16x16x32_bf16 v[6:9], v[150:153], v[208:211], v[6:9]
	v_mfma_f32_16x16x32_bf16 v[2:5], v[158:161], v[208:211], v[2:5]
	s_barrier
	s_setprio 0
	s_add_i32 s40, s40, 2
	s_add_u32 s22, s22, 0x100
	s_addc_u32 s23, s23, 0
	s_add_u32 s21, s21, 0x100
	s_addc_u32 s33, s33, 0
	s_cmp_gt_u32 s40, 29
	s_cbranch_scc1 .Lpeel_done_1
	s_branch .LBB0_672
.Ltrip0_strict_1:
	s_add_u32 s24, s22, 0xfff80080
	s_addc_u32 s25, s23, -1
	s_add_i32 s41, 0, 0x10000
	s_cmp_eq_u32 s40, 28
	s_cselect_b32 s27, s11, s25
	s_cselect_b32 s26, s18, s24
	s_cselect_b32 s25, s9, s33
	s_cselect_b32 s24, s19, s21
	s_add_i32 s46, 0, 0x14000
	v_add_u32_e32 v142, s41, v214
	v_add_u32_e32 v158, s46, v214
	ds_read_b128 v[130:133], v142
	ds_read_b128 v[134:137], v142 offset:1024
	ds_read_b128 v[138:141], v142 offset:2048
	ds_read_b128 v[142:145], v142 offset:3072
	ds_read_b128 v[146:149], v158
	ds_read_b128 v[150:153], v158 offset:1024
	ds_read_b128 v[154:157], v158 offset:2048
	ds_read_b128 v[158:161], v158 offset:3072
	v_lshl_add_u64 v[212:213], s[22:23], 0, v[182:183]
	s_add_i32 m0, s17, 0xc000
	ds_read_b128 v[162:165], v216
	ds_read_b128 v[166:169], v216 offset:1024
	ds_read_b128 v[170:173], v216 offset:2048
	ds_read_b128 v[186:189], v216 offset:3072
	ds_read_b128 v[196:199], v216 offset:4096
	ds_read_b128 v[200:203], v216 offset:5120
	ds_read_b128 v[204:207], v216 offset:6144
	ds_read_b128 v[208:211], v216 offset:7168
	global_load_lds_dwordx4 v[212:213], off
	s_add_i32 m0, s17, 0xe000
	v_lshl_add_u64 v[212:213], s[22:23], 0, v[184:185]
	global_load_lds_dwordx4 v[212:213], off
	s_waitcnt vmcnt(8) lgkmcnt(0)
	s_setprio 1
	s_barrier
	v_mfma_f32_16x16x32_bf16 v[126:129], v[130:133], v[162:165], 0
	v_mfma_f32_16x16x32_bf16 v[122:125], v[138:141], v[162:165], 0
	v_mfma_f32_16x16x32_bf16 v[110:113], v[130:133], v[170:173], 0
	v_mfma_f32_16x16x32_bf16 v[106:109], v[138:141], v[170:173], 0
	v_mfma_f32_16x16x32_bf16 v[94:97], v[130:133], v[196:199], 0
	v_mfma_f32_16x16x32_bf16 v[90:93], v[138:141], v[196:199], 0
	v_mfma_f32_16x16x32_bf16 v[78:81], v[130:133], v[204:207], 0
	v_mfma_f32_16x16x32_bf16 v[74:77], v[138:141], v[204:207], 0
	v_mfma_f32_16x16x32_bf16 v[126:129], v[134:137], v[166:169], v[126:129]
	v_mfma_f32_16x16x32_bf16 v[122:125], v[142:145], v[166:169], v[122:125]
	v_mfma_f32_16x16x32_bf16 v[110:113], v[134:137], v[186:189], v[110:113]
	v_mfma_f32_16x16x32_bf16 v[106:109], v[142:145], v[186:189], v[106:109]
	v_mfma_f32_16x16x32_bf16 v[94:97], v[134:137], v[200:203], v[94:97]
	v_mfma_f32_16x16x32_bf16 v[90:93], v[142:145], v[200:203], v[90:93]
	v_mfma_f32_16x16x32_bf16 v[78:81], v[134:137], v[208:211], v[78:81]
	v_mfma_f32_16x16x32_bf16 v[74:77], v[142:145], v[208:211], v[74:77]
	s_setprio 0
	s_setprio 1
	v_mfma_f32_16x16x32_bf16 v[118:121], v[146:149], v[162:165], 0
	v_mfma_f32_16x16x32_bf16 v[114:117], v[154:157], v[162:165], 0
	v_mfma_f32_16x16x32_bf16 v[102:105], v[146:149], v[170:173], 0
	v_mfma_f32_16x16x32_bf16 v[98:101], v[154:157], v[170:173], 0
	v_mfma_f32_16x16x32_bf16 v[86:89], v[146:149], v[196:199], 0
	v_mfma_f32_16x16x32_bf16 v[82:85], v[154:157], v[196:199], 0
	v_mfma_f32_16x16x32_bf16 v[70:73], v[146:149], v[204:207], 0
	v_mfma_f32_16x16x32_bf16 v[66:69], v[154:157], v[204:207], 0
	v_mfma_f32_16x16x32_bf16 v[118:121], v[150:153], v[166:169], v[118:121]
	v_mfma_f32_16x16x32_bf16 v[114:117], v[158:161], v[166:169], v[114:117]
	v_mfma_f32_16x16x32_bf16 v[102:105], v[150:153], v[186:189], v[102:105]
	v_mfma_f32_16x16x32_bf16 v[98:101], v[158:161], v[186:189], v[98:101]
	v_mfma_f32_16x16x32_bf16 v[86:89], v[150:153], v[200:203], v[86:89]
	v_mfma_f32_16x16x32_bf16 v[82:85], v[158:161], v[200:203], v[82:85]
	v_mfma_f32_16x16x32_bf16 v[70:73], v[150:153], v[208:211], v[70:73]
	v_mfma_f32_16x16x32_bf16 v[66:69], v[158:161], v[208:211], v[66:69]
	s_barrier
	s_setprio 0
	s_add_i32 s41, s41, s29
	v_lshl_add_u64 v[212:213], s[24:25], 0, v[178:179]
	s_mov_b32 m0, s41
	ds_read_b128 v[162:165], v216 offset:16384
	ds_read_b128 v[166:169], v216 offset:17408
	ds_read_b128 v[170:173], v216 offset:18432
	ds_read_b128 v[186:189], v216 offset:19456
	ds_read_b128 v[196:199], v216 offset:20480
	ds_read_b128 v[200:203], v216 offset:21504
	ds_read_b128 v[204:207], v216 offset:22528
	ds_read_b128 v[208:211], v216 offset:23552
	global_load_lds_dwordx4 v[212:213], off
	s_add_i32 m0, s41, 0x2000
	s_add_u32 s42, s24, 0x80000
	v_lshl_add_u64 v[218:219], s[24:25], 0, v[174:175]
	s_addc_u32 s43, s25, 0
	s_add_i32 s41, s46, s29
	global_load_lds_dwordx4 v[218:219], off
	v_lshl_add_u64 v[220:221], s[42:43], 0, v[178:179]
	s_mov_b32 m0, s41
	v_lshl_add_u64 v[222:223], s[26:27], 0, v[176:177]
	global_load_lds_dwordx4 v[220:221], off
	s_add_i32 m0, s41, 0x2000
	v_lshl_add_u64 v[220:221], s[42:43], 0, v[174:175]
	global_load_lds_dwordx4 v[220:221], off
	s_mov_b32 m0, s17
	v_lshl_add_u64 v[220:221], s[26:27], 0, v[180:181]
	global_load_lds_dwordx4 v[220:221], off
	s_mov_b32 m0, s31
	s_nop 0
	global_load_lds_dwordx4 v[222:223], off
	s_waitcnt vmcnt(8) lgkmcnt(0)
	s_setprio 1
	s_barrier
	v_mfma_f32_16x16x32_bf16 v[62:65], v[130:133], v[162:165], 0
	v_mfma_f32_16x16x32_bf16 v[58:61], v[138:141], v[162:165], 0
	v_mfma_f32_16x16x32_bf16 v[46:49], v[130:133], v[170:173], 0
	v_mfma_f32_16x16x32_bf16 v[42:45], v[138:141], v[170:173], 0
	v_mfma_f32_16x16x32_bf16 v[30:33], v[130:133], v[196:199], 0
	v_mfma_f32_16x16x32_bf16 v[26:29], v[138:141], v[196:199], 0
	v_mfma_f32_16x16x32_bf16 v[14:17], v[130:133], v[204:207], 0
	v_mfma_f32_16x16x32_bf16 v[10:13], v[138:141], v[204:207], 0
	v_mfma_f32_16x16x32_bf16 v[62:65], v[134:137], v[166:169], v[62:65]
	v_mfma_f32_16x16x32_bf16 v[58:61], v[142:145], v[166:169], v[58:61]
	v_mfma_f32_16x16x32_bf16 v[46:49], v[134:137], v[186:189], v[46:49]
	v_mfma_f32_16x16x32_bf16 v[42:45], v[142:145], v[186:189], v[42:45]
	v_mfma_f32_16x16x32_bf16 v[30:33], v[134:137], v[200:203], v[30:33]
	v_mfma_f32_16x16x32_bf16 v[26:29], v[142:145], v[200:203], v[26:29]
	v_mfma_f32_16x16x32_bf16 v[14:17], v[134:137], v[208:211], v[14:17]
	v_mfma_f32_16x16x32_bf16 v[10:13], v[142:145], v[208:211], v[10:13]
	s_setprio 0
	s_setprio 1
	v_mfma_f32_16x16x32_bf16 v[54:57], v[146:149], v[162:165], 0
	v_mfma_f32_16x16x32_bf16 v[50:53], v[154:157], v[162:165], 0
	v_mfma_f32_16x16x32_bf16 v[38:41], v[146:149], v[170:173], 0
	v_mfma_f32_16x16x32_bf16 v[34:37], v[154:157], v[170:173], 0
	v_mfma_f32_16x16x32_bf16 v[22:25], v[146:149], v[196:199], 0
	v_mfma_f32_16x16x32_bf16 v[18:21], v[154:157], v[196:199], 0
	v_mfma_f32_16x16x32_bf16 v[6:9], v[146:149], v[204:207], 0
	v_mfma_f32_16x16x32_bf16 v[2:5], v[154:157], v[204:207], 0
	v_mfma_f32_16x16x32_bf16 v[54:57], v[150:153], v[166:169], v[54:57]
	v_mfma_f32_16x16x32_bf16 v[50:53], v[158:161], v[166:169], v[50:53]
	v_mfma_f32_16x16x32_bf16 v[38:41], v[150:153], v[186:189], v[38:41]
	v_mfma_f32_16x16x32_bf16 v[34:37], v[158:161], v[186:189], v[34:37]
	v_mfma_f32_16x16x32_bf16 v[22:25], v[150:153], v[200:203], v[22:25]
	v_mfma_f32_16x16x32_bf16 v[18:21], v[158:161], v[200:203], v[18:21]
	v_mfma_f32_16x16x32_bf16 v[6:9], v[150:153], v[208:211], v[6:9]
	v_mfma_f32_16x16x32_bf16 v[2:5], v[158:161], v[208:211], v[2:5]
	s_barrier
	s_setprio 0
	s_add_i32 s41, 0, 0x18000
	s_add_i32 s42, 0, 0x1c000
	v_add_u32_e32 v142, s41, v214
	v_add_u32_e32 v158, s42, v214
	ds_read_b128 v[130:133], v142
	ds_read_b128 v[134:137], v142 offset:1024
	ds_read_b128 v[138:141], v142 offset:2048
	ds_read_b128 v[142:145], v142 offset:3072
	ds_read_b128 v[146:149], v158
	ds_read_b128 v[150:153], v158 offset:1024
	ds_read_b128 v[154:157], v158 offset:2048
	ds_read_b128 v[158:161], v158 offset:3072
	s_add_u32 s26, s26, 0x80000
	s_addc_u32 s27, s27, 0
	s_mov_b32 m0, s34
	v_lshl_add_u64 v[224:225], s[26:27], 0, v[180:181]
	ds_read_b128 v[162:165], v216 offset:32768
	ds_read_b128 v[166:169], v216 offset:33792
	ds_read_b128 v[170:173], v216 offset:34816
	ds_read_b128 v[186:189], v216 offset:35840
	ds_read_b128 v[196:199], v216 offset:36864
	ds_read_b128 v[200:203], v216 offset:37888
	ds_read_b128 v[204:207], v216 offset:38912
	ds_read_b128 v[208:211], v216 offset:39936
	global_load_lds_dwordx4 v[224:225], off
	s_mov_b32 m0, s35
	v_lshl_add_u64 v[224:225], s[26:27], 0, v[176:177]
	global_load_lds_dwordx4 v[224:225], off
	s_waitcnt vmcnt(8) lgkmcnt(0)
	s_setprio 1
	s_barrier
	v_mfma_f32_16x16x32_bf16 v[126:129], v[130:133], v[162:165], v[126:129]
	v_mfma_f32_16x16x32_bf16 v[122:125], v[138:141], v[162:165], v[122:125]
	v_mfma_f32_16x16x32_bf16 v[110:113], v[130:133], v[170:173], v[110:113]
	v_mfma_f32_16x16x32_bf16 v[106:109], v[138:141], v[170:173], v[106:109]
	v_mfma_f32_16x16x32_bf16 v[94:97], v[130:133], v[196:199], v[94:97]
	v_mfma_f32_16x16x32_bf16 v[90:93], v[138:141], v[196:199], v[90:93]
	v_mfma_f32_16x16x32_bf16 v[78:81], v[130:133], v[204:207], v[78:81]
	v_mfma_f32_16x16x32_bf16 v[74:77], v[138:141], v[204:207], v[74:77]
	v_mfma_f32_16x16x32_bf16 v[126:129], v[134:137], v[166:169], v[126:129]
	v_mfma_f32_16x16x32_bf16 v[122:125], v[142:145], v[166:169], v[122:125]
	v_mfma_f32_16x16x32_bf16 v[110:113], v[134:137], v[186:189], v[110:113]
	v_mfma_f32_16x16x32_bf16 v[106:109], v[142:145], v[186:189], v[106:109]
	v_mfma_f32_16x16x32_bf16 v[94:97], v[134:137], v[200:203], v[94:97]
	v_mfma_f32_16x16x32_bf16 v[90:93], v[142:145], v[200:203], v[90:93]
	v_mfma_f32_16x16x32_bf16 v[78:81], v[134:137], v[208:211], v[78:81]
	v_mfma_f32_16x16x32_bf16 v[74:77], v[142:145], v[208:211], v[74:77]
	s_setprio 0
	s_setprio 1
	v_mfma_f32_16x16x32_bf16 v[118:121], v[146:149], v[162:165], v[118:121]
	v_mfma_f32_16x16x32_bf16 v[114:117], v[154:157], v[162:165], v[114:117]
	v_mfma_f32_16x16x32_bf16 v[102:105], v[146:149], v[170:173], v[102:105]
	v_mfma_f32_16x16x32_bf16 v[98:101], v[154:157], v[170:173], v[98:101]
	v_mfma_f32_16x16x32_bf16 v[86:89], v[146:149], v[196:199], v[86:89]
	v_mfma_f32_16x16x32_bf16 v[82:85], v[154:157], v[196:199], v[82:85]
	v_mfma_f32_16x16x32_bf16 v[70:73], v[146:149], v[204:207], v[70:73]
	v_mfma_f32_16x16x32_bf16 v[66:69], v[154:157], v[204:207], v[66:69]
	v_mfma_f32_16x16x32_bf16 v[118:121], v[150:153], v[166:169], v[118:121]
	v_mfma_f32_16x16x32_bf16 v[114:117], v[158:161], v[166:169], v[114:117]
	v_mfma_f32_16x16x32_bf16 v[102:105], v[150:153], v[186:189], v[102:105]
	v_mfma_f32_16x16x32_bf16 v[98:101], v[158:161], v[186:189], v[98:101]
	v_mfma_f32_16x16x32_bf16 v[86:89], v[150:153], v[200:203], v[86:89]
	v_mfma_f32_16x16x32_bf16 v[82:85], v[158:161], v[200:203], v[82:85]
	v_mfma_f32_16x16x32_bf16 v[70:73], v[150:153], v[208:211], v[70:73]
	v_mfma_f32_16x16x32_bf16 v[66:69], v[158:161], v[208:211], v[66:69]
	s_barrier
	s_setprio 0
	s_add_i32 s26, s41, s29
	v_lshl_add_u64 v[212:213], v[212:213], 0, s[58:59]
	s_mov_b32 m0, s26
	ds_read_b128 v[162:165], v216 offset:49152
	ds_read_b128 v[166:169], v216 offset:50176
	ds_read_b128 v[170:173], v216 offset:51200
	ds_read_b128 v[186:189], v216 offset:52224
	ds_read_b128 v[196:199], v216 offset:53248
	ds_read_b128 v[200:203], v216 offset:54272
	ds_read_b128 v[204:207], v216 offset:55296
	ds_read_b128 v[208:211], v216 offset:56320
	global_load_lds_dwordx4 v[212:213], off
	s_add_i32 m0, s26, 0x2000
	s_add_u32 s24, s24, 0x80080
	v_lshl_add_u64 v[212:213], v[218:219], 0, s[58:59]
	s_addc_u32 s25, s25, 0
	s_add_i32 s26, s42, s29
	global_load_lds_dwordx4 v[212:213], off
	s_mov_b32 m0, s26
	v_lshl_add_u64 v[212:213], s[24:25], 0, v[178:179]
	global_load_lds_dwordx4 v[212:213], off
	s_add_i32 m0, s26, 0x2000
	v_lshl_add_u64 v[212:213], s[24:25], 0, v[174:175]
	global_load_lds_dwordx4 v[212:213], off
	s_mov_b32 m0, s38
	v_lshl_add_u64 v[212:213], v[220:221], 0, s[58:59]
	global_load_lds_dwordx4 v[212:213], off
	s_mov_b32 m0, s39
	v_lshl_add_u64 v[212:213], v[222:223], 0, s[58:59]
	global_load_lds_dwordx4 v[212:213], off
	s_waitcnt vmcnt(8) lgkmcnt(0)
	s_setprio 1
	s_barrier
	v_mfma_f32_16x16x32_bf16 v[62:65], v[130:133], v[162:165], v[62:65]
	v_mfma_f32_16x16x32_bf16 v[58:61], v[138:141], v[162:165], v[58:61]
	v_mfma_f32_16x16x32_bf16 v[46:49], v[130:133], v[170:173], v[46:49]
	v_mfma_f32_16x16x32_bf16 v[42:45], v[138:141], v[170:173], v[42:45]
	v_mfma_f32_16x16x32_bf16 v[30:33], v[130:133], v[196:199], v[30:33]
	v_mfma_f32_16x16x32_bf16 v[26:29], v[138:141], v[196:199], v[26:29]
	v_mfma_f32_16x16x32_bf16 v[14:17], v[130:133], v[204:207], v[14:17]
	v_mfma_f32_16x16x32_bf16 v[10:13], v[138:141], v[204:207], v[10:13]
	v_mfma_f32_16x16x32_bf16 v[62:65], v[134:137], v[166:169], v[62:65]
	v_mfma_f32_16x16x32_bf16 v[58:61], v[142:145], v[166:169], v[58:61]
	v_mfma_f32_16x16x32_bf16 v[46:49], v[134:137], v[186:189], v[46:49]
	v_mfma_f32_16x16x32_bf16 v[42:45], v[142:145], v[186:189], v[42:45]
	v_mfma_f32_16x16x32_bf16 v[30:33], v[134:137], v[200:203], v[30:33]
	v_mfma_f32_16x16x32_bf16 v[26:29], v[142:145], v[200:203], v[26:29]
	v_mfma_f32_16x16x32_bf16 v[14:17], v[134:137], v[208:211], v[14:17]
	v_mfma_f32_16x16x32_bf16 v[10:13], v[142:145], v[208:211], v[10:13]
	s_setprio 0
	s_setprio 1
	v_mfma_f32_16x16x32_bf16 v[54:57], v[146:149], v[162:165], v[54:57]
	v_mfma_f32_16x16x32_bf16 v[50:53], v[154:157], v[162:165], v[50:53]
	v_mfma_f32_16x16x32_bf16 v[38:41], v[146:149], v[170:173], v[38:41]
	v_mfma_f32_16x16x32_bf16 v[34:37], v[154:157], v[170:173], v[34:37]
	v_mfma_f32_16x16x32_bf16 v[22:25], v[146:149], v[196:199], v[22:25]
	v_mfma_f32_16x16x32_bf16 v[18:21], v[154:157], v[196:199], v[18:21]
	v_mfma_f32_16x16x32_bf16 v[6:9], v[146:149], v[204:207], v[6:9]
	v_mfma_f32_16x16x32_bf16 v[2:5], v[154:157], v[204:207], v[2:5]
	v_mfma_f32_16x16x32_bf16 v[54:57], v[150:153], v[166:169], v[54:57]
	v_mfma_f32_16x16x32_bf16 v[50:53], v[158:161], v[166:169], v[50:53]
	v_mfma_f32_16x16x32_bf16 v[38:41], v[150:153], v[186:189], v[38:41]
	v_mfma_f32_16x16x32_bf16 v[34:37], v[158:161], v[186:189], v[34:37]
	v_mfma_f32_16x16x32_bf16 v[22:25], v[150:153], v[200:203], v[22:25]
	v_mfma_f32_16x16x32_bf16 v[18:21], v[158:161], v[200:203], v[18:21]
	v_mfma_f32_16x16x32_bf16 v[6:9], v[150:153], v[208:211], v[6:9]
	v_mfma_f32_16x16x32_bf16 v[2:5], v[158:161], v[208:211], v[2:5]
	s_barrier
	s_setprio 0
	s_add_i32 s40, s40, 2
	s_add_u32 s22, s22, 0x100
	s_addc_u32 s23, s23, 0
	s_add_u32 s21, s21, 0x100
	s_addc_u32 s33, s33, 0
	s_cmp_gt_u32 s40, 29
	s_cbranch_scc1 .Lpeel_done_1
.LBB0_672:
	s_add_u32 s24, s22, 0xfff80080
	s_addc_u32 s25, s23, -1
	s_add_i32 s41, 0, 0x10000
	s_cmp_eq_u32 s40, 28
	s_cselect_b32 s27, s11, s25
	s_cselect_b32 s26, s18, s24
	s_cselect_b32 s25, s9, s33
	s_cselect_b32 s24, s19, s21
	s_add_i32 s46, 0, 0x14000
	v_add_u32_e32 v142, s41, v214
	v_add_u32_e32 v158, s46, v214
	ds_read_b128 v[130:133], v142
	ds_read_b128 v[134:137], v142 offset:1024
	ds_read_b128 v[138:141], v142 offset:2048
	ds_read_b128 v[142:145], v142 offset:3072
	ds_read_b128 v[146:149], v158
	ds_read_b128 v[150:153], v158 offset:1024
	ds_read_b128 v[154:157], v158 offset:2048
	ds_read_b128 v[158:161], v158 offset:3072
	v_lshl_add_u64 v[212:213], s[22:23], 0, v[182:183]
	s_add_i32 m0, s17, 0xc000
	ds_read_b128 v[162:165], v216
	ds_read_b128 v[166:169], v216 offset:1024
	ds_read_b128 v[170:173], v216 offset:2048
	ds_read_b128 v[186:189], v216 offset:3072
	ds_read_b128 v[196:199], v216 offset:4096
	ds_read_b128 v[200:203], v216 offset:5120
	ds_read_b128 v[204:207], v216 offset:6144
	ds_read_b128 v[208:211], v216 offset:7168
	global_load_lds_dwordx4 v[212:213], off
	s_add_i32 m0, s17, 0xe000
	v_lshl_add_u64 v[212:213], s[22:23], 0, v[184:185]
	global_load_lds_dwordx4 v[212:213], off
	s_waitcnt vmcnt(8) lgkmcnt(0)
	s_setprio 1
	s_barrier
	v_mfma_f32_16x16x32_bf16 v[126:129], v[130:133], v[162:165], v[126:129]
	v_mfma_f32_16x16x32_bf16 v[122:125], v[138:141], v[162:165], v[122:125]
	v_mfma_f32_16x16x32_bf16 v[110:113], v[130:133], v[170:173], v[110:113]
	v_mfma_f32_16x16x32_bf16 v[106:109], v[138:141], v[170:173], v[106:109]
	v_mfma_f32_16x16x32_bf16 v[94:97], v[130:133], v[196:199], v[94:97]
	v_mfma_f32_16x16x32_bf16 v[90:93], v[138:141], v[196:199], v[90:93]
	v_mfma_f32_16x16x32_bf16 v[78:81], v[130:133], v[204:207], v[78:81]
	v_mfma_f32_16x16x32_bf16 v[74:77], v[138:141], v[204:207], v[74:77]
	v_mfma_f32_16x16x32_bf16 v[126:129], v[134:137], v[166:169], v[126:129]
	v_mfma_f32_16x16x32_bf16 v[122:125], v[142:145], v[166:169], v[122:125]
	v_mfma_f32_16x16x32_bf16 v[110:113], v[134:137], v[186:189], v[110:113]
	v_mfma_f32_16x16x32_bf16 v[106:109], v[142:145], v[186:189], v[106:109]
	v_mfma_f32_16x16x32_bf16 v[94:97], v[134:137], v[200:203], v[94:97]
	v_mfma_f32_16x16x32_bf16 v[90:93], v[142:145], v[200:203], v[90:93]
	v_mfma_f32_16x16x32_bf16 v[78:81], v[134:137], v[208:211], v[78:81]
	v_mfma_f32_16x16x32_bf16 v[74:77], v[142:145], v[208:211], v[74:77]
	s_setprio 0
	s_setprio 1
	v_mfma_f32_16x16x32_bf16 v[118:121], v[146:149], v[162:165], v[118:121]
	v_mfma_f32_16x16x32_bf16 v[114:117], v[154:157], v[162:165], v[114:117]
	v_mfma_f32_16x16x32_bf16 v[102:105], v[146:149], v[170:173], v[102:105]
	v_mfma_f32_16x16x32_bf16 v[98:101], v[154:157], v[170:173], v[98:101]
	v_mfma_f32_16x16x32_bf16 v[86:89], v[146:149], v[196:199], v[86:89]
	v_mfma_f32_16x16x32_bf16 v[82:85], v[154:157], v[196:199], v[82:85]
	v_mfma_f32_16x16x32_bf16 v[70:73], v[146:149], v[204:207], v[70:73]
	v_mfma_f32_16x16x32_bf16 v[66:69], v[154:157], v[204:207], v[66:69]
	v_mfma_f32_16x16x32_bf16 v[118:121], v[150:153], v[166:169], v[118:121]
	v_mfma_f32_16x16x32_bf16 v[114:117], v[158:161], v[166:169], v[114:117]
	v_mfma_f32_16x16x32_bf16 v[102:105], v[150:153], v[186:189], v[102:105]
	v_mfma_f32_16x16x32_bf16 v[98:101], v[158:161], v[186:189], v[98:101]
	v_mfma_f32_16x16x32_bf16 v[86:89], v[150:153], v[200:203], v[86:89]
	v_mfma_f32_16x16x32_bf16 v[82:85], v[158:161], v[200:203], v[82:85]
	v_mfma_f32_16x16x32_bf16 v[70:73], v[150:153], v[208:211], v[70:73]
	v_mfma_f32_16x16x32_bf16 v[66:69], v[158:161], v[208:211], v[66:69]
	s_setprio 0
	s_barrier
	s_add_i32 s41, s41, s29
	v_lshl_add_u64 v[212:213], s[24:25], 0, v[178:179]
	s_mov_b32 m0, s41
	ds_read_b128 v[162:165], v216 offset:16384
	ds_read_b128 v[166:169], v216 offset:17408
	ds_read_b128 v[170:173], v216 offset:18432
	ds_read_b128 v[186:189], v216 offset:19456
	ds_read_b128 v[196:199], v216 offset:20480
	ds_read_b128 v[200:203], v216 offset:21504
	ds_read_b128 v[204:207], v216 offset:22528
	ds_read_b128 v[208:211], v216 offset:23552
	global_load_lds_dwordx4 v[212:213], off
	s_add_i32 m0, s41, 0x2000
	s_add_u32 s42, s24, 0x80000
	v_lshl_add_u64 v[218:219], s[24:25], 0, v[174:175]
	s_addc_u32 s43, s25, 0
	s_add_i32 s41, s46, s29
	global_load_lds_dwordx4 v[218:219], off
	v_lshl_add_u64 v[220:221], s[42:43], 0, v[178:179]
	s_mov_b32 m0, s41
	v_lshl_add_u64 v[222:223], s[26:27], 0, v[176:177]
	global_load_lds_dwordx4 v[220:221], off
	s_add_i32 m0, s41, 0x2000
	v_lshl_add_u64 v[220:221], s[42:43], 0, v[174:175]
	global_load_lds_dwordx4 v[220:221], off
	s_mov_b32 m0, s17
	v_lshl_add_u64 v[220:221], s[26:27], 0, v[180:181]
	global_load_lds_dwordx4 v[220:221], off
	s_mov_b32 m0, s31
	s_nop 0
	global_load_lds_dwordx4 v[222:223], off
	s_waitcnt vmcnt(8) lgkmcnt(0)
	s_setprio 1
	s_barrier
	v_mfma_f32_16x16x32_bf16 v[62:65], v[130:133], v[162:165], v[62:65]
	v_mfma_f32_16x16x32_bf16 v[58:61], v[138:141], v[162:165], v[58:61]
	v_mfma_f32_16x16x32_bf16 v[46:49], v[130:133], v[170:173], v[46:49]
	v_mfma_f32_16x16x32_bf16 v[42:45], v[138:141], v[170:173], v[42:45]
	v_mfma_f32_16x16x32_bf16 v[30:33], v[130:133], v[196:199], v[30:33]
	v_mfma_f32_16x16x32_bf16 v[26:29], v[138:141], v[196:199], v[26:29]
	v_mfma_f32_16x16x32_bf16 v[14:17], v[130:133], v[204:207], v[14:17]
	v_mfma_f32_16x16x32_bf16 v[10:13], v[138:141], v[204:207], v[10:13]
	v_mfma_f32_16x16x32_bf16 v[62:65], v[134:137], v[166:169], v[62:65]
	v_mfma_f32_16x16x32_bf16 v[58:61], v[142:145], v[166:169], v[58:61]
	v_mfma_f32_16x16x32_bf16 v[46:49], v[134:137], v[186:189], v[46:49]
	v_mfma_f32_16x16x32_bf16 v[42:45], v[142:145], v[186:189], v[42:45]
	v_mfma_f32_16x16x32_bf16 v[30:33], v[134:137], v[200:203], v[30:33]
	v_mfma_f32_16x16x32_bf16 v[26:29], v[142:145], v[200:203], v[26:29]
	v_mfma_f32_16x16x32_bf16 v[14:17], v[134:137], v[208:211], v[14:17]
	v_mfma_f32_16x16x32_bf16 v[10:13], v[142:145], v[208:211], v[10:13]
	s_setprio 0
	s_setprio 1
	v_mfma_f32_16x16x32_bf16 v[54:57], v[146:149], v[162:165], v[54:57]
	v_mfma_f32_16x16x32_bf16 v[50:53], v[154:157], v[162:165], v[50:53]
	v_mfma_f32_16x16x32_bf16 v[38:41], v[146:149], v[170:173], v[38:41]
	v_mfma_f32_16x16x32_bf16 v[34:37], v[154:157], v[170:173], v[34:37]
	v_mfma_f32_16x16x32_bf16 v[22:25], v[146:149], v[196:199], v[22:25]
	v_mfma_f32_16x16x32_bf16 v[18:21], v[154:157], v[196:199], v[18:21]
	v_mfma_f32_16x16x32_bf16 v[6:9], v[146:149], v[204:207], v[6:9]
	v_mfma_f32_16x16x32_bf16 v[2:5], v[154:157], v[204:207], v[2:5]
	v_mfma_f32_16x16x32_bf16 v[54:57], v[150:153], v[166:169], v[54:57]
	v_mfma_f32_16x16x32_bf16 v[50:53], v[158:161], v[166:169], v[50:53]
	v_mfma_f32_16x16x32_bf16 v[38:41], v[150:153], v[186:189], v[38:41]
	v_mfma_f32_16x16x32_bf16 v[34:37], v[158:161], v[186:189], v[34:37]
	v_mfma_f32_16x16x32_bf16 v[22:25], v[150:153], v[200:203], v[22:25]
	v_mfma_f32_16x16x32_bf16 v[18:21], v[158:161], v[200:203], v[18:21]
	v_mfma_f32_16x16x32_bf16 v[6:9], v[150:153], v[208:211], v[6:9]
	v_mfma_f32_16x16x32_bf16 v[2:5], v[158:161], v[208:211], v[2:5]
	s_setprio 0
	s_barrier
	s_add_i32 s41, 0, 0x18000
	s_add_i32 s42, 0, 0x1c000
	v_add_u32_e32 v142, s41, v214
	v_add_u32_e32 v158, s42, v214
	ds_read_b128 v[130:133], v142
	ds_read_b128 v[134:137], v142 offset:1024
	ds_read_b128 v[138:141], v142 offset:2048
	ds_read_b128 v[142:145], v142 offset:3072
	ds_read_b128 v[146:149], v158
	ds_read_b128 v[150:153], v158 offset:1024
	ds_read_b128 v[154:157], v158 offset:2048
	ds_read_b128 v[158:161], v158 offset:3072
	s_add_u32 s26, s26, 0x80000
	s_addc_u32 s27, s27, 0
	s_mov_b32 m0, s34
	v_lshl_add_u64 v[224:225], s[26:27], 0, v[180:181]
	ds_read_b128 v[162:165], v216 offset:32768
	ds_read_b128 v[166:169], v216 offset:33792
	ds_read_b128 v[170:173], v216 offset:34816
	ds_read_b128 v[186:189], v216 offset:35840
	ds_read_b128 v[196:199], v216 offset:36864
	ds_read_b128 v[200:203], v216 offset:37888
	ds_read_b128 v[204:207], v216 offset:38912
	ds_read_b128 v[208:211], v216 offset:39936
	global_load_lds_dwordx4 v[224:225], off
	s_mov_b32 m0, s35
	v_lshl_add_u64 v[224:225], s[26:27], 0, v[176:177]
	global_load_lds_dwordx4 v[224:225], off
	s_waitcnt vmcnt(8) lgkmcnt(0)
	s_setprio 1
	s_barrier
	v_mfma_f32_16x16x32_bf16 v[126:129], v[130:133], v[162:165], v[126:129]
	v_mfma_f32_16x16x32_bf16 v[122:125], v[138:141], v[162:165], v[122:125]
	v_mfma_f32_16x16x32_bf16 v[110:113], v[130:133], v[170:173], v[110:113]
	v_mfma_f32_16x16x32_bf16 v[106:109], v[138:141], v[170:173], v[106:109]
	v_mfma_f32_16x16x32_bf16 v[94:97], v[130:133], v[196:199], v[94:97]
	v_mfma_f32_16x16x32_bf16 v[90:93], v[138:141], v[196:199], v[90:93]
	v_mfma_f32_16x16x32_bf16 v[78:81], v[130:133], v[204:207], v[78:81]
	v_mfma_f32_16x16x32_bf16 v[74:77], v[138:141], v[204:207], v[74:77]
	v_mfma_f32_16x16x32_bf16 v[126:129], v[134:137], v[166:169], v[126:129]
	v_mfma_f32_16x16x32_bf16 v[122:125], v[142:145], v[166:169], v[122:125]
	v_mfma_f32_16x16x32_bf16 v[110:113], v[134:137], v[186:189], v[110:113]
	v_mfma_f32_16x16x32_bf16 v[106:109], v[142:145], v[186:189], v[106:109]
	v_mfma_f32_16x16x32_bf16 v[94:97], v[134:137], v[200:203], v[94:97]
	v_mfma_f32_16x16x32_bf16 v[90:93], v[142:145], v[200:203], v[90:93]
	v_mfma_f32_16x16x32_bf16 v[78:81], v[134:137], v[208:211], v[78:81]
	v_mfma_f32_16x16x32_bf16 v[74:77], v[142:145], v[208:211], v[74:77]
	s_setprio 0
	s_setprio 1
	v_mfma_f32_16x16x32_bf16 v[118:121], v[146:149], v[162:165], v[118:121]
	v_mfma_f32_16x16x32_bf16 v[114:117], v[154:157], v[162:165], v[114:117]
	v_mfma_f32_16x16x32_bf16 v[102:105], v[146:149], v[170:173], v[102:105]
	v_mfma_f32_16x16x32_bf16 v[98:101], v[154:157], v[170:173], v[98:101]
	v_mfma_f32_16x16x32_bf16 v[86:89], v[146:149], v[196:199], v[86:89]
	v_mfma_f32_16x16x32_bf16 v[82:85], v[154:157], v[196:199], v[82:85]
	v_mfma_f32_16x16x32_bf16 v[70:73], v[146:149], v[204:207], v[70:73]
	v_mfma_f32_16x16x32_bf16 v[66:69], v[154:157], v[204:207], v[66:69]
	v_mfma_f32_16x16x32_bf16 v[118:121], v[150:153], v[166:169], v[118:121]
	v_mfma_f32_16x16x32_bf16 v[114:117], v[158:161], v[166:169], v[114:117]
	v_mfma_f32_16x16x32_bf16 v[102:105], v[150:153], v[186:189], v[102:105]
	v_mfma_f32_16x16x32_bf16 v[98:101], v[158:161], v[186:189], v[98:101]
	v_mfma_f32_16x16x32_bf16 v[86:89], v[150:153], v[200:203], v[86:89]
	v_mfma_f32_16x16x32_bf16 v[82:85], v[158:161], v[200:203], v[82:85]
	v_mfma_f32_16x16x32_bf16 v[70:73], v[150:153], v[208:211], v[70:73]
	v_mfma_f32_16x16x32_bf16 v[66:69], v[158:161], v[208:211], v[66:69]
	s_setprio 0
	s_barrier
	s_add_i32 s26, s41, s29
	v_lshl_add_u64 v[212:213], v[212:213], 0, s[58:59]
	s_mov_b32 m0, s26
	ds_read_b128 v[162:165], v216 offset:49152
	ds_read_b128 v[166:169], v216 offset:50176
	ds_read_b128 v[170:173], v216 offset:51200
	ds_read_b128 v[186:189], v216 offset:52224
	ds_read_b128 v[196:199], v216 offset:53248
	ds_read_b128 v[200:203], v216 offset:54272
	ds_read_b128 v[204:207], v216 offset:55296
	ds_read_b128 v[208:211], v216 offset:56320
	global_load_lds_dwordx4 v[212:213], off
	s_add_i32 m0, s26, 0x2000
	s_add_u32 s24, s24, 0x80080
	v_lshl_add_u64 v[212:213], v[218:219], 0, s[58:59]
	s_addc_u32 s25, s25, 0
	s_add_i32 s26, s42, s29
	global_load_lds_dwordx4 v[212:213], off
	s_mov_b32 m0, s26
	v_lshl_add_u64 v[212:213], s[24:25], 0, v[178:179]
	global_load_lds_dwordx4 v[212:213], off
	s_add_i32 m0, s26, 0x2000
	v_lshl_add_u64 v[212:213], s[24:25], 0, v[174:175]
	global_load_lds_dwordx4 v[212:213], off
	s_mov_b32 m0, s38
	v_lshl_add_u64 v[212:213], v[220:221], 0, s[58:59]
	global_load_lds_dwordx4 v[212:213], off
	s_mov_b32 m0, s39
	v_lshl_add_u64 v[212:213], v[222:223], 0, s[58:59]
	global_load_lds_dwordx4 v[212:213], off
	s_waitcnt vmcnt(8) lgkmcnt(0)
	s_setprio 1
	s_barrier
	v_mfma_f32_16x16x32_bf16 v[62:65], v[130:133], v[162:165], v[62:65]
	v_mfma_f32_16x16x32_bf16 v[58:61], v[138:141], v[162:165], v[58:61]
	v_mfma_f32_16x16x32_bf16 v[46:49], v[130:133], v[170:173], v[46:49]
	v_mfma_f32_16x16x32_bf16 v[42:45], v[138:141], v[170:173], v[42:45]
	v_mfma_f32_16x16x32_bf16 v[30:33], v[130:133], v[196:199], v[30:33]
	v_mfma_f32_16x16x32_bf16 v[26:29], v[138:141], v[196:199], v[26:29]
	v_mfma_f32_16x16x32_bf16 v[14:17], v[130:133], v[204:207], v[14:17]
	v_mfma_f32_16x16x32_bf16 v[10:13], v[138:141], v[204:207], v[10:13]
	v_mfma_f32_16x16x32_bf16 v[62:65], v[134:137], v[166:169], v[62:65]
	v_mfma_f32_16x16x32_bf16 v[58:61], v[142:145], v[166:169], v[58:61]
	v_mfma_f32_16x16x32_bf16 v[46:49], v[134:137], v[186:189], v[46:49]
	v_mfma_f32_16x16x32_bf16 v[42:45], v[142:145], v[186:189], v[42:45]
	v_mfma_f32_16x16x32_bf16 v[30:33], v[134:137], v[200:203], v[30:33]
	v_mfma_f32_16x16x32_bf16 v[26:29], v[142:145], v[200:203], v[26:29]
	v_mfma_f32_16x16x32_bf16 v[14:17], v[134:137], v[208:211], v[14:17]
	v_mfma_f32_16x16x32_bf16 v[10:13], v[142:145], v[208:211], v[10:13]
	s_setprio 0
	s_setprio 1
	v_mfma_f32_16x16x32_bf16 v[54:57], v[146:149], v[162:165], v[54:57]
	v_mfma_f32_16x16x32_bf16 v[50:53], v[154:157], v[162:165], v[50:53]
	v_mfma_f32_16x16x32_bf16 v[38:41], v[146:149], v[170:173], v[38:41]
	v_mfma_f32_16x16x32_bf16 v[34:37], v[154:157], v[170:173], v[34:37]
	v_mfma_f32_16x16x32_bf16 v[22:25], v[146:149], v[196:199], v[22:25]
	v_mfma_f32_16x16x32_bf16 v[18:21], v[154:157], v[196:199], v[18:21]
	v_mfma_f32_16x16x32_bf16 v[6:9], v[146:149], v[204:207], v[6:9]
	v_mfma_f32_16x16x32_bf16 v[2:5], v[154:157], v[204:207], v[2:5]
	v_mfma_f32_16x16x32_bf16 v[54:57], v[150:153], v[166:169], v[54:57]
	v_mfma_f32_16x16x32_bf16 v[50:53], v[158:161], v[166:169], v[50:53]
	v_mfma_f32_16x16x32_bf16 v[38:41], v[150:153], v[186:189], v[38:41]
	v_mfma_f32_16x16x32_bf16 v[34:37], v[158:161], v[186:189], v[34:37]
	v_mfma_f32_16x16x32_bf16 v[22:25], v[150:153], v[200:203], v[22:25]
	v_mfma_f32_16x16x32_bf16 v[18:21], v[158:161], v[200:203], v[18:21]
	v_mfma_f32_16x16x32_bf16 v[6:9], v[150:153], v[208:211], v[6:9]
	v_mfma_f32_16x16x32_bf16 v[2:5], v[158:161], v[208:211], v[2:5]
	s_setprio 0
	s_barrier
	s_add_i32 s40, s40, 2
	s_add_u32 s22, s22, 0x100
	s_addc_u32 s23, s23, 0
	s_add_u32 s21, s21, 0x100
	s_addc_u32 s33, s33, 0
	s_cmp_gt_u32 s40, 29
	s_cbranch_scc0 .LBB0_672

.LBB0_747:
	s_ashr_i32 s9, s8, 31
	s_lshl_b64 s[10:11], s[8:9], 20
	s_add_u32 s10, s69, s10
	s_addc_u32 s11, s77, s11
	s_and_b64 s[12:13], s[4:5], exec
	s_cselect_b32 s9, s11, s17
	s_cselect_b32 s31, s10, s16
	s_ashr_i32 s7, s6, 31
	s_lshl_b64 s[12:13], s[6:7], 20
	v_readlane_b32 s22, v254, 42
	v_readlane_b32 s23, v254, 43
	s_add_u32 s12, s22, s12
	s_addc_u32 s13, s23, s13
	s_and_b64 s[22:23], s[4:5], exec
	s_cselect_b32 s7, s13, s21
	s_cselect_b32 s33, s12, s20
	s_add_u32 s16, s16, 0x80080
	s_addc_u32 s17, s17, 0
	s_add_u32 s34, s20, 0x100
	s_addc_u32 s35, s21, 0
	s_mov_b32 s36, -2
	v_readlane_b32 s37, v255, 49
	s_nop 3
	s_cmp_eq_u32 s37, 3
	v_writelane_b32 v255, 3, 49
	s_cbranch_scc0 .Ltrip0_strict_2
	s_add_u32 s20, s16, 0xfff80080
	s_addc_u32 s21, s17, -1
	s_add_i32 s37, 0, 0x10000
	s_cmp_eq_u32 s36, 28
	s_cselect_b32 s23, s9, s21
	s_cselect_b32 s22, s31, s20
	s_cselect_b32 s21, s7, s35
	s_cselect_b32 s20, s33, s34
	s_add_i32 s40, 0, 0x14000
	v_add_u32_e32 v142, s37, v238
	v_add_u32_e32 v158, s40, v238
	ds_read_b128 v[130:133], v142
	ds_read_b128 v[134:137], v142 offset:1024
	ds_read_b128 v[138:141], v142 offset:2048
	ds_read_b128 v[142:145], v142 offset:3072
	ds_read_b128 v[146:149], v158
	ds_read_b128 v[150:153], v158 offset:1024
	ds_read_b128 v[154:157], v158 offset:2048
	ds_read_b128 v[158:161], v158 offset:3072
	v_lshl_add_u64 v[210:211], s[16:17], 0, v[206:207]
	s_add_i32 m0, s25, 0xc000
	ds_read_b128 v[162:165], v240
	ds_read_b128 v[166:169], v240 offset:1024
	ds_read_b128 v[170:173], v240 offset:2048
	ds_read_b128 v[174:177], v240 offset:3072
	ds_read_b128 v[178:181], v240 offset:4096
	ds_read_b128 v[182:185], v240 offset:5120
	ds_read_b128 v[186:189], v240 offset:6144
	ds_read_b128 v[196:199], v240 offset:7168
	global_load_lds_dwordx4 v[210:211], off
	s_add_i32 m0, s25, 0xe000
	v_lshl_add_u64 v[210:211], s[16:17], 0, v[208:209]
	global_load_lds_dwordx4 v[210:211], off
	s_waitcnt vmcnt(24) lgkmcnt(0)
	s_setprio 1
	s_barrier
	v_mfma_f32_16x16x32_bf16 v[126:129], v[130:133], v[162:165], 0
	v_mfma_f32_16x16x32_bf16 v[122:125], v[138:141], v[162:165], 0
	v_mfma_f32_16x16x32_bf16 v[110:113], v[130:133], v[170:173], 0
	v_mfma_f32_16x16x32_bf16 v[106:109], v[138:141], v[170:173], 0
	v_mfma_f32_16x16x32_bf16 v[98:101], v[130:133], v[178:181], 0
	v_mfma_f32_16x16x32_bf16 v[90:93], v[138:141], v[178:181], 0
	v_mfma_f32_16x16x32_bf16 v[82:85], v[130:133], v[186:189], 0
	v_mfma_f32_16x16x32_bf16 v[74:77], v[138:141], v[186:189], 0
	v_mfma_f32_16x16x32_bf16 v[126:129], v[134:137], v[166:169], v[126:129]
	v_mfma_f32_16x16x32_bf16 v[122:125], v[142:145], v[166:169], v[122:125]
	v_mfma_f32_16x16x32_bf16 v[110:113], v[134:137], v[174:177], v[110:113]
	v_mfma_f32_16x16x32_bf16 v[106:109], v[142:145], v[174:177], v[106:109]
	v_mfma_f32_16x16x32_bf16 v[98:101], v[134:137], v[182:185], v[98:101]
	v_mfma_f32_16x16x32_bf16 v[90:93], v[142:145], v[182:185], v[90:93]
	v_mfma_f32_16x16x32_bf16 v[82:85], v[134:137], v[196:199], v[82:85]
	v_mfma_f32_16x16x32_bf16 v[74:77], v[142:145], v[196:199], v[74:77]
	s_setprio 0
	s_setprio 1
	v_mfma_f32_16x16x32_bf16 v[118:121], v[146:149], v[162:165], 0
	v_mfma_f32_16x16x32_bf16 v[114:117], v[154:157], v[162:165], 0
	v_mfma_f32_16x16x32_bf16 v[102:105], v[146:149], v[170:173], 0
	v_mfma_f32_16x16x32_bf16 v[94:97], v[154:157], v[170:173], 0
	v_mfma_f32_16x16x32_bf16 v[86:89], v[146:149], v[178:181], 0
	v_mfma_f32_16x16x32_bf16 v[78:81], v[154:157], v[178:181], 0
	v_mfma_f32_16x16x32_bf16 v[70:73], v[146:149], v[186:189], 0
	v_mfma_f32_16x16x32_bf16 v[66:69], v[154:157], v[186:189], 0
	v_mfma_f32_16x16x32_bf16 v[118:121], v[150:153], v[166:169], v[118:121]
	v_mfma_f32_16x16x32_bf16 v[114:117], v[158:161], v[166:169], v[114:117]
	v_mfma_f32_16x16x32_bf16 v[102:105], v[150:153], v[174:177], v[102:105]
	v_mfma_f32_16x16x32_bf16 v[94:97], v[158:161], v[174:177], v[94:97]
	v_mfma_f32_16x16x32_bf16 v[86:89], v[150:153], v[182:185], v[86:89]
	v_mfma_f32_16x16x32_bf16 v[78:81], v[158:161], v[182:185], v[78:81]
	v_mfma_f32_16x16x32_bf16 v[70:73], v[150:153], v[196:199], v[70:73]
	v_mfma_f32_16x16x32_bf16 v[66:69], v[158:161], v[196:199], v[66:69]
	s_barrier
	s_setprio 0
	s_add_i32 s37, s37, s24
	v_lshl_add_u64 v[210:211], s[20:21], 0, v[190:191]
	s_mov_b32 m0, s37
	ds_read_b128 v[162:165], v240 offset:16384
	ds_read_b128 v[166:169], v240 offset:17408
	ds_read_b128 v[170:173], v240 offset:18432
	ds_read_b128 v[174:177], v240 offset:19456
	ds_read_b128 v[178:181], v240 offset:20480
	ds_read_b128 v[182:185], v240 offset:21504
	ds_read_b128 v[186:189], v240 offset:22528
	ds_read_b128 v[196:199], v240 offset:23552
	global_load_lds_dwordx4 v[210:211], off
	s_add_i32 m0, s37, 0x2000
	s_add_u32 s38, s20, 0x80000
	v_lshl_add_u64 v[212:213], s[20:21], 0, v[204:205]
	s_addc_u32 s39, s21, 0
	s_add_i32 s37, s40, s24
	global_load_lds_dwordx4 v[212:213], off
	v_lshl_add_u64 v[214:215], s[38:39], 0, v[190:191]
	s_mov_b32 m0, s37
	v_lshl_add_u64 v[216:217], s[22:23], 0, v[202:203]
	global_load_lds_dwordx4 v[214:215], off
	s_add_i32 m0, s37, 0x2000
	v_lshl_add_u64 v[214:215], s[38:39], 0, v[204:205]
	global_load_lds_dwordx4 v[214:215], off
	s_mov_b32 m0, s25
	v_lshl_add_u64 v[214:215], s[22:23], 0, v[200:201]
	global_load_lds_dwordx4 v[214:215], off
	s_mov_b32 m0, s26
	s_nop 0
	global_load_lds_dwordx4 v[216:217], off
	s_waitcnt vmcnt(24) lgkmcnt(0)
	s_setprio 1
	s_barrier
	v_mfma_f32_16x16x32_bf16 v[62:65], v[130:133], v[162:165], 0
	v_mfma_f32_16x16x32_bf16 v[58:61], v[138:141], v[162:165], 0
	v_mfma_f32_16x16x32_bf16 v[50:53], v[130:133], v[170:173], 0
	v_mfma_f32_16x16x32_bf16 v[42:45], v[138:141], v[170:173], 0
	v_mfma_f32_16x16x32_bf16 v[34:37], v[130:133], v[178:181], 0
	v_mfma_f32_16x16x32_bf16 v[26:29], v[138:141], v[178:181], 0
	v_mfma_f32_16x16x32_bf16 v[18:21], v[130:133], v[186:189], 0
	v_mfma_f32_16x16x32_bf16 v[10:13], v[138:141], v[186:189], 0
	v_mfma_f32_16x16x32_bf16 v[62:65], v[134:137], v[166:169], v[62:65]
	v_mfma_f32_16x16x32_bf16 v[58:61], v[142:145], v[166:169], v[58:61]
	v_mfma_f32_16x16x32_bf16 v[50:53], v[134:137], v[174:177], v[50:53]
	v_mfma_f32_16x16x32_bf16 v[42:45], v[142:145], v[174:177], v[42:45]
	v_mfma_f32_16x16x32_bf16 v[34:37], v[134:137], v[182:185], v[34:37]
	v_mfma_f32_16x16x32_bf16 v[26:29], v[142:145], v[182:185], v[26:29]
	v_mfma_f32_16x16x32_bf16 v[18:21], v[134:137], v[196:199], v[18:21]
	v_mfma_f32_16x16x32_bf16 v[10:13], v[142:145], v[196:199], v[10:13]
	s_setprio 0
	s_setprio 1
	v_mfma_f32_16x16x32_bf16 v[54:57], v[146:149], v[162:165], 0
	v_mfma_f32_16x16x32_bf16 v[46:49], v[154:157], v[162:165], 0
	v_mfma_f32_16x16x32_bf16 v[38:41], v[146:149], v[170:173], 0
	v_mfma_f32_16x16x32_bf16 v[30:33], v[154:157], v[170:173], 0
	v_mfma_f32_16x16x32_bf16 v[22:25], v[146:149], v[178:181], 0
	v_mfma_f32_16x16x32_bf16 v[14:17], v[154:157], v[178:181], 0
	v_mfma_f32_16x16x32_bf16 v[6:9], v[146:149], v[186:189], 0
	v_mfma_f32_16x16x32_bf16 v[2:5], v[154:157], v[186:189], 0
	v_mfma_f32_16x16x32_bf16 v[54:57], v[150:153], v[166:169], v[54:57]
	v_mfma_f32_16x16x32_bf16 v[46:49], v[158:161], v[166:169], v[46:49]
	v_mfma_f32_16x16x32_bf16 v[38:41], v[150:153], v[174:177], v[38:41]
	v_mfma_f32_16x16x32_bf16 v[30:33], v[158:161], v[174:177], v[30:33]
	v_mfma_f32_16x16x32_bf16 v[22:25], v[150:153], v[182:185], v[22:25]
	v_mfma_f32_16x16x32_bf16 v[14:17], v[158:161], v[182:185], v[14:17]
	v_mfma_f32_16x16x32_bf16 v[6:9], v[150:153], v[196:199], v[6:9]
	v_mfma_f32_16x16x32_bf16 v[2:5], v[158:161], v[196:199], v[2:5]
	s_barrier
	s_setprio 0
	s_add_i32 s37, 0, 0x18000
	s_add_i32 s38, 0, 0x1c000
	v_add_u32_e32 v142, s37, v238
	v_add_u32_e32 v158, s38, v238
	ds_read_b128 v[130:133], v142
	ds_read_b128 v[134:137], v142 offset:1024
	ds_read_b128 v[138:141], v142 offset:2048
	ds_read_b128 v[142:145], v142 offset:3072
	ds_read_b128 v[146:149], v158
	ds_read_b128 v[150:153], v158 offset:1024
	ds_read_b128 v[154:157], v158 offset:2048
	ds_read_b128 v[158:161], v158 offset:3072
	s_add_u32 s22, s22, 0x80000
	s_addc_u32 s23, s23, 0
	s_mov_b32 m0, s27
	v_lshl_add_u64 v[218:219], s[22:23], 0, v[200:201]
	ds_read_b128 v[162:165], v240 offset:32768
	ds_read_b128 v[166:169], v240 offset:33792
	ds_read_b128 v[170:173], v240 offset:34816
	ds_read_b128 v[174:177], v240 offset:35840
	ds_read_b128 v[178:181], v240 offset:36864
	ds_read_b128 v[182:185], v240 offset:37888
	ds_read_b128 v[186:189], v240 offset:38912
	ds_read_b128 v[196:199], v240 offset:39936
	global_load_lds_dwordx4 v[218:219], off
	s_mov_b32 m0, s28
	v_lshl_add_u64 v[218:219], s[22:23], 0, v[202:203]
	global_load_lds_dwordx4 v[218:219], off
	s_waitcnt vmcnt(8) lgkmcnt(0)
	s_setprio 1
	s_barrier
	v_mfma_f32_16x16x32_bf16 v[126:129], v[130:133], v[162:165], v[126:129]
	v_mfma_f32_16x16x32_bf16 v[122:125], v[138:141], v[162:165], v[122:125]
	v_mfma_f32_16x16x32_bf16 v[110:113], v[130:133], v[170:173], v[110:113]
	v_mfma_f32_16x16x32_bf16 v[106:109], v[138:141], v[170:173], v[106:109]
	v_mfma_f32_16x16x32_bf16 v[98:101], v[130:133], v[178:181], v[98:101]
	v_mfma_f32_16x16x32_bf16 v[90:93], v[138:141], v[178:181], v[90:93]
	v_mfma_f32_16x16x32_bf16 v[82:85], v[130:133], v[186:189], v[82:85]
	v_mfma_f32_16x16x32_bf16 v[74:77], v[138:141], v[186:189], v[74:77]
	v_mfma_f32_16x16x32_bf16 v[126:129], v[134:137], v[166:169], v[126:129]
	v_mfma_f32_16x16x32_bf16 v[122:125], v[142:145], v[166:169], v[122:125]
	v_mfma_f32_16x16x32_bf16 v[110:113], v[134:137], v[174:177], v[110:113]
	v_mfma_f32_16x16x32_bf16 v[106:109], v[142:145], v[174:177], v[106:109]
	v_mfma_f32_16x16x32_bf16 v[98:101], v[134:137], v[182:185], v[98:101]
	v_mfma_f32_16x16x32_bf16 v[90:93], v[142:145], v[182:185], v[90:93]
	v_mfma_f32_16x16x32_bf16 v[82:85], v[134:137], v[196:199], v[82:85]
	v_mfma_f32_16x16x32_bf16 v[74:77], v[142:145], v[196:199], v[74:77]
	s_setprio 0
	s_setprio 1
	v_mfma_f32_16x16x32_bf16 v[118:121], v[146:149], v[162:165], v[118:121]
	v_mfma_f32_16x16x32_bf16 v[114:117], v[154:157], v[162:165], v[114:117]
	v_mfma_f32_16x16x32_bf16 v[102:105], v[146:149], v[170:173], v[102:105]
	v_mfma_f32_16x16x32_bf16 v[94:97], v[154:157], v[170:173], v[94:97]
	v_mfma_f32_16x16x32_bf16 v[86:89], v[146:149], v[178:181], v[86:89]
	v_mfma_f32_16x16x32_bf16 v[78:81], v[154:157], v[178:181], v[78:81]
	v_mfma_f32_16x16x32_bf16 v[70:73], v[146:149], v[186:189], v[70:73]
	v_mfma_f32_16x16x32_bf16 v[66:69], v[154:157], v[186:189], v[66:69]
	v_mfma_f32_16x16x32_bf16 v[118:121], v[150:153], v[166:169], v[118:121]
	v_mfma_f32_16x16x32_bf16 v[114:117], v[158:161], v[166:169], v[114:117]
	v_mfma_f32_16x16x32_bf16 v[102:105], v[150:153], v[174:177], v[102:105]
	v_mfma_f32_16x16x32_bf16 v[94:97], v[158:161], v[174:177], v[94:97]
	v_mfma_f32_16x16x32_bf16 v[86:89], v[150:153], v[182:185], v[86:89]
	v_mfma_f32_16x16x32_bf16 v[78:81], v[158:161], v[182:185], v[78:81]
	v_mfma_f32_16x16x32_bf16 v[70:73], v[150:153], v[196:199], v[70:73]
	v_mfma_f32_16x16x32_bf16 v[66:69], v[158:161], v[196:199], v[66:69]
	s_barrier
	s_setprio 0
	s_add_i32 s22, s37, s24
	v_lshl_add_u64 v[210:211], v[210:211], 0, s[58:59]
	s_mov_b32 m0, s22
	ds_read_b128 v[162:165], v240 offset:49152
	ds_read_b128 v[166:169], v240 offset:50176
	ds_read_b128 v[170:173], v240 offset:51200
	ds_read_b128 v[174:177], v240 offset:52224
	ds_read_b128 v[178:181], v240 offset:53248
	ds_read_b128 v[182:185], v240 offset:54272
	ds_read_b128 v[186:189], v240 offset:55296
	ds_read_b128 v[196:199], v240 offset:56320
	global_load_lds_dwordx4 v[210:211], off
	s_add_i32 m0, s22, 0x2000
	s_add_u32 s20, s20, 0x80080
	v_lshl_add_u64 v[210:211], v[212:213], 0, s[58:59]
	s_addc_u32 s21, s21, 0
	s_add_i32 s22, s38, s24
	global_load_lds_dwordx4 v[210:211], off
	s_mov_b32 m0, s22
	v_lshl_add_u64 v[210:211], s[20:21], 0, v[190:191]
	global_load_lds_dwordx4 v[210:211], off
	s_add_i32 m0, s22, 0x2000
	v_lshl_add_u64 v[210:211], s[20:21], 0, v[204:205]
	global_load_lds_dwordx4 v[210:211], off
	s_mov_b32 m0, s29
	v_lshl_add_u64 v[210:211], v[214:215], 0, s[58:59]
	global_load_lds_dwordx4 v[210:211], off
	s_mov_b32 m0, s30
	v_lshl_add_u64 v[210:211], v[216:217], 0, s[58:59]
	global_load_lds_dwordx4 v[210:211], off
	s_waitcnt vmcnt(8) lgkmcnt(0)
	s_setprio 1
	s_barrier
	v_mfma_f32_16x16x32_bf16 v[62:65], v[130:133], v[162:165], v[62:65]
	v_mfma_f32_16x16x32_bf16 v[58:61], v[138:141], v[162:165], v[58:61]
	v_mfma_f32_16x16x32_bf16 v[50:53], v[130:133], v[170:173], v[50:53]
	v_mfma_f32_16x16x32_bf16 v[42:45], v[138:141], v[170:173], v[42:45]
	v_mfma_f32_16x16x32_bf16 v[34:37], v[130:133], v[178:181], v[34:37]
	v_mfma_f32_16x16x32_bf16 v[26:29], v[138:141], v[178:181], v[26:29]
	v_mfma_f32_16x16x32_bf16 v[18:21], v[130:133], v[186:189], v[18:21]
	v_mfma_f32_16x16x32_bf16 v[10:13], v[138:141], v[186:189], v[10:13]
	v_mfma_f32_16x16x32_bf16 v[62:65], v[134:137], v[166:169], v[62:65]
	v_mfma_f32_16x16x32_bf16 v[58:61], v[142:145], v[166:169], v[58:61]
	v_mfma_f32_16x16x32_bf16 v[50:53], v[134:137], v[174:177], v[50:53]
	v_mfma_f32_16x16x32_bf16 v[42:45], v[142:145], v[174:177], v[42:45]
	v_mfma_f32_16x16x32_bf16 v[34:37], v[134:137], v[182:185], v[34:37]
	v_mfma_f32_16x16x32_bf16 v[26:29], v[142:145], v[182:185], v[26:29]
	v_mfma_f32_16x16x32_bf16 v[18:21], v[134:137], v[196:199], v[18:21]
	v_mfma_f32_16x16x32_bf16 v[10:13], v[142:145], v[196:199], v[10:13]
	s_setprio 0
	s_setprio 1
	v_mfma_f32_16x16x32_bf16 v[54:57], v[146:149], v[162:165], v[54:57]
	v_mfma_f32_16x16x32_bf16 v[46:49], v[154:157], v[162:165], v[46:49]
	v_mfma_f32_16x16x32_bf16 v[38:41], v[146:149], v[170:173], v[38:41]
	v_mfma_f32_16x16x32_bf16 v[30:33], v[154:157], v[170:173], v[30:33]
	v_mfma_f32_16x16x32_bf16 v[22:25], v[146:149], v[178:181], v[22:25]
	v_mfma_f32_16x16x32_bf16 v[14:17], v[154:157], v[178:181], v[14:17]
	v_mfma_f32_16x16x32_bf16 v[6:9], v[146:149], v[186:189], v[6:9]
	v_mfma_f32_16x16x32_bf16 v[2:5], v[154:157], v[186:189], v[2:5]
	v_mfma_f32_16x16x32_bf16 v[54:57], v[150:153], v[166:169], v[54:57]
	v_mfma_f32_16x16x32_bf16 v[46:49], v[158:161], v[166:169], v[46:49]
	v_mfma_f32_16x16x32_bf16 v[38:41], v[150:153], v[174:177], v[38:41]
	v_mfma_f32_16x16x32_bf16 v[30:33], v[158:161], v[174:177], v[30:33]
	v_mfma_f32_16x16x32_bf16 v[22:25], v[150:153], v[182:185], v[22:25]
	v_mfma_f32_16x16x32_bf16 v[14:17], v[158:161], v[182:185], v[14:17]
	v_mfma_f32_16x16x32_bf16 v[6:9], v[150:153], v[196:199], v[6:9]
	v_mfma_f32_16x16x32_bf16 v[2:5], v[158:161], v[196:199], v[2:5]
	s_barrier
	s_setprio 0
	s_add_i32 s36, s36, 2
	s_add_u32 s16, s16, 0x100
	s_addc_u32 s17, s17, 0
	s_add_u32 s34, s34, 0x100
	s_addc_u32 s35, s35, 0
	s_cmp_gt_u32 s36, 29
	s_cbranch_scc1 .Lpeel_done_2
	s_branch .LBB0_748
.Ltrip0_strict_2:
	s_add_u32 s20, s16, 0xfff80080
	s_addc_u32 s21, s17, -1
	s_add_i32 s37, 0, 0x10000
	s_cmp_eq_u32 s36, 28
	s_cselect_b32 s23, s9, s21
	s_cselect_b32 s22, s31, s20
	s_cselect_b32 s21, s7, s35
	s_cselect_b32 s20, s33, s34
	s_add_i32 s40, 0, 0x14000
	v_add_u32_e32 v142, s37, v238
	v_add_u32_e32 v158, s40, v238
	ds_read_b128 v[130:133], v142
	ds_read_b128 v[134:137], v142 offset:1024
	ds_read_b128 v[138:141], v142 offset:2048
	ds_read_b128 v[142:145], v142 offset:3072
	ds_read_b128 v[146:149], v158
	ds_read_b128 v[150:153], v158 offset:1024
	ds_read_b128 v[154:157], v158 offset:2048
	ds_read_b128 v[158:161], v158 offset:3072
	v_lshl_add_u64 v[210:211], s[16:17], 0, v[206:207]
	s_add_i32 m0, s25, 0xc000
	ds_read_b128 v[162:165], v240
	ds_read_b128 v[166:169], v240 offset:1024
	ds_read_b128 v[170:173], v240 offset:2048
	ds_read_b128 v[174:177], v240 offset:3072
	ds_read_b128 v[178:181], v240 offset:4096
	ds_read_b128 v[182:185], v240 offset:5120
	ds_read_b128 v[186:189], v240 offset:6144
	ds_read_b128 v[196:199], v240 offset:7168
	global_load_lds_dwordx4 v[210:211], off
	s_add_i32 m0, s25, 0xe000
	v_lshl_add_u64 v[210:211], s[16:17], 0, v[208:209]
	global_load_lds_dwordx4 v[210:211], off
	s_waitcnt vmcnt(8) lgkmcnt(0)
	s_setprio 1
	s_barrier
	v_mfma_f32_16x16x32_bf16 v[126:129], v[130:133], v[162:165], 0
	v_mfma_f32_16x16x32_bf16 v[122:125], v[138:141], v[162:165], 0
	v_mfma_f32_16x16x32_bf16 v[110:113], v[130:133], v[170:173], 0
	v_mfma_f32_16x16x32_bf16 v[106:109], v[138:141], v[170:173], 0
	v_mfma_f32_16x16x32_bf16 v[98:101], v[130:133], v[178:181], 0
	v_mfma_f32_16x16x32_bf16 v[90:93], v[138:141], v[178:181], 0
	v_mfma_f32_16x16x32_bf16 v[82:85], v[130:133], v[186:189], 0
	v_mfma_f32_16x16x32_bf16 v[74:77], v[138:141], v[186:189], 0
	v_mfma_f32_16x16x32_bf16 v[126:129], v[134:137], v[166:169], v[126:129]
	v_mfma_f32_16x16x32_bf16 v[122:125], v[142:145], v[166:169], v[122:125]
	v_mfma_f32_16x16x32_bf16 v[110:113], v[134:137], v[174:177], v[110:113]
	v_mfma_f32_16x16x32_bf16 v[106:109], v[142:145], v[174:177], v[106:109]
	v_mfma_f32_16x16x32_bf16 v[98:101], v[134:137], v[182:185], v[98:101]
	v_mfma_f32_16x16x32_bf16 v[90:93], v[142:145], v[182:185], v[90:93]
	v_mfma_f32_16x16x32_bf16 v[82:85], v[134:137], v[196:199], v[82:85]
	v_mfma_f32_16x16x32_bf16 v[74:77], v[142:145], v[196:199], v[74:77]
	s_setprio 0
	s_setprio 1
	v_mfma_f32_16x16x32_bf16 v[118:121], v[146:149], v[162:165], 0
	v_mfma_f32_16x16x32_bf16 v[114:117], v[154:157], v[162:165], 0
	v_mfma_f32_16x16x32_bf16 v[102:105], v[146:149], v[170:173], 0
	v_mfma_f32_16x16x32_bf16 v[94:97], v[154:157], v[170:173], 0
	v_mfma_f32_16x16x32_bf16 v[86:89], v[146:149], v[178:181], 0
	v_mfma_f32_16x16x32_bf16 v[78:81], v[154:157], v[178:181], 0
	v_mfma_f32_16x16x32_bf16 v[70:73], v[146:149], v[186:189], 0
	v_mfma_f32_16x16x32_bf16 v[66:69], v[154:157], v[186:189], 0
	v_mfma_f32_16x16x32_bf16 v[118:121], v[150:153], v[166:169], v[118:121]
	v_mfma_f32_16x16x32_bf16 v[114:117], v[158:161], v[166:169], v[114:117]
	v_mfma_f32_16x16x32_bf16 v[102:105], v[150:153], v[174:177], v[102:105]
	v_mfma_f32_16x16x32_bf16 v[94:97], v[158:161], v[174:177], v[94:97]
	v_mfma_f32_16x16x32_bf16 v[86:89], v[150:153], v[182:185], v[86:89]
	v_mfma_f32_16x16x32_bf16 v[78:81], v[158:161], v[182:185], v[78:81]
	v_mfma_f32_16x16x32_bf16 v[70:73], v[150:153], v[196:199], v[70:73]
	v_mfma_f32_16x16x32_bf16 v[66:69], v[158:161], v[196:199], v[66:69]
	s_barrier
	s_setprio 0
	s_add_i32 s37, s37, s24
	v_lshl_add_u64 v[210:211], s[20:21], 0, v[190:191]
	s_mov_b32 m0, s37
	ds_read_b128 v[162:165], v240 offset:16384
	ds_read_b128 v[166:169], v240 offset:17408
	ds_read_b128 v[170:173], v240 offset:18432
	ds_read_b128 v[174:177], v240 offset:19456
	ds_read_b128 v[178:181], v240 offset:20480
	ds_read_b128 v[182:185], v240 offset:21504
	ds_read_b128 v[186:189], v240 offset:22528
	ds_read_b128 v[196:199], v240 offset:23552
	global_load_lds_dwordx4 v[210:211], off
	s_add_i32 m0, s37, 0x2000
	s_add_u32 s38, s20, 0x80000
	v_lshl_add_u64 v[212:213], s[20:21], 0, v[204:205]
	s_addc_u32 s39, s21, 0
	s_add_i32 s37, s40, s24
	global_load_lds_dwordx4 v[212:213], off
	v_lshl_add_u64 v[214:215], s[38:39], 0, v[190:191]
	s_mov_b32 m0, s37
	v_lshl_add_u64 v[216:217], s[22:23], 0, v[202:203]
	global_load_lds_dwordx4 v[214:215], off
	s_add_i32 m0, s37, 0x2000
	v_lshl_add_u64 v[214:215], s[38:39], 0, v[204:205]
	global_load_lds_dwordx4 v[214:215], off
	s_mov_b32 m0, s25
	v_lshl_add_u64 v[214:215], s[22:23], 0, v[200:201]
	global_load_lds_dwordx4 v[214:215], off
	s_mov_b32 m0, s26
	s_nop 0
	global_load_lds_dwordx4 v[216:217], off
	s_waitcnt vmcnt(8) lgkmcnt(0)
	s_setprio 1
	s_barrier
	v_mfma_f32_16x16x32_bf16 v[62:65], v[130:133], v[162:165], 0
	v_mfma_f32_16x16x32_bf16 v[58:61], v[138:141], v[162:165], 0
	v_mfma_f32_16x16x32_bf16 v[50:53], v[130:133], v[170:173], 0
	v_mfma_f32_16x16x32_bf16 v[42:45], v[138:141], v[170:173], 0
	v_mfma_f32_16x16x32_bf16 v[34:37], v[130:133], v[178:181], 0
	v_mfma_f32_16x16x32_bf16 v[26:29], v[138:141], v[178:181], 0
	v_mfma_f32_16x16x32_bf16 v[18:21], v[130:133], v[186:189], 0
	v_mfma_f32_16x16x32_bf16 v[10:13], v[138:141], v[186:189], 0
	v_mfma_f32_16x16x32_bf16 v[62:65], v[134:137], v[166:169], v[62:65]
	v_mfma_f32_16x16x32_bf16 v[58:61], v[142:145], v[166:169], v[58:61]
	v_mfma_f32_16x16x32_bf16 v[50:53], v[134:137], v[174:177], v[50:53]
	v_mfma_f32_16x16x32_bf16 v[42:45], v[142:145], v[174:177], v[42:45]
	v_mfma_f32_16x16x32_bf16 v[34:37], v[134:137], v[182:185], v[34:37]
	v_mfma_f32_16x16x32_bf16 v[26:29], v[142:145], v[182:185], v[26:29]
	v_mfma_f32_16x16x32_bf16 v[18:21], v[134:137], v[196:199], v[18:21]
	v_mfma_f32_16x16x32_bf16 v[10:13], v[142:145], v[196:199], v[10:13]
	s_setprio 0
	s_setprio 1
	v_mfma_f32_16x16x32_bf16 v[54:57], v[146:149], v[162:165], 0
	v_mfma_f32_16x16x32_bf16 v[46:49], v[154:157], v[162:165], 0
	v_mfma_f32_16x16x32_bf16 v[38:41], v[146:149], v[170:173], 0
	v_mfma_f32_16x16x32_bf16 v[30:33], v[154:157], v[170:173], 0
	v_mfma_f32_16x16x32_bf16 v[22:25], v[146:149], v[178:181], 0
	v_mfma_f32_16x16x32_bf16 v[14:17], v[154:157], v[178:181], 0
	v_mfma_f32_16x16x32_bf16 v[6:9], v[146:149], v[186:189], 0
	v_mfma_f32_16x16x32_bf16 v[2:5], v[154:157], v[186:189], 0
	v_mfma_f32_16x16x32_bf16 v[54:57], v[150:153], v[166:169], v[54:57]
	v_mfma_f32_16x16x32_bf16 v[46:49], v[158:161], v[166:169], v[46:49]
	v_mfma_f32_16x16x32_bf16 v[38:41], v[150:153], v[174:177], v[38:41]
	v_mfma_f32_16x16x32_bf16 v[30:33], v[158:161], v[174:177], v[30:33]
	v_mfma_f32_16x16x32_bf16 v[22:25], v[150:153], v[182:185], v[22:25]
	v_mfma_f32_16x16x32_bf16 v[14:17], v[158:161], v[182:185], v[14:17]
	v_mfma_f32_16x16x32_bf16 v[6:9], v[150:153], v[196:199], v[6:9]
	v_mfma_f32_16x16x32_bf16 v[2:5], v[158:161], v[196:199], v[2:5]
	s_barrier
	s_setprio 0
	s_add_i32 s37, 0, 0x18000
	s_add_i32 s38, 0, 0x1c000
	v_add_u32_e32 v142, s37, v238
	v_add_u32_e32 v158, s38, v238
	ds_read_b128 v[130:133], v142
	ds_read_b128 v[134:137], v142 offset:1024
	ds_read_b128 v[138:141], v142 offset:2048
	ds_read_b128 v[142:145], v142 offset:3072
	ds_read_b128 v[146:149], v158
	ds_read_b128 v[150:153], v158 offset:1024
	ds_read_b128 v[154:157], v158 offset:2048
	ds_read_b128 v[158:161], v158 offset:3072
	s_add_u32 s22, s22, 0x80000
	s_addc_u32 s23, s23, 0
	s_mov_b32 m0, s27
	v_lshl_add_u64 v[218:219], s[22:23], 0, v[200:201]
	ds_read_b128 v[162:165], v240 offset:32768
	ds_read_b128 v[166:169], v240 offset:33792
	ds_read_b128 v[170:173], v240 offset:34816
	ds_read_b128 v[174:177], v240 offset:35840
	ds_read_b128 v[178:181], v240 offset:36864
	ds_read_b128 v[182:185], v240 offset:37888
	ds_read_b128 v[186:189], v240 offset:38912
	ds_read_b128 v[196:199], v240 offset:39936
	global_load_lds_dwordx4 v[218:219], off
	s_mov_b32 m0, s28
	v_lshl_add_u64 v[218:219], s[22:23], 0, v[202:203]
	global_load_lds_dwordx4 v[218:219], off
	s_waitcnt vmcnt(8) lgkmcnt(0)
	s_setprio 1
	s_barrier
	v_mfma_f32_16x16x32_bf16 v[126:129], v[130:133], v[162:165], v[126:129]
	v_mfma_f32_16x16x32_bf16 v[122:125], v[138:141], v[162:165], v[122:125]
	v_mfma_f32_16x16x32_bf16 v[110:113], v[130:133], v[170:173], v[110:113]
	v_mfma_f32_16x16x32_bf16 v[106:109], v[138:141], v[170:173], v[106:109]
	v_mfma_f32_16x16x32_bf16 v[98:101], v[130:133], v[178:181], v[98:101]
	v_mfma_f32_16x16x32_bf16 v[90:93], v[138:141], v[178:181], v[90:93]
	v_mfma_f32_16x16x32_bf16 v[82:85], v[130:133], v[186:189], v[82:85]
	v_mfma_f32_16x16x32_bf16 v[74:77], v[138:141], v[186:189], v[74:77]
	v_mfma_f32_16x16x32_bf16 v[126:129], v[134:137], v[166:169], v[126:129]
	v_mfma_f32_16x16x32_bf16 v[122:125], v[142:145], v[166:169], v[122:125]
	v_mfma_f32_16x16x32_bf16 v[110:113], v[134:137], v[174:177], v[110:113]
	v_mfma_f32_16x16x32_bf16 v[106:109], v[142:145], v[174:177], v[106:109]
	v_mfma_f32_16x16x32_bf16 v[98:101], v[134:137], v[182:185], v[98:101]
	v_mfma_f32_16x16x32_bf16 v[90:93], v[142:145], v[182:185], v[90:93]
	v_mfma_f32_16x16x32_bf16 v[82:85], v[134:137], v[196:199], v[82:85]
	v_mfma_f32_16x16x32_bf16 v[74:77], v[142:145], v[196:199], v[74:77]
	s_setprio 0
	s_setprio 1
	v_mfma_f32_16x16x32_bf16 v[118:121], v[146:149], v[162:165], v[118:121]
	v_mfma_f32_16x16x32_bf16 v[114:117], v[154:157], v[162:165], v[114:117]
	v_mfma_f32_16x16x32_bf16 v[102:105], v[146:149], v[170:173], v[102:105]
	v_mfma_f32_16x16x32_bf16 v[94:97], v[154:157], v[170:173], v[94:97]
	v_mfma_f32_16x16x32_bf16 v[86:89], v[146:149], v[178:181], v[86:89]
	v_mfma_f32_16x16x32_bf16 v[78:81], v[154:157], v[178:181], v[78:81]
	v_mfma_f32_16x16x32_bf16 v[70:73], v[146:149], v[186:189], v[70:73]
	v_mfma_f32_16x16x32_bf16 v[66:69], v[154:157], v[186:189], v[66:69]
	v_mfma_f32_16x16x32_bf16 v[118:121], v[150:153], v[166:169], v[118:121]
	v_mfma_f32_16x16x32_bf16 v[114:117], v[158:161], v[166:169], v[114:117]
	v_mfma_f32_16x16x32_bf16 v[102:105], v[150:153], v[174:177], v[102:105]
	v_mfma_f32_16x16x32_bf16 v[94:97], v[158:161], v[174:177], v[94:97]
	v_mfma_f32_16x16x32_bf16 v[86:89], v[150:153], v[182:185], v[86:89]
	v_mfma_f32_16x16x32_bf16 v[78:81], v[158:161], v[182:185], v[78:81]
	v_mfma_f32_16x16x32_bf16 v[70:73], v[150:153], v[196:199], v[70:73]
	v_mfma_f32_16x16x32_bf16 v[66:69], v[158:161], v[196:199], v[66:69]
	s_barrier
	s_setprio 0
	s_add_i32 s22, s37, s24
	v_lshl_add_u64 v[210:211], v[210:211], 0, s[58:59]
	s_mov_b32 m0, s22
	ds_read_b128 v[162:165], v240 offset:49152
	ds_read_b128 v[166:169], v240 offset:50176
	ds_read_b128 v[170:173], v240 offset:51200
	ds_read_b128 v[174:177], v240 offset:52224
	ds_read_b128 v[178:181], v240 offset:53248
	ds_read_b128 v[182:185], v240 offset:54272
	ds_read_b128 v[186:189], v240 offset:55296
	ds_read_b128 v[196:199], v240 offset:56320
	global_load_lds_dwordx4 v[210:211], off
	s_add_i32 m0, s22, 0x2000
	s_add_u32 s20, s20, 0x80080
	v_lshl_add_u64 v[210:211], v[212:213], 0, s[58:59]
	s_addc_u32 s21, s21, 0
	s_add_i32 s22, s38, s24
	global_load_lds_dwordx4 v[210:211], off
	s_mov_b32 m0, s22
	v_lshl_add_u64 v[210:211], s[20:21], 0, v[190:191]
	global_load_lds_dwordx4 v[210:211], off
	s_add_i32 m0, s22, 0x2000
	v_lshl_add_u64 v[210:211], s[20:21], 0, v[204:205]
	global_load_lds_dwordx4 v[210:211], off
	s_mov_b32 m0, s29
	v_lshl_add_u64 v[210:211], v[214:215], 0, s[58:59]
	global_load_lds_dwordx4 v[210:211], off
	s_mov_b32 m0, s30
	v_lshl_add_u64 v[210:211], v[216:217], 0, s[58:59]
	global_load_lds_dwordx4 v[210:211], off
	s_waitcnt vmcnt(8) lgkmcnt(0)
	s_setprio 1
	s_barrier
	v_mfma_f32_16x16x32_bf16 v[62:65], v[130:133], v[162:165], v[62:65]
	v_mfma_f32_16x16x32_bf16 v[58:61], v[138:141], v[162:165], v[58:61]
	v_mfma_f32_16x16x32_bf16 v[50:53], v[130:133], v[170:173], v[50:53]
	v_mfma_f32_16x16x32_bf16 v[42:45], v[138:141], v[170:173], v[42:45]
	v_mfma_f32_16x16x32_bf16 v[34:37], v[130:133], v[178:181], v[34:37]
	v_mfma_f32_16x16x32_bf16 v[26:29], v[138:141], v[178:181], v[26:29]
	v_mfma_f32_16x16x32_bf16 v[18:21], v[130:133], v[186:189], v[18:21]
	v_mfma_f32_16x16x32_bf16 v[10:13], v[138:141], v[186:189], v[10:13]
	v_mfma_f32_16x16x32_bf16 v[62:65], v[134:137], v[166:169], v[62:65]
	v_mfma_f32_16x16x32_bf16 v[58:61], v[142:145], v[166:169], v[58:61]
	v_mfma_f32_16x16x32_bf16 v[50:53], v[134:137], v[174:177], v[50:53]
	v_mfma_f32_16x16x32_bf16 v[42:45], v[142:145], v[174:177], v[42:45]
	v_mfma_f32_16x16x32_bf16 v[34:37], v[134:137], v[182:185], v[34:37]
	v_mfma_f32_16x16x32_bf16 v[26:29], v[142:145], v[182:185], v[26:29]
	v_mfma_f32_16x16x32_bf16 v[18:21], v[134:137], v[196:199], v[18:21]
	v_mfma_f32_16x16x32_bf16 v[10:13], v[142:145], v[196:199], v[10:13]
	s_setprio 0
	s_setprio 1
	v_mfma_f32_16x16x32_bf16 v[54:57], v[146:149], v[162:165], v[54:57]
	v_mfma_f32_16x16x32_bf16 v[46:49], v[154:157], v[162:165], v[46:49]
	v_mfma_f32_16x16x32_bf16 v[38:41], v[146:149], v[170:173], v[38:41]
	v_mfma_f32_16x16x32_bf16 v[30:33], v[154:157], v[170:173], v[30:33]
	v_mfma_f32_16x16x32_bf16 v[22:25], v[146:149], v[178:181], v[22:25]
	v_mfma_f32_16x16x32_bf16 v[14:17], v[154:157], v[178:181], v[14:17]
	v_mfma_f32_16x16x32_bf16 v[6:9], v[146:149], v[186:189], v[6:9]
	v_mfma_f32_16x16x32_bf16 v[2:5], v[154:157], v[186:189], v[2:5]
	v_mfma_f32_16x16x32_bf16 v[54:57], v[150:153], v[166:169], v[54:57]
	v_mfma_f32_16x16x32_bf16 v[46:49], v[158:161], v[166:169], v[46:49]
	v_mfma_f32_16x16x32_bf16 v[38:41], v[150:153], v[174:177], v[38:41]
	v_mfma_f32_16x16x32_bf16 v[30:33], v[158:161], v[174:177], v[30:33]
	v_mfma_f32_16x16x32_bf16 v[22:25], v[150:153], v[182:185], v[22:25]
	v_mfma_f32_16x16x32_bf16 v[14:17], v[158:161], v[182:185], v[14:17]
	v_mfma_f32_16x16x32_bf16 v[6:9], v[150:153], v[196:199], v[6:9]
	v_mfma_f32_16x16x32_bf16 v[2:5], v[158:161], v[196:199], v[2:5]
	s_barrier
	s_setprio 0
	s_add_i32 s36, s36, 2
	s_add_u32 s16, s16, 0x100
	s_addc_u32 s17, s17, 0
	s_add_u32 s34, s34, 0x100
	s_addc_u32 s35, s35, 0
	s_cmp_gt_u32 s36, 29
	s_cbranch_scc1 .Lpeel_done_2
.LBB0_748:
	s_add_u32 s20, s16, 0xfff80080
	s_addc_u32 s21, s17, -1
	s_add_i32 s37, 0, 0x10000
	s_cmp_eq_u32 s36, 28
	s_cselect_b32 s23, s9, s21
	s_cselect_b32 s22, s31, s20
	s_cselect_b32 s21, s7, s35
	s_cselect_b32 s20, s33, s34
	s_add_i32 s40, 0, 0x14000
	v_add_u32_e32 v142, s37, v238
	v_add_u32_e32 v158, s40, v238
	ds_read_b128 v[130:133], v142
	ds_read_b128 v[134:137], v142 offset:1024
	ds_read_b128 v[138:141], v142 offset:2048
	ds_read_b128 v[142:145], v142 offset:3072
	ds_read_b128 v[146:149], v158
	ds_read_b128 v[150:153], v158 offset:1024
	ds_read_b128 v[154:157], v158 offset:2048
	ds_read_b128 v[158:161], v158 offset:3072
	v_lshl_add_u64 v[210:211], s[16:17], 0, v[206:207]
	s_add_i32 m0, s25, 0xc000
	ds_read_b128 v[162:165], v240
	ds_read_b128 v[166:169], v240 offset:1024
	ds_read_b128 v[170:173], v240 offset:2048
	ds_read_b128 v[174:177], v240 offset:3072
	ds_read_b128 v[178:181], v240 offset:4096
	ds_read_b128 v[182:185], v240 offset:5120
	ds_read_b128 v[186:189], v240 offset:6144
	ds_read_b128 v[196:199], v240 offset:7168
	global_load_lds_dwordx4 v[210:211], off
	s_add_i32 m0, s25, 0xe000
	v_lshl_add_u64 v[210:211], s[16:17], 0, v[208:209]
	global_load_lds_dwordx4 v[210:211], off
	s_waitcnt vmcnt(8) lgkmcnt(0)
	s_setprio 1
	s_barrier
	v_mfma_f32_16x16x32_bf16 v[126:129], v[130:133], v[162:165], v[126:129]
	v_mfma_f32_16x16x32_bf16 v[122:125], v[138:141], v[162:165], v[122:125]
	v_mfma_f32_16x16x32_bf16 v[110:113], v[130:133], v[170:173], v[110:113]
	v_mfma_f32_16x16x32_bf16 v[106:109], v[138:141], v[170:173], v[106:109]
	v_mfma_f32_16x16x32_bf16 v[98:101], v[130:133], v[178:181], v[98:101]
	v_mfma_f32_16x16x32_bf16 v[90:93], v[138:141], v[178:181], v[90:93]
	v_mfma_f32_16x16x32_bf16 v[82:85], v[130:133], v[186:189], v[82:85]
	v_mfma_f32_16x16x32_bf16 v[74:77], v[138:141], v[186:189], v[74:77]
	v_mfma_f32_16x16x32_bf16 v[126:129], v[134:137], v[166:169], v[126:129]
	v_mfma_f32_16x16x32_bf16 v[122:125], v[142:145], v[166:169], v[122:125]
	v_mfma_f32_16x16x32_bf16 v[110:113], v[134:137], v[174:177], v[110:113]
	v_mfma_f32_16x16x32_bf16 v[106:109], v[142:145], v[174:177], v[106:109]
	v_mfma_f32_16x16x32_bf16 v[98:101], v[134:137], v[182:185], v[98:101]
	v_mfma_f32_16x16x32_bf16 v[90:93], v[142:145], v[182:185], v[90:93]
	v_mfma_f32_16x16x32_bf16 v[82:85], v[134:137], v[196:199], v[82:85]
	v_mfma_f32_16x16x32_bf16 v[74:77], v[142:145], v[196:199], v[74:77]
	s_setprio 0
	s_setprio 1
	v_mfma_f32_16x16x32_bf16 v[118:121], v[146:149], v[162:165], v[118:121]
	v_mfma_f32_16x16x32_bf16 v[114:117], v[154:157], v[162:165], v[114:117]
	v_mfma_f32_16x16x32_bf16 v[102:105], v[146:149], v[170:173], v[102:105]
	v_mfma_f32_16x16x32_bf16 v[94:97], v[154:157], v[170:173], v[94:97]
	v_mfma_f32_16x16x32_bf16 v[86:89], v[146:149], v[178:181], v[86:89]
	v_mfma_f32_16x16x32_bf16 v[78:81], v[154:157], v[178:181], v[78:81]
	v_mfma_f32_16x16x32_bf16 v[70:73], v[146:149], v[186:189], v[70:73]
	v_mfma_f32_16x16x32_bf16 v[66:69], v[154:157], v[186:189], v[66:69]
	v_mfma_f32_16x16x32_bf16 v[118:121], v[150:153], v[166:169], v[118:121]
	v_mfma_f32_16x16x32_bf16 v[114:117], v[158:161], v[166:169], v[114:117]
	v_mfma_f32_16x16x32_bf16 v[102:105], v[150:153], v[174:177], v[102:105]
	v_mfma_f32_16x16x32_bf16 v[94:97], v[158:161], v[174:177], v[94:97]
	v_mfma_f32_16x16x32_bf16 v[86:89], v[150:153], v[182:185], v[86:89]
	v_mfma_f32_16x16x32_bf16 v[78:81], v[158:161], v[182:185], v[78:81]
	v_mfma_f32_16x16x32_bf16 v[70:73], v[150:153], v[196:199], v[70:73]
	v_mfma_f32_16x16x32_bf16 v[66:69], v[158:161], v[196:199], v[66:69]
	s_setprio 0
	s_barrier
	s_add_i32 s37, s37, s24
	v_lshl_add_u64 v[210:211], s[20:21], 0, v[190:191]
	s_mov_b32 m0, s37
	ds_read_b128 v[162:165], v240 offset:16384
	ds_read_b128 v[166:169], v240 offset:17408
	ds_read_b128 v[170:173], v240 offset:18432
	ds_read_b128 v[174:177], v240 offset:19456
	ds_read_b128 v[178:181], v240 offset:20480
	ds_read_b128 v[182:185], v240 offset:21504
	ds_read_b128 v[186:189], v240 offset:22528
	ds_read_b128 v[196:199], v240 offset:23552
	global_load_lds_dwordx4 v[210:211], off
	s_add_i32 m0, s37, 0x2000
	s_add_u32 s38, s20, 0x80000
	v_lshl_add_u64 v[212:213], s[20:21], 0, v[204:205]
	s_addc_u32 s39, s21, 0
	s_add_i32 s37, s40, s24
	global_load_lds_dwordx4 v[212:213], off
	v_lshl_add_u64 v[214:215], s[38:39], 0, v[190:191]
	s_mov_b32 m0, s37
	v_lshl_add_u64 v[216:217], s[22:23], 0, v[202:203]
	global_load_lds_dwordx4 v[214:215], off
	s_add_i32 m0, s37, 0x2000
	v_lshl_add_u64 v[214:215], s[38:39], 0, v[204:205]
	global_load_lds_dwordx4 v[214:215], off
	s_mov_b32 m0, s25
	v_lshl_add_u64 v[214:215], s[22:23], 0, v[200:201]
	global_load_lds_dwordx4 v[214:215], off
	s_mov_b32 m0, s26
	s_nop 0
	global_load_lds_dwordx4 v[216:217], off
	s_waitcnt vmcnt(8) lgkmcnt(0)
	s_setprio 1
	s_barrier
	v_mfma_f32_16x16x32_bf16 v[62:65], v[130:133], v[162:165], v[62:65]
	v_mfma_f32_16x16x32_bf16 v[58:61], v[138:141], v[162:165], v[58:61]
	v_mfma_f32_16x16x32_bf16 v[50:53], v[130:133], v[170:173], v[50:53]
	v_mfma_f32_16x16x32_bf16 v[42:45], v[138:141], v[170:173], v[42:45]
	v_mfma_f32_16x16x32_bf16 v[34:37], v[130:133], v[178:181], v[34:37]
	v_mfma_f32_16x16x32_bf16 v[26:29], v[138:141], v[178:181], v[26:29]
	v_mfma_f32_16x16x32_bf16 v[18:21], v[130:133], v[186:189], v[18:21]
	v_mfma_f32_16x16x32_bf16 v[10:13], v[138:141], v[186:189], v[10:13]
	v_mfma_f32_16x16x32_bf16 v[62:65], v[134:137], v[166:169], v[62:65]
	v_mfma_f32_16x16x32_bf16 v[58:61], v[142:145], v[166:169], v[58:61]
	v_mfma_f32_16x16x32_bf16 v[50:53], v[134:137], v[174:177], v[50:53]
	v_mfma_f32_16x16x32_bf16 v[42:45], v[142:145], v[174:177], v[42:45]
	v_mfma_f32_16x16x32_bf16 v[34:37], v[134:137], v[182:185], v[34:37]
	v_mfma_f32_16x16x32_bf16 v[26:29], v[142:145], v[182:185], v[26:29]
	v_mfma_f32_16x16x32_bf16 v[18:21], v[134:137], v[196:199], v[18:21]
	v_mfma_f32_16x16x32_bf16 v[10:13], v[142:145], v[196:199], v[10:13]
	s_setprio 0
	s_setprio 1
	v_mfma_f32_16x16x32_bf16 v[54:57], v[146:149], v[162:165], v[54:57]
	v_mfma_f32_16x16x32_bf16 v[46:49], v[154:157], v[162:165], v[46:49]
	v_mfma_f32_16x16x32_bf16 v[38:41], v[146:149], v[170:173], v[38:41]
	v_mfma_f32_16x16x32_bf16 v[30:33], v[154:157], v[170:173], v[30:33]
	v_mfma_f32_16x16x32_bf16 v[22:25], v[146:149], v[178:181], v[22:25]
	v_mfma_f32_16x16x32_bf16 v[14:17], v[154:157], v[178:181], v[14:17]
	v_mfma_f32_16x16x32_bf16 v[6:9], v[146:149], v[186:189], v[6:9]
	v_mfma_f32_16x16x32_bf16 v[2:5], v[154:157], v[186:189], v[2:5]
	v_mfma_f32_16x16x32_bf16 v[54:57], v[150:153], v[166:169], v[54:57]
	v_mfma_f32_16x16x32_bf16 v[46:49], v[158:161], v[166:169], v[46:49]
	v_mfma_f32_16x16x32_bf16 v[38:41], v[150:153], v[174:177], v[38:41]
	v_mfma_f32_16x16x32_bf16 v[30:33], v[158:161], v[174:177], v[30:33]
	v_mfma_f32_16x16x32_bf16 v[22:25], v[150:153], v[182:185], v[22:25]
	v_mfma_f32_16x16x32_bf16 v[14:17], v[158:161], v[182:185], v[14:17]
	v_mfma_f32_16x16x32_bf16 v[6:9], v[150:153], v[196:199], v[6:9]
	v_mfma_f32_16x16x32_bf16 v[2:5], v[158:161], v[196:199], v[2:5]
	s_setprio 0
	s_barrier
	s_add_i32 s37, 0, 0x18000
	s_add_i32 s38, 0, 0x1c000
	v_add_u32_e32 v142, s37, v238
	v_add_u32_e32 v158, s38, v238
	ds_read_b128 v[130:133], v142
	ds_read_b128 v[134:137], v142 offset:1024
	ds_read_b128 v[138:141], v142 offset:2048
	ds_read_b128 v[142:145], v142 offset:3072
	ds_read_b128 v[146:149], v158
	ds_read_b128 v[150:153], v158 offset:1024
	ds_read_b128 v[154:157], v158 offset:2048
	ds_read_b128 v[158:161], v158 offset:3072
	s_add_u32 s22, s22, 0x80000
	s_addc_u32 s23, s23, 0
	s_mov_b32 m0, s27
	v_lshl_add_u64 v[218:219], s[22:23], 0, v[200:201]
	ds_read_b128 v[162:165], v240 offset:32768
	ds_read_b128 v[166:169], v240 offset:33792
	ds_read_b128 v[170:173], v240 offset:34816
	ds_read_b128 v[174:177], v240 offset:35840
	ds_read_b128 v[178:181], v240 offset:36864
	ds_read_b128 v[182:185], v240 offset:37888
	ds_read_b128 v[186:189], v240 offset:38912
	ds_read_b128 v[196:199], v240 offset:39936
	global_load_lds_dwordx4 v[218:219], off
	s_mov_b32 m0, s28
	v_lshl_add_u64 v[218:219], s[22:23], 0, v[202:203]
	global_load_lds_dwordx4 v[218:219], off
	s_waitcnt vmcnt(8) lgkmcnt(0)
	s_setprio 1
	s_barrier
	v_mfma_f32_16x16x32_bf16 v[126:129], v[130:133], v[162:165], v[126:129]
	v_mfma_f32_16x16x32_bf16 v[122:125], v[138:141], v[162:165], v[122:125]
	v_mfma_f32_16x16x32_bf16 v[110:113], v[130:133], v[170:173], v[110:113]
	v_mfma_f32_16x16x32_bf16 v[106:109], v[138:141], v[170:173], v[106:109]
	v_mfma_f32_16x16x32_bf16 v[98:101], v[130:133], v[178:181], v[98:101]
	v_mfma_f32_16x16x32_bf16 v[90:93], v[138:141], v[178:181], v[90:93]
	v_mfma_f32_16x16x32_bf16 v[82:85], v[130:133], v[186:189], v[82:85]
	v_mfma_f32_16x16x32_bf16 v[74:77], v[138:141], v[186:189], v[74:77]
	v_mfma_f32_16x16x32_bf16 v[126:129], v[134:137], v[166:169], v[126:129]
	v_mfma_f32_16x16x32_bf16 v[122:125], v[142:145], v[166:169], v[122:125]
	v_mfma_f32_16x16x32_bf16 v[110:113], v[134:137], v[174:177], v[110:113]
	v_mfma_f32_16x16x32_bf16 v[106:109], v[142:145], v[174:177], v[106:109]
	v_mfma_f32_16x16x32_bf16 v[98:101], v[134:137], v[182:185], v[98:101]
	v_mfma_f32_16x16x32_bf16 v[90:93], v[142:145], v[182:185], v[90:93]
	v_mfma_f32_16x16x32_bf16 v[82:85], v[134:137], v[196:199], v[82:85]
	v_mfma_f32_16x16x32_bf16 v[74:77], v[142:145], v[196:199], v[74:77]
	s_setprio 0
	s_setprio 1
	v_mfma_f32_16x16x32_bf16 v[118:121], v[146:149], v[162:165], v[118:121]
	v_mfma_f32_16x16x32_bf16 v[114:117], v[154:157], v[162:165], v[114:117]
	v_mfma_f32_16x16x32_bf16 v[102:105], v[146:149], v[170:173], v[102:105]
	v_mfma_f32_16x16x32_bf16 v[94:97], v[154:157], v[170:173], v[94:97]
	v_mfma_f32_16x16x32_bf16 v[86:89], v[146:149], v[178:181], v[86:89]
	v_mfma_f32_16x16x32_bf16 v[78:81], v[154:157], v[178:181], v[78:81]
	v_mfma_f32_16x16x32_bf16 v[70:73], v[146:149], v[186:189], v[70:73]
	v_mfma_f32_16x16x32_bf16 v[66:69], v[154:157], v[186:189], v[66:69]
	v_mfma_f32_16x16x32_bf16 v[118:121], v[150:153], v[166:169], v[118:121]
	v_mfma_f32_16x16x32_bf16 v[114:117], v[158:161], v[166:169], v[114:117]
	v_mfma_f32_16x16x32_bf16 v[102:105], v[150:153], v[174:177], v[102:105]
	v_mfma_f32_16x16x32_bf16 v[94:97], v[158:161], v[174:177], v[94:97]
	v_mfma_f32_16x16x32_bf16 v[86:89], v[150:153], v[182:185], v[86:89]
	v_mfma_f32_16x16x32_bf16 v[78:81], v[158:161], v[182:185], v[78:81]
	v_mfma_f32_16x16x32_bf16 v[70:73], v[150:153], v[196:199], v[70:73]
	v_mfma_f32_16x16x32_bf16 v[66:69], v[158:161], v[196:199], v[66:69]
	s_setprio 0
	s_barrier
	s_add_i32 s22, s37, s24
	v_lshl_add_u64 v[210:211], v[210:211], 0, s[58:59]
	s_mov_b32 m0, s22
	ds_read_b128 v[162:165], v240 offset:49152
	ds_read_b128 v[166:169], v240 offset:50176
	ds_read_b128 v[170:173], v240 offset:51200
	ds_read_b128 v[174:177], v240 offset:52224
	ds_read_b128 v[178:181], v240 offset:53248
	ds_read_b128 v[182:185], v240 offset:54272
	ds_read_b128 v[186:189], v240 offset:55296
	ds_read_b128 v[196:199], v240 offset:56320
	global_load_lds_dwordx4 v[210:211], off
	s_add_i32 m0, s22, 0x2000
	s_add_u32 s20, s20, 0x80080
	v_lshl_add_u64 v[210:211], v[212:213], 0, s[58:59]
	s_addc_u32 s21, s21, 0
	s_add_i32 s22, s38, s24
	global_load_lds_dwordx4 v[210:211], off
	s_mov_b32 m0, s22
	v_lshl_add_u64 v[210:211], s[20:21], 0, v[190:191]
	global_load_lds_dwordx4 v[210:211], off
	s_add_i32 m0, s22, 0x2000
	v_lshl_add_u64 v[210:211], s[20:21], 0, v[204:205]
	global_load_lds_dwordx4 v[210:211], off
	s_mov_b32 m0, s29
	v_lshl_add_u64 v[210:211], v[214:215], 0, s[58:59]
	global_load_lds_dwordx4 v[210:211], off
	s_mov_b32 m0, s30
	v_lshl_add_u64 v[210:211], v[216:217], 0, s[58:59]
	global_load_lds_dwordx4 v[210:211], off
	s_waitcnt vmcnt(8) lgkmcnt(0)
	s_setprio 1
	s_barrier
	v_mfma_f32_16x16x32_bf16 v[62:65], v[130:133], v[162:165], v[62:65]
	v_mfma_f32_16x16x32_bf16 v[58:61], v[138:141], v[162:165], v[58:61]
	v_mfma_f32_16x16x32_bf16 v[50:53], v[130:133], v[170:173], v[50:53]
	v_mfma_f32_16x16x32_bf16 v[42:45], v[138:141], v[170:173], v[42:45]
	v_mfma_f32_16x16x32_bf16 v[34:37], v[130:133], v[178:181], v[34:37]
	v_mfma_f32_16x16x32_bf16 v[26:29], v[138:141], v[178:181], v[26:29]
	v_mfma_f32_16x16x32_bf16 v[18:21], v[130:133], v[186:189], v[18:21]
	v_mfma_f32_16x16x32_bf16 v[10:13], v[138:141], v[186:189], v[10:13]
	v_mfma_f32_16x16x32_bf16 v[62:65], v[134:137], v[166:169], v[62:65]
	v_mfma_f32_16x16x32_bf16 v[58:61], v[142:145], v[166:169], v[58:61]
	v_mfma_f32_16x16x32_bf16 v[50:53], v[134:137], v[174:177], v[50:53]
	v_mfma_f32_16x16x32_bf16 v[42:45], v[142:145], v[174:177], v[42:45]
	v_mfma_f32_16x16x32_bf16 v[34:37], v[134:137], v[182:185], v[34:37]
	v_mfma_f32_16x16x32_bf16 v[26:29], v[142:145], v[182:185], v[26:29]
	v_mfma_f32_16x16x32_bf16 v[18:21], v[134:137], v[196:199], v[18:21]
	v_mfma_f32_16x16x32_bf16 v[10:13], v[142:145], v[196:199], v[10:13]
	s_setprio 0
	s_setprio 1
	v_mfma_f32_16x16x32_bf16 v[54:57], v[146:149], v[162:165], v[54:57]
	v_mfma_f32_16x16x32_bf16 v[46:49], v[154:157], v[162:165], v[46:49]
	v_mfma_f32_16x16x32_bf16 v[38:41], v[146:149], v[170:173], v[38:41]
	v_mfma_f32_16x16x32_bf16 v[30:33], v[154:157], v[170:173], v[30:33]
	v_mfma_f32_16x16x32_bf16 v[22:25], v[146:149], v[178:181], v[22:25]
	v_mfma_f32_16x16x32_bf16 v[14:17], v[154:157], v[178:181], v[14:17]
	v_mfma_f32_16x16x32_bf16 v[6:9], v[146:149], v[186:189], v[6:9]
	v_mfma_f32_16x16x32_bf16 v[2:5], v[154:157], v[186:189], v[2:5]
	v_mfma_f32_16x16x32_bf16 v[54:57], v[150:153], v[166:169], v[54:57]
	v_mfma_f32_16x16x32_bf16 v[46:49], v[158:161], v[166:169], v[46:49]
	v_mfma_f32_16x16x32_bf16 v[38:41], v[150:153], v[174:177], v[38:41]
	v_mfma_f32_16x16x32_bf16 v[30:33], v[158:161], v[174:177], v[30:33]
	v_mfma_f32_16x16x32_bf16 v[22:25], v[150:153], v[182:185], v[22:25]
	v_mfma_f32_16x16x32_bf16 v[14:17], v[158:161], v[182:185], v[14:17]
	v_mfma_f32_16x16x32_bf16 v[6:9], v[150:153], v[196:199], v[6:9]
	v_mfma_f32_16x16x32_bf16 v[2:5], v[158:161], v[196:199], v[2:5]
	s_setprio 0
	s_barrier
	s_add_i32 s36, s36, 2
	s_add_u32 s16, s16, 0x100
	s_addc_u32 s17, s17, 0
	s_add_u32 s34, s34, 0x100
	s_addc_u32 s35, s35, 0
	s_cmp_gt_u32 s36, 29
	s_cbranch_scc0 .LBB0_748

.LBB0_771:
	s_ashr_i32 s17, s16, 31
	s_lshl_b64 s[20:21], s[16:17], 20
	v_readlane_b32 s0, v254, 60
	s_add_u32 s20, s0, s20
	v_readlane_b32 s0, v254, 61
	s_addc_u32 s21, s0, s21
	s_and_b64 s[22:23], s[6:7], exec
	s_cselect_b32 s17, s21, s27
	s_cselect_b32 s40, s20, s26
	s_ashr_i32 s15, s14, 31
	s_lshl_b64 s[22:23], s[14:15], 20
	v_readlane_b32 s0, v254, 40
	v_readlane_b32 s1, v254, 41
	s_add_u32 s22, s0, s22
	s_addc_u32 s23, s1, s23
	s_and_b64 s[30:31], s[6:7], exec
	s_cselect_b32 s15, s23, s29
	s_cselect_b32 s41, s22, s28
	s_add_u32 s26, s26, 0x80080
	s_addc_u32 s27, s27, 0
	s_add_u32 s42, s28, 0x100
	s_addc_u32 s43, s29, 0
	s_mov_b32 s46, -2
	v_readlane_b32 s47, v255, 49
	s_nop 3
	s_cmp_eq_u32 s47, 4
	v_writelane_b32 v255, 4, 49
	s_cbranch_scc0 .Ltrip0_strict_3
	s_add_u32 s28, s26, 0xfff80080
	s_addc_u32 s29, s27, -1
	s_add_i32 s47, 0, 0x10000
	s_cmp_eq_u32 s46, 28
	s_cselect_b32 s31, s17, s29
	s_cselect_b32 s30, s40, s28
	s_cselect_b32 s29, s15, s43
	s_cselect_b32 s28, s41, s42
	s_add_i32 s55, 0, 0x14000
	v_add_u32_e32 v142, s47, v220
	v_add_u32_e32 v158, s55, v220
	ds_read_b128 v[130:133], v142
	ds_read_b128 v[134:137], v142 offset:1024
	ds_read_b128 v[138:141], v142 offset:2048
	ds_read_b128 v[142:145], v142 offset:3072
	ds_read_b128 v[146:149], v158
	ds_read_b128 v[150:153], v158 offset:1024
	ds_read_b128 v[154:157], v158 offset:2048
	ds_read_b128 v[158:161], v158 offset:3072
	v_lshl_add_u64 v[210:211], s[26:27], 0, v[202:203]
	s_add_i32 m0, s34, 0xc000
	ds_read_b128 v[162:165], v222
	ds_read_b128 v[166:169], v222 offset:1024
	ds_read_b128 v[170:173], v222 offset:2048
	ds_read_b128 v[174:177], v222 offset:3072
	ds_read_b128 v[178:181], v222 offset:4096
	ds_read_b128 v[182:185], v222 offset:5120
	ds_read_b128 v[196:199], v222 offset:6144
	ds_read_b128 v[206:209], v222 offset:7168
	global_load_lds_dwordx4 v[210:211], off
	s_add_i32 m0, s34, 0xe000
	v_lshl_add_u64 v[210:211], s[26:27], 0, v[204:205]
	global_load_lds_dwordx4 v[210:211], off
	s_waitcnt vmcnt(24) lgkmcnt(0)
	s_setprio 1
	s_barrier
	v_mfma_f32_16x16x32_bf16 v[126:129], v[130:133], v[162:165], 0
	v_mfma_f32_16x16x32_bf16 v[122:125], v[138:141], v[162:165], 0
	v_mfma_f32_16x16x32_bf16 v[110:113], v[130:133], v[170:173], 0
	v_mfma_f32_16x16x32_bf16 v[106:109], v[138:141], v[170:173], 0
	v_mfma_f32_16x16x32_bf16 v[94:97], v[130:133], v[178:181], 0
	v_mfma_f32_16x16x32_bf16 v[90:93], v[138:141], v[178:181], 0
	v_mfma_f32_16x16x32_bf16 v[78:81], v[130:133], v[196:199], 0
	v_mfma_f32_16x16x32_bf16 v[74:77], v[138:141], v[196:199], 0
	v_mfma_f32_16x16x32_bf16 v[126:129], v[134:137], v[166:169], v[126:129]
	v_mfma_f32_16x16x32_bf16 v[122:125], v[142:145], v[166:169], v[122:125]
	v_mfma_f32_16x16x32_bf16 v[110:113], v[134:137], v[174:177], v[110:113]
	v_mfma_f32_16x16x32_bf16 v[106:109], v[142:145], v[174:177], v[106:109]
	v_mfma_f32_16x16x32_bf16 v[94:97], v[134:137], v[182:185], v[94:97]
	v_mfma_f32_16x16x32_bf16 v[90:93], v[142:145], v[182:185], v[90:93]
	v_mfma_f32_16x16x32_bf16 v[78:81], v[134:137], v[206:209], v[78:81]
	v_mfma_f32_16x16x32_bf16 v[74:77], v[142:145], v[206:209], v[74:77]
	s_setprio 0
	s_setprio 1
	v_mfma_f32_16x16x32_bf16 v[118:121], v[146:149], v[162:165], 0
	v_mfma_f32_16x16x32_bf16 v[114:117], v[154:157], v[162:165], 0
	v_mfma_f32_16x16x32_bf16 v[102:105], v[146:149], v[170:173], 0
	v_mfma_f32_16x16x32_bf16 v[98:101], v[154:157], v[170:173], 0
	v_mfma_f32_16x16x32_bf16 v[86:89], v[146:149], v[178:181], 0
	v_mfma_f32_16x16x32_bf16 v[82:85], v[154:157], v[178:181], 0
	v_mfma_f32_16x16x32_bf16 v[70:73], v[146:149], v[196:199], 0
	v_mfma_f32_16x16x32_bf16 v[66:69], v[154:157], v[196:199], 0
	v_mfma_f32_16x16x32_bf16 v[118:121], v[150:153], v[166:169], v[118:121]
	v_mfma_f32_16x16x32_bf16 v[114:117], v[158:161], v[166:169], v[114:117]
	v_mfma_f32_16x16x32_bf16 v[102:105], v[150:153], v[174:177], v[102:105]
	v_mfma_f32_16x16x32_bf16 v[98:101], v[158:161], v[174:177], v[98:101]
	v_mfma_f32_16x16x32_bf16 v[86:89], v[150:153], v[182:185], v[86:89]
	v_mfma_f32_16x16x32_bf16 v[82:85], v[158:161], v[182:185], v[82:85]
	v_mfma_f32_16x16x32_bf16 v[70:73], v[150:153], v[206:209], v[70:73]
	v_mfma_f32_16x16x32_bf16 v[66:69], v[158:161], v[206:209], v[66:69]
	s_barrier
	s_setprio 0
	s_add_i32 s47, s47, s33
	v_lshl_add_u64 v[210:211], s[28:29], 0, v[190:191]
	s_mov_b32 m0, s47
	ds_read_b128 v[162:165], v222 offset:16384
	ds_read_b128 v[166:169], v222 offset:17408
	ds_read_b128 v[170:173], v222 offset:18432
	ds_read_b128 v[174:177], v222 offset:19456
	ds_read_b128 v[178:181], v222 offset:20480
	ds_read_b128 v[182:185], v222 offset:21504
	ds_read_b128 v[196:199], v222 offset:22528
	ds_read_b128 v[206:209], v222 offset:23552
	global_load_lds_dwordx4 v[210:211], off
	s_add_i32 m0, s47, 0x2000
	s_add_u32 s52, s28, 0x80000
	v_lshl_add_u64 v[212:213], s[28:29], 0, v[200:201]
	s_addc_u32 s53, s29, 0
	s_add_i32 s47, s55, s33
	global_load_lds_dwordx4 v[212:213], off
	v_lshl_add_u64 v[214:215], s[52:53], 0, v[190:191]
	s_mov_b32 m0, s47
	v_lshl_add_u64 v[216:217], s[30:31], 0, v[188:189]
	global_load_lds_dwordx4 v[214:215], off
	s_add_i32 m0, s47, 0x2000
	v_lshl_add_u64 v[214:215], s[52:53], 0, v[200:201]
	global_load_lds_dwordx4 v[214:215], off
	s_mov_b32 m0, s34
	v_lshl_add_u64 v[214:215], s[30:31], 0, v[186:187]
	global_load_lds_dwordx4 v[214:215], off
	s_mov_b32 m0, s35
	s_nop 0
	global_load_lds_dwordx4 v[216:217], off
	s_waitcnt vmcnt(24) lgkmcnt(0)
	s_setprio 1
	s_barrier
	v_mfma_f32_16x16x32_bf16 v[62:65], v[130:133], v[162:165], 0
	v_mfma_f32_16x16x32_bf16 v[58:61], v[138:141], v[162:165], 0
	v_mfma_f32_16x16x32_bf16 v[46:49], v[130:133], v[170:173], 0
	v_mfma_f32_16x16x32_bf16 v[42:45], v[138:141], v[170:173], 0
	v_mfma_f32_16x16x32_bf16 v[30:33], v[130:133], v[178:181], 0
	v_mfma_f32_16x16x32_bf16 v[26:29], v[138:141], v[178:181], 0
	v_mfma_f32_16x16x32_bf16 v[14:17], v[130:133], v[196:199], 0
	v_mfma_f32_16x16x32_bf16 v[10:13], v[138:141], v[196:199], 0
	v_mfma_f32_16x16x32_bf16 v[62:65], v[134:137], v[166:169], v[62:65]
	v_mfma_f32_16x16x32_bf16 v[58:61], v[142:145], v[166:169], v[58:61]
	v_mfma_f32_16x16x32_bf16 v[46:49], v[134:137], v[174:177], v[46:49]
	v_mfma_f32_16x16x32_bf16 v[42:45], v[142:145], v[174:177], v[42:45]
	v_mfma_f32_16x16x32_bf16 v[30:33], v[134:137], v[182:185], v[30:33]
	v_mfma_f32_16x16x32_bf16 v[26:29], v[142:145], v[182:185], v[26:29]
	v_mfma_f32_16x16x32_bf16 v[14:17], v[134:137], v[206:209], v[14:17]
	v_mfma_f32_16x16x32_bf16 v[10:13], v[142:145], v[206:209], v[10:13]
	s_setprio 0
	s_setprio 1
	v_mfma_f32_16x16x32_bf16 v[54:57], v[146:149], v[162:165], 0
	v_mfma_f32_16x16x32_bf16 v[50:53], v[154:157], v[162:165], 0
	v_mfma_f32_16x16x32_bf16 v[38:41], v[146:149], v[170:173], 0
	v_mfma_f32_16x16x32_bf16 v[34:37], v[154:157], v[170:173], 0
	v_mfma_f32_16x16x32_bf16 v[22:25], v[146:149], v[178:181], 0
	v_mfma_f32_16x16x32_bf16 v[18:21], v[154:157], v[178:181], 0
	v_mfma_f32_16x16x32_bf16 v[6:9], v[146:149], v[196:199], 0
	v_mfma_f32_16x16x32_bf16 v[2:5], v[154:157], v[196:199], 0
	v_mfma_f32_16x16x32_bf16 v[54:57], v[150:153], v[166:169], v[54:57]
	v_mfma_f32_16x16x32_bf16 v[50:53], v[158:161], v[166:169], v[50:53]
	v_mfma_f32_16x16x32_bf16 v[38:41], v[150:153], v[174:177], v[38:41]
	v_mfma_f32_16x16x32_bf16 v[34:37], v[158:161], v[174:177], v[34:37]
	v_mfma_f32_16x16x32_bf16 v[22:25], v[150:153], v[182:185], v[22:25]
	v_mfma_f32_16x16x32_bf16 v[18:21], v[158:161], v[182:185], v[18:21]
	v_mfma_f32_16x16x32_bf16 v[6:9], v[150:153], v[206:209], v[6:9]
	v_mfma_f32_16x16x32_bf16 v[2:5], v[158:161], v[206:209], v[2:5]
	s_barrier
	s_setprio 0
	s_add_i32 s47, 0, 0x18000
	s_add_i32 s52, 0, 0x1c000
	v_add_u32_e32 v142, s47, v220
	v_add_u32_e32 v158, s52, v220
	ds_read_b128 v[130:133], v142
	ds_read_b128 v[134:137], v142 offset:1024
	ds_read_b128 v[138:141], v142 offset:2048
	ds_read_b128 v[142:145], v142 offset:3072
	ds_read_b128 v[146:149], v158
	ds_read_b128 v[150:153], v158 offset:1024
	ds_read_b128 v[154:157], v158 offset:2048
	ds_read_b128 v[158:161], v158 offset:3072
	s_add_u32 s30, s30, 0x80000
	s_addc_u32 s31, s31, 0
	s_mov_b32 m0, s36
	v_lshl_add_u64 v[218:219], s[30:31], 0, v[186:187]
	ds_read_b128 v[162:165], v222 offset:32768
	ds_read_b128 v[166:169], v222 offset:33792
	ds_read_b128 v[170:173], v222 offset:34816
	ds_read_b128 v[174:177], v222 offset:35840
	ds_read_b128 v[178:181], v222 offset:36864
	ds_read_b128 v[182:185], v222 offset:37888
	ds_read_b128 v[196:199], v222 offset:38912
	ds_read_b128 v[206:209], v222 offset:39936
	global_load_lds_dwordx4 v[218:219], off
	s_mov_b32 m0, s37
	v_lshl_add_u64 v[218:219], s[30:31], 0, v[188:189]
	global_load_lds_dwordx4 v[218:219], off
	s_waitcnt vmcnt(8) lgkmcnt(0)
	s_setprio 1
	s_barrier
	v_mfma_f32_16x16x32_bf16 v[126:129], v[130:133], v[162:165], v[126:129]
	v_mfma_f32_16x16x32_bf16 v[122:125], v[138:141], v[162:165], v[122:125]
	v_mfma_f32_16x16x32_bf16 v[110:113], v[130:133], v[170:173], v[110:113]
	v_mfma_f32_16x16x32_bf16 v[106:109], v[138:141], v[170:173], v[106:109]
	v_mfma_f32_16x16x32_bf16 v[94:97], v[130:133], v[178:181], v[94:97]
	v_mfma_f32_16x16x32_bf16 v[90:93], v[138:141], v[178:181], v[90:93]
	v_mfma_f32_16x16x32_bf16 v[78:81], v[130:133], v[196:199], v[78:81]
	v_mfma_f32_16x16x32_bf16 v[74:77], v[138:141], v[196:199], v[74:77]
	v_mfma_f32_16x16x32_bf16 v[126:129], v[134:137], v[166:169], v[126:129]
	v_mfma_f32_16x16x32_bf16 v[122:125], v[142:145], v[166:169], v[122:125]
	v_mfma_f32_16x16x32_bf16 v[110:113], v[134:137], v[174:177], v[110:113]
	v_mfma_f32_16x16x32_bf16 v[106:109], v[142:145], v[174:177], v[106:109]
	v_mfma_f32_16x16x32_bf16 v[94:97], v[134:137], v[182:185], v[94:97]
	v_mfma_f32_16x16x32_bf16 v[90:93], v[142:145], v[182:185], v[90:93]
	v_mfma_f32_16x16x32_bf16 v[78:81], v[134:137], v[206:209], v[78:81]
	v_mfma_f32_16x16x32_bf16 v[74:77], v[142:145], v[206:209], v[74:77]
	s_setprio 0
	s_setprio 1
	v_mfma_f32_16x16x32_bf16 v[118:121], v[146:149], v[162:165], v[118:121]
	v_mfma_f32_16x16x32_bf16 v[114:117], v[154:157], v[162:165], v[114:117]
	v_mfma_f32_16x16x32_bf16 v[102:105], v[146:149], v[170:173], v[102:105]
	v_mfma_f32_16x16x32_bf16 v[98:101], v[154:157], v[170:173], v[98:101]
	v_mfma_f32_16x16x32_bf16 v[86:89], v[146:149], v[178:181], v[86:89]
	v_mfma_f32_16x16x32_bf16 v[82:85], v[154:157], v[178:181], v[82:85]
	v_mfma_f32_16x16x32_bf16 v[70:73], v[146:149], v[196:199], v[70:73]
	v_mfma_f32_16x16x32_bf16 v[66:69], v[154:157], v[196:199], v[66:69]
	v_mfma_f32_16x16x32_bf16 v[118:121], v[150:153], v[166:169], v[118:121]
	v_mfma_f32_16x16x32_bf16 v[114:117], v[158:161], v[166:169], v[114:117]
	v_mfma_f32_16x16x32_bf16 v[102:105], v[150:153], v[174:177], v[102:105]
	v_mfma_f32_16x16x32_bf16 v[98:101], v[158:161], v[174:177], v[98:101]
	v_mfma_f32_16x16x32_bf16 v[86:89], v[150:153], v[182:185], v[86:89]
	v_mfma_f32_16x16x32_bf16 v[82:85], v[158:161], v[182:185], v[82:85]
	v_mfma_f32_16x16x32_bf16 v[70:73], v[150:153], v[206:209], v[70:73]
	v_mfma_f32_16x16x32_bf16 v[66:69], v[158:161], v[206:209], v[66:69]
	s_barrier
	s_setprio 0
	s_add_i32 s30, s47, s33
	v_lshl_add_u64 v[210:211], v[210:211], 0, s[58:59]
	s_mov_b32 m0, s30
	ds_read_b128 v[162:165], v222 offset:49152
	ds_read_b128 v[166:169], v222 offset:50176
	ds_read_b128 v[170:173], v222 offset:51200
	ds_read_b128 v[174:177], v222 offset:52224
	ds_read_b128 v[178:181], v222 offset:53248
	ds_read_b128 v[182:185], v222 offset:54272
	ds_read_b128 v[196:199], v222 offset:55296
	ds_read_b128 v[206:209], v222 offset:56320
	global_load_lds_dwordx4 v[210:211], off
	s_add_i32 m0, s30, 0x2000
	s_add_u32 s28, s28, 0x80080
	v_lshl_add_u64 v[210:211], v[212:213], 0, s[58:59]
	s_addc_u32 s29, s29, 0
	s_add_i32 s30, s52, s33
	global_load_lds_dwordx4 v[210:211], off
	s_mov_b32 m0, s30
	v_lshl_add_u64 v[210:211], s[28:29], 0, v[190:191]
	global_load_lds_dwordx4 v[210:211], off
	s_add_i32 m0, s30, 0x2000
	v_lshl_add_u64 v[210:211], s[28:29], 0, v[200:201]
	global_load_lds_dwordx4 v[210:211], off
	s_mov_b32 m0, s38
	v_lshl_add_u64 v[210:211], v[214:215], 0, s[58:59]
	global_load_lds_dwordx4 v[210:211], off
	s_mov_b32 m0, s39
	v_lshl_add_u64 v[210:211], v[216:217], 0, s[58:59]
	global_load_lds_dwordx4 v[210:211], off
	s_waitcnt vmcnt(8) lgkmcnt(0)
	s_setprio 1
	s_barrier
	v_mfma_f32_16x16x32_bf16 v[62:65], v[130:133], v[162:165], v[62:65]
	v_mfma_f32_16x16x32_bf16 v[58:61], v[138:141], v[162:165], v[58:61]
	v_mfma_f32_16x16x32_bf16 v[46:49], v[130:133], v[170:173], v[46:49]
	v_mfma_f32_16x16x32_bf16 v[42:45], v[138:141], v[170:173], v[42:45]
	v_mfma_f32_16x16x32_bf16 v[30:33], v[130:133], v[178:181], v[30:33]
	v_mfma_f32_16x16x32_bf16 v[26:29], v[138:141], v[178:181], v[26:29]
	v_mfma_f32_16x16x32_bf16 v[14:17], v[130:133], v[196:199], v[14:17]
	v_mfma_f32_16x16x32_bf16 v[10:13], v[138:141], v[196:199], v[10:13]
	v_mfma_f32_16x16x32_bf16 v[62:65], v[134:137], v[166:169], v[62:65]
	v_mfma_f32_16x16x32_bf16 v[58:61], v[142:145], v[166:169], v[58:61]
	v_mfma_f32_16x16x32_bf16 v[46:49], v[134:137], v[174:177], v[46:49]
	v_mfma_f32_16x16x32_bf16 v[42:45], v[142:145], v[174:177], v[42:45]
	v_mfma_f32_16x16x32_bf16 v[30:33], v[134:137], v[182:185], v[30:33]
	v_mfma_f32_16x16x32_bf16 v[26:29], v[142:145], v[182:185], v[26:29]
	v_mfma_f32_16x16x32_bf16 v[14:17], v[134:137], v[206:209], v[14:17]
	v_mfma_f32_16x16x32_bf16 v[10:13], v[142:145], v[206:209], v[10:13]
	s_setprio 0
	s_setprio 1
	v_mfma_f32_16x16x32_bf16 v[54:57], v[146:149], v[162:165], v[54:57]
	v_mfma_f32_16x16x32_bf16 v[50:53], v[154:157], v[162:165], v[50:53]
	v_mfma_f32_16x16x32_bf16 v[38:41], v[146:149], v[170:173], v[38:41]
	v_mfma_f32_16x16x32_bf16 v[34:37], v[154:157], v[170:173], v[34:37]
	v_mfma_f32_16x16x32_bf16 v[22:25], v[146:149], v[178:181], v[22:25]
	v_mfma_f32_16x16x32_bf16 v[18:21], v[154:157], v[178:181], v[18:21]
	v_mfma_f32_16x16x32_bf16 v[6:9], v[146:149], v[196:199], v[6:9]
	v_mfma_f32_16x16x32_bf16 v[2:5], v[154:157], v[196:199], v[2:5]
	v_mfma_f32_16x16x32_bf16 v[54:57], v[150:153], v[166:169], v[54:57]
	v_mfma_f32_16x16x32_bf16 v[50:53], v[158:161], v[166:169], v[50:53]
	v_mfma_f32_16x16x32_bf16 v[38:41], v[150:153], v[174:177], v[38:41]
	v_mfma_f32_16x16x32_bf16 v[34:37], v[158:161], v[174:177], v[34:37]
	v_mfma_f32_16x16x32_bf16 v[22:25], v[150:153], v[182:185], v[22:25]
	v_mfma_f32_16x16x32_bf16 v[18:21], v[158:161], v[182:185], v[18:21]
	v_mfma_f32_16x16x32_bf16 v[6:9], v[150:153], v[206:209], v[6:9]
	v_mfma_f32_16x16x32_bf16 v[2:5], v[158:161], v[206:209], v[2:5]
	s_barrier
	s_setprio 0
	s_add_i32 s46, s46, 2
	s_add_u32 s26, s26, 0x100
	s_addc_u32 s27, s27, 0
	s_add_u32 s42, s42, 0x100
	s_addc_u32 s43, s43, 0
	s_cmp_gt_u32 s46, 29
	s_cbranch_scc1 .Lpeel_done_3
	s_branch .LBB0_772
.Ltrip0_strict_3:
	s_add_u32 s28, s26, 0xfff80080
	s_addc_u32 s29, s27, -1
	s_add_i32 s47, 0, 0x10000
	s_cmp_eq_u32 s46, 28
	s_cselect_b32 s31, s17, s29
	s_cselect_b32 s30, s40, s28
	s_cselect_b32 s29, s15, s43
	s_cselect_b32 s28, s41, s42
	s_add_i32 s55, 0, 0x14000
	v_add_u32_e32 v142, s47, v220
	v_add_u32_e32 v158, s55, v220
	ds_read_b128 v[130:133], v142
	ds_read_b128 v[134:137], v142 offset:1024
	ds_read_b128 v[138:141], v142 offset:2048
	ds_read_b128 v[142:145], v142 offset:3072
	ds_read_b128 v[146:149], v158
	ds_read_b128 v[150:153], v158 offset:1024
	ds_read_b128 v[154:157], v158 offset:2048
	ds_read_b128 v[158:161], v158 offset:3072
	v_lshl_add_u64 v[210:211], s[26:27], 0, v[202:203]
	s_add_i32 m0, s34, 0xc000
	ds_read_b128 v[162:165], v222
	ds_read_b128 v[166:169], v222 offset:1024
	ds_read_b128 v[170:173], v222 offset:2048
	ds_read_b128 v[174:177], v222 offset:3072
	ds_read_b128 v[178:181], v222 offset:4096
	ds_read_b128 v[182:185], v222 offset:5120
	ds_read_b128 v[196:199], v222 offset:6144
	ds_read_b128 v[206:209], v222 offset:7168
	global_load_lds_dwordx4 v[210:211], off
	s_add_i32 m0, s34, 0xe000
	v_lshl_add_u64 v[210:211], s[26:27], 0, v[204:205]
	global_load_lds_dwordx4 v[210:211], off
	s_waitcnt vmcnt(8) lgkmcnt(0)
	s_setprio 1
	s_barrier
	v_mfma_f32_16x16x32_bf16 v[126:129], v[130:133], v[162:165], 0
	v_mfma_f32_16x16x32_bf16 v[122:125], v[138:141], v[162:165], 0
	v_mfma_f32_16x16x32_bf16 v[110:113], v[130:133], v[170:173], 0
	v_mfma_f32_16x16x32_bf16 v[106:109], v[138:141], v[170:173], 0
	v_mfma_f32_16x16x32_bf16 v[94:97], v[130:133], v[178:181], 0
	v_mfma_f32_16x16x32_bf16 v[90:93], v[138:141], v[178:181], 0
	v_mfma_f32_16x16x32_bf16 v[78:81], v[130:133], v[196:199], 0
	v_mfma_f32_16x16x32_bf16 v[74:77], v[138:141], v[196:199], 0
	v_mfma_f32_16x16x32_bf16 v[126:129], v[134:137], v[166:169], v[126:129]
	v_mfma_f32_16x16x32_bf16 v[122:125], v[142:145], v[166:169], v[122:125]
	v_mfma_f32_16x16x32_bf16 v[110:113], v[134:137], v[174:177], v[110:113]
	v_mfma_f32_16x16x32_bf16 v[106:109], v[142:145], v[174:177], v[106:109]
	v_mfma_f32_16x16x32_bf16 v[94:97], v[134:137], v[182:185], v[94:97]
	v_mfma_f32_16x16x32_bf16 v[90:93], v[142:145], v[182:185], v[90:93]
	v_mfma_f32_16x16x32_bf16 v[78:81], v[134:137], v[206:209], v[78:81]
	v_mfma_f32_16x16x32_bf16 v[74:77], v[142:145], v[206:209], v[74:77]
	s_setprio 0
	s_setprio 1
	v_mfma_f32_16x16x32_bf16 v[118:121], v[146:149], v[162:165], 0
	v_mfma_f32_16x16x32_bf16 v[114:117], v[154:157], v[162:165], 0
	v_mfma_f32_16x16x32_bf16 v[102:105], v[146:149], v[170:173], 0
	v_mfma_f32_16x16x32_bf16 v[98:101], v[154:157], v[170:173], 0
	v_mfma_f32_16x16x32_bf16 v[86:89], v[146:149], v[178:181], 0
	v_mfma_f32_16x16x32_bf16 v[82:85], v[154:157], v[178:181], 0
	v_mfma_f32_16x16x32_bf16 v[70:73], v[146:149], v[196:199], 0
	v_mfma_f32_16x16x32_bf16 v[66:69], v[154:157], v[196:199], 0
	v_mfma_f32_16x16x32_bf16 v[118:121], v[150:153], v[166:169], v[118:121]
	v_mfma_f32_16x16x32_bf16 v[114:117], v[158:161], v[166:169], v[114:117]
	v_mfma_f32_16x16x32_bf16 v[102:105], v[150:153], v[174:177], v[102:105]
	v_mfma_f32_16x16x32_bf16 v[98:101], v[158:161], v[174:177], v[98:101]
	v_mfma_f32_16x16x32_bf16 v[86:89], v[150:153], v[182:185], v[86:89]
	v_mfma_f32_16x16x32_bf16 v[82:85], v[158:161], v[182:185], v[82:85]
	v_mfma_f32_16x16x32_bf16 v[70:73], v[150:153], v[206:209], v[70:73]
	v_mfma_f32_16x16x32_bf16 v[66:69], v[158:161], v[206:209], v[66:69]
	s_barrier
	s_setprio 0
	s_add_i32 s47, s47, s33
	v_lshl_add_u64 v[210:211], s[28:29], 0, v[190:191]
	s_mov_b32 m0, s47
	ds_read_b128 v[162:165], v222 offset:16384
	ds_read_b128 v[166:169], v222 offset:17408
	ds_read_b128 v[170:173], v222 offset:18432
	ds_read_b128 v[174:177], v222 offset:19456
	ds_read_b128 v[178:181], v222 offset:20480
	ds_read_b128 v[182:185], v222 offset:21504
	ds_read_b128 v[196:199], v222 offset:22528
	ds_read_b128 v[206:209], v222 offset:23552
	global_load_lds_dwordx4 v[210:211], off
	s_add_i32 m0, s47, 0x2000
	s_add_u32 s52, s28, 0x80000
	v_lshl_add_u64 v[212:213], s[28:29], 0, v[200:201]
	s_addc_u32 s53, s29, 0
	s_add_i32 s47, s55, s33
	global_load_lds_dwordx4 v[212:213], off
	v_lshl_add_u64 v[214:215], s[52:53], 0, v[190:191]
	s_mov_b32 m0, s47
	v_lshl_add_u64 v[216:217], s[30:31], 0, v[188:189]
	global_load_lds_dwordx4 v[214:215], off
	s_add_i32 m0, s47, 0x2000
	v_lshl_add_u64 v[214:215], s[52:53], 0, v[200:201]
	global_load_lds_dwordx4 v[214:215], off
	s_mov_b32 m0, s34
	v_lshl_add_u64 v[214:215], s[30:31], 0, v[186:187]
	global_load_lds_dwordx4 v[214:215], off
	s_mov_b32 m0, s35
	s_nop 0
	global_load_lds_dwordx4 v[216:217], off
	s_waitcnt vmcnt(8) lgkmcnt(0)
	s_setprio 1
	s_barrier
	v_mfma_f32_16x16x32_bf16 v[62:65], v[130:133], v[162:165], 0
	v_mfma_f32_16x16x32_bf16 v[58:61], v[138:141], v[162:165], 0
	v_mfma_f32_16x16x32_bf16 v[46:49], v[130:133], v[170:173], 0
	v_mfma_f32_16x16x32_bf16 v[42:45], v[138:141], v[170:173], 0
	v_mfma_f32_16x16x32_bf16 v[30:33], v[130:133], v[178:181], 0
	v_mfma_f32_16x16x32_bf16 v[26:29], v[138:141], v[178:181], 0
	v_mfma_f32_16x16x32_bf16 v[14:17], v[130:133], v[196:199], 0
	v_mfma_f32_16x16x32_bf16 v[10:13], v[138:141], v[196:199], 0
	v_mfma_f32_16x16x32_bf16 v[62:65], v[134:137], v[166:169], v[62:65]
	v_mfma_f32_16x16x32_bf16 v[58:61], v[142:145], v[166:169], v[58:61]
	v_mfma_f32_16x16x32_bf16 v[46:49], v[134:137], v[174:177], v[46:49]
	v_mfma_f32_16x16x32_bf16 v[42:45], v[142:145], v[174:177], v[42:45]
	v_mfma_f32_16x16x32_bf16 v[30:33], v[134:137], v[182:185], v[30:33]
	v_mfma_f32_16x16x32_bf16 v[26:29], v[142:145], v[182:185], v[26:29]
	v_mfma_f32_16x16x32_bf16 v[14:17], v[134:137], v[206:209], v[14:17]
	v_mfma_f32_16x16x32_bf16 v[10:13], v[142:145], v[206:209], v[10:13]
	s_setprio 0
	s_setprio 1
	v_mfma_f32_16x16x32_bf16 v[54:57], v[146:149], v[162:165], 0
	v_mfma_f32_16x16x32_bf16 v[50:53], v[154:157], v[162:165], 0
	v_mfma_f32_16x16x32_bf16 v[38:41], v[146:149], v[170:173], 0
	v_mfma_f32_16x16x32_bf16 v[34:37], v[154:157], v[170:173], 0
	v_mfma_f32_16x16x32_bf16 v[22:25], v[146:149], v[178:181], 0
	v_mfma_f32_16x16x32_bf16 v[18:21], v[154:157], v[178:181], 0
	v_mfma_f32_16x16x32_bf16 v[6:9], v[146:149], v[196:199], 0
	v_mfma_f32_16x16x32_bf16 v[2:5], v[154:157], v[196:199], 0
	v_mfma_f32_16x16x32_bf16 v[54:57], v[150:153], v[166:169], v[54:57]
	v_mfma_f32_16x16x32_bf16 v[50:53], v[158:161], v[166:169], v[50:53]
	v_mfma_f32_16x16x32_bf16 v[38:41], v[150:153], v[174:177], v[38:41]
	v_mfma_f32_16x16x32_bf16 v[34:37], v[158:161], v[174:177], v[34:37]
	v_mfma_f32_16x16x32_bf16 v[22:25], v[150:153], v[182:185], v[22:25]
	v_mfma_f32_16x16x32_bf16 v[18:21], v[158:161], v[182:185], v[18:21]
	v_mfma_f32_16x16x32_bf16 v[6:9], v[150:153], v[206:209], v[6:9]
	v_mfma_f32_16x16x32_bf16 v[2:5], v[158:161], v[206:209], v[2:5]
	s_barrier
	s_setprio 0
	s_add_i32 s47, 0, 0x18000
	s_add_i32 s52, 0, 0x1c000
	v_add_u32_e32 v142, s47, v220
	v_add_u32_e32 v158, s52, v220
	ds_read_b128 v[130:133], v142
	ds_read_b128 v[134:137], v142 offset:1024
	ds_read_b128 v[138:141], v142 offset:2048
	ds_read_b128 v[142:145], v142 offset:3072
	ds_read_b128 v[146:149], v158
	ds_read_b128 v[150:153], v158 offset:1024
	ds_read_b128 v[154:157], v158 offset:2048
	ds_read_b128 v[158:161], v158 offset:3072
	s_add_u32 s30, s30, 0x80000
	s_addc_u32 s31, s31, 0
	s_mov_b32 m0, s36
	v_lshl_add_u64 v[218:219], s[30:31], 0, v[186:187]
	ds_read_b128 v[162:165], v222 offset:32768
	ds_read_b128 v[166:169], v222 offset:33792
	ds_read_b128 v[170:173], v222 offset:34816
	ds_read_b128 v[174:177], v222 offset:35840
	ds_read_b128 v[178:181], v222 offset:36864
	ds_read_b128 v[182:185], v222 offset:37888
	ds_read_b128 v[196:199], v222 offset:38912
	ds_read_b128 v[206:209], v222 offset:39936
	global_load_lds_dwordx4 v[218:219], off
	s_mov_b32 m0, s37
	v_lshl_add_u64 v[218:219], s[30:31], 0, v[188:189]
	global_load_lds_dwordx4 v[218:219], off
	s_waitcnt vmcnt(8) lgkmcnt(0)
	s_setprio 1
	s_barrier
	v_mfma_f32_16x16x32_bf16 v[126:129], v[130:133], v[162:165], v[126:129]
	v_mfma_f32_16x16x32_bf16 v[122:125], v[138:141], v[162:165], v[122:125]
	v_mfma_f32_16x16x32_bf16 v[110:113], v[130:133], v[170:173], v[110:113]
	v_mfma_f32_16x16x32_bf16 v[106:109], v[138:141], v[170:173], v[106:109]
	v_mfma_f32_16x16x32_bf16 v[94:97], v[130:133], v[178:181], v[94:97]
	v_mfma_f32_16x16x32_bf16 v[90:93], v[138:141], v[178:181], v[90:93]
	v_mfma_f32_16x16x32_bf16 v[78:81], v[130:133], v[196:199], v[78:81]
	v_mfma_f32_16x16x32_bf16 v[74:77], v[138:141], v[196:199], v[74:77]
	v_mfma_f32_16x16x32_bf16 v[126:129], v[134:137], v[166:169], v[126:129]
	v_mfma_f32_16x16x32_bf16 v[122:125], v[142:145], v[166:169], v[122:125]
	v_mfma_f32_16x16x32_bf16 v[110:113], v[134:137], v[174:177], v[110:113]
	v_mfma_f32_16x16x32_bf16 v[106:109], v[142:145], v[174:177], v[106:109]
	v_mfma_f32_16x16x32_bf16 v[94:97], v[134:137], v[182:185], v[94:97]
	v_mfma_f32_16x16x32_bf16 v[90:93], v[142:145], v[182:185], v[90:93]
	v_mfma_f32_16x16x32_bf16 v[78:81], v[134:137], v[206:209], v[78:81]
	v_mfma_f32_16x16x32_bf16 v[74:77], v[142:145], v[206:209], v[74:77]
	s_setprio 0
	s_setprio 1
	v_mfma_f32_16x16x32_bf16 v[118:121], v[146:149], v[162:165], v[118:121]
	v_mfma_f32_16x16x32_bf16 v[114:117], v[154:157], v[162:165], v[114:117]
	v_mfma_f32_16x16x32_bf16 v[102:105], v[146:149], v[170:173], v[102:105]
	v_mfma_f32_16x16x32_bf16 v[98:101], v[154:157], v[170:173], v[98:101]
	v_mfma_f32_16x16x32_bf16 v[86:89], v[146:149], v[178:181], v[86:89]
	v_mfma_f32_16x16x32_bf16 v[82:85], v[154:157], v[178:181], v[82:85]
	v_mfma_f32_16x16x32_bf16 v[70:73], v[146:149], v[196:199], v[70:73]
	v_mfma_f32_16x16x32_bf16 v[66:69], v[154:157], v[196:199], v[66:69]
	v_mfma_f32_16x16x32_bf16 v[118:121], v[150:153], v[166:169], v[118:121]
	v_mfma_f32_16x16x32_bf16 v[114:117], v[158:161], v[166:169], v[114:117]
	v_mfma_f32_16x16x32_bf16 v[102:105], v[150:153], v[174:177], v[102:105]
	v_mfma_f32_16x16x32_bf16 v[98:101], v[158:161], v[174:177], v[98:101]
	v_mfma_f32_16x16x32_bf16 v[86:89], v[150:153], v[182:185], v[86:89]
	v_mfma_f32_16x16x32_bf16 v[82:85], v[158:161], v[182:185], v[82:85]
	v_mfma_f32_16x16x32_bf16 v[70:73], v[150:153], v[206:209], v[70:73]
	v_mfma_f32_16x16x32_bf16 v[66:69], v[158:161], v[206:209], v[66:69]
	s_barrier
	s_setprio 0
	s_add_i32 s30, s47, s33
	v_lshl_add_u64 v[210:211], v[210:211], 0, s[58:59]
	s_mov_b32 m0, s30
	ds_read_b128 v[162:165], v222 offset:49152
	ds_read_b128 v[166:169], v222 offset:50176
	ds_read_b128 v[170:173], v222 offset:51200
	ds_read_b128 v[174:177], v222 offset:52224
	ds_read_b128 v[178:181], v222 offset:53248
	ds_read_b128 v[182:185], v222 offset:54272
	ds_read_b128 v[196:199], v222 offset:55296
	ds_read_b128 v[206:209], v222 offset:56320
	global_load_lds_dwordx4 v[210:211], off
	s_add_i32 m0, s30, 0x2000
	s_add_u32 s28, s28, 0x80080
	v_lshl_add_u64 v[210:211], v[212:213], 0, s[58:59]
	s_addc_u32 s29, s29, 0
	s_add_i32 s30, s52, s33
	global_load_lds_dwordx4 v[210:211], off
	s_mov_b32 m0, s30
	v_lshl_add_u64 v[210:211], s[28:29], 0, v[190:191]
	global_load_lds_dwordx4 v[210:211], off
	s_add_i32 m0, s30, 0x2000
	v_lshl_add_u64 v[210:211], s[28:29], 0, v[200:201]
	global_load_lds_dwordx4 v[210:211], off
	s_mov_b32 m0, s38
	v_lshl_add_u64 v[210:211], v[214:215], 0, s[58:59]
	global_load_lds_dwordx4 v[210:211], off
	s_mov_b32 m0, s39
	v_lshl_add_u64 v[210:211], v[216:217], 0, s[58:59]
	global_load_lds_dwordx4 v[210:211], off
	s_waitcnt vmcnt(8) lgkmcnt(0)
	s_setprio 1
	s_barrier
	v_mfma_f32_16x16x32_bf16 v[62:65], v[130:133], v[162:165], v[62:65]
	v_mfma_f32_16x16x32_bf16 v[58:61], v[138:141], v[162:165], v[58:61]
	v_mfma_f32_16x16x32_bf16 v[46:49], v[130:133], v[170:173], v[46:49]
	v_mfma_f32_16x16x32_bf16 v[42:45], v[138:141], v[170:173], v[42:45]
	v_mfma_f32_16x16x32_bf16 v[30:33], v[130:133], v[178:181], v[30:33]
	v_mfma_f32_16x16x32_bf16 v[26:29], v[138:141], v[178:181], v[26:29]
	v_mfma_f32_16x16x32_bf16 v[14:17], v[130:133], v[196:199], v[14:17]
	v_mfma_f32_16x16x32_bf16 v[10:13], v[138:141], v[196:199], v[10:13]
	v_mfma_f32_16x16x32_bf16 v[62:65], v[134:137], v[166:169], v[62:65]
	v_mfma_f32_16x16x32_bf16 v[58:61], v[142:145], v[166:169], v[58:61]
	v_mfma_f32_16x16x32_bf16 v[46:49], v[134:137], v[174:177], v[46:49]
	v_mfma_f32_16x16x32_bf16 v[42:45], v[142:145], v[174:177], v[42:45]
	v_mfma_f32_16x16x32_bf16 v[30:33], v[134:137], v[182:185], v[30:33]
	v_mfma_f32_16x16x32_bf16 v[26:29], v[142:145], v[182:185], v[26:29]
	v_mfma_f32_16x16x32_bf16 v[14:17], v[134:137], v[206:209], v[14:17]
	v_mfma_f32_16x16x32_bf16 v[10:13], v[142:145], v[206:209], v[10:13]
	s_setprio 0
	s_setprio 1
	v_mfma_f32_16x16x32_bf16 v[54:57], v[146:149], v[162:165], v[54:57]
	v_mfma_f32_16x16x32_bf16 v[50:53], v[154:157], v[162:165], v[50:53]
	v_mfma_f32_16x16x32_bf16 v[38:41], v[146:149], v[170:173], v[38:41]
	v_mfma_f32_16x16x32_bf16 v[34:37], v[154:157], v[170:173], v[34:37]
	v_mfma_f32_16x16x32_bf16 v[22:25], v[146:149], v[178:181], v[22:25]
	v_mfma_f32_16x16x32_bf16 v[18:21], v[154:157], v[178:181], v[18:21]
	v_mfma_f32_16x16x32_bf16 v[6:9], v[146:149], v[196:199], v[6:9]
	v_mfma_f32_16x16x32_bf16 v[2:5], v[154:157], v[196:199], v[2:5]
	v_mfma_f32_16x16x32_bf16 v[54:57], v[150:153], v[166:169], v[54:57]
	v_mfma_f32_16x16x32_bf16 v[50:53], v[158:161], v[166:169], v[50:53]
	v_mfma_f32_16x16x32_bf16 v[38:41], v[150:153], v[174:177], v[38:41]
	v_mfma_f32_16x16x32_bf16 v[34:37], v[158:161], v[174:177], v[34:37]
	v_mfma_f32_16x16x32_bf16 v[22:25], v[150:153], v[182:185], v[22:25]
	v_mfma_f32_16x16x32_bf16 v[18:21], v[158:161], v[182:185], v[18:21]
	v_mfma_f32_16x16x32_bf16 v[6:9], v[150:153], v[206:209], v[6:9]
	v_mfma_f32_16x16x32_bf16 v[2:5], v[158:161], v[206:209], v[2:5]
	s_barrier
	s_setprio 0
	s_add_i32 s46, s46, 2
	s_add_u32 s26, s26, 0x100
	s_addc_u32 s27, s27, 0
	s_add_u32 s42, s42, 0x100
	s_addc_u32 s43, s43, 0
	s_cmp_gt_u32 s46, 29
	s_cbranch_scc1 .Lpeel_done_3
.LBB0_772:
	s_add_u32 s28, s26, 0xfff80080
	s_addc_u32 s29, s27, -1
	s_add_i32 s47, 0, 0x10000
	s_cmp_eq_u32 s46, 28
	s_cselect_b32 s31, s17, s29
	s_cselect_b32 s30, s40, s28
	s_cselect_b32 s29, s15, s43
	s_cselect_b32 s28, s41, s42
	s_add_i32 s55, 0, 0x14000
	v_add_u32_e32 v142, s47, v220
	v_add_u32_e32 v158, s55, v220
	ds_read_b128 v[130:133], v142
	ds_read_b128 v[134:137], v142 offset:1024
	ds_read_b128 v[138:141], v142 offset:2048
	ds_read_b128 v[142:145], v142 offset:3072
	ds_read_b128 v[146:149], v158
	ds_read_b128 v[150:153], v158 offset:1024
	ds_read_b128 v[154:157], v158 offset:2048
	ds_read_b128 v[158:161], v158 offset:3072
	v_lshl_add_u64 v[210:211], s[26:27], 0, v[202:203]
	s_add_i32 m0, s34, 0xc000
	ds_read_b128 v[162:165], v222
	ds_read_b128 v[166:169], v222 offset:1024
	ds_read_b128 v[170:173], v222 offset:2048
	ds_read_b128 v[174:177], v222 offset:3072
	ds_read_b128 v[178:181], v222 offset:4096
	ds_read_b128 v[182:185], v222 offset:5120
	ds_read_b128 v[196:199], v222 offset:6144
	ds_read_b128 v[206:209], v222 offset:7168
	global_load_lds_dwordx4 v[210:211], off
	s_add_i32 m0, s34, 0xe000
	v_lshl_add_u64 v[210:211], s[26:27], 0, v[204:205]
	global_load_lds_dwordx4 v[210:211], off
	s_waitcnt vmcnt(8) lgkmcnt(0)
	s_setprio 1
	s_barrier
	v_mfma_f32_16x16x32_bf16 v[126:129], v[130:133], v[162:165], v[126:129]
	v_mfma_f32_16x16x32_bf16 v[122:125], v[138:141], v[162:165], v[122:125]
	v_mfma_f32_16x16x32_bf16 v[110:113], v[130:133], v[170:173], v[110:113]
	v_mfma_f32_16x16x32_bf16 v[106:109], v[138:141], v[170:173], v[106:109]
	v_mfma_f32_16x16x32_bf16 v[94:97], v[130:133], v[178:181], v[94:97]
	v_mfma_f32_16x16x32_bf16 v[90:93], v[138:141], v[178:181], v[90:93]
	v_mfma_f32_16x16x32_bf16 v[78:81], v[130:133], v[196:199], v[78:81]
	v_mfma_f32_16x16x32_bf16 v[74:77], v[138:141], v[196:199], v[74:77]
	v_mfma_f32_16x16x32_bf16 v[126:129], v[134:137], v[166:169], v[126:129]
	v_mfma_f32_16x16x32_bf16 v[122:125], v[142:145], v[166:169], v[122:125]
	v_mfma_f32_16x16x32_bf16 v[110:113], v[134:137], v[174:177], v[110:113]
	v_mfma_f32_16x16x32_bf16 v[106:109], v[142:145], v[174:177], v[106:109]
	v_mfma_f32_16x16x32_bf16 v[94:97], v[134:137], v[182:185], v[94:97]
	v_mfma_f32_16x16x32_bf16 v[90:93], v[142:145], v[182:185], v[90:93]
	v_mfma_f32_16x16x32_bf16 v[78:81], v[134:137], v[206:209], v[78:81]
	v_mfma_f32_16x16x32_bf16 v[74:77], v[142:145], v[206:209], v[74:77]
	s_setprio 0
	s_setprio 1
	v_mfma_f32_16x16x32_bf16 v[118:121], v[146:149], v[162:165], v[118:121]
	v_mfma_f32_16x16x32_bf16 v[114:117], v[154:157], v[162:165], v[114:117]
	v_mfma_f32_16x16x32_bf16 v[102:105], v[146:149], v[170:173], v[102:105]
	v_mfma_f32_16x16x32_bf16 v[98:101], v[154:157], v[170:173], v[98:101]
	v_mfma_f32_16x16x32_bf16 v[86:89], v[146:149], v[178:181], v[86:89]
	v_mfma_f32_16x16x32_bf16 v[82:85], v[154:157], v[178:181], v[82:85]
	v_mfma_f32_16x16x32_bf16 v[70:73], v[146:149], v[196:199], v[70:73]
	v_mfma_f32_16x16x32_bf16 v[66:69], v[154:157], v[196:199], v[66:69]
	v_mfma_f32_16x16x32_bf16 v[118:121], v[150:153], v[166:169], v[118:121]
	v_mfma_f32_16x16x32_bf16 v[114:117], v[158:161], v[166:169], v[114:117]
	v_mfma_f32_16x16x32_bf16 v[102:105], v[150:153], v[174:177], v[102:105]
	v_mfma_f32_16x16x32_bf16 v[98:101], v[158:161], v[174:177], v[98:101]
	v_mfma_f32_16x16x32_bf16 v[86:89], v[150:153], v[182:185], v[86:89]
	v_mfma_f32_16x16x32_bf16 v[82:85], v[158:161], v[182:185], v[82:85]
	v_mfma_f32_16x16x32_bf16 v[70:73], v[150:153], v[206:209], v[70:73]
	v_mfma_f32_16x16x32_bf16 v[66:69], v[158:161], v[206:209], v[66:69]
	s_setprio 0
	s_barrier
	s_add_i32 s47, s47, s33
	v_lshl_add_u64 v[210:211], s[28:29], 0, v[190:191]
	s_mov_b32 m0, s47
	ds_read_b128 v[162:165], v222 offset:16384
	ds_read_b128 v[166:169], v222 offset:17408
	ds_read_b128 v[170:173], v222 offset:18432
	ds_read_b128 v[174:177], v222 offset:19456
	ds_read_b128 v[178:181], v222 offset:20480
	ds_read_b128 v[182:185], v222 offset:21504
	ds_read_b128 v[196:199], v222 offset:22528
	ds_read_b128 v[206:209], v222 offset:23552
	global_load_lds_dwordx4 v[210:211], off
	s_add_i32 m0, s47, 0x2000
	s_add_u32 s52, s28, 0x80000
	v_lshl_add_u64 v[212:213], s[28:29], 0, v[200:201]
	s_addc_u32 s53, s29, 0
	s_add_i32 s47, s55, s33
	global_load_lds_dwordx4 v[212:213], off
	v_lshl_add_u64 v[214:215], s[52:53], 0, v[190:191]
	s_mov_b32 m0, s47
	v_lshl_add_u64 v[216:217], s[30:31], 0, v[188:189]
	global_load_lds_dwordx4 v[214:215], off
	s_add_i32 m0, s47, 0x2000
	v_lshl_add_u64 v[214:215], s[52:53], 0, v[200:201]
	global_load_lds_dwordx4 v[214:215], off
	s_mov_b32 m0, s34
	v_lshl_add_u64 v[214:215], s[30:31], 0, v[186:187]
	global_load_lds_dwordx4 v[214:215], off
	s_mov_b32 m0, s35
	s_nop 0
	global_load_lds_dwordx4 v[216:217], off
	s_waitcnt vmcnt(8) lgkmcnt(0)
	s_setprio 1
	s_barrier
	v_mfma_f32_16x16x32_bf16 v[62:65], v[130:133], v[162:165], v[62:65]
	v_mfma_f32_16x16x32_bf16 v[58:61], v[138:141], v[162:165], v[58:61]
	v_mfma_f32_16x16x32_bf16 v[46:49], v[130:133], v[170:173], v[46:49]
	v_mfma_f32_16x16x32_bf16 v[42:45], v[138:141], v[170:173], v[42:45]
	v_mfma_f32_16x16x32_bf16 v[30:33], v[130:133], v[178:181], v[30:33]
	v_mfma_f32_16x16x32_bf16 v[26:29], v[138:141], v[178:181], v[26:29]
	v_mfma_f32_16x16x32_bf16 v[14:17], v[130:133], v[196:199], v[14:17]
	v_mfma_f32_16x16x32_bf16 v[10:13], v[138:141], v[196:199], v[10:13]
	v_mfma_f32_16x16x32_bf16 v[62:65], v[134:137], v[166:169], v[62:65]
	v_mfma_f32_16x16x32_bf16 v[58:61], v[142:145], v[166:169], v[58:61]
	v_mfma_f32_16x16x32_bf16 v[46:49], v[134:137], v[174:177], v[46:49]
	v_mfma_f32_16x16x32_bf16 v[42:45], v[142:145], v[174:177], v[42:45]
	v_mfma_f32_16x16x32_bf16 v[30:33], v[134:137], v[182:185], v[30:33]
	v_mfma_f32_16x16x32_bf16 v[26:29], v[142:145], v[182:185], v[26:29]
	v_mfma_f32_16x16x32_bf16 v[14:17], v[134:137], v[206:209], v[14:17]
	v_mfma_f32_16x16x32_bf16 v[10:13], v[142:145], v[206:209], v[10:13]
	s_setprio 0
	s_setprio 1
	v_mfma_f32_16x16x32_bf16 v[54:57], v[146:149], v[162:165], v[54:57]
	v_mfma_f32_16x16x32_bf16 v[50:53], v[154:157], v[162:165], v[50:53]
	v_mfma_f32_16x16x32_bf16 v[38:41], v[146:149], v[170:173], v[38:41]
	v_mfma_f32_16x16x32_bf16 v[34:37], v[154:157], v[170:173], v[34:37]
	v_mfma_f32_16x16x32_bf16 v[22:25], v[146:149], v[178:181], v[22:25]
	v_mfma_f32_16x16x32_bf16 v[18:21], v[154:157], v[178:181], v[18:21]
	v_mfma_f32_16x16x32_bf16 v[6:9], v[146:149], v[196:199], v[6:9]
	v_mfma_f32_16x16x32_bf16 v[2:5], v[154:157], v[196:199], v[2:5]
	v_mfma_f32_16x16x32_bf16 v[54:57], v[150:153], v[166:169], v[54:57]
	v_mfma_f32_16x16x32_bf16 v[50:53], v[158:161], v[166:169], v[50:53]
	v_mfma_f32_16x16x32_bf16 v[38:41], v[150:153], v[174:177], v[38:41]
	v_mfma_f32_16x16x32_bf16 v[34:37], v[158:161], v[174:177], v[34:37]
	v_mfma_f32_16x16x32_bf16 v[22:25], v[150:153], v[182:185], v[22:25]
	v_mfma_f32_16x16x32_bf16 v[18:21], v[158:161], v[182:185], v[18:21]
	v_mfma_f32_16x16x32_bf16 v[6:9], v[150:153], v[206:209], v[6:9]
	v_mfma_f32_16x16x32_bf16 v[2:5], v[158:161], v[206:209], v[2:5]
	s_setprio 0
	s_barrier
	s_add_i32 s47, 0, 0x18000
	s_add_i32 s52, 0, 0x1c000
	v_add_u32_e32 v142, s47, v220
	v_add_u32_e32 v158, s52, v220
	ds_read_b128 v[130:133], v142
	ds_read_b128 v[134:137], v142 offset:1024
	ds_read_b128 v[138:141], v142 offset:2048
	ds_read_b128 v[142:145], v142 offset:3072
	ds_read_b128 v[146:149], v158
	ds_read_b128 v[150:153], v158 offset:1024
	ds_read_b128 v[154:157], v158 offset:2048
	ds_read_b128 v[158:161], v158 offset:3072
	s_add_u32 s30, s30, 0x80000
	s_addc_u32 s31, s31, 0
	s_mov_b32 m0, s36
	v_lshl_add_u64 v[218:219], s[30:31], 0, v[186:187]
	ds_read_b128 v[162:165], v222 offset:32768
	ds_read_b128 v[166:169], v222 offset:33792
	ds_read_b128 v[170:173], v222 offset:34816
	ds_read_b128 v[174:177], v222 offset:35840
	ds_read_b128 v[178:181], v222 offset:36864
	ds_read_b128 v[182:185], v222 offset:37888
	ds_read_b128 v[196:199], v222 offset:38912
	ds_read_b128 v[206:209], v222 offset:39936
	global_load_lds_dwordx4 v[218:219], off
	s_mov_b32 m0, s37
	v_lshl_add_u64 v[218:219], s[30:31], 0, v[188:189]
	global_load_lds_dwordx4 v[218:219], off
	s_waitcnt vmcnt(8) lgkmcnt(0)
	s_setprio 1
	s_barrier
	v_mfma_f32_16x16x32_bf16 v[126:129], v[130:133], v[162:165], v[126:129]
	v_mfma_f32_16x16x32_bf16 v[122:125], v[138:141], v[162:165], v[122:125]
	v_mfma_f32_16x16x32_bf16 v[110:113], v[130:133], v[170:173], v[110:113]
	v_mfma_f32_16x16x32_bf16 v[106:109], v[138:141], v[170:173], v[106:109]
	v_mfma_f32_16x16x32_bf16 v[94:97], v[130:133], v[178:181], v[94:97]
	v_mfma_f32_16x16x32_bf16 v[90:93], v[138:141], v[178:181], v[90:93]
	v_mfma_f32_16x16x32_bf16 v[78:81], v[130:133], v[196:199], v[78:81]
	v_mfma_f32_16x16x32_bf16 v[74:77], v[138:141], v[196:199], v[74:77]
	v_mfma_f32_16x16x32_bf16 v[126:129], v[134:137], v[166:169], v[126:129]
	v_mfma_f32_16x16x32_bf16 v[122:125], v[142:145], v[166:169], v[122:125]
	v_mfma_f32_16x16x32_bf16 v[110:113], v[134:137], v[174:177], v[110:113]
	v_mfma_f32_16x16x32_bf16 v[106:109], v[142:145], v[174:177], v[106:109]
	v_mfma_f32_16x16x32_bf16 v[94:97], v[134:137], v[182:185], v[94:97]
	v_mfma_f32_16x16x32_bf16 v[90:93], v[142:145], v[182:185], v[90:93]
	v_mfma_f32_16x16x32_bf16 v[78:81], v[134:137], v[206:209], v[78:81]
	v_mfma_f32_16x16x32_bf16 v[74:77], v[142:145], v[206:209], v[74:77]
	s_setprio 0
	s_setprio 1
	v_mfma_f32_16x16x32_bf16 v[118:121], v[146:149], v[162:165], v[118:121]
	v_mfma_f32_16x16x32_bf16 v[114:117], v[154:157], v[162:165], v[114:117]
	v_mfma_f32_16x16x32_bf16 v[102:105], v[146:149], v[170:173], v[102:105]
	v_mfma_f32_16x16x32_bf16 v[98:101], v[154:157], v[170:173], v[98:101]
	v_mfma_f32_16x16x32_bf16 v[86:89], v[146:149], v[178:181], v[86:89]
	v_mfma_f32_16x16x32_bf16 v[82:85], v[154:157], v[178:181], v[82:85]
	v_mfma_f32_16x16x32_bf16 v[70:73], v[146:149], v[196:199], v[70:73]
	v_mfma_f32_16x16x32_bf16 v[66:69], v[154:157], v[196:199], v[66:69]
	v_mfma_f32_16x16x32_bf16 v[118:121], v[150:153], v[166:169], v[118:121]
	v_mfma_f32_16x16x32_bf16 v[114:117], v[158:161], v[166:169], v[114:117]
	v_mfma_f32_16x16x32_bf16 v[102:105], v[150:153], v[174:177], v[102:105]
	v_mfma_f32_16x16x32_bf16 v[98:101], v[158:161], v[174:177], v[98:101]
	v_mfma_f32_16x16x32_bf16 v[86:89], v[150:153], v[182:185], v[86:89]
	v_mfma_f32_16x16x32_bf16 v[82:85], v[158:161], v[182:185], v[82:85]
	v_mfma_f32_16x16x32_bf16 v[70:73], v[150:153], v[206:209], v[70:73]
	v_mfma_f32_16x16x32_bf16 v[66:69], v[158:161], v[206:209], v[66:69]
	s_setprio 0
	s_barrier
	s_add_i32 s30, s47, s33
	v_lshl_add_u64 v[210:211], v[210:211], 0, s[58:59]
	s_mov_b32 m0, s30
	ds_read_b128 v[162:165], v222 offset:49152
	ds_read_b128 v[166:169], v222 offset:50176
	ds_read_b128 v[170:173], v222 offset:51200
	ds_read_b128 v[174:177], v222 offset:52224
	ds_read_b128 v[178:181], v222 offset:53248
	ds_read_b128 v[182:185], v222 offset:54272
	ds_read_b128 v[196:199], v222 offset:55296
	ds_read_b128 v[206:209], v222 offset:56320
	global_load_lds_dwordx4 v[210:211], off
	s_add_i32 m0, s30, 0x2000
	s_add_u32 s28, s28, 0x80080
	v_lshl_add_u64 v[210:211], v[212:213], 0, s[58:59]
	s_addc_u32 s29, s29, 0
	s_add_i32 s30, s52, s33
	global_load_lds_dwordx4 v[210:211], off
	s_mov_b32 m0, s30
	v_lshl_add_u64 v[210:211], s[28:29], 0, v[190:191]
	global_load_lds_dwordx4 v[210:211], off
	s_add_i32 m0, s30, 0x2000
	v_lshl_add_u64 v[210:211], s[28:29], 0, v[200:201]
	global_load_lds_dwordx4 v[210:211], off
	s_mov_b32 m0, s38
	v_lshl_add_u64 v[210:211], v[214:215], 0, s[58:59]
	global_load_lds_dwordx4 v[210:211], off
	s_mov_b32 m0, s39
	v_lshl_add_u64 v[210:211], v[216:217], 0, s[58:59]
	global_load_lds_dwordx4 v[210:211], off
	s_waitcnt vmcnt(8) lgkmcnt(0)
	s_setprio 1
	s_barrier
	v_mfma_f32_16x16x32_bf16 v[62:65], v[130:133], v[162:165], v[62:65]
	v_mfma_f32_16x16x32_bf16 v[58:61], v[138:141], v[162:165], v[58:61]
	v_mfma_f32_16x16x32_bf16 v[46:49], v[130:133], v[170:173], v[46:49]
	v_mfma_f32_16x16x32_bf16 v[42:45], v[138:141], v[170:173], v[42:45]
	v_mfma_f32_16x16x32_bf16 v[30:33], v[130:133], v[178:181], v[30:33]
	v_mfma_f32_16x16x32_bf16 v[26:29], v[138:141], v[178:181], v[26:29]
	v_mfma_f32_16x16x32_bf16 v[14:17], v[130:133], v[196:199], v[14:17]
	v_mfma_f32_16x16x32_bf16 v[10:13], v[138:141], v[196:199], v[10:13]
	v_mfma_f32_16x16x32_bf16 v[62:65], v[134:137], v[166:169], v[62:65]
	v_mfma_f32_16x16x32_bf16 v[58:61], v[142:145], v[166:169], v[58:61]
	v_mfma_f32_16x16x32_bf16 v[46:49], v[134:137], v[174:177], v[46:49]
	v_mfma_f32_16x16x32_bf16 v[42:45], v[142:145], v[174:177], v[42:45]
	v_mfma_f32_16x16x32_bf16 v[30:33], v[134:137], v[182:185], v[30:33]
	v_mfma_f32_16x16x32_bf16 v[26:29], v[142:145], v[182:185], v[26:29]
	v_mfma_f32_16x16x32_bf16 v[14:17], v[134:137], v[206:209], v[14:17]
	v_mfma_f32_16x16x32_bf16 v[10:13], v[142:145], v[206:209], v[10:13]
	s_setprio 0
	s_setprio 1
	v_mfma_f32_16x16x32_bf16 v[54:57], v[146:149], v[162:165], v[54:57]
	v_mfma_f32_16x16x32_bf16 v[50:53], v[154:157], v[162:165], v[50:53]
	v_mfma_f32_16x16x32_bf16 v[38:41], v[146:149], v[170:173], v[38:41]
	v_mfma_f32_16x16x32_bf16 v[34:37], v[154:157], v[170:173], v[34:37]
	v_mfma_f32_16x16x32_bf16 v[22:25], v[146:149], v[178:181], v[22:25]
	v_mfma_f32_16x16x32_bf16 v[18:21], v[154:157], v[178:181], v[18:21]
	v_mfma_f32_16x16x32_bf16 v[6:9], v[146:149], v[196:199], v[6:9]
	v_mfma_f32_16x16x32_bf16 v[2:5], v[154:157], v[196:199], v[2:5]
	v_mfma_f32_16x16x32_bf16 v[54:57], v[150:153], v[166:169], v[54:57]
	v_mfma_f32_16x16x32_bf16 v[50:53], v[158:161], v[166:169], v[50:53]
	v_mfma_f32_16x16x32_bf16 v[38:41], v[150:153], v[174:177], v[38:41]
	v_mfma_f32_16x16x32_bf16 v[34:37], v[158:161], v[174:177], v[34:37]
	v_mfma_f32_16x16x32_bf16 v[22:25], v[150:153], v[182:185], v[22:25]
	v_mfma_f32_16x16x32_bf16 v[18:21], v[158:161], v[182:185], v[18:21]
	v_mfma_f32_16x16x32_bf16 v[6:9], v[150:153], v[206:209], v[6:9]
	v_mfma_f32_16x16x32_bf16 v[2:5], v[158:161], v[206:209], v[2:5]
	s_setprio 0
	s_barrier
	s_add_i32 s46, s46, 2
	s_add_u32 s26, s26, 0x100
	s_addc_u32 s27, s27, 0
	s_add_u32 s42, s42, 0x100
	s_addc_u32 s43, s43, 0
	s_cmp_gt_u32 s46, 29
	s_cbranch_scc0 .LBB0_772

.LBB0_799:
	s_ashr_i32 s11, s10, 31
	s_lshl_b64 s[14:15], s[10:11], 20
	s_add_u32 s14, s69, s14
	s_addc_u32 s15, s77, s15
	s_and_b64 s[16:17], s[12:13], exec
	s_cselect_b32 s11, s15, s25
	s_cselect_b32 s21, s14, s24
	s_ashr_i32 s9, s8, 31
	s_lshl_b64 s[16:17], s[8:9], 20
	v_readlane_b32 s0, v254, 42
	v_readlane_b32 s1, v254, 43
	s_add_u32 s16, s0, s16
	s_addc_u32 s17, s1, s17
	s_and_b64 s[28:29], s[12:13], exec
	s_cselect_b32 s9, s17, s27
	s_cselect_b32 s47, s16, s26
	s_add_u32 s24, s24, 0x80080
	s_addc_u32 s25, s25, 0
	s_add_u32 s52, s26, 0x100
	s_addc_u32 s53, s27, 0
	s_mov_b32 s55, -2
	v_readlane_b32 s56, v255, 49
	s_nop 3
	s_cmp_eq_u32 s56, 5
	v_writelane_b32 v255, 5, 49
	s_cbranch_scc0 .Ltrip0_strict_4
	s_add_u32 s26, s24, 0xfff80080
	s_addc_u32 s27, s25, -1
	s_add_i32 s56, 0, 0x10000
	s_cmp_eq_u32 s55, 28
	s_cselect_b32 s29, s11, s27
	s_cselect_b32 s28, s21, s26
	s_cselect_b32 s27, s9, s53
	s_cselect_b32 s26, s47, s52
	s_add_i32 s60, 0, 0x14000
	v_add_u32_e32 v142, s56, v238
	v_add_u32_e32 v158, s60, v238
	ds_read_b128 v[130:133], v142
	ds_read_b128 v[134:137], v142 offset:1024
	ds_read_b128 v[138:141], v142 offset:2048
	ds_read_b128 v[142:145], v142 offset:3072
	ds_read_b128 v[146:149], v158
	ds_read_b128 v[150:153], v158 offset:1024
	ds_read_b128 v[154:157], v158 offset:2048
	ds_read_b128 v[158:161], v158 offset:3072
	v_lshl_add_u64 v[210:211], s[24:25], 0, v[206:207]
	s_add_i32 m0, s23, 0xc000
	ds_read_b128 v[162:165], v240
	ds_read_b128 v[166:169], v240 offset:1024
	ds_read_b128 v[170:173], v240 offset:2048
	ds_read_b128 v[174:177], v240 offset:3072
	ds_read_b128 v[178:181], v240 offset:4096
	ds_read_b128 v[182:185], v240 offset:5120
	ds_read_b128 v[186:189], v240 offset:6144
	ds_read_b128 v[196:199], v240 offset:7168
	global_load_lds_dwordx4 v[210:211], off
	s_add_i32 m0, s23, 0xe000
	v_lshl_add_u64 v[210:211], s[24:25], 0, v[208:209]
	global_load_lds_dwordx4 v[210:211], off
	s_waitcnt vmcnt(24) lgkmcnt(0)
	s_setprio 1
	s_barrier
	v_mfma_f32_16x16x32_bf16 v[126:129], v[130:133], v[162:165], 0
	v_mfma_f32_16x16x32_bf16 v[122:125], v[138:141], v[162:165], 0
	v_mfma_f32_16x16x32_bf16 v[110:113], v[130:133], v[170:173], 0
	v_mfma_f32_16x16x32_bf16 v[106:109], v[138:141], v[170:173], 0
	v_mfma_f32_16x16x32_bf16 v[98:101], v[130:133], v[178:181], 0
	v_mfma_f32_16x16x32_bf16 v[90:93], v[138:141], v[178:181], 0
	v_mfma_f32_16x16x32_bf16 v[82:85], v[130:133], v[186:189], 0
	v_mfma_f32_16x16x32_bf16 v[74:77], v[138:141], v[186:189], 0
	v_mfma_f32_16x16x32_bf16 v[126:129], v[134:137], v[166:169], v[126:129]
	v_mfma_f32_16x16x32_bf16 v[122:125], v[142:145], v[166:169], v[122:125]
	v_mfma_f32_16x16x32_bf16 v[110:113], v[134:137], v[174:177], v[110:113]
	v_mfma_f32_16x16x32_bf16 v[106:109], v[142:145], v[174:177], v[106:109]
	v_mfma_f32_16x16x32_bf16 v[98:101], v[134:137], v[182:185], v[98:101]
	v_mfma_f32_16x16x32_bf16 v[90:93], v[142:145], v[182:185], v[90:93]
	v_mfma_f32_16x16x32_bf16 v[82:85], v[134:137], v[196:199], v[82:85]
	v_mfma_f32_16x16x32_bf16 v[74:77], v[142:145], v[196:199], v[74:77]
	s_setprio 0
	s_setprio 1
	v_mfma_f32_16x16x32_bf16 v[118:121], v[146:149], v[162:165], 0
	v_mfma_f32_16x16x32_bf16 v[114:117], v[154:157], v[162:165], 0
	v_mfma_f32_16x16x32_bf16 v[102:105], v[146:149], v[170:173], 0
	v_mfma_f32_16x16x32_bf16 v[94:97], v[154:157], v[170:173], 0
	v_mfma_f32_16x16x32_bf16 v[86:89], v[146:149], v[178:181], 0
	v_mfma_f32_16x16x32_bf16 v[78:81], v[154:157], v[178:181], 0
	v_mfma_f32_16x16x32_bf16 v[70:73], v[146:149], v[186:189], 0
	v_mfma_f32_16x16x32_bf16 v[66:69], v[154:157], v[186:189], 0
	v_mfma_f32_16x16x32_bf16 v[118:121], v[150:153], v[166:169], v[118:121]
	v_mfma_f32_16x16x32_bf16 v[114:117], v[158:161], v[166:169], v[114:117]
	v_mfma_f32_16x16x32_bf16 v[102:105], v[150:153], v[174:177], v[102:105]
	v_mfma_f32_16x16x32_bf16 v[94:97], v[158:161], v[174:177], v[94:97]
	v_mfma_f32_16x16x32_bf16 v[86:89], v[150:153], v[182:185], v[86:89]
	v_mfma_f32_16x16x32_bf16 v[78:81], v[158:161], v[182:185], v[78:81]
	v_mfma_f32_16x16x32_bf16 v[70:73], v[150:153], v[196:199], v[70:73]
	v_mfma_f32_16x16x32_bf16 v[66:69], v[158:161], v[196:199], v[66:69]
	s_barrier
	s_setprio 0
	s_add_i32 s56, s56, s34
	v_lshl_add_u64 v[210:211], s[26:27], 0, v[190:191]
	s_mov_b32 m0, s56
	ds_read_b128 v[162:165], v240 offset:16384
	ds_read_b128 v[166:169], v240 offset:17408
	ds_read_b128 v[170:173], v240 offset:18432
	ds_read_b128 v[174:177], v240 offset:19456
	ds_read_b128 v[178:181], v240 offset:20480
	ds_read_b128 v[182:185], v240 offset:21504
	ds_read_b128 v[186:189], v240 offset:22528
	ds_read_b128 v[196:199], v240 offset:23552
	global_load_lds_dwordx4 v[210:211], off
	s_add_i32 m0, s56, 0x2000
	s_add_u32 s56, s26, 0x80000
	v_lshl_add_u64 v[212:213], s[26:27], 0, v[204:205]
	s_addc_u32 s57, s27, 0
	s_add_i32 s60, s60, s34
	global_load_lds_dwordx4 v[212:213], off
	v_lshl_add_u64 v[214:215], s[56:57], 0, v[190:191]
	s_mov_b32 m0, s60
	v_lshl_add_u64 v[216:217], s[28:29], 0, v[202:203]
	global_load_lds_dwordx4 v[214:215], off
	s_add_i32 m0, s60, 0x2000
	v_lshl_add_u64 v[214:215], s[56:57], 0, v[204:205]
	global_load_lds_dwordx4 v[214:215], off
	s_mov_b32 m0, s23
	v_lshl_add_u64 v[214:215], s[28:29], 0, v[200:201]
	global_load_lds_dwordx4 v[214:215], off
	s_mov_b32 m0, s35
	s_nop 0
	global_load_lds_dwordx4 v[216:217], off
	s_waitcnt vmcnt(24) lgkmcnt(0)
	s_setprio 1
	s_barrier
	v_mfma_f32_16x16x32_bf16 v[62:65], v[130:133], v[162:165], 0
	v_mfma_f32_16x16x32_bf16 v[58:61], v[138:141], v[162:165], 0
	v_mfma_f32_16x16x32_bf16 v[50:53], v[130:133], v[170:173], 0
	v_mfma_f32_16x16x32_bf16 v[42:45], v[138:141], v[170:173], 0
	v_mfma_f32_16x16x32_bf16 v[34:37], v[130:133], v[178:181], 0
	v_mfma_f32_16x16x32_bf16 v[26:29], v[138:141], v[178:181], 0
	v_mfma_f32_16x16x32_bf16 v[18:21], v[130:133], v[186:189], 0
	v_mfma_f32_16x16x32_bf16 v[10:13], v[138:141], v[186:189], 0
	v_mfma_f32_16x16x32_bf16 v[62:65], v[134:137], v[166:169], v[62:65]
	v_mfma_f32_16x16x32_bf16 v[58:61], v[142:145], v[166:169], v[58:61]
	v_mfma_f32_16x16x32_bf16 v[50:53], v[134:137], v[174:177], v[50:53]
	v_mfma_f32_16x16x32_bf16 v[42:45], v[142:145], v[174:177], v[42:45]
	v_mfma_f32_16x16x32_bf16 v[34:37], v[134:137], v[182:185], v[34:37]
	v_mfma_f32_16x16x32_bf16 v[26:29], v[142:145], v[182:185], v[26:29]
	v_mfma_f32_16x16x32_bf16 v[18:21], v[134:137], v[196:199], v[18:21]
	v_mfma_f32_16x16x32_bf16 v[10:13], v[142:145], v[196:199], v[10:13]
	s_setprio 0
	s_setprio 1
	v_mfma_f32_16x16x32_bf16 v[54:57], v[146:149], v[162:165], 0
	v_mfma_f32_16x16x32_bf16 v[46:49], v[154:157], v[162:165], 0
	v_mfma_f32_16x16x32_bf16 v[38:41], v[146:149], v[170:173], 0
	v_mfma_f32_16x16x32_bf16 v[30:33], v[154:157], v[170:173], 0
	v_mfma_f32_16x16x32_bf16 v[22:25], v[146:149], v[178:181], 0
	v_mfma_f32_16x16x32_bf16 v[14:17], v[154:157], v[178:181], 0
	v_mfma_f32_16x16x32_bf16 v[6:9], v[146:149], v[186:189], 0
	v_mfma_f32_16x16x32_bf16 v[2:5], v[154:157], v[186:189], 0
	v_mfma_f32_16x16x32_bf16 v[54:57], v[150:153], v[166:169], v[54:57]
	v_mfma_f32_16x16x32_bf16 v[46:49], v[158:161], v[166:169], v[46:49]
	v_mfma_f32_16x16x32_bf16 v[38:41], v[150:153], v[174:177], v[38:41]
	v_mfma_f32_16x16x32_bf16 v[30:33], v[158:161], v[174:177], v[30:33]
	v_mfma_f32_16x16x32_bf16 v[22:25], v[150:153], v[182:185], v[22:25]
	v_mfma_f32_16x16x32_bf16 v[14:17], v[158:161], v[182:185], v[14:17]
	v_mfma_f32_16x16x32_bf16 v[6:9], v[150:153], v[196:199], v[6:9]
	v_mfma_f32_16x16x32_bf16 v[2:5], v[158:161], v[196:199], v[2:5]
	s_barrier
	s_setprio 0
	s_add_i32 s56, 0, 0x18000
	s_add_i32 s57, 0, 0x1c000
	v_add_u32_e32 v142, s56, v238
	v_add_u32_e32 v158, s57, v238
	ds_read_b128 v[130:133], v142
	ds_read_b128 v[134:137], v142 offset:1024
	ds_read_b128 v[138:141], v142 offset:2048
	ds_read_b128 v[142:145], v142 offset:3072
	ds_read_b128 v[146:149], v158
	ds_read_b128 v[150:153], v158 offset:1024
	ds_read_b128 v[154:157], v158 offset:2048
	ds_read_b128 v[158:161], v158 offset:3072
	s_add_u32 s28, s28, 0x80000
	s_addc_u32 s29, s29, 0
	s_mov_b32 m0, s41
	v_lshl_add_u64 v[218:219], s[28:29], 0, v[200:201]
	ds_read_b128 v[162:165], v240 offset:32768
	ds_read_b128 v[166:169], v240 offset:33792
	ds_read_b128 v[170:173], v240 offset:34816
	ds_read_b128 v[174:177], v240 offset:35840
	ds_read_b128 v[178:181], v240 offset:36864
	ds_read_b128 v[182:185], v240 offset:37888
	ds_read_b128 v[186:189], v240 offset:38912
	ds_read_b128 v[196:199], v240 offset:39936
	global_load_lds_dwordx4 v[218:219], off
	s_mov_b32 m0, s42
	v_lshl_add_u64 v[218:219], s[28:29], 0, v[202:203]
	global_load_lds_dwordx4 v[218:219], off
	s_waitcnt vmcnt(8) lgkmcnt(0)
	s_setprio 1
	s_barrier
	v_mfma_f32_16x16x32_bf16 v[126:129], v[130:133], v[162:165], v[126:129]
	v_mfma_f32_16x16x32_bf16 v[122:125], v[138:141], v[162:165], v[122:125]
	v_mfma_f32_16x16x32_bf16 v[110:113], v[130:133], v[170:173], v[110:113]
	v_mfma_f32_16x16x32_bf16 v[106:109], v[138:141], v[170:173], v[106:109]
	v_mfma_f32_16x16x32_bf16 v[98:101], v[130:133], v[178:181], v[98:101]
	v_mfma_f32_16x16x32_bf16 v[90:93], v[138:141], v[178:181], v[90:93]
	v_mfma_f32_16x16x32_bf16 v[82:85], v[130:133], v[186:189], v[82:85]
	v_mfma_f32_16x16x32_bf16 v[74:77], v[138:141], v[186:189], v[74:77]
	v_mfma_f32_16x16x32_bf16 v[126:129], v[134:137], v[166:169], v[126:129]
	v_mfma_f32_16x16x32_bf16 v[122:125], v[142:145], v[166:169], v[122:125]
	v_mfma_f32_16x16x32_bf16 v[110:113], v[134:137], v[174:177], v[110:113]
	v_mfma_f32_16x16x32_bf16 v[106:109], v[142:145], v[174:177], v[106:109]
	v_mfma_f32_16x16x32_bf16 v[98:101], v[134:137], v[182:185], v[98:101]
	v_mfma_f32_16x16x32_bf16 v[90:93], v[142:145], v[182:185], v[90:93]
	v_mfma_f32_16x16x32_bf16 v[82:85], v[134:137], v[196:199], v[82:85]
	v_mfma_f32_16x16x32_bf16 v[74:77], v[142:145], v[196:199], v[74:77]
	s_setprio 0
	s_setprio 1
	v_mfma_f32_16x16x32_bf16 v[118:121], v[146:149], v[162:165], v[118:121]
	v_mfma_f32_16x16x32_bf16 v[114:117], v[154:157], v[162:165], v[114:117]
	v_mfma_f32_16x16x32_bf16 v[102:105], v[146:149], v[170:173], v[102:105]
	v_mfma_f32_16x16x32_bf16 v[94:97], v[154:157], v[170:173], v[94:97]
	v_mfma_f32_16x16x32_bf16 v[86:89], v[146:149], v[178:181], v[86:89]
	v_mfma_f32_16x16x32_bf16 v[78:81], v[154:157], v[178:181], v[78:81]
	v_mfma_f32_16x16x32_bf16 v[70:73], v[146:149], v[186:189], v[70:73]
	v_mfma_f32_16x16x32_bf16 v[66:69], v[154:157], v[186:189], v[66:69]
	v_mfma_f32_16x16x32_bf16 v[118:121], v[150:153], v[166:169], v[118:121]
	v_mfma_f32_16x16x32_bf16 v[114:117], v[158:161], v[166:169], v[114:117]
	v_mfma_f32_16x16x32_bf16 v[102:105], v[150:153], v[174:177], v[102:105]
	v_mfma_f32_16x16x32_bf16 v[94:97], v[158:161], v[174:177], v[94:97]
	v_mfma_f32_16x16x32_bf16 v[86:89], v[150:153], v[182:185], v[86:89]
	v_mfma_f32_16x16x32_bf16 v[78:81], v[158:161], v[182:185], v[78:81]
	v_mfma_f32_16x16x32_bf16 v[70:73], v[150:153], v[196:199], v[70:73]
	v_mfma_f32_16x16x32_bf16 v[66:69], v[158:161], v[196:199], v[66:69]
	s_barrier
	s_setprio 0
	s_add_i32 s28, s56, s34
	v_lshl_add_u64 v[210:211], v[210:211], 0, s[58:59]
	s_mov_b32 m0, s28
	ds_read_b128 v[162:165], v240 offset:49152
	ds_read_b128 v[166:169], v240 offset:50176
	ds_read_b128 v[170:173], v240 offset:51200
	ds_read_b128 v[174:177], v240 offset:52224
	ds_read_b128 v[178:181], v240 offset:53248
	ds_read_b128 v[182:185], v240 offset:54272
	ds_read_b128 v[186:189], v240 offset:55296
	ds_read_b128 v[196:199], v240 offset:56320
	global_load_lds_dwordx4 v[210:211], off
	s_add_i32 m0, s28, 0x2000
	s_add_u32 s26, s26, 0x80080
	v_lshl_add_u64 v[210:211], v[212:213], 0, s[58:59]
	s_addc_u32 s27, s27, 0
	s_add_i32 s28, s57, s34
	global_load_lds_dwordx4 v[210:211], off
	s_mov_b32 m0, s28
	v_lshl_add_u64 v[210:211], s[26:27], 0, v[190:191]
	global_load_lds_dwordx4 v[210:211], off
	s_add_i32 m0, s28, 0x2000
	v_lshl_add_u64 v[210:211], s[26:27], 0, v[204:205]
	global_load_lds_dwordx4 v[210:211], off
	s_mov_b32 m0, s43
	v_lshl_add_u64 v[210:211], v[214:215], 0, s[58:59]
	global_load_lds_dwordx4 v[210:211], off
	s_mov_b32 m0, s46
	v_lshl_add_u64 v[210:211], v[216:217], 0, s[58:59]
	global_load_lds_dwordx4 v[210:211], off
	s_waitcnt vmcnt(8) lgkmcnt(0)
	s_setprio 1
	s_barrier
	v_mfma_f32_16x16x32_bf16 v[62:65], v[130:133], v[162:165], v[62:65]
	v_mfma_f32_16x16x32_bf16 v[58:61], v[138:141], v[162:165], v[58:61]
	v_mfma_f32_16x16x32_bf16 v[50:53], v[130:133], v[170:173], v[50:53]
	v_mfma_f32_16x16x32_bf16 v[42:45], v[138:141], v[170:173], v[42:45]
	v_mfma_f32_16x16x32_bf16 v[34:37], v[130:133], v[178:181], v[34:37]
	v_mfma_f32_16x16x32_bf16 v[26:29], v[138:141], v[178:181], v[26:29]
	v_mfma_f32_16x16x32_bf16 v[18:21], v[130:133], v[186:189], v[18:21]
	v_mfma_f32_16x16x32_bf16 v[10:13], v[138:141], v[186:189], v[10:13]
	v_mfma_f32_16x16x32_bf16 v[62:65], v[134:137], v[166:169], v[62:65]
	v_mfma_f32_16x16x32_bf16 v[58:61], v[142:145], v[166:169], v[58:61]
	v_mfma_f32_16x16x32_bf16 v[50:53], v[134:137], v[174:177], v[50:53]
	v_mfma_f32_16x16x32_bf16 v[42:45], v[142:145], v[174:177], v[42:45]
	v_mfma_f32_16x16x32_bf16 v[34:37], v[134:137], v[182:185], v[34:37]
	v_mfma_f32_16x16x32_bf16 v[26:29], v[142:145], v[182:185], v[26:29]
	v_mfma_f32_16x16x32_bf16 v[18:21], v[134:137], v[196:199], v[18:21]
	v_mfma_f32_16x16x32_bf16 v[10:13], v[142:145], v[196:199], v[10:13]
	s_setprio 0
	s_setprio 1
	v_mfma_f32_16x16x32_bf16 v[54:57], v[146:149], v[162:165], v[54:57]
	v_mfma_f32_16x16x32_bf16 v[46:49], v[154:157], v[162:165], v[46:49]
	v_mfma_f32_16x16x32_bf16 v[38:41], v[146:149], v[170:173], v[38:41]
	v_mfma_f32_16x16x32_bf16 v[30:33], v[154:157], v[170:173], v[30:33]
	v_mfma_f32_16x16x32_bf16 v[22:25], v[146:149], v[178:181], v[22:25]
	v_mfma_f32_16x16x32_bf16 v[14:17], v[154:157], v[178:181], v[14:17]
	v_mfma_f32_16x16x32_bf16 v[6:9], v[146:149], v[186:189], v[6:9]
	v_mfma_f32_16x16x32_bf16 v[2:5], v[154:157], v[186:189], v[2:5]
	v_mfma_f32_16x16x32_bf16 v[54:57], v[150:153], v[166:169], v[54:57]
	v_mfma_f32_16x16x32_bf16 v[46:49], v[158:161], v[166:169], v[46:49]
	v_mfma_f32_16x16x32_bf16 v[38:41], v[150:153], v[174:177], v[38:41]
	v_mfma_f32_16x16x32_bf16 v[30:33], v[158:161], v[174:177], v[30:33]
	v_mfma_f32_16x16x32_bf16 v[22:25], v[150:153], v[182:185], v[22:25]
	v_mfma_f32_16x16x32_bf16 v[14:17], v[158:161], v[182:185], v[14:17]
	v_mfma_f32_16x16x32_bf16 v[6:9], v[150:153], v[196:199], v[6:9]
	v_mfma_f32_16x16x32_bf16 v[2:5], v[158:161], v[196:199], v[2:5]
	s_barrier
	s_setprio 0
	s_add_i32 s55, s55, 2
	s_add_u32 s24, s24, 0x100
	s_addc_u32 s25, s25, 0
	s_add_u32 s52, s52, 0x100
	s_addc_u32 s53, s53, 0
	s_cmp_gt_u32 s55, 29
	s_cbranch_scc1 .Lpeel_done_4
	s_branch .LBB0_800
.Ltrip0_strict_4:
	s_add_u32 s26, s24, 0xfff80080
	s_addc_u32 s27, s25, -1
	s_add_i32 s56, 0, 0x10000
	s_cmp_eq_u32 s55, 28
	s_cselect_b32 s29, s11, s27
	s_cselect_b32 s28, s21, s26
	s_cselect_b32 s27, s9, s53
	s_cselect_b32 s26, s47, s52
	s_add_i32 s60, 0, 0x14000
	v_add_u32_e32 v142, s56, v238
	v_add_u32_e32 v158, s60, v238
	ds_read_b128 v[130:133], v142
	ds_read_b128 v[134:137], v142 offset:1024
	ds_read_b128 v[138:141], v142 offset:2048
	ds_read_b128 v[142:145], v142 offset:3072
	ds_read_b128 v[146:149], v158
	ds_read_b128 v[150:153], v158 offset:1024
	ds_read_b128 v[154:157], v158 offset:2048
	ds_read_b128 v[158:161], v158 offset:3072
	v_lshl_add_u64 v[210:211], s[24:25], 0, v[206:207]
	s_add_i32 m0, s23, 0xc000
	ds_read_b128 v[162:165], v240
	ds_read_b128 v[166:169], v240 offset:1024
	ds_read_b128 v[170:173], v240 offset:2048
	ds_read_b128 v[174:177], v240 offset:3072
	ds_read_b128 v[178:181], v240 offset:4096
	ds_read_b128 v[182:185], v240 offset:5120
	ds_read_b128 v[186:189], v240 offset:6144
	ds_read_b128 v[196:199], v240 offset:7168
	global_load_lds_dwordx4 v[210:211], off
	s_add_i32 m0, s23, 0xe000
	v_lshl_add_u64 v[210:211], s[24:25], 0, v[208:209]
	global_load_lds_dwordx4 v[210:211], off
	s_waitcnt vmcnt(8) lgkmcnt(0)
	s_setprio 1
	s_barrier
	v_mfma_f32_16x16x32_bf16 v[126:129], v[130:133], v[162:165], 0
	v_mfma_f32_16x16x32_bf16 v[122:125], v[138:141], v[162:165], 0
	v_mfma_f32_16x16x32_bf16 v[110:113], v[130:133], v[170:173], 0
	v_mfma_f32_16x16x32_bf16 v[106:109], v[138:141], v[170:173], 0
	v_mfma_f32_16x16x32_bf16 v[98:101], v[130:133], v[178:181], 0
	v_mfma_f32_16x16x32_bf16 v[90:93], v[138:141], v[178:181], 0
	v_mfma_f32_16x16x32_bf16 v[82:85], v[130:133], v[186:189], 0
	v_mfma_f32_16x16x32_bf16 v[74:77], v[138:141], v[186:189], 0
	v_mfma_f32_16x16x32_bf16 v[126:129], v[134:137], v[166:169], v[126:129]
	v_mfma_f32_16x16x32_bf16 v[122:125], v[142:145], v[166:169], v[122:125]
	v_mfma_f32_16x16x32_bf16 v[110:113], v[134:137], v[174:177], v[110:113]
	v_mfma_f32_16x16x32_bf16 v[106:109], v[142:145], v[174:177], v[106:109]
	v_mfma_f32_16x16x32_bf16 v[98:101], v[134:137], v[182:185], v[98:101]
	v_mfma_f32_16x16x32_bf16 v[90:93], v[142:145], v[182:185], v[90:93]
	v_mfma_f32_16x16x32_bf16 v[82:85], v[134:137], v[196:199], v[82:85]
	v_mfma_f32_16x16x32_bf16 v[74:77], v[142:145], v[196:199], v[74:77]
	s_setprio 0
	s_setprio 1
	v_mfma_f32_16x16x32_bf16 v[118:121], v[146:149], v[162:165], 0
	v_mfma_f32_16x16x32_bf16 v[114:117], v[154:157], v[162:165], 0
	v_mfma_f32_16x16x32_bf16 v[102:105], v[146:149], v[170:173], 0
	v_mfma_f32_16x16x32_bf16 v[94:97], v[154:157], v[170:173], 0
	v_mfma_f32_16x16x32_bf16 v[86:89], v[146:149], v[178:181], 0
	v_mfma_f32_16x16x32_bf16 v[78:81], v[154:157], v[178:181], 0
	v_mfma_f32_16x16x32_bf16 v[70:73], v[146:149], v[186:189], 0
	v_mfma_f32_16x16x32_bf16 v[66:69], v[154:157], v[186:189], 0
	v_mfma_f32_16x16x32_bf16 v[118:121], v[150:153], v[166:169], v[118:121]
	v_mfma_f32_16x16x32_bf16 v[114:117], v[158:161], v[166:169], v[114:117]
	v_mfma_f32_16x16x32_bf16 v[102:105], v[150:153], v[174:177], v[102:105]
	v_mfma_f32_16x16x32_bf16 v[94:97], v[158:161], v[174:177], v[94:97]
	v_mfma_f32_16x16x32_bf16 v[86:89], v[150:153], v[182:185], v[86:89]
	v_mfma_f32_16x16x32_bf16 v[78:81], v[158:161], v[182:185], v[78:81]
	v_mfma_f32_16x16x32_bf16 v[70:73], v[150:153], v[196:199], v[70:73]
	v_mfma_f32_16x16x32_bf16 v[66:69], v[158:161], v[196:199], v[66:69]
	s_barrier
	s_setprio 0
	s_add_i32 s56, s56, s34
	v_lshl_add_u64 v[210:211], s[26:27], 0, v[190:191]
	s_mov_b32 m0, s56
	ds_read_b128 v[162:165], v240 offset:16384
	ds_read_b128 v[166:169], v240 offset:17408
	ds_read_b128 v[170:173], v240 offset:18432
	ds_read_b128 v[174:177], v240 offset:19456
	ds_read_b128 v[178:181], v240 offset:20480
	ds_read_b128 v[182:185], v240 offset:21504
	ds_read_b128 v[186:189], v240 offset:22528
	ds_read_b128 v[196:199], v240 offset:23552
	global_load_lds_dwordx4 v[210:211], off
	s_add_i32 m0, s56, 0x2000
	s_add_u32 s56, s26, 0x80000
	v_lshl_add_u64 v[212:213], s[26:27], 0, v[204:205]
	s_addc_u32 s57, s27, 0
	s_add_i32 s60, s60, s34
	global_load_lds_dwordx4 v[212:213], off
	v_lshl_add_u64 v[214:215], s[56:57], 0, v[190:191]
	s_mov_b32 m0, s60
	v_lshl_add_u64 v[216:217], s[28:29], 0, v[202:203]
	global_load_lds_dwordx4 v[214:215], off
	s_add_i32 m0, s60, 0x2000
	v_lshl_add_u64 v[214:215], s[56:57], 0, v[204:205]
	global_load_lds_dwordx4 v[214:215], off
	s_mov_b32 m0, s23
	v_lshl_add_u64 v[214:215], s[28:29], 0, v[200:201]
	global_load_lds_dwordx4 v[214:215], off
	s_mov_b32 m0, s35
	s_nop 0
	global_load_lds_dwordx4 v[216:217], off
	s_waitcnt vmcnt(8) lgkmcnt(0)
	s_setprio 1
	s_barrier
	v_mfma_f32_16x16x32_bf16 v[62:65], v[130:133], v[162:165], 0
	v_mfma_f32_16x16x32_bf16 v[58:61], v[138:141], v[162:165], 0
	v_mfma_f32_16x16x32_bf16 v[50:53], v[130:133], v[170:173], 0
	v_mfma_f32_16x16x32_bf16 v[42:45], v[138:141], v[170:173], 0
	v_mfma_f32_16x16x32_bf16 v[34:37], v[130:133], v[178:181], 0
	v_mfma_f32_16x16x32_bf16 v[26:29], v[138:141], v[178:181], 0
	v_mfma_f32_16x16x32_bf16 v[18:21], v[130:133], v[186:189], 0
	v_mfma_f32_16x16x32_bf16 v[10:13], v[138:141], v[186:189], 0
	v_mfma_f32_16x16x32_bf16 v[62:65], v[134:137], v[166:169], v[62:65]
	v_mfma_f32_16x16x32_bf16 v[58:61], v[142:145], v[166:169], v[58:61]
	v_mfma_f32_16x16x32_bf16 v[50:53], v[134:137], v[174:177], v[50:53]
	v_mfma_f32_16x16x32_bf16 v[42:45], v[142:145], v[174:177], v[42:45]
	v_mfma_f32_16x16x32_bf16 v[34:37], v[134:137], v[182:185], v[34:37]
	v_mfma_f32_16x16x32_bf16 v[26:29], v[142:145], v[182:185], v[26:29]
	v_mfma_f32_16x16x32_bf16 v[18:21], v[134:137], v[196:199], v[18:21]
	v_mfma_f32_16x16x32_bf16 v[10:13], v[142:145], v[196:199], v[10:13]
	s_setprio 0
	s_setprio 1
	v_mfma_f32_16x16x32_bf16 v[54:57], v[146:149], v[162:165], 0
	v_mfma_f32_16x16x32_bf16 v[46:49], v[154:157], v[162:165], 0
	v_mfma_f32_16x16x32_bf16 v[38:41], v[146:149], v[170:173], 0
	v_mfma_f32_16x16x32_bf16 v[30:33], v[154:157], v[170:173], 0
	v_mfma_f32_16x16x32_bf16 v[22:25], v[146:149], v[178:181], 0
	v_mfma_f32_16x16x32_bf16 v[14:17], v[154:157], v[178:181], 0
	v_mfma_f32_16x16x32_bf16 v[6:9], v[146:149], v[186:189], 0
	v_mfma_f32_16x16x32_bf16 v[2:5], v[154:157], v[186:189], 0
	v_mfma_f32_16x16x32_bf16 v[54:57], v[150:153], v[166:169], v[54:57]
	v_mfma_f32_16x16x32_bf16 v[46:49], v[158:161], v[166:169], v[46:49]
	v_mfma_f32_16x16x32_bf16 v[38:41], v[150:153], v[174:177], v[38:41]
	v_mfma_f32_16x16x32_bf16 v[30:33], v[158:161], v[174:177], v[30:33]
	v_mfma_f32_16x16x32_bf16 v[22:25], v[150:153], v[182:185], v[22:25]
	v_mfma_f32_16x16x32_bf16 v[14:17], v[158:161], v[182:185], v[14:17]
	v_mfma_f32_16x16x32_bf16 v[6:9], v[150:153], v[196:199], v[6:9]
	v_mfma_f32_16x16x32_bf16 v[2:5], v[158:161], v[196:199], v[2:5]
	s_barrier
	s_setprio 0
	s_add_i32 s56, 0, 0x18000
	s_add_i32 s57, 0, 0x1c000
	v_add_u32_e32 v142, s56, v238
	v_add_u32_e32 v158, s57, v238
	ds_read_b128 v[130:133], v142
	ds_read_b128 v[134:137], v142 offset:1024
	ds_read_b128 v[138:141], v142 offset:2048
	ds_read_b128 v[142:145], v142 offset:3072
	ds_read_b128 v[146:149], v158
	ds_read_b128 v[150:153], v158 offset:1024
	ds_read_b128 v[154:157], v158 offset:2048
	ds_read_b128 v[158:161], v158 offset:3072
	s_add_u32 s28, s28, 0x80000
	s_addc_u32 s29, s29, 0
	s_mov_b32 m0, s41
	v_lshl_add_u64 v[218:219], s[28:29], 0, v[200:201]
	ds_read_b128 v[162:165], v240 offset:32768
	ds_read_b128 v[166:169], v240 offset:33792
	ds_read_b128 v[170:173], v240 offset:34816
	ds_read_b128 v[174:177], v240 offset:35840
	ds_read_b128 v[178:181], v240 offset:36864
	ds_read_b128 v[182:185], v240 offset:37888
	ds_read_b128 v[186:189], v240 offset:38912
	ds_read_b128 v[196:199], v240 offset:39936
	global_load_lds_dwordx4 v[218:219], off
	s_mov_b32 m0, s42
	v_lshl_add_u64 v[218:219], s[28:29], 0, v[202:203]
	global_load_lds_dwordx4 v[218:219], off
	s_waitcnt vmcnt(8) lgkmcnt(0)
	s_setprio 1
	s_barrier
	v_mfma_f32_16x16x32_bf16 v[126:129], v[130:133], v[162:165], v[126:129]
	v_mfma_f32_16x16x32_bf16 v[122:125], v[138:141], v[162:165], v[122:125]
	v_mfma_f32_16x16x32_bf16 v[110:113], v[130:133], v[170:173], v[110:113]
	v_mfma_f32_16x16x32_bf16 v[106:109], v[138:141], v[170:173], v[106:109]
	v_mfma_f32_16x16x32_bf16 v[98:101], v[130:133], v[178:181], v[98:101]
	v_mfma_f32_16x16x32_bf16 v[90:93], v[138:141], v[178:181], v[90:93]
	v_mfma_f32_16x16x32_bf16 v[82:85], v[130:133], v[186:189], v[82:85]
	v_mfma_f32_16x16x32_bf16 v[74:77], v[138:141], v[186:189], v[74:77]
	v_mfma_f32_16x16x32_bf16 v[126:129], v[134:137], v[166:169], v[126:129]
	v_mfma_f32_16x16x32_bf16 v[122:125], v[142:145], v[166:169], v[122:125]
	v_mfma_f32_16x16x32_bf16 v[110:113], v[134:137], v[174:177], v[110:113]
	v_mfma_f32_16x16x32_bf16 v[106:109], v[142:145], v[174:177], v[106:109]
	v_mfma_f32_16x16x32_bf16 v[98:101], v[134:137], v[182:185], v[98:101]
	v_mfma_f32_16x16x32_bf16 v[90:93], v[142:145], v[182:185], v[90:93]
	v_mfma_f32_16x16x32_bf16 v[82:85], v[134:137], v[196:199], v[82:85]
	v_mfma_f32_16x16x32_bf16 v[74:77], v[142:145], v[196:199], v[74:77]
	s_setprio 0
	s_setprio 1
	v_mfma_f32_16x16x32_bf16 v[118:121], v[146:149], v[162:165], v[118:121]
	v_mfma_f32_16x16x32_bf16 v[114:117], v[154:157], v[162:165], v[114:117]
	v_mfma_f32_16x16x32_bf16 v[102:105], v[146:149], v[170:173], v[102:105]
	v_mfma_f32_16x16x32_bf16 v[94:97], v[154:157], v[170:173], v[94:97]
	v_mfma_f32_16x16x32_bf16 v[86:89], v[146:149], v[178:181], v[86:89]
	v_mfma_f32_16x16x32_bf16 v[78:81], v[154:157], v[178:181], v[78:81]
	v_mfma_f32_16x16x32_bf16 v[70:73], v[146:149], v[186:189], v[70:73]
	v_mfma_f32_16x16x32_bf16 v[66:69], v[154:157], v[186:189], v[66:69]
	v_mfma_f32_16x16x32_bf16 v[118:121], v[150:153], v[166:169], v[118:121]
	v_mfma_f32_16x16x32_bf16 v[114:117], v[158:161], v[166:169], v[114:117]
	v_mfma_f32_16x16x32_bf16 v[102:105], v[150:153], v[174:177], v[102:105]
	v_mfma_f32_16x16x32_bf16 v[94:97], v[158:161], v[174:177], v[94:97]
	v_mfma_f32_16x16x32_bf16 v[86:89], v[150:153], v[182:185], v[86:89]
	v_mfma_f32_16x16x32_bf16 v[78:81], v[158:161], v[182:185], v[78:81]
	v_mfma_f32_16x16x32_bf16 v[70:73], v[150:153], v[196:199], v[70:73]
	v_mfma_f32_16x16x32_bf16 v[66:69], v[158:161], v[196:199], v[66:69]
	s_barrier
	s_setprio 0
	s_add_i32 s28, s56, s34
	v_lshl_add_u64 v[210:211], v[210:211], 0, s[58:59]
	s_mov_b32 m0, s28
	ds_read_b128 v[162:165], v240 offset:49152
	ds_read_b128 v[166:169], v240 offset:50176
	ds_read_b128 v[170:173], v240 offset:51200
	ds_read_b128 v[174:177], v240 offset:52224
	ds_read_b128 v[178:181], v240 offset:53248
	ds_read_b128 v[182:185], v240 offset:54272
	ds_read_b128 v[186:189], v240 offset:55296
	ds_read_b128 v[196:199], v240 offset:56320
	global_load_lds_dwordx4 v[210:211], off
	s_add_i32 m0, s28, 0x2000
	s_add_u32 s26, s26, 0x80080
	v_lshl_add_u64 v[210:211], v[212:213], 0, s[58:59]
	s_addc_u32 s27, s27, 0
	s_add_i32 s28, s57, s34
	global_load_lds_dwordx4 v[210:211], off
	s_mov_b32 m0, s28
	v_lshl_add_u64 v[210:211], s[26:27], 0, v[190:191]
	global_load_lds_dwordx4 v[210:211], off
	s_add_i32 m0, s28, 0x2000
	v_lshl_add_u64 v[210:211], s[26:27], 0, v[204:205]
	global_load_lds_dwordx4 v[210:211], off
	s_mov_b32 m0, s43
	v_lshl_add_u64 v[210:211], v[214:215], 0, s[58:59]
	global_load_lds_dwordx4 v[210:211], off
	s_mov_b32 m0, s46
	v_lshl_add_u64 v[210:211], v[216:217], 0, s[58:59]
	global_load_lds_dwordx4 v[210:211], off
	s_waitcnt vmcnt(8) lgkmcnt(0)
	s_setprio 1
	s_barrier
	v_mfma_f32_16x16x32_bf16 v[62:65], v[130:133], v[162:165], v[62:65]
	v_mfma_f32_16x16x32_bf16 v[58:61], v[138:141], v[162:165], v[58:61]
	v_mfma_f32_16x16x32_bf16 v[50:53], v[130:133], v[170:173], v[50:53]
	v_mfma_f32_16x16x32_bf16 v[42:45], v[138:141], v[170:173], v[42:45]
	v_mfma_f32_16x16x32_bf16 v[34:37], v[130:133], v[178:181], v[34:37]
	v_mfma_f32_16x16x32_bf16 v[26:29], v[138:141], v[178:181], v[26:29]
	v_mfma_f32_16x16x32_bf16 v[18:21], v[130:133], v[186:189], v[18:21]
	v_mfma_f32_16x16x32_bf16 v[10:13], v[138:141], v[186:189], v[10:13]
	v_mfma_f32_16x16x32_bf16 v[62:65], v[134:137], v[166:169], v[62:65]
	v_mfma_f32_16x16x32_bf16 v[58:61], v[142:145], v[166:169], v[58:61]
	v_mfma_f32_16x16x32_bf16 v[50:53], v[134:137], v[174:177], v[50:53]
	v_mfma_f32_16x16x32_bf16 v[42:45], v[142:145], v[174:177], v[42:45]
	v_mfma_f32_16x16x32_bf16 v[34:37], v[134:137], v[182:185], v[34:37]
	v_mfma_f32_16x16x32_bf16 v[26:29], v[142:145], v[182:185], v[26:29]
	v_mfma_f32_16x16x32_bf16 v[18:21], v[134:137], v[196:199], v[18:21]
	v_mfma_f32_16x16x32_bf16 v[10:13], v[142:145], v[196:199], v[10:13]
	s_setprio 0
	s_setprio 1
	v_mfma_f32_16x16x32_bf16 v[54:57], v[146:149], v[162:165], v[54:57]
	v_mfma_f32_16x16x32_bf16 v[46:49], v[154:157], v[162:165], v[46:49]
	v_mfma_f32_16x16x32_bf16 v[38:41], v[146:149], v[170:173], v[38:41]
	v_mfma_f32_16x16x32_bf16 v[30:33], v[154:157], v[170:173], v[30:33]
	v_mfma_f32_16x16x32_bf16 v[22:25], v[146:149], v[178:181], v[22:25]
	v_mfma_f32_16x16x32_bf16 v[14:17], v[154:157], v[178:181], v[14:17]
	v_mfma_f32_16x16x32_bf16 v[6:9], v[146:149], v[186:189], v[6:9]
	v_mfma_f32_16x16x32_bf16 v[2:5], v[154:157], v[186:189], v[2:5]
	v_mfma_f32_16x16x32_bf16 v[54:57], v[150:153], v[166:169], v[54:57]
	v_mfma_f32_16x16x32_bf16 v[46:49], v[158:161], v[166:169], v[46:49]
	v_mfma_f32_16x16x32_bf16 v[38:41], v[150:153], v[174:177], v[38:41]
	v_mfma_f32_16x16x32_bf16 v[30:33], v[158:161], v[174:177], v[30:33]
	v_mfma_f32_16x16x32_bf16 v[22:25], v[150:153], v[182:185], v[22:25]
	v_mfma_f32_16x16x32_bf16 v[14:17], v[158:161], v[182:185], v[14:17]
	v_mfma_f32_16x16x32_bf16 v[6:9], v[150:153], v[196:199], v[6:9]
	v_mfma_f32_16x16x32_bf16 v[2:5], v[158:161], v[196:199], v[2:5]
	s_barrier
	s_setprio 0
	s_add_i32 s55, s55, 2
	s_add_u32 s24, s24, 0x100
	s_addc_u32 s25, s25, 0
	s_add_u32 s52, s52, 0x100
	s_addc_u32 s53, s53, 0
	s_cmp_gt_u32 s55, 29
	s_cbranch_scc1 .Lpeel_done_4
.LBB0_800:
	s_add_u32 s26, s24, 0xfff80080
	s_addc_u32 s27, s25, -1
	s_add_i32 s56, 0, 0x10000
	s_cmp_eq_u32 s55, 28
	s_cselect_b32 s29, s11, s27
	s_cselect_b32 s28, s21, s26
	s_cselect_b32 s27, s9, s53
	s_cselect_b32 s26, s47, s52
	s_add_i32 s60, 0, 0x14000
	v_add_u32_e32 v142, s56, v238
	v_add_u32_e32 v158, s60, v238
	ds_read_b128 v[130:133], v142
	ds_read_b128 v[134:137], v142 offset:1024
	ds_read_b128 v[138:141], v142 offset:2048
	ds_read_b128 v[142:145], v142 offset:3072
	ds_read_b128 v[146:149], v158
	ds_read_b128 v[150:153], v158 offset:1024
	ds_read_b128 v[154:157], v158 offset:2048
	ds_read_b128 v[158:161], v158 offset:3072
	v_lshl_add_u64 v[210:211], s[24:25], 0, v[206:207]
	s_add_i32 m0, s23, 0xc000
	ds_read_b128 v[162:165], v240
	ds_read_b128 v[166:169], v240 offset:1024
	ds_read_b128 v[170:173], v240 offset:2048
	ds_read_b128 v[174:177], v240 offset:3072
	ds_read_b128 v[178:181], v240 offset:4096
	ds_read_b128 v[182:185], v240 offset:5120
	ds_read_b128 v[186:189], v240 offset:6144
	ds_read_b128 v[196:199], v240 offset:7168
	global_load_lds_dwordx4 v[210:211], off
	s_add_i32 m0, s23, 0xe000
	v_lshl_add_u64 v[210:211], s[24:25], 0, v[208:209]
	global_load_lds_dwordx4 v[210:211], off
	s_waitcnt vmcnt(8) lgkmcnt(0)
	s_setprio 1
	s_barrier
	v_mfma_f32_16x16x32_bf16 v[126:129], v[130:133], v[162:165], v[126:129]
	v_mfma_f32_16x16x32_bf16 v[122:125], v[138:141], v[162:165], v[122:125]
	v_mfma_f32_16x16x32_bf16 v[110:113], v[130:133], v[170:173], v[110:113]
	v_mfma_f32_16x16x32_bf16 v[106:109], v[138:141], v[170:173], v[106:109]
	v_mfma_f32_16x16x32_bf16 v[98:101], v[130:133], v[178:181], v[98:101]
	v_mfma_f32_16x16x32_bf16 v[90:93], v[138:141], v[178:181], v[90:93]
	v_mfma_f32_16x16x32_bf16 v[82:85], v[130:133], v[186:189], v[82:85]
	v_mfma_f32_16x16x32_bf16 v[74:77], v[138:141], v[186:189], v[74:77]
	v_mfma_f32_16x16x32_bf16 v[126:129], v[134:137], v[166:169], v[126:129]
	v_mfma_f32_16x16x32_bf16 v[122:125], v[142:145], v[166:169], v[122:125]
	v_mfma_f32_16x16x32_bf16 v[110:113], v[134:137], v[174:177], v[110:113]
	v_mfma_f32_16x16x32_bf16 v[106:109], v[142:145], v[174:177], v[106:109]
	v_mfma_f32_16x16x32_bf16 v[98:101], v[134:137], v[182:185], v[98:101]
	v_mfma_f32_16x16x32_bf16 v[90:93], v[142:145], v[182:185], v[90:93]
	v_mfma_f32_16x16x32_bf16 v[82:85], v[134:137], v[196:199], v[82:85]
	v_mfma_f32_16x16x32_bf16 v[74:77], v[142:145], v[196:199], v[74:77]
	s_setprio 0
	s_setprio 1
	v_mfma_f32_16x16x32_bf16 v[118:121], v[146:149], v[162:165], v[118:121]
	v_mfma_f32_16x16x32_bf16 v[114:117], v[154:157], v[162:165], v[114:117]
	v_mfma_f32_16x16x32_bf16 v[102:105], v[146:149], v[170:173], v[102:105]
	v_mfma_f32_16x16x32_bf16 v[94:97], v[154:157], v[170:173], v[94:97]
	v_mfma_f32_16x16x32_bf16 v[86:89], v[146:149], v[178:181], v[86:89]
	v_mfma_f32_16x16x32_bf16 v[78:81], v[154:157], v[178:181], v[78:81]
	v_mfma_f32_16x16x32_bf16 v[70:73], v[146:149], v[186:189], v[70:73]
	v_mfma_f32_16x16x32_bf16 v[66:69], v[154:157], v[186:189], v[66:69]
	v_mfma_f32_16x16x32_bf16 v[118:121], v[150:153], v[166:169], v[118:121]
	v_mfma_f32_16x16x32_bf16 v[114:117], v[158:161], v[166:169], v[114:117]
	v_mfma_f32_16x16x32_bf16 v[102:105], v[150:153], v[174:177], v[102:105]
	v_mfma_f32_16x16x32_bf16 v[94:97], v[158:161], v[174:177], v[94:97]
	v_mfma_f32_16x16x32_bf16 v[86:89], v[150:153], v[182:185], v[86:89]
	v_mfma_f32_16x16x32_bf16 v[78:81], v[158:161], v[182:185], v[78:81]
	v_mfma_f32_16x16x32_bf16 v[70:73], v[150:153], v[196:199], v[70:73]
	v_mfma_f32_16x16x32_bf16 v[66:69], v[158:161], v[196:199], v[66:69]
	s_setprio 0
	s_barrier
	s_add_i32 s56, s56, s34
	v_lshl_add_u64 v[210:211], s[26:27], 0, v[190:191]
	s_mov_b32 m0, s56
	ds_read_b128 v[162:165], v240 offset:16384
	ds_read_b128 v[166:169], v240 offset:17408
	ds_read_b128 v[170:173], v240 offset:18432
	ds_read_b128 v[174:177], v240 offset:19456
	ds_read_b128 v[178:181], v240 offset:20480
	ds_read_b128 v[182:185], v240 offset:21504
	ds_read_b128 v[186:189], v240 offset:22528
	ds_read_b128 v[196:199], v240 offset:23552
	global_load_lds_dwordx4 v[210:211], off
	s_add_i32 m0, s56, 0x2000
	s_add_u32 s56, s26, 0x80000
	v_lshl_add_u64 v[212:213], s[26:27], 0, v[204:205]
	s_addc_u32 s57, s27, 0
	s_add_i32 s60, s60, s34
	global_load_lds_dwordx4 v[212:213], off
	v_lshl_add_u64 v[214:215], s[56:57], 0, v[190:191]
	s_mov_b32 m0, s60
	v_lshl_add_u64 v[216:217], s[28:29], 0, v[202:203]
	global_load_lds_dwordx4 v[214:215], off
	s_add_i32 m0, s60, 0x2000
	v_lshl_add_u64 v[214:215], s[56:57], 0, v[204:205]
	global_load_lds_dwordx4 v[214:215], off
	s_mov_b32 m0, s23
	v_lshl_add_u64 v[214:215], s[28:29], 0, v[200:201]
	global_load_lds_dwordx4 v[214:215], off
	s_mov_b32 m0, s35
	s_nop 0
	global_load_lds_dwordx4 v[216:217], off
	s_waitcnt vmcnt(8) lgkmcnt(0)
	s_setprio 1
	s_barrier
	v_mfma_f32_16x16x32_bf16 v[62:65], v[130:133], v[162:165], v[62:65]
	v_mfma_f32_16x16x32_bf16 v[58:61], v[138:141], v[162:165], v[58:61]
	v_mfma_f32_16x16x32_bf16 v[50:53], v[130:133], v[170:173], v[50:53]
	v_mfma_f32_16x16x32_bf16 v[42:45], v[138:141], v[170:173], v[42:45]
	v_mfma_f32_16x16x32_bf16 v[34:37], v[130:133], v[178:181], v[34:37]
	v_mfma_f32_16x16x32_bf16 v[26:29], v[138:141], v[178:181], v[26:29]
	v_mfma_f32_16x16x32_bf16 v[18:21], v[130:133], v[186:189], v[18:21]
	v_mfma_f32_16x16x32_bf16 v[10:13], v[138:141], v[186:189], v[10:13]
	v_mfma_f32_16x16x32_bf16 v[62:65], v[134:137], v[166:169], v[62:65]
	v_mfma_f32_16x16x32_bf16 v[58:61], v[142:145], v[166:169], v[58:61]
	v_mfma_f32_16x16x32_bf16 v[50:53], v[134:137], v[174:177], v[50:53]
	v_mfma_f32_16x16x32_bf16 v[42:45], v[142:145], v[174:177], v[42:45]
	v_mfma_f32_16x16x32_bf16 v[34:37], v[134:137], v[182:185], v[34:37]
	v_mfma_f32_16x16x32_bf16 v[26:29], v[142:145], v[182:185], v[26:29]
	v_mfma_f32_16x16x32_bf16 v[18:21], v[134:137], v[196:199], v[18:21]
	v_mfma_f32_16x16x32_bf16 v[10:13], v[142:145], v[196:199], v[10:13]
	s_setprio 0
	s_setprio 1
	v_mfma_f32_16x16x32_bf16 v[54:57], v[146:149], v[162:165], v[54:57]
	v_mfma_f32_16x16x32_bf16 v[46:49], v[154:157], v[162:165], v[46:49]
	v_mfma_f32_16x16x32_bf16 v[38:41], v[146:149], v[170:173], v[38:41]
	v_mfma_f32_16x16x32_bf16 v[30:33], v[154:157], v[170:173], v[30:33]
	v_mfma_f32_16x16x32_bf16 v[22:25], v[146:149], v[178:181], v[22:25]
	v_mfma_f32_16x16x32_bf16 v[14:17], v[154:157], v[178:181], v[14:17]
	v_mfma_f32_16x16x32_bf16 v[6:9], v[146:149], v[186:189], v[6:9]
	v_mfma_f32_16x16x32_bf16 v[2:5], v[154:157], v[186:189], v[2:5]
	v_mfma_f32_16x16x32_bf16 v[54:57], v[150:153], v[166:169], v[54:57]
	v_mfma_f32_16x16x32_bf16 v[46:49], v[158:161], v[166:169], v[46:49]
	v_mfma_f32_16x16x32_bf16 v[38:41], v[150:153], v[174:177], v[38:41]
	v_mfma_f32_16x16x32_bf16 v[30:33], v[158:161], v[174:177], v[30:33]
	v_mfma_f32_16x16x32_bf16 v[22:25], v[150:153], v[182:185], v[22:25]
	v_mfma_f32_16x16x32_bf16 v[14:17], v[158:161], v[182:185], v[14:17]
	v_mfma_f32_16x16x32_bf16 v[6:9], v[150:153], v[196:199], v[6:9]
	v_mfma_f32_16x16x32_bf16 v[2:5], v[158:161], v[196:199], v[2:5]
	s_setprio 0
	s_barrier
	s_add_i32 s56, 0, 0x18000
	s_add_i32 s57, 0, 0x1c000
	v_add_u32_e32 v142, s56, v238
	v_add_u32_e32 v158, s57, v238
	ds_read_b128 v[130:133], v142
	ds_read_b128 v[134:137], v142 offset:1024
	ds_read_b128 v[138:141], v142 offset:2048
	ds_read_b128 v[142:145], v142 offset:3072
	ds_read_b128 v[146:149], v158
	ds_read_b128 v[150:153], v158 offset:1024
	ds_read_b128 v[154:157], v158 offset:2048
	ds_read_b128 v[158:161], v158 offset:3072
	s_add_u32 s28, s28, 0x80000
	s_addc_u32 s29, s29, 0
	s_mov_b32 m0, s41
	v_lshl_add_u64 v[218:219], s[28:29], 0, v[200:201]
	ds_read_b128 v[162:165], v240 offset:32768
	ds_read_b128 v[166:169], v240 offset:33792
	ds_read_b128 v[170:173], v240 offset:34816
	ds_read_b128 v[174:177], v240 offset:35840
	ds_read_b128 v[178:181], v240 offset:36864
	ds_read_b128 v[182:185], v240 offset:37888
	ds_read_b128 v[186:189], v240 offset:38912
	ds_read_b128 v[196:199], v240 offset:39936
	global_load_lds_dwordx4 v[218:219], off
	s_mov_b32 m0, s42
	v_lshl_add_u64 v[218:219], s[28:29], 0, v[202:203]
	global_load_lds_dwordx4 v[218:219], off
	s_waitcnt vmcnt(8) lgkmcnt(0)
	s_setprio 1
	s_barrier
	v_mfma_f32_16x16x32_bf16 v[126:129], v[130:133], v[162:165], v[126:129]
	v_mfma_f32_16x16x32_bf16 v[122:125], v[138:141], v[162:165], v[122:125]
	v_mfma_f32_16x16x32_bf16 v[110:113], v[130:133], v[170:173], v[110:113]
	v_mfma_f32_16x16x32_bf16 v[106:109], v[138:141], v[170:173], v[106:109]
	v_mfma_f32_16x16x32_bf16 v[98:101], v[130:133], v[178:181], v[98:101]
	v_mfma_f32_16x16x32_bf16 v[90:93], v[138:141], v[178:181], v[90:93]
	v_mfma_f32_16x16x32_bf16 v[82:85], v[130:133], v[186:189], v[82:85]
	v_mfma_f32_16x16x32_bf16 v[74:77], v[138:141], v[186:189], v[74:77]
	v_mfma_f32_16x16x32_bf16 v[126:129], v[134:137], v[166:169], v[126:129]
	v_mfma_f32_16x16x32_bf16 v[122:125], v[142:145], v[166:169], v[122:125]
	v_mfma_f32_16x16x32_bf16 v[110:113], v[134:137], v[174:177], v[110:113]
	v_mfma_f32_16x16x32_bf16 v[106:109], v[142:145], v[174:177], v[106:109]
	v_mfma_f32_16x16x32_bf16 v[98:101], v[134:137], v[182:185], v[98:101]
	v_mfma_f32_16x16x32_bf16 v[90:93], v[142:145], v[182:185], v[90:93]
	v_mfma_f32_16x16x32_bf16 v[82:85], v[134:137], v[196:199], v[82:85]
	v_mfma_f32_16x16x32_bf16 v[74:77], v[142:145], v[196:199], v[74:77]
	s_setprio 0
	s_setprio 1
	v_mfma_f32_16x16x32_bf16 v[118:121], v[146:149], v[162:165], v[118:121]
	v_mfma_f32_16x16x32_bf16 v[114:117], v[154:157], v[162:165], v[114:117]
	v_mfma_f32_16x16x32_bf16 v[102:105], v[146:149], v[170:173], v[102:105]
	v_mfma_f32_16x16x32_bf16 v[94:97], v[154:157], v[170:173], v[94:97]
	v_mfma_f32_16x16x32_bf16 v[86:89], v[146:149], v[178:181], v[86:89]
	v_mfma_f32_16x16x32_bf16 v[78:81], v[154:157], v[178:181], v[78:81]
	v_mfma_f32_16x16x32_bf16 v[70:73], v[146:149], v[186:189], v[70:73]
	v_mfma_f32_16x16x32_bf16 v[66:69], v[154:157], v[186:189], v[66:69]
	v_mfma_f32_16x16x32_bf16 v[118:121], v[150:153], v[166:169], v[118:121]
	v_mfma_f32_16x16x32_bf16 v[114:117], v[158:161], v[166:169], v[114:117]
	v_mfma_f32_16x16x32_bf16 v[102:105], v[150:153], v[174:177], v[102:105]
	v_mfma_f32_16x16x32_bf16 v[94:97], v[158:161], v[174:177], v[94:97]
	v_mfma_f32_16x16x32_bf16 v[86:89], v[150:153], v[182:185], v[86:89]
	v_mfma_f32_16x16x32_bf16 v[78:81], v[158:161], v[182:185], v[78:81]
	v_mfma_f32_16x16x32_bf16 v[70:73], v[150:153], v[196:199], v[70:73]
	v_mfma_f32_16x16x32_bf16 v[66:69], v[158:161], v[196:199], v[66:69]
	s_setprio 0
	s_barrier
	s_add_i32 s28, s56, s34
	v_lshl_add_u64 v[210:211], v[210:211], 0, s[58:59]
	s_mov_b32 m0, s28
	ds_read_b128 v[162:165], v240 offset:49152
	ds_read_b128 v[166:169], v240 offset:50176
	ds_read_b128 v[170:173], v240 offset:51200
	ds_read_b128 v[174:177], v240 offset:52224
	ds_read_b128 v[178:181], v240 offset:53248
	ds_read_b128 v[182:185], v240 offset:54272
	ds_read_b128 v[186:189], v240 offset:55296
	ds_read_b128 v[196:199], v240 offset:56320
	global_load_lds_dwordx4 v[210:211], off
	s_add_i32 m0, s28, 0x2000
	s_add_u32 s26, s26, 0x80080
	v_lshl_add_u64 v[210:211], v[212:213], 0, s[58:59]
	s_addc_u32 s27, s27, 0
	s_add_i32 s28, s57, s34
	global_load_lds_dwordx4 v[210:211], off
	s_mov_b32 m0, s28
	v_lshl_add_u64 v[210:211], s[26:27], 0, v[190:191]
	global_load_lds_dwordx4 v[210:211], off
	s_add_i32 m0, s28, 0x2000
	v_lshl_add_u64 v[210:211], s[26:27], 0, v[204:205]
	global_load_lds_dwordx4 v[210:211], off
	s_mov_b32 m0, s43
	v_lshl_add_u64 v[210:211], v[214:215], 0, s[58:59]
	global_load_lds_dwordx4 v[210:211], off
	s_mov_b32 m0, s46
	v_lshl_add_u64 v[210:211], v[216:217], 0, s[58:59]
	global_load_lds_dwordx4 v[210:211], off
	s_waitcnt vmcnt(8) lgkmcnt(0)
	s_setprio 1
	s_barrier
	v_mfma_f32_16x16x32_bf16 v[62:65], v[130:133], v[162:165], v[62:65]
	v_mfma_f32_16x16x32_bf16 v[58:61], v[138:141], v[162:165], v[58:61]
	v_mfma_f32_16x16x32_bf16 v[50:53], v[130:133], v[170:173], v[50:53]
	v_mfma_f32_16x16x32_bf16 v[42:45], v[138:141], v[170:173], v[42:45]
	v_mfma_f32_16x16x32_bf16 v[34:37], v[130:133], v[178:181], v[34:37]
	v_mfma_f32_16x16x32_bf16 v[26:29], v[138:141], v[178:181], v[26:29]
	v_mfma_f32_16x16x32_bf16 v[18:21], v[130:133], v[186:189], v[18:21]
	v_mfma_f32_16x16x32_bf16 v[10:13], v[138:141], v[186:189], v[10:13]
	v_mfma_f32_16x16x32_bf16 v[62:65], v[134:137], v[166:169], v[62:65]
	v_mfma_f32_16x16x32_bf16 v[58:61], v[142:145], v[166:169], v[58:61]
	v_mfma_f32_16x16x32_bf16 v[50:53], v[134:137], v[174:177], v[50:53]
	v_mfma_f32_16x16x32_bf16 v[42:45], v[142:145], v[174:177], v[42:45]
	v_mfma_f32_16x16x32_bf16 v[34:37], v[134:137], v[182:185], v[34:37]
	v_mfma_f32_16x16x32_bf16 v[26:29], v[142:145], v[182:185], v[26:29]
	v_mfma_f32_16x16x32_bf16 v[18:21], v[134:137], v[196:199], v[18:21]
	v_mfma_f32_16x16x32_bf16 v[10:13], v[142:145], v[196:199], v[10:13]
	s_setprio 0
	s_setprio 1
	v_mfma_f32_16x16x32_bf16 v[54:57], v[146:149], v[162:165], v[54:57]
	v_mfma_f32_16x16x32_bf16 v[46:49], v[154:157], v[162:165], v[46:49]
	v_mfma_f32_16x16x32_bf16 v[38:41], v[146:149], v[170:173], v[38:41]
	v_mfma_f32_16x16x32_bf16 v[30:33], v[154:157], v[170:173], v[30:33]
	v_mfma_f32_16x16x32_bf16 v[22:25], v[146:149], v[178:181], v[22:25]
	v_mfma_f32_16x16x32_bf16 v[14:17], v[154:157], v[178:181], v[14:17]
	v_mfma_f32_16x16x32_bf16 v[6:9], v[146:149], v[186:189], v[6:9]
	v_mfma_f32_16x16x32_bf16 v[2:5], v[154:157], v[186:189], v[2:5]
	v_mfma_f32_16x16x32_bf16 v[54:57], v[150:153], v[166:169], v[54:57]
	v_mfma_f32_16x16x32_bf16 v[46:49], v[158:161], v[166:169], v[46:49]
	v_mfma_f32_16x16x32_bf16 v[38:41], v[150:153], v[174:177], v[38:41]
	v_mfma_f32_16x16x32_bf16 v[30:33], v[158:161], v[174:177], v[30:33]
	v_mfma_f32_16x16x32_bf16 v[22:25], v[150:153], v[182:185], v[22:25]
	v_mfma_f32_16x16x32_bf16 v[14:17], v[158:161], v[182:185], v[14:17]
	v_mfma_f32_16x16x32_bf16 v[6:9], v[150:153], v[196:199], v[6:9]
	v_mfma_f32_16x16x32_bf16 v[2:5], v[158:161], v[196:199], v[2:5]
	s_setprio 0
	s_barrier
	s_add_i32 s55, s55, 2
	s_add_u32 s24, s24, 0x100
	s_addc_u32 s25, s25, 0
	s_add_u32 s52, s52, 0x100
	s_addc_u32 s53, s53, 0
	s_cmp_gt_u32 s55, 29
	s_cbranch_scc0 .LBB0_800

.LBB0_822:
	s_ashr_i32 s17, s16, 31
	s_lshl_b64 s[22:23], s[16:17], 20
	v_readlane_b32 s0, v254, 60
	s_add_u32 s22, s0, s22
	v_readlane_b32 s0, v254, 61
	s_addc_u32 s23, s0, s23
	s_and_b64 s[24:25], s[20:21], exec
	s_cselect_b32 s17, s23, s31
	s_cselect_b32 s27, s22, s30
	s_ashr_i32 s15, s14, 31
	s_lshl_b64 s[24:25], s[14:15], 20
	v_readlane_b32 s0, v254, 40
	v_readlane_b32 s1, v254, 41
	s_add_u32 s24, s0, s24
	s_addc_u32 s25, s1, s25
	s_and_b64 s[52:53], s[20:21], exec
	s_cselect_b32 s15, s25, s35
	s_cselect_b32 s29, s24, s34
	s_add_u32 s30, s30, 0x80080
	s_addc_u32 s31, s31, 0
	s_add_u32 s81, s34, 0x100
	s_addc_u32 s88, s35, 0
	s_mov_b32 s89, -2
	v_readlane_b32 s90, v255, 49
	s_nop 3
	s_cmp_eq_u32 s90, 6
	v_writelane_b32 v255, 6, 49
	s_cbranch_scc0 .Ltrip0_strict_5
	s_add_u32 s34, s30, 0xfff80080
	s_addc_u32 s35, s31, -1
	s_add_i32 s90, 0, 0x10000
	s_cmp_eq_u32 s89, 28
	s_cselect_b32 s53, s17, s35
	s_cselect_b32 s52, s27, s34
	s_cselect_b32 s35, s15, s88
	s_cselect_b32 s34, s29, s81
	s_add_i32 s96, 0, 0x14000
	v_add_u32_e32 v142, s90, v220
	v_add_u32_e32 v158, s96, v220
	ds_read_b128 v[130:133], v142
	ds_read_b128 v[134:137], v142 offset:1024
	ds_read_b128 v[138:141], v142 offset:2048
	ds_read_b128 v[142:145], v142 offset:3072
	ds_read_b128 v[146:149], v158
	ds_read_b128 v[150:153], v158 offset:1024
	ds_read_b128 v[154:157], v158 offset:2048
	ds_read_b128 v[158:161], v158 offset:3072
	v_lshl_add_u64 v[210:211], s[30:31], 0, v[202:203]
	s_add_i32 m0, s55, 0xc000
	ds_read_b128 v[162:165], v222
	ds_read_b128 v[166:169], v222 offset:1024
	ds_read_b128 v[170:173], v222 offset:2048
	ds_read_b128 v[174:177], v222 offset:3072
	ds_read_b128 v[178:181], v222 offset:4096
	ds_read_b128 v[182:185], v222 offset:5120
	ds_read_b128 v[196:199], v222 offset:6144
	ds_read_b128 v[206:209], v222 offset:7168
	global_load_lds_dwordx4 v[210:211], off
	s_add_i32 m0, s55, 0xe000
	v_lshl_add_u64 v[210:211], s[30:31], 0, v[204:205]
	global_load_lds_dwordx4 v[210:211], off
	s_waitcnt vmcnt(24) lgkmcnt(0)
	s_setprio 1
	s_barrier
	v_mfma_f32_16x16x32_bf16 v[126:129], v[130:133], v[162:165], 0
	v_mfma_f32_16x16x32_bf16 v[122:125], v[138:141], v[162:165], 0
	v_mfma_f32_16x16x32_bf16 v[110:113], v[130:133], v[170:173], 0
	v_mfma_f32_16x16x32_bf16 v[106:109], v[138:141], v[170:173], 0
	v_mfma_f32_16x16x32_bf16 v[94:97], v[130:133], v[178:181], 0
	v_mfma_f32_16x16x32_bf16 v[90:93], v[138:141], v[178:181], 0
	v_mfma_f32_16x16x32_bf16 v[78:81], v[130:133], v[196:199], 0
	v_mfma_f32_16x16x32_bf16 v[74:77], v[138:141], v[196:199], 0
	v_mfma_f32_16x16x32_bf16 v[126:129], v[134:137], v[166:169], v[126:129]
	v_mfma_f32_16x16x32_bf16 v[122:125], v[142:145], v[166:169], v[122:125]
	v_mfma_f32_16x16x32_bf16 v[110:113], v[134:137], v[174:177], v[110:113]
	v_mfma_f32_16x16x32_bf16 v[106:109], v[142:145], v[174:177], v[106:109]
	v_mfma_f32_16x16x32_bf16 v[94:97], v[134:137], v[182:185], v[94:97]
	v_mfma_f32_16x16x32_bf16 v[90:93], v[142:145], v[182:185], v[90:93]
	v_mfma_f32_16x16x32_bf16 v[78:81], v[134:137], v[206:209], v[78:81]
	v_mfma_f32_16x16x32_bf16 v[74:77], v[142:145], v[206:209], v[74:77]
	s_setprio 0
	s_setprio 1
	v_mfma_f32_16x16x32_bf16 v[118:121], v[146:149], v[162:165], 0
	v_mfma_f32_16x16x32_bf16 v[114:117], v[154:157], v[162:165], 0
	v_mfma_f32_16x16x32_bf16 v[102:105], v[146:149], v[170:173], 0
	v_mfma_f32_16x16x32_bf16 v[98:101], v[154:157], v[170:173], 0
	v_mfma_f32_16x16x32_bf16 v[86:89], v[146:149], v[178:181], 0
	v_mfma_f32_16x16x32_bf16 v[82:85], v[154:157], v[178:181], 0
	v_mfma_f32_16x16x32_bf16 v[70:73], v[146:149], v[196:199], 0
	v_mfma_f32_16x16x32_bf16 v[66:69], v[154:157], v[196:199], 0
	v_mfma_f32_16x16x32_bf16 v[118:121], v[150:153], v[166:169], v[118:121]
	v_mfma_f32_16x16x32_bf16 v[114:117], v[158:161], v[166:169], v[114:117]
	v_mfma_f32_16x16x32_bf16 v[102:105], v[150:153], v[174:177], v[102:105]
	v_mfma_f32_16x16x32_bf16 v[98:101], v[158:161], v[174:177], v[98:101]
	v_mfma_f32_16x16x32_bf16 v[86:89], v[150:153], v[182:185], v[86:89]
	v_mfma_f32_16x16x32_bf16 v[82:85], v[158:161], v[182:185], v[82:85]
	v_mfma_f32_16x16x32_bf16 v[70:73], v[150:153], v[206:209], v[70:73]
	v_mfma_f32_16x16x32_bf16 v[66:69], v[158:161], v[206:209], v[66:69]
	s_barrier
	s_setprio 0
	s_add_i32 s90, s90, s47
	v_lshl_add_u64 v[210:211], s[34:35], 0, v[190:191]
	s_mov_b32 m0, s90
	ds_read_b128 v[162:165], v222 offset:16384
	ds_read_b128 v[166:169], v222 offset:17408
	ds_read_b128 v[170:173], v222 offset:18432
	ds_read_b128 v[174:177], v222 offset:19456
	ds_read_b128 v[178:181], v222 offset:20480
	ds_read_b128 v[182:185], v222 offset:21504
	ds_read_b128 v[196:199], v222 offset:22528
	ds_read_b128 v[206:209], v222 offset:23552
	global_load_lds_dwordx4 v[210:211], off
	s_add_i32 m0, s90, 0x2000
	s_add_u32 s90, s34, 0x80000
	v_lshl_add_u64 v[212:213], s[34:35], 0, v[200:201]
	s_addc_u32 s91, s35, 0
	s_add_i32 s96, s96, s47
	global_load_lds_dwordx4 v[212:213], off
	v_lshl_add_u64 v[214:215], s[90:91], 0, v[190:191]
	s_mov_b32 m0, s96
	v_lshl_add_u64 v[216:217], s[52:53], 0, v[188:189]
	global_load_lds_dwordx4 v[214:215], off
	s_add_i32 m0, s96, 0x2000
	v_lshl_add_u64 v[214:215], s[90:91], 0, v[200:201]
	global_load_lds_dwordx4 v[214:215], off
	s_mov_b32 m0, s55
	v_lshl_add_u64 v[214:215], s[52:53], 0, v[186:187]
	global_load_lds_dwordx4 v[214:215], off
	s_mov_b32 m0, s56
	s_nop 0
	global_load_lds_dwordx4 v[216:217], off
	s_waitcnt vmcnt(24) lgkmcnt(0)
	s_setprio 1
	s_barrier
	v_mfma_f32_16x16x32_bf16 v[62:65], v[130:133], v[162:165], 0
	v_mfma_f32_16x16x32_bf16 v[58:61], v[138:141], v[162:165], 0
	v_mfma_f32_16x16x32_bf16 v[46:49], v[130:133], v[170:173], 0
	v_mfma_f32_16x16x32_bf16 v[42:45], v[138:141], v[170:173], 0
	v_mfma_f32_16x16x32_bf16 v[30:33], v[130:133], v[178:181], 0
	v_mfma_f32_16x16x32_bf16 v[26:29], v[138:141], v[178:181], 0
	v_mfma_f32_16x16x32_bf16 v[14:17], v[130:133], v[196:199], 0
	v_mfma_f32_16x16x32_bf16 v[10:13], v[138:141], v[196:199], 0
	v_mfma_f32_16x16x32_bf16 v[62:65], v[134:137], v[166:169], v[62:65]
	v_mfma_f32_16x16x32_bf16 v[58:61], v[142:145], v[166:169], v[58:61]
	v_mfma_f32_16x16x32_bf16 v[46:49], v[134:137], v[174:177], v[46:49]
	v_mfma_f32_16x16x32_bf16 v[42:45], v[142:145], v[174:177], v[42:45]
	v_mfma_f32_16x16x32_bf16 v[30:33], v[134:137], v[182:185], v[30:33]
	v_mfma_f32_16x16x32_bf16 v[26:29], v[142:145], v[182:185], v[26:29]
	v_mfma_f32_16x16x32_bf16 v[14:17], v[134:137], v[206:209], v[14:17]
	v_mfma_f32_16x16x32_bf16 v[10:13], v[142:145], v[206:209], v[10:13]
	s_setprio 0
	s_setprio 1
	v_mfma_f32_16x16x32_bf16 v[54:57], v[146:149], v[162:165], 0
	v_mfma_f32_16x16x32_bf16 v[50:53], v[154:157], v[162:165], 0
	v_mfma_f32_16x16x32_bf16 v[38:41], v[146:149], v[170:173], 0
	v_mfma_f32_16x16x32_bf16 v[34:37], v[154:157], v[170:173], 0
	v_mfma_f32_16x16x32_bf16 v[22:25], v[146:149], v[178:181], 0
	v_mfma_f32_16x16x32_bf16 v[18:21], v[154:157], v[178:181], 0
	v_mfma_f32_16x16x32_bf16 v[6:9], v[146:149], v[196:199], 0
	v_mfma_f32_16x16x32_bf16 v[2:5], v[154:157], v[196:199], 0
	v_mfma_f32_16x16x32_bf16 v[54:57], v[150:153], v[166:169], v[54:57]
	v_mfma_f32_16x16x32_bf16 v[50:53], v[158:161], v[166:169], v[50:53]
	v_mfma_f32_16x16x32_bf16 v[38:41], v[150:153], v[174:177], v[38:41]
	v_mfma_f32_16x16x32_bf16 v[34:37], v[158:161], v[174:177], v[34:37]
	v_mfma_f32_16x16x32_bf16 v[22:25], v[150:153], v[182:185], v[22:25]
	v_mfma_f32_16x16x32_bf16 v[18:21], v[158:161], v[182:185], v[18:21]
	v_mfma_f32_16x16x32_bf16 v[6:9], v[150:153], v[206:209], v[6:9]
	v_mfma_f32_16x16x32_bf16 v[2:5], v[158:161], v[206:209], v[2:5]
	s_barrier
	s_setprio 0
	s_add_i32 s90, 0, 0x18000
	s_add_i32 s91, 0, 0x1c000
	v_add_u32_e32 v142, s90, v220
	v_add_u32_e32 v158, s91, v220
	ds_read_b128 v[130:133], v142
	ds_read_b128 v[134:137], v142 offset:1024
	ds_read_b128 v[138:141], v142 offset:2048
	ds_read_b128 v[142:145], v142 offset:3072
	ds_read_b128 v[146:149], v158
	ds_read_b128 v[150:153], v158 offset:1024
	ds_read_b128 v[154:157], v158 offset:2048
	ds_read_b128 v[158:161], v158 offset:3072
	s_add_u32 s52, s52, 0x80000
	s_addc_u32 s53, s53, 0
	s_mov_b32 m0, s57
	v_lshl_add_u64 v[218:219], s[52:53], 0, v[186:187]
	ds_read_b128 v[162:165], v222 offset:32768
	ds_read_b128 v[166:169], v222 offset:33792
	ds_read_b128 v[170:173], v222 offset:34816
	ds_read_b128 v[174:177], v222 offset:35840
	ds_read_b128 v[178:181], v222 offset:36864
	ds_read_b128 v[182:185], v222 offset:37888
	ds_read_b128 v[196:199], v222 offset:38912
	ds_read_b128 v[206:209], v222 offset:39936
	global_load_lds_dwordx4 v[218:219], off
	s_mov_b32 m0, s60
	v_lshl_add_u64 v[218:219], s[52:53], 0, v[188:189]
	global_load_lds_dwordx4 v[218:219], off
	s_waitcnt vmcnt(8) lgkmcnt(0)
	s_setprio 1
	s_barrier
	v_mfma_f32_16x16x32_bf16 v[126:129], v[130:133], v[162:165], v[126:129]
	v_mfma_f32_16x16x32_bf16 v[122:125], v[138:141], v[162:165], v[122:125]
	v_mfma_f32_16x16x32_bf16 v[110:113], v[130:133], v[170:173], v[110:113]
	v_mfma_f32_16x16x32_bf16 v[106:109], v[138:141], v[170:173], v[106:109]
	v_mfma_f32_16x16x32_bf16 v[94:97], v[130:133], v[178:181], v[94:97]
	v_mfma_f32_16x16x32_bf16 v[90:93], v[138:141], v[178:181], v[90:93]
	v_mfma_f32_16x16x32_bf16 v[78:81], v[130:133], v[196:199], v[78:81]
	v_mfma_f32_16x16x32_bf16 v[74:77], v[138:141], v[196:199], v[74:77]
	v_mfma_f32_16x16x32_bf16 v[126:129], v[134:137], v[166:169], v[126:129]
	v_mfma_f32_16x16x32_bf16 v[122:125], v[142:145], v[166:169], v[122:125]
	v_mfma_f32_16x16x32_bf16 v[110:113], v[134:137], v[174:177], v[110:113]
	v_mfma_f32_16x16x32_bf16 v[106:109], v[142:145], v[174:177], v[106:109]
	v_mfma_f32_16x16x32_bf16 v[94:97], v[134:137], v[182:185], v[94:97]
	v_mfma_f32_16x16x32_bf16 v[90:93], v[142:145], v[182:185], v[90:93]
	v_mfma_f32_16x16x32_bf16 v[78:81], v[134:137], v[206:209], v[78:81]
	v_mfma_f32_16x16x32_bf16 v[74:77], v[142:145], v[206:209], v[74:77]
	s_setprio 0
	s_setprio 1
	v_mfma_f32_16x16x32_bf16 v[118:121], v[146:149], v[162:165], v[118:121]
	v_mfma_f32_16x16x32_bf16 v[114:117], v[154:157], v[162:165], v[114:117]
	v_mfma_f32_16x16x32_bf16 v[102:105], v[146:149], v[170:173], v[102:105]
	v_mfma_f32_16x16x32_bf16 v[98:101], v[154:157], v[170:173], v[98:101]
	v_mfma_f32_16x16x32_bf16 v[86:89], v[146:149], v[178:181], v[86:89]
	v_mfma_f32_16x16x32_bf16 v[82:85], v[154:157], v[178:181], v[82:85]
	v_mfma_f32_16x16x32_bf16 v[70:73], v[146:149], v[196:199], v[70:73]
	v_mfma_f32_16x16x32_bf16 v[66:69], v[154:157], v[196:199], v[66:69]
	v_mfma_f32_16x16x32_bf16 v[118:121], v[150:153], v[166:169], v[118:121]
	v_mfma_f32_16x16x32_bf16 v[114:117], v[158:161], v[166:169], v[114:117]
	v_mfma_f32_16x16x32_bf16 v[102:105], v[150:153], v[174:177], v[102:105]
	v_mfma_f32_16x16x32_bf16 v[98:101], v[158:161], v[174:177], v[98:101]
	v_mfma_f32_16x16x32_bf16 v[86:89], v[150:153], v[182:185], v[86:89]
	v_mfma_f32_16x16x32_bf16 v[82:85], v[158:161], v[182:185], v[82:85]
	v_mfma_f32_16x16x32_bf16 v[70:73], v[150:153], v[206:209], v[70:73]
	v_mfma_f32_16x16x32_bf16 v[66:69], v[158:161], v[206:209], v[66:69]
	s_barrier
	s_setprio 0
	s_add_i32 s52, s90, s47
	v_lshl_add_u64 v[210:211], v[210:211], 0, s[58:59]
	s_mov_b32 m0, s52
	ds_read_b128 v[162:165], v222 offset:49152
	ds_read_b128 v[166:169], v222 offset:50176
	ds_read_b128 v[170:173], v222 offset:51200
	ds_read_b128 v[174:177], v222 offset:52224
	ds_read_b128 v[178:181], v222 offset:53248
	ds_read_b128 v[182:185], v222 offset:54272
	ds_read_b128 v[196:199], v222 offset:55296
	ds_read_b128 v[206:209], v222 offset:56320
	global_load_lds_dwordx4 v[210:211], off
	s_add_i32 m0, s52, 0x2000
	s_add_u32 s34, s34, 0x80080
	v_lshl_add_u64 v[210:211], v[212:213], 0, s[58:59]
	s_addc_u32 s35, s35, 0
	s_add_i32 s52, s91, s47
	global_load_lds_dwordx4 v[210:211], off
	s_mov_b32 m0, s52
	v_lshl_add_u64 v[210:211], s[34:35], 0, v[190:191]
	global_load_lds_dwordx4 v[210:211], off
	s_add_i32 m0, s52, 0x2000
	v_lshl_add_u64 v[210:211], s[34:35], 0, v[200:201]
	global_load_lds_dwordx4 v[210:211], off
	s_mov_b32 m0, s61
	v_lshl_add_u64 v[210:211], v[214:215], 0, s[58:59]
	global_load_lds_dwordx4 v[210:211], off
	s_mov_b32 m0, s69
	v_lshl_add_u64 v[210:211], v[216:217], 0, s[58:59]
	global_load_lds_dwordx4 v[210:211], off
	s_waitcnt vmcnt(8) lgkmcnt(0)
	s_setprio 1
	s_barrier
	v_mfma_f32_16x16x32_bf16 v[62:65], v[130:133], v[162:165], v[62:65]
	v_mfma_f32_16x16x32_bf16 v[58:61], v[138:141], v[162:165], v[58:61]
	v_mfma_f32_16x16x32_bf16 v[46:49], v[130:133], v[170:173], v[46:49]
	v_mfma_f32_16x16x32_bf16 v[42:45], v[138:141], v[170:173], v[42:45]
	v_mfma_f32_16x16x32_bf16 v[30:33], v[130:133], v[178:181], v[30:33]
	v_mfma_f32_16x16x32_bf16 v[26:29], v[138:141], v[178:181], v[26:29]
	v_mfma_f32_16x16x32_bf16 v[14:17], v[130:133], v[196:199], v[14:17]
	v_mfma_f32_16x16x32_bf16 v[10:13], v[138:141], v[196:199], v[10:13]
	v_mfma_f32_16x16x32_bf16 v[62:65], v[134:137], v[166:169], v[62:65]
	v_mfma_f32_16x16x32_bf16 v[58:61], v[142:145], v[166:169], v[58:61]
	v_mfma_f32_16x16x32_bf16 v[46:49], v[134:137], v[174:177], v[46:49]
	v_mfma_f32_16x16x32_bf16 v[42:45], v[142:145], v[174:177], v[42:45]
	v_mfma_f32_16x16x32_bf16 v[30:33], v[134:137], v[182:185], v[30:33]
	v_mfma_f32_16x16x32_bf16 v[26:29], v[142:145], v[182:185], v[26:29]
	v_mfma_f32_16x16x32_bf16 v[14:17], v[134:137], v[206:209], v[14:17]
	v_mfma_f32_16x16x32_bf16 v[10:13], v[142:145], v[206:209], v[10:13]
	s_setprio 0
	s_setprio 1
	v_mfma_f32_16x16x32_bf16 v[54:57], v[146:149], v[162:165], v[54:57]
	v_mfma_f32_16x16x32_bf16 v[50:53], v[154:157], v[162:165], v[50:53]
	v_mfma_f32_16x16x32_bf16 v[38:41], v[146:149], v[170:173], v[38:41]
	v_mfma_f32_16x16x32_bf16 v[34:37], v[154:157], v[170:173], v[34:37]
	v_mfma_f32_16x16x32_bf16 v[22:25], v[146:149], v[178:181], v[22:25]
	v_mfma_f32_16x16x32_bf16 v[18:21], v[154:157], v[178:181], v[18:21]
	v_mfma_f32_16x16x32_bf16 v[6:9], v[146:149], v[196:199], v[6:9]
	v_mfma_f32_16x16x32_bf16 v[2:5], v[154:157], v[196:199], v[2:5]
	v_mfma_f32_16x16x32_bf16 v[54:57], v[150:153], v[166:169], v[54:57]
	v_mfma_f32_16x16x32_bf16 v[50:53], v[158:161], v[166:169], v[50:53]
	v_mfma_f32_16x16x32_bf16 v[38:41], v[150:153], v[174:177], v[38:41]
	v_mfma_f32_16x16x32_bf16 v[34:37], v[158:161], v[174:177], v[34:37]
	v_mfma_f32_16x16x32_bf16 v[22:25], v[150:153], v[182:185], v[22:25]
	v_mfma_f32_16x16x32_bf16 v[18:21], v[158:161], v[182:185], v[18:21]
	v_mfma_f32_16x16x32_bf16 v[6:9], v[150:153], v[206:209], v[6:9]
	v_mfma_f32_16x16x32_bf16 v[2:5], v[158:161], v[206:209], v[2:5]
	s_barrier
	s_setprio 0
	s_add_i32 s89, s89, 2
	s_add_u32 s30, s30, 0x100
	s_addc_u32 s31, s31, 0
	s_add_u32 s81, s81, 0x100
	s_addc_u32 s88, s88, 0
	s_cmp_gt_u32 s89, 29
	s_cbranch_scc1 .Lpeel_done_5
	s_branch .LBB0_823
.Ltrip0_strict_5:
	s_add_u32 s34, s30, 0xfff80080
	s_addc_u32 s35, s31, -1
	s_add_i32 s90, 0, 0x10000
	s_cmp_eq_u32 s89, 28
	s_cselect_b32 s53, s17, s35
	s_cselect_b32 s52, s27, s34
	s_cselect_b32 s35, s15, s88
	s_cselect_b32 s34, s29, s81
	s_add_i32 s96, 0, 0x14000
	v_add_u32_e32 v142, s90, v220
	v_add_u32_e32 v158, s96, v220
	ds_read_b128 v[130:133], v142
	ds_read_b128 v[134:137], v142 offset:1024
	ds_read_b128 v[138:141], v142 offset:2048
	ds_read_b128 v[142:145], v142 offset:3072
	ds_read_b128 v[146:149], v158
	ds_read_b128 v[150:153], v158 offset:1024
	ds_read_b128 v[154:157], v158 offset:2048
	ds_read_b128 v[158:161], v158 offset:3072
	v_lshl_add_u64 v[210:211], s[30:31], 0, v[202:203]
	s_add_i32 m0, s55, 0xc000
	ds_read_b128 v[162:165], v222
	ds_read_b128 v[166:169], v222 offset:1024
	ds_read_b128 v[170:173], v222 offset:2048
	ds_read_b128 v[174:177], v222 offset:3072
	ds_read_b128 v[178:181], v222 offset:4096
	ds_read_b128 v[182:185], v222 offset:5120
	ds_read_b128 v[196:199], v222 offset:6144
	ds_read_b128 v[206:209], v222 offset:7168
	global_load_lds_dwordx4 v[210:211], off
	s_add_i32 m0, s55, 0xe000
	v_lshl_add_u64 v[210:211], s[30:31], 0, v[204:205]
	global_load_lds_dwordx4 v[210:211], off
	s_waitcnt vmcnt(8) lgkmcnt(0)
	s_setprio 1
	s_barrier
	v_mfma_f32_16x16x32_bf16 v[126:129], v[130:133], v[162:165], 0
	v_mfma_f32_16x16x32_bf16 v[122:125], v[138:141], v[162:165], 0
	v_mfma_f32_16x16x32_bf16 v[110:113], v[130:133], v[170:173], 0
	v_mfma_f32_16x16x32_bf16 v[106:109], v[138:141], v[170:173], 0
	v_mfma_f32_16x16x32_bf16 v[94:97], v[130:133], v[178:181], 0
	v_mfma_f32_16x16x32_bf16 v[90:93], v[138:141], v[178:181], 0
	v_mfma_f32_16x16x32_bf16 v[78:81], v[130:133], v[196:199], 0
	v_mfma_f32_16x16x32_bf16 v[74:77], v[138:141], v[196:199], 0
	v_mfma_f32_16x16x32_bf16 v[126:129], v[134:137], v[166:169], v[126:129]
	v_mfma_f32_16x16x32_bf16 v[122:125], v[142:145], v[166:169], v[122:125]
	v_mfma_f32_16x16x32_bf16 v[110:113], v[134:137], v[174:177], v[110:113]
	v_mfma_f32_16x16x32_bf16 v[106:109], v[142:145], v[174:177], v[106:109]
	v_mfma_f32_16x16x32_bf16 v[94:97], v[134:137], v[182:185], v[94:97]
	v_mfma_f32_16x16x32_bf16 v[90:93], v[142:145], v[182:185], v[90:93]
	v_mfma_f32_16x16x32_bf16 v[78:81], v[134:137], v[206:209], v[78:81]
	v_mfma_f32_16x16x32_bf16 v[74:77], v[142:145], v[206:209], v[74:77]
	s_setprio 0
	s_setprio 1
	v_mfma_f32_16x16x32_bf16 v[118:121], v[146:149], v[162:165], 0
	v_mfma_f32_16x16x32_bf16 v[114:117], v[154:157], v[162:165], 0
	v_mfma_f32_16x16x32_bf16 v[102:105], v[146:149], v[170:173], 0
	v_mfma_f32_16x16x32_bf16 v[98:101], v[154:157], v[170:173], 0
	v_mfma_f32_16x16x32_bf16 v[86:89], v[146:149], v[178:181], 0
	v_mfma_f32_16x16x32_bf16 v[82:85], v[154:157], v[178:181], 0
	v_mfma_f32_16x16x32_bf16 v[70:73], v[146:149], v[196:199], 0
	v_mfma_f32_16x16x32_bf16 v[66:69], v[154:157], v[196:199], 0
	v_mfma_f32_16x16x32_bf16 v[118:121], v[150:153], v[166:169], v[118:121]
	v_mfma_f32_16x16x32_bf16 v[114:117], v[158:161], v[166:169], v[114:117]
	v_mfma_f32_16x16x32_bf16 v[102:105], v[150:153], v[174:177], v[102:105]
	v_mfma_f32_16x16x32_bf16 v[98:101], v[158:161], v[174:177], v[98:101]
	v_mfma_f32_16x16x32_bf16 v[86:89], v[150:153], v[182:185], v[86:89]
	v_mfma_f32_16x16x32_bf16 v[82:85], v[158:161], v[182:185], v[82:85]
	v_mfma_f32_16x16x32_bf16 v[70:73], v[150:153], v[206:209], v[70:73]
	v_mfma_f32_16x16x32_bf16 v[66:69], v[158:161], v[206:209], v[66:69]
	s_barrier
	s_setprio 0
	s_add_i32 s90, s90, s47
	v_lshl_add_u64 v[210:211], s[34:35], 0, v[190:191]
	s_mov_b32 m0, s90
	ds_read_b128 v[162:165], v222 offset:16384
	ds_read_b128 v[166:169], v222 offset:17408
	ds_read_b128 v[170:173], v222 offset:18432
	ds_read_b128 v[174:177], v222 offset:19456
	ds_read_b128 v[178:181], v222 offset:20480
	ds_read_b128 v[182:185], v222 offset:21504
	ds_read_b128 v[196:199], v222 offset:22528
	ds_read_b128 v[206:209], v222 offset:23552
	global_load_lds_dwordx4 v[210:211], off
	s_add_i32 m0, s90, 0x2000
	s_add_u32 s90, s34, 0x80000
	v_lshl_add_u64 v[212:213], s[34:35], 0, v[200:201]
	s_addc_u32 s91, s35, 0
	s_add_i32 s96, s96, s47
	global_load_lds_dwordx4 v[212:213], off
	v_lshl_add_u64 v[214:215], s[90:91], 0, v[190:191]
	s_mov_b32 m0, s96
	v_lshl_add_u64 v[216:217], s[52:53], 0, v[188:189]
	global_load_lds_dwordx4 v[214:215], off
	s_add_i32 m0, s96, 0x2000
	v_lshl_add_u64 v[214:215], s[90:91], 0, v[200:201]
	global_load_lds_dwordx4 v[214:215], off
	s_mov_b32 m0, s55
	v_lshl_add_u64 v[214:215], s[52:53], 0, v[186:187]
	global_load_lds_dwordx4 v[214:215], off
	s_mov_b32 m0, s56
	s_nop 0
	global_load_lds_dwordx4 v[216:217], off
	s_waitcnt vmcnt(8) lgkmcnt(0)
	s_setprio 1
	s_barrier
	v_mfma_f32_16x16x32_bf16 v[62:65], v[130:133], v[162:165], 0
	v_mfma_f32_16x16x32_bf16 v[58:61], v[138:141], v[162:165], 0
	v_mfma_f32_16x16x32_bf16 v[46:49], v[130:133], v[170:173], 0
	v_mfma_f32_16x16x32_bf16 v[42:45], v[138:141], v[170:173], 0
	v_mfma_f32_16x16x32_bf16 v[30:33], v[130:133], v[178:181], 0
	v_mfma_f32_16x16x32_bf16 v[26:29], v[138:141], v[178:181], 0
	v_mfma_f32_16x16x32_bf16 v[14:17], v[130:133], v[196:199], 0
	v_mfma_f32_16x16x32_bf16 v[10:13], v[138:141], v[196:199], 0
	v_mfma_f32_16x16x32_bf16 v[62:65], v[134:137], v[166:169], v[62:65]
	v_mfma_f32_16x16x32_bf16 v[58:61], v[142:145], v[166:169], v[58:61]
	v_mfma_f32_16x16x32_bf16 v[46:49], v[134:137], v[174:177], v[46:49]
	v_mfma_f32_16x16x32_bf16 v[42:45], v[142:145], v[174:177], v[42:45]
	v_mfma_f32_16x16x32_bf16 v[30:33], v[134:137], v[182:185], v[30:33]
	v_mfma_f32_16x16x32_bf16 v[26:29], v[142:145], v[182:185], v[26:29]
	v_mfma_f32_16x16x32_bf16 v[14:17], v[134:137], v[206:209], v[14:17]
	v_mfma_f32_16x16x32_bf16 v[10:13], v[142:145], v[206:209], v[10:13]
	s_setprio 0
	s_setprio 1
	v_mfma_f32_16x16x32_bf16 v[54:57], v[146:149], v[162:165], 0
	v_mfma_f32_16x16x32_bf16 v[50:53], v[154:157], v[162:165], 0
	v_mfma_f32_16x16x32_bf16 v[38:41], v[146:149], v[170:173], 0
	v_mfma_f32_16x16x32_bf16 v[34:37], v[154:157], v[170:173], 0
	v_mfma_f32_16x16x32_bf16 v[22:25], v[146:149], v[178:181], 0
	v_mfma_f32_16x16x32_bf16 v[18:21], v[154:157], v[178:181], 0
	v_mfma_f32_16x16x32_bf16 v[6:9], v[146:149], v[196:199], 0
	v_mfma_f32_16x16x32_bf16 v[2:5], v[154:157], v[196:199], 0
	v_mfma_f32_16x16x32_bf16 v[54:57], v[150:153], v[166:169], v[54:57]
	v_mfma_f32_16x16x32_bf16 v[50:53], v[158:161], v[166:169], v[50:53]
	v_mfma_f32_16x16x32_bf16 v[38:41], v[150:153], v[174:177], v[38:41]
	v_mfma_f32_16x16x32_bf16 v[34:37], v[158:161], v[174:177], v[34:37]
	v_mfma_f32_16x16x32_bf16 v[22:25], v[150:153], v[182:185], v[22:25]
	v_mfma_f32_16x16x32_bf16 v[18:21], v[158:161], v[182:185], v[18:21]
	v_mfma_f32_16x16x32_bf16 v[6:9], v[150:153], v[206:209], v[6:9]
	v_mfma_f32_16x16x32_bf16 v[2:5], v[158:161], v[206:209], v[2:5]
	s_barrier
	s_setprio 0
	s_add_i32 s90, 0, 0x18000
	s_add_i32 s91, 0, 0x1c000
	v_add_u32_e32 v142, s90, v220
	v_add_u32_e32 v158, s91, v220
	ds_read_b128 v[130:133], v142
	ds_read_b128 v[134:137], v142 offset:1024
	ds_read_b128 v[138:141], v142 offset:2048
	ds_read_b128 v[142:145], v142 offset:3072
	ds_read_b128 v[146:149], v158
	ds_read_b128 v[150:153], v158 offset:1024
	ds_read_b128 v[154:157], v158 offset:2048
	ds_read_b128 v[158:161], v158 offset:3072
	s_add_u32 s52, s52, 0x80000
	s_addc_u32 s53, s53, 0
	s_mov_b32 m0, s57
	v_lshl_add_u64 v[218:219], s[52:53], 0, v[186:187]
	ds_read_b128 v[162:165], v222 offset:32768
	ds_read_b128 v[166:169], v222 offset:33792
	ds_read_b128 v[170:173], v222 offset:34816
	ds_read_b128 v[174:177], v222 offset:35840
	ds_read_b128 v[178:181], v222 offset:36864
	ds_read_b128 v[182:185], v222 offset:37888
	ds_read_b128 v[196:199], v222 offset:38912
	ds_read_b128 v[206:209], v222 offset:39936
	global_load_lds_dwordx4 v[218:219], off
	s_mov_b32 m0, s60
	v_lshl_add_u64 v[218:219], s[52:53], 0, v[188:189]
	global_load_lds_dwordx4 v[218:219], off
	s_waitcnt vmcnt(8) lgkmcnt(0)
	s_setprio 1
	s_barrier
	v_mfma_f32_16x16x32_bf16 v[126:129], v[130:133], v[162:165], v[126:129]
	v_mfma_f32_16x16x32_bf16 v[122:125], v[138:141], v[162:165], v[122:125]
	v_mfma_f32_16x16x32_bf16 v[110:113], v[130:133], v[170:173], v[110:113]
	v_mfma_f32_16x16x32_bf16 v[106:109], v[138:141], v[170:173], v[106:109]
	v_mfma_f32_16x16x32_bf16 v[94:97], v[130:133], v[178:181], v[94:97]
	v_mfma_f32_16x16x32_bf16 v[90:93], v[138:141], v[178:181], v[90:93]
	v_mfma_f32_16x16x32_bf16 v[78:81], v[130:133], v[196:199], v[78:81]
	v_mfma_f32_16x16x32_bf16 v[74:77], v[138:141], v[196:199], v[74:77]
	v_mfma_f32_16x16x32_bf16 v[126:129], v[134:137], v[166:169], v[126:129]
	v_mfma_f32_16x16x32_bf16 v[122:125], v[142:145], v[166:169], v[122:125]
	v_mfma_f32_16x16x32_bf16 v[110:113], v[134:137], v[174:177], v[110:113]
	v_mfma_f32_16x16x32_bf16 v[106:109], v[142:145], v[174:177], v[106:109]
	v_mfma_f32_16x16x32_bf16 v[94:97], v[134:137], v[182:185], v[94:97]
	v_mfma_f32_16x16x32_bf16 v[90:93], v[142:145], v[182:185], v[90:93]
	v_mfma_f32_16x16x32_bf16 v[78:81], v[134:137], v[206:209], v[78:81]
	v_mfma_f32_16x16x32_bf16 v[74:77], v[142:145], v[206:209], v[74:77]
	s_setprio 0
	s_setprio 1
	v_mfma_f32_16x16x32_bf16 v[118:121], v[146:149], v[162:165], v[118:121]
	v_mfma_f32_16x16x32_bf16 v[114:117], v[154:157], v[162:165], v[114:117]
	v_mfma_f32_16x16x32_bf16 v[102:105], v[146:149], v[170:173], v[102:105]
	v_mfma_f32_16x16x32_bf16 v[98:101], v[154:157], v[170:173], v[98:101]
	v_mfma_f32_16x16x32_bf16 v[86:89], v[146:149], v[178:181], v[86:89]
	v_mfma_f32_16x16x32_bf16 v[82:85], v[154:157], v[178:181], v[82:85]
	v_mfma_f32_16x16x32_bf16 v[70:73], v[146:149], v[196:199], v[70:73]
	v_mfma_f32_16x16x32_bf16 v[66:69], v[154:157], v[196:199], v[66:69]
	v_mfma_f32_16x16x32_bf16 v[118:121], v[150:153], v[166:169], v[118:121]
	v_mfma_f32_16x16x32_bf16 v[114:117], v[158:161], v[166:169], v[114:117]
	v_mfma_f32_16x16x32_bf16 v[102:105], v[150:153], v[174:177], v[102:105]
	v_mfma_f32_16x16x32_bf16 v[98:101], v[158:161], v[174:177], v[98:101]
	v_mfma_f32_16x16x32_bf16 v[86:89], v[150:153], v[182:185], v[86:89]
	v_mfma_f32_16x16x32_bf16 v[82:85], v[158:161], v[182:185], v[82:85]
	v_mfma_f32_16x16x32_bf16 v[70:73], v[150:153], v[206:209], v[70:73]
	v_mfma_f32_16x16x32_bf16 v[66:69], v[158:161], v[206:209], v[66:69]
	s_barrier
	s_setprio 0
	s_add_i32 s52, s90, s47
	v_lshl_add_u64 v[210:211], v[210:211], 0, s[58:59]
	s_mov_b32 m0, s52
	ds_read_b128 v[162:165], v222 offset:49152
	ds_read_b128 v[166:169], v222 offset:50176
	ds_read_b128 v[170:173], v222 offset:51200
	ds_read_b128 v[174:177], v222 offset:52224
	ds_read_b128 v[178:181], v222 offset:53248
	ds_read_b128 v[182:185], v222 offset:54272
	ds_read_b128 v[196:199], v222 offset:55296
	ds_read_b128 v[206:209], v222 offset:56320
	global_load_lds_dwordx4 v[210:211], off
	s_add_i32 m0, s52, 0x2000
	s_add_u32 s34, s34, 0x80080
	v_lshl_add_u64 v[210:211], v[212:213], 0, s[58:59]
	s_addc_u32 s35, s35, 0
	s_add_i32 s52, s91, s47
	global_load_lds_dwordx4 v[210:211], off
	s_mov_b32 m0, s52
	v_lshl_add_u64 v[210:211], s[34:35], 0, v[190:191]
	global_load_lds_dwordx4 v[210:211], off
	s_add_i32 m0, s52, 0x2000
	v_lshl_add_u64 v[210:211], s[34:35], 0, v[200:201]
	global_load_lds_dwordx4 v[210:211], off
	s_mov_b32 m0, s61
	v_lshl_add_u64 v[210:211], v[214:215], 0, s[58:59]
	global_load_lds_dwordx4 v[210:211], off
	s_mov_b32 m0, s69
	v_lshl_add_u64 v[210:211], v[216:217], 0, s[58:59]
	global_load_lds_dwordx4 v[210:211], off
	s_waitcnt vmcnt(8) lgkmcnt(0)
	s_setprio 1
	s_barrier
	v_mfma_f32_16x16x32_bf16 v[62:65], v[130:133], v[162:165], v[62:65]
	v_mfma_f32_16x16x32_bf16 v[58:61], v[138:141], v[162:165], v[58:61]
	v_mfma_f32_16x16x32_bf16 v[46:49], v[130:133], v[170:173], v[46:49]
	v_mfma_f32_16x16x32_bf16 v[42:45], v[138:141], v[170:173], v[42:45]
	v_mfma_f32_16x16x32_bf16 v[30:33], v[130:133], v[178:181], v[30:33]
	v_mfma_f32_16x16x32_bf16 v[26:29], v[138:141], v[178:181], v[26:29]
	v_mfma_f32_16x16x32_bf16 v[14:17], v[130:133], v[196:199], v[14:17]
	v_mfma_f32_16x16x32_bf16 v[10:13], v[138:141], v[196:199], v[10:13]
	v_mfma_f32_16x16x32_bf16 v[62:65], v[134:137], v[166:169], v[62:65]
	v_mfma_f32_16x16x32_bf16 v[58:61], v[142:145], v[166:169], v[58:61]
	v_mfma_f32_16x16x32_bf16 v[46:49], v[134:137], v[174:177], v[46:49]
	v_mfma_f32_16x16x32_bf16 v[42:45], v[142:145], v[174:177], v[42:45]
	v_mfma_f32_16x16x32_bf16 v[30:33], v[134:137], v[182:185], v[30:33]
	v_mfma_f32_16x16x32_bf16 v[26:29], v[142:145], v[182:185], v[26:29]
	v_mfma_f32_16x16x32_bf16 v[14:17], v[134:137], v[206:209], v[14:17]
	v_mfma_f32_16x16x32_bf16 v[10:13], v[142:145], v[206:209], v[10:13]
	s_setprio 0
	s_setprio 1
	v_mfma_f32_16x16x32_bf16 v[54:57], v[146:149], v[162:165], v[54:57]
	v_mfma_f32_16x16x32_bf16 v[50:53], v[154:157], v[162:165], v[50:53]
	v_mfma_f32_16x16x32_bf16 v[38:41], v[146:149], v[170:173], v[38:41]
	v_mfma_f32_16x16x32_bf16 v[34:37], v[154:157], v[170:173], v[34:37]
	v_mfma_f32_16x16x32_bf16 v[22:25], v[146:149], v[178:181], v[22:25]
	v_mfma_f32_16x16x32_bf16 v[18:21], v[154:157], v[178:181], v[18:21]
	v_mfma_f32_16x16x32_bf16 v[6:9], v[146:149], v[196:199], v[6:9]
	v_mfma_f32_16x16x32_bf16 v[2:5], v[154:157], v[196:199], v[2:5]
	v_mfma_f32_16x16x32_bf16 v[54:57], v[150:153], v[166:169], v[54:57]
	v_mfma_f32_16x16x32_bf16 v[50:53], v[158:161], v[166:169], v[50:53]
	v_mfma_f32_16x16x32_bf16 v[38:41], v[150:153], v[174:177], v[38:41]
	v_mfma_f32_16x16x32_bf16 v[34:37], v[158:161], v[174:177], v[34:37]
	v_mfma_f32_16x16x32_bf16 v[22:25], v[150:153], v[182:185], v[22:25]
	v_mfma_f32_16x16x32_bf16 v[18:21], v[158:161], v[182:185], v[18:21]
	v_mfma_f32_16x16x32_bf16 v[6:9], v[150:153], v[206:209], v[6:9]
	v_mfma_f32_16x16x32_bf16 v[2:5], v[158:161], v[206:209], v[2:5]
	s_barrier
	s_setprio 0
	s_add_i32 s89, s89, 2
	s_add_u32 s30, s30, 0x100
	s_addc_u32 s31, s31, 0
	s_add_u32 s81, s81, 0x100
	s_addc_u32 s88, s88, 0
	s_cmp_gt_u32 s89, 29
	s_cbranch_scc1 .Lpeel_done_5
.LBB0_823:
	s_add_u32 s34, s30, 0xfff80080
	s_addc_u32 s35, s31, -1
	s_add_i32 s90, 0, 0x10000
	s_cmp_eq_u32 s89, 28
	s_cselect_b32 s53, s17, s35
	s_cselect_b32 s52, s27, s34
	s_cselect_b32 s35, s15, s88
	s_cselect_b32 s34, s29, s81
	s_add_i32 s96, 0, 0x14000
	v_add_u32_e32 v142, s90, v220
	v_add_u32_e32 v158, s96, v220
	ds_read_b128 v[130:133], v142
	ds_read_b128 v[134:137], v142 offset:1024
	ds_read_b128 v[138:141], v142 offset:2048
	ds_read_b128 v[142:145], v142 offset:3072
	ds_read_b128 v[146:149], v158
	ds_read_b128 v[150:153], v158 offset:1024
	ds_read_b128 v[154:157], v158 offset:2048
	ds_read_b128 v[158:161], v158 offset:3072
	v_lshl_add_u64 v[210:211], s[30:31], 0, v[202:203]
	s_add_i32 m0, s55, 0xc000
	ds_read_b128 v[162:165], v222
	ds_read_b128 v[166:169], v222 offset:1024
	ds_read_b128 v[170:173], v222 offset:2048
	ds_read_b128 v[174:177], v222 offset:3072
	ds_read_b128 v[178:181], v222 offset:4096
	ds_read_b128 v[182:185], v222 offset:5120
	ds_read_b128 v[196:199], v222 offset:6144
	ds_read_b128 v[206:209], v222 offset:7168
	global_load_lds_dwordx4 v[210:211], off
	s_add_i32 m0, s55, 0xe000
	v_lshl_add_u64 v[210:211], s[30:31], 0, v[204:205]
	global_load_lds_dwordx4 v[210:211], off
	s_waitcnt vmcnt(8) lgkmcnt(0)
	s_setprio 1
	s_barrier
	v_mfma_f32_16x16x32_bf16 v[126:129], v[130:133], v[162:165], v[126:129]
	v_mfma_f32_16x16x32_bf16 v[122:125], v[138:141], v[162:165], v[122:125]
	v_mfma_f32_16x16x32_bf16 v[110:113], v[130:133], v[170:173], v[110:113]
	v_mfma_f32_16x16x32_bf16 v[106:109], v[138:141], v[170:173], v[106:109]
	v_mfma_f32_16x16x32_bf16 v[94:97], v[130:133], v[178:181], v[94:97]
	v_mfma_f32_16x16x32_bf16 v[90:93], v[138:141], v[178:181], v[90:93]
	v_mfma_f32_16x16x32_bf16 v[78:81], v[130:133], v[196:199], v[78:81]
	v_mfma_f32_16x16x32_bf16 v[74:77], v[138:141], v[196:199], v[74:77]
	v_mfma_f32_16x16x32_bf16 v[126:129], v[134:137], v[166:169], v[126:129]
	v_mfma_f32_16x16x32_bf16 v[122:125], v[142:145], v[166:169], v[122:125]
	v_mfma_f32_16x16x32_bf16 v[110:113], v[134:137], v[174:177], v[110:113]
	v_mfma_f32_16x16x32_bf16 v[106:109], v[142:145], v[174:177], v[106:109]
	v_mfma_f32_16x16x32_bf16 v[94:97], v[134:137], v[182:185], v[94:97]
	v_mfma_f32_16x16x32_bf16 v[90:93], v[142:145], v[182:185], v[90:93]
	v_mfma_f32_16x16x32_bf16 v[78:81], v[134:137], v[206:209], v[78:81]
	v_mfma_f32_16x16x32_bf16 v[74:77], v[142:145], v[206:209], v[74:77]
	s_setprio 0
	s_setprio 1
	v_mfma_f32_16x16x32_bf16 v[118:121], v[146:149], v[162:165], v[118:121]
	v_mfma_f32_16x16x32_bf16 v[114:117], v[154:157], v[162:165], v[114:117]
	v_mfma_f32_16x16x32_bf16 v[102:105], v[146:149], v[170:173], v[102:105]
	v_mfma_f32_16x16x32_bf16 v[98:101], v[154:157], v[170:173], v[98:101]
	v_mfma_f32_16x16x32_bf16 v[86:89], v[146:149], v[178:181], v[86:89]
	v_mfma_f32_16x16x32_bf16 v[82:85], v[154:157], v[178:181], v[82:85]
	v_mfma_f32_16x16x32_bf16 v[70:73], v[146:149], v[196:199], v[70:73]
	v_mfma_f32_16x16x32_bf16 v[66:69], v[154:157], v[196:199], v[66:69]
	v_mfma_f32_16x16x32_bf16 v[118:121], v[150:153], v[166:169], v[118:121]
	v_mfma_f32_16x16x32_bf16 v[114:117], v[158:161], v[166:169], v[114:117]
	v_mfma_f32_16x16x32_bf16 v[102:105], v[150:153], v[174:177], v[102:105]
	v_mfma_f32_16x16x32_bf16 v[98:101], v[158:161], v[174:177], v[98:101]
	v_mfma_f32_16x16x32_bf16 v[86:89], v[150:153], v[182:185], v[86:89]
	v_mfma_f32_16x16x32_bf16 v[82:85], v[158:161], v[182:185], v[82:85]
	v_mfma_f32_16x16x32_bf16 v[70:73], v[150:153], v[206:209], v[70:73]
	v_mfma_f32_16x16x32_bf16 v[66:69], v[158:161], v[206:209], v[66:69]
	s_setprio 0
	s_barrier
	s_add_i32 s90, s90, s47
	v_lshl_add_u64 v[210:211], s[34:35], 0, v[190:191]
	s_mov_b32 m0, s90
	ds_read_b128 v[162:165], v222 offset:16384
	ds_read_b128 v[166:169], v222 offset:17408
	ds_read_b128 v[170:173], v222 offset:18432
	ds_read_b128 v[174:177], v222 offset:19456
	ds_read_b128 v[178:181], v222 offset:20480
	ds_read_b128 v[182:185], v222 offset:21504
	ds_read_b128 v[196:199], v222 offset:22528
	ds_read_b128 v[206:209], v222 offset:23552
	global_load_lds_dwordx4 v[210:211], off
	s_add_i32 m0, s90, 0x2000
	s_add_u32 s90, s34, 0x80000
	v_lshl_add_u64 v[212:213], s[34:35], 0, v[200:201]
	s_addc_u32 s91, s35, 0
	s_add_i32 s96, s96, s47
	global_load_lds_dwordx4 v[212:213], off
	v_lshl_add_u64 v[214:215], s[90:91], 0, v[190:191]
	s_mov_b32 m0, s96
	v_lshl_add_u64 v[216:217], s[52:53], 0, v[188:189]
	global_load_lds_dwordx4 v[214:215], off
	s_add_i32 m0, s96, 0x2000
	v_lshl_add_u64 v[214:215], s[90:91], 0, v[200:201]
	global_load_lds_dwordx4 v[214:215], off
	s_mov_b32 m0, s55
	v_lshl_add_u64 v[214:215], s[52:53], 0, v[186:187]
	global_load_lds_dwordx4 v[214:215], off
	s_mov_b32 m0, s56
	s_nop 0
	global_load_lds_dwordx4 v[216:217], off
	s_waitcnt vmcnt(8) lgkmcnt(0)
	s_setprio 1
	s_barrier
	v_mfma_f32_16x16x32_bf16 v[62:65], v[130:133], v[162:165], v[62:65]
	v_mfma_f32_16x16x32_bf16 v[58:61], v[138:141], v[162:165], v[58:61]
	v_mfma_f32_16x16x32_bf16 v[46:49], v[130:133], v[170:173], v[46:49]
	v_mfma_f32_16x16x32_bf16 v[42:45], v[138:141], v[170:173], v[42:45]
	v_mfma_f32_16x16x32_bf16 v[30:33], v[130:133], v[178:181], v[30:33]
	v_mfma_f32_16x16x32_bf16 v[26:29], v[138:141], v[178:181], v[26:29]
	v_mfma_f32_16x16x32_bf16 v[14:17], v[130:133], v[196:199], v[14:17]
	v_mfma_f32_16x16x32_bf16 v[10:13], v[138:141], v[196:199], v[10:13]
	v_mfma_f32_16x16x32_bf16 v[62:65], v[134:137], v[166:169], v[62:65]
	v_mfma_f32_16x16x32_bf16 v[58:61], v[142:145], v[166:169], v[58:61]
	v_mfma_f32_16x16x32_bf16 v[46:49], v[134:137], v[174:177], v[46:49]
	v_mfma_f32_16x16x32_bf16 v[42:45], v[142:145], v[174:177], v[42:45]
	v_mfma_f32_16x16x32_bf16 v[30:33], v[134:137], v[182:185], v[30:33]
	v_mfma_f32_16x16x32_bf16 v[26:29], v[142:145], v[182:185], v[26:29]
	v_mfma_f32_16x16x32_bf16 v[14:17], v[134:137], v[206:209], v[14:17]
	v_mfma_f32_16x16x32_bf16 v[10:13], v[142:145], v[206:209], v[10:13]
	s_setprio 0
	s_setprio 1
	v_mfma_f32_16x16x32_bf16 v[54:57], v[146:149], v[162:165], v[54:57]
	v_mfma_f32_16x16x32_bf16 v[50:53], v[154:157], v[162:165], v[50:53]
	v_mfma_f32_16x16x32_bf16 v[38:41], v[146:149], v[170:173], v[38:41]
	v_mfma_f32_16x16x32_bf16 v[34:37], v[154:157], v[170:173], v[34:37]
	v_mfma_f32_16x16x32_bf16 v[22:25], v[146:149], v[178:181], v[22:25]
	v_mfma_f32_16x16x32_bf16 v[18:21], v[154:157], v[178:181], v[18:21]
	v_mfma_f32_16x16x32_bf16 v[6:9], v[146:149], v[196:199], v[6:9]
	v_mfma_f32_16x16x32_bf16 v[2:5], v[154:157], v[196:199], v[2:5]
	v_mfma_f32_16x16x32_bf16 v[54:57], v[150:153], v[166:169], v[54:57]
	v_mfma_f32_16x16x32_bf16 v[50:53], v[158:161], v[166:169], v[50:53]
	v_mfma_f32_16x16x32_bf16 v[38:41], v[150:153], v[174:177], v[38:41]
	v_mfma_f32_16x16x32_bf16 v[34:37], v[158:161], v[174:177], v[34:37]
	v_mfma_f32_16x16x32_bf16 v[22:25], v[150:153], v[182:185], v[22:25]
	v_mfma_f32_16x16x32_bf16 v[18:21], v[158:161], v[182:185], v[18:21]
	v_mfma_f32_16x16x32_bf16 v[6:9], v[150:153], v[206:209], v[6:9]
	v_mfma_f32_16x16x32_bf16 v[2:5], v[158:161], v[206:209], v[2:5]
	s_setprio 0
	s_barrier
	s_add_i32 s90, 0, 0x18000
	s_add_i32 s91, 0, 0x1c000
	v_add_u32_e32 v142, s90, v220
	v_add_u32_e32 v158, s91, v220
	ds_read_b128 v[130:133], v142
	ds_read_b128 v[134:137], v142 offset:1024
	ds_read_b128 v[138:141], v142 offset:2048
	ds_read_b128 v[142:145], v142 offset:3072
	ds_read_b128 v[146:149], v158
	ds_read_b128 v[150:153], v158 offset:1024
	ds_read_b128 v[154:157], v158 offset:2048
	ds_read_b128 v[158:161], v158 offset:3072
	s_add_u32 s52, s52, 0x80000
	s_addc_u32 s53, s53, 0
	s_mov_b32 m0, s57
	v_lshl_add_u64 v[218:219], s[52:53], 0, v[186:187]
	ds_read_b128 v[162:165], v222 offset:32768
	ds_read_b128 v[166:169], v222 offset:33792
	ds_read_b128 v[170:173], v222 offset:34816
	ds_read_b128 v[174:177], v222 offset:35840
	ds_read_b128 v[178:181], v222 offset:36864
	ds_read_b128 v[182:185], v222 offset:37888
	ds_read_b128 v[196:199], v222 offset:38912
	ds_read_b128 v[206:209], v222 offset:39936
	global_load_lds_dwordx4 v[218:219], off
	s_mov_b32 m0, s60
	v_lshl_add_u64 v[218:219], s[52:53], 0, v[188:189]
	global_load_lds_dwordx4 v[218:219], off
	s_waitcnt vmcnt(8) lgkmcnt(0)
	s_setprio 1
	s_barrier
	v_mfma_f32_16x16x32_bf16 v[126:129], v[130:133], v[162:165], v[126:129]
	v_mfma_f32_16x16x32_bf16 v[122:125], v[138:141], v[162:165], v[122:125]
	v_mfma_f32_16x16x32_bf16 v[110:113], v[130:133], v[170:173], v[110:113]
	v_mfma_f32_16x16x32_bf16 v[106:109], v[138:141], v[170:173], v[106:109]
	v_mfma_f32_16x16x32_bf16 v[94:97], v[130:133], v[178:181], v[94:97]
	v_mfma_f32_16x16x32_bf16 v[90:93], v[138:141], v[178:181], v[90:93]
	v_mfma_f32_16x16x32_bf16 v[78:81], v[130:133], v[196:199], v[78:81]
	v_mfma_f32_16x16x32_bf16 v[74:77], v[138:141], v[196:199], v[74:77]
	v_mfma_f32_16x16x32_bf16 v[126:129], v[134:137], v[166:169], v[126:129]
	v_mfma_f32_16x16x32_bf16 v[122:125], v[142:145], v[166:169], v[122:125]
	v_mfma_f32_16x16x32_bf16 v[110:113], v[134:137], v[174:177], v[110:113]
	v_mfma_f32_16x16x32_bf16 v[106:109], v[142:145], v[174:177], v[106:109]
	v_mfma_f32_16x16x32_bf16 v[94:97], v[134:137], v[182:185], v[94:97]
	v_mfma_f32_16x16x32_bf16 v[90:93], v[142:145], v[182:185], v[90:93]
	v_mfma_f32_16x16x32_bf16 v[78:81], v[134:137], v[206:209], v[78:81]
	v_mfma_f32_16x16x32_bf16 v[74:77], v[142:145], v[206:209], v[74:77]
	s_setprio 0
	s_setprio 1
	v_mfma_f32_16x16x32_bf16 v[118:121], v[146:149], v[162:165], v[118:121]
	v_mfma_f32_16x16x32_bf16 v[114:117], v[154:157], v[162:165], v[114:117]
	v_mfma_f32_16x16x32_bf16 v[102:105], v[146:149], v[170:173], v[102:105]
	v_mfma_f32_16x16x32_bf16 v[98:101], v[154:157], v[170:173], v[98:101]
	v_mfma_f32_16x16x32_bf16 v[86:89], v[146:149], v[178:181], v[86:89]
	v_mfma_f32_16x16x32_bf16 v[82:85], v[154:157], v[178:181], v[82:85]
	v_mfma_f32_16x16x32_bf16 v[70:73], v[146:149], v[196:199], v[70:73]
	v_mfma_f32_16x16x32_bf16 v[66:69], v[154:157], v[196:199], v[66:69]
	v_mfma_f32_16x16x32_bf16 v[118:121], v[150:153], v[166:169], v[118:121]
	v_mfma_f32_16x16x32_bf16 v[114:117], v[158:161], v[166:169], v[114:117]
	v_mfma_f32_16x16x32_bf16 v[102:105], v[150:153], v[174:177], v[102:105]
	v_mfma_f32_16x16x32_bf16 v[98:101], v[158:161], v[174:177], v[98:101]
	v_mfma_f32_16x16x32_bf16 v[86:89], v[150:153], v[182:185], v[86:89]
	v_mfma_f32_16x16x32_bf16 v[82:85], v[158:161], v[182:185], v[82:85]
	v_mfma_f32_16x16x32_bf16 v[70:73], v[150:153], v[206:209], v[70:73]
	v_mfma_f32_16x16x32_bf16 v[66:69], v[158:161], v[206:209], v[66:69]
	s_setprio 0
	s_barrier
	s_add_i32 s52, s90, s47
	v_lshl_add_u64 v[210:211], v[210:211], 0, s[58:59]
	s_mov_b32 m0, s52
	ds_read_b128 v[162:165], v222 offset:49152
	ds_read_b128 v[166:169], v222 offset:50176
	ds_read_b128 v[170:173], v222 offset:51200
	ds_read_b128 v[174:177], v222 offset:52224
	ds_read_b128 v[178:181], v222 offset:53248
	ds_read_b128 v[182:185], v222 offset:54272
	ds_read_b128 v[196:199], v222 offset:55296
	ds_read_b128 v[206:209], v222 offset:56320
	global_load_lds_dwordx4 v[210:211], off
	s_add_i32 m0, s52, 0x2000
	s_add_u32 s34, s34, 0x80080
	v_lshl_add_u64 v[210:211], v[212:213], 0, s[58:59]
	s_addc_u32 s35, s35, 0
	s_add_i32 s52, s91, s47
	global_load_lds_dwordx4 v[210:211], off
	s_mov_b32 m0, s52
	v_lshl_add_u64 v[210:211], s[34:35], 0, v[190:191]
	global_load_lds_dwordx4 v[210:211], off
	s_add_i32 m0, s52, 0x2000
	v_lshl_add_u64 v[210:211], s[34:35], 0, v[200:201]
	global_load_lds_dwordx4 v[210:211], off
	s_mov_b32 m0, s61
	v_lshl_add_u64 v[210:211], v[214:215], 0, s[58:59]
	global_load_lds_dwordx4 v[210:211], off
	s_mov_b32 m0, s69
	v_lshl_add_u64 v[210:211], v[216:217], 0, s[58:59]
	global_load_lds_dwordx4 v[210:211], off
	s_waitcnt vmcnt(8) lgkmcnt(0)
	s_setprio 1
	s_barrier
	v_mfma_f32_16x16x32_bf16 v[62:65], v[130:133], v[162:165], v[62:65]
	v_mfma_f32_16x16x32_bf16 v[58:61], v[138:141], v[162:165], v[58:61]
	v_mfma_f32_16x16x32_bf16 v[46:49], v[130:133], v[170:173], v[46:49]
	v_mfma_f32_16x16x32_bf16 v[42:45], v[138:141], v[170:173], v[42:45]
	v_mfma_f32_16x16x32_bf16 v[30:33], v[130:133], v[178:181], v[30:33]
	v_mfma_f32_16x16x32_bf16 v[26:29], v[138:141], v[178:181], v[26:29]
	v_mfma_f32_16x16x32_bf16 v[14:17], v[130:133], v[196:199], v[14:17]
	v_mfma_f32_16x16x32_bf16 v[10:13], v[138:141], v[196:199], v[10:13]
	v_mfma_f32_16x16x32_bf16 v[62:65], v[134:137], v[166:169], v[62:65]
	v_mfma_f32_16x16x32_bf16 v[58:61], v[142:145], v[166:169], v[58:61]
	v_mfma_f32_16x16x32_bf16 v[46:49], v[134:137], v[174:177], v[46:49]
	v_mfma_f32_16x16x32_bf16 v[42:45], v[142:145], v[174:177], v[42:45]
	v_mfma_f32_16x16x32_bf16 v[30:33], v[134:137], v[182:185], v[30:33]
	v_mfma_f32_16x16x32_bf16 v[26:29], v[142:145], v[182:185], v[26:29]
	v_mfma_f32_16x16x32_bf16 v[14:17], v[134:137], v[206:209], v[14:17]
	v_mfma_f32_16x16x32_bf16 v[10:13], v[142:145], v[206:209], v[10:13]
	s_setprio 0
	s_setprio 1
	v_mfma_f32_16x16x32_bf16 v[54:57], v[146:149], v[162:165], v[54:57]
	v_mfma_f32_16x16x32_bf16 v[50:53], v[154:157], v[162:165], v[50:53]
	v_mfma_f32_16x16x32_bf16 v[38:41], v[146:149], v[170:173], v[38:41]
	v_mfma_f32_16x16x32_bf16 v[34:37], v[154:157], v[170:173], v[34:37]
	v_mfma_f32_16x16x32_bf16 v[22:25], v[146:149], v[178:181], v[22:25]
	v_mfma_f32_16x16x32_bf16 v[18:21], v[154:157], v[178:181], v[18:21]
	v_mfma_f32_16x16x32_bf16 v[6:9], v[146:149], v[196:199], v[6:9]
	v_mfma_f32_16x16x32_bf16 v[2:5], v[154:157], v[196:199], v[2:5]
	v_mfma_f32_16x16x32_bf16 v[54:57], v[150:153], v[166:169], v[54:57]
	v_mfma_f32_16x16x32_bf16 v[50:53], v[158:161], v[166:169], v[50:53]
	v_mfma_f32_16x16x32_bf16 v[38:41], v[150:153], v[174:177], v[38:41]
	v_mfma_f32_16x16x32_bf16 v[34:37], v[158:161], v[174:177], v[34:37]
	v_mfma_f32_16x16x32_bf16 v[22:25], v[150:153], v[182:185], v[22:25]
	v_mfma_f32_16x16x32_bf16 v[18:21], v[158:161], v[182:185], v[18:21]
	v_mfma_f32_16x16x32_bf16 v[6:9], v[150:153], v[206:209], v[6:9]
	v_mfma_f32_16x16x32_bf16 v[2:5], v[158:161], v[206:209], v[2:5]
	s_setprio 0
	s_barrier
	s_add_i32 s89, s89, 2
	s_add_u32 s30, s30, 0x100
	s_addc_u32 s31, s31, 0
	s_add_u32 s81, s81, 0x100
	s_addc_u32 s88, s88, 0
	s_cmp_gt_u32 s89, 29
	s_cbranch_scc0 .LBB0_823

.LBB0_937:
	s_ashr_i32 s23, s22, 31
	s_lshl_b64 s[4:5], s[22:23], 20
	s_add_u32 s4, s86, s4
	s_addc_u32 s5, s87, s5
	s_and_b64 s[26:27], s[24:25], exec
	s_cselect_b32 s11, s5, s29
	s_cselect_b32 s23, s4, s28
	s_ashr_i32 s21, s20, 31
	s_lshl_b64 s[26:27], s[20:21], 20
	v_readlane_b32 s0, v254, 38
	v_readlane_b32 s1, v254, 39
	s_add_u32 s26, s0, s26
	s_addc_u32 s27, s1, s27
	s_and_b64 s[34:35], s[24:25], exec
	s_cselect_b32 s21, s27, s31
	s_cselect_b32 s53, s26, s30
	s_add_u32 s28, s28, 0x80080
	s_addc_u32 s29, s29, 0
	s_add_u32 s55, s30, 0x100
	s_addc_u32 s56, s31, 0
	s_mov_b32 s57, -2
	v_readlane_b32 s60, v255, 49
	s_nop 3
	s_cmp_eq_u32 s60, 7
	v_writelane_b32 v255, 7, 49
	s_cbranch_scc0 .Ltrip0_strict_6
	s_add_u32 s30, s28, 0xfff80080
	s_addc_u32 s31, s29, -1
	s_add_i32 s60, 0, 0x10000
	s_cmp_eq_u32 s57, 28
	s_cselect_b32 s35, s11, s31
	s_cselect_b32 s34, s23, s30
	s_cselect_b32 s31, s21, s56
	s_cselect_b32 s30, s53, s55
	s_add_i32 s66, 0, 0x14000
	v_add_u32_e32 v154, s60, v139
	v_add_u32_e32 v170, s66, v139
	ds_read_b128 v[142:145], v154
	ds_read_b128 v[146:149], v154 offset:1024
	ds_read_b128 v[150:153], v154 offset:2048
	ds_read_b128 v[154:157], v154 offset:3072
	ds_read_b128 v[158:161], v170
	ds_read_b128 v[162:165], v170 offset:1024
	ds_read_b128 v[166:169], v170 offset:2048
	ds_read_b128 v[170:173], v170 offset:3072
	v_lshl_add_u64 v[186:187], s[28:29], 0, v[134:135]
	s_add_i32 m0, s13, 0xc000
	ds_read_b128 v[174:177], v141
	ds_read_b128 v[178:181], v141 offset:1024
	ds_read_b128 v[182:185], v141 offset:2048
	ds_read_b128 v[196:199], v141 offset:3072
	ds_read_b128 v[200:203], v141 offset:4096
	ds_read_b128 v[204:207], v141 offset:5120
	ds_read_b128 v[208:211], v141 offset:6144
	ds_read_b128 v[212:215], v141 offset:7168
	global_load_lds_dwordx4 v[186:187], off
	s_add_i32 m0, s13, 0xe000
	v_lshl_add_u64 v[186:187], s[28:29], 0, v[136:137]
	global_load_lds_dwordx4 v[186:187], off
	s_waitcnt vmcnt(24) lgkmcnt(0)
	s_setprio 1
	s_barrier
	v_mfma_f32_16x16x32_bf16 v[124:127], v[142:145], v[174:177], 0
	v_mfma_f32_16x16x32_bf16 v[120:123], v[150:153], v[174:177], 0
	v_mfma_f32_16x16x32_bf16 v[116:119], v[142:145], v[182:185], 0
	v_mfma_f32_16x16x32_bf16 v[112:115], v[150:153], v[182:185], 0
	v_mfma_f32_16x16x32_bf16 v[100:103], v[142:145], v[200:203], 0
	v_mfma_f32_16x16x32_bf16 v[96:99], v[150:153], v[200:203], 0
	v_mfma_f32_16x16x32_bf16 v[84:87], v[142:145], v[208:211], 0
	v_mfma_f32_16x16x32_bf16 v[80:83], v[150:153], v[208:211], 0
	v_mfma_f32_16x16x32_bf16 v[124:127], v[146:149], v[178:181], v[124:127]
	v_mfma_f32_16x16x32_bf16 v[120:123], v[154:157], v[178:181], v[120:123]
	v_mfma_f32_16x16x32_bf16 v[116:119], v[146:149], v[196:199], v[116:119]
	v_mfma_f32_16x16x32_bf16 v[112:115], v[154:157], v[196:199], v[112:115]
	v_mfma_f32_16x16x32_bf16 v[100:103], v[146:149], v[204:207], v[100:103]
	v_mfma_f32_16x16x32_bf16 v[96:99], v[154:157], v[204:207], v[96:99]
	v_mfma_f32_16x16x32_bf16 v[84:87], v[146:149], v[212:215], v[84:87]
	v_mfma_f32_16x16x32_bf16 v[80:83], v[154:157], v[212:215], v[80:83]
	s_setprio 0
	s_setprio 1
	v_mfma_f32_16x16x32_bf16 v[108:111], v[158:161], v[174:177], 0
	v_mfma_f32_16x16x32_bf16 v[104:107], v[166:169], v[174:177], 0
	v_mfma_f32_16x16x32_bf16 v[92:95], v[158:161], v[182:185], 0
	v_mfma_f32_16x16x32_bf16 v[88:91], v[166:169], v[182:185], 0
	v_mfma_f32_16x16x32_bf16 v[76:79], v[158:161], v[200:203], 0
	v_mfma_f32_16x16x32_bf16 v[72:75], v[166:169], v[200:203], 0
	v_mfma_f32_16x16x32_bf16 v[68:71], v[158:161], v[208:211], 0
	v_mfma_f32_16x16x32_bf16 v[64:67], v[166:169], v[208:211], 0
	v_mfma_f32_16x16x32_bf16 v[108:111], v[162:165], v[178:181], v[108:111]
	v_mfma_f32_16x16x32_bf16 v[104:107], v[170:173], v[178:181], v[104:107]
	v_mfma_f32_16x16x32_bf16 v[92:95], v[162:165], v[196:199], v[92:95]
	v_mfma_f32_16x16x32_bf16 v[88:91], v[170:173], v[196:199], v[88:91]
	v_mfma_f32_16x16x32_bf16 v[76:79], v[162:165], v[204:207], v[76:79]
	v_mfma_f32_16x16x32_bf16 v[72:75], v[170:173], v[204:207], v[72:75]
	v_mfma_f32_16x16x32_bf16 v[68:71], v[162:165], v[212:215], v[68:71]
	v_mfma_f32_16x16x32_bf16 v[64:67], v[170:173], v[212:215], v[64:67]
	s_barrier
	s_setprio 0
	s_add_i32 s60, s60, s38
	v_lshl_add_u64 v[186:187], s[30:31], 0, v[190:191]
	s_mov_b32 m0, s60
	ds_read_b128 v[174:177], v141 offset:16384
	ds_read_b128 v[178:181], v141 offset:17408
	ds_read_b128 v[182:185], v141 offset:18432
	ds_read_b128 v[196:199], v141 offset:19456
	ds_read_b128 v[200:203], v141 offset:20480
	ds_read_b128 v[204:207], v141 offset:21504
	ds_read_b128 v[208:211], v141 offset:22528
	ds_read_b128 v[212:215], v141 offset:23552
	global_load_lds_dwordx4 v[186:187], off
	s_add_i32 m0, s60, 0x2000
	s_add_u32 s60, s30, 0x80000
	v_lshl_add_u64 v[216:217], s[30:31], 0, v[132:133]
	s_addc_u32 s61, s31, 0
	s_add_i32 s66, s66, s38
	global_load_lds_dwordx4 v[216:217], off
	v_lshl_add_u64 v[218:219], s[60:61], 0, v[190:191]
	s_mov_b32 m0, s66
	v_lshl_add_u64 v[220:221], s[34:35], 0, v[130:131]
	global_load_lds_dwordx4 v[218:219], off
	s_add_i32 m0, s66, 0x2000
	v_lshl_add_u64 v[218:219], s[60:61], 0, v[132:133]
	global_load_lds_dwordx4 v[218:219], off
	s_mov_b32 m0, s13
	v_lshl_add_u64 v[218:219], s[34:35], 0, v[128:129]
	global_load_lds_dwordx4 v[218:219], off
	s_mov_b32 m0, s39
	s_nop 0
	global_load_lds_dwordx4 v[220:221], off
	s_waitcnt vmcnt(24) lgkmcnt(0)
	s_setprio 1
	s_barrier
	v_mfma_f32_16x16x32_bf16 v[60:63], v[142:145], v[174:177], 0
	v_mfma_f32_16x16x32_bf16 v[56:59], v[150:153], v[174:177], 0
	v_mfma_f32_16x16x32_bf16 v[52:55], v[142:145], v[182:185], 0
	v_mfma_f32_16x16x32_bf16 v[48:51], v[150:153], v[182:185], 0
	v_mfma_f32_16x16x32_bf16 v[36:39], v[142:145], v[200:203], 0
	v_mfma_f32_16x16x32_bf16 v[32:35], v[150:153], v[200:203], 0
	v_mfma_f32_16x16x32_bf16 v[20:23], v[142:145], v[208:211], 0
	v_mfma_f32_16x16x32_bf16 v[16:19], v[150:153], v[208:211], 0
	v_mfma_f32_16x16x32_bf16 v[60:63], v[146:149], v[178:181], v[60:63]
	v_mfma_f32_16x16x32_bf16 v[56:59], v[154:157], v[178:181], v[56:59]
	v_mfma_f32_16x16x32_bf16 v[52:55], v[146:149], v[196:199], v[52:55]
	v_mfma_f32_16x16x32_bf16 v[48:51], v[154:157], v[196:199], v[48:51]
	v_mfma_f32_16x16x32_bf16 v[36:39], v[146:149], v[204:207], v[36:39]
	v_mfma_f32_16x16x32_bf16 v[32:35], v[154:157], v[204:207], v[32:35]
	v_mfma_f32_16x16x32_bf16 v[20:23], v[146:149], v[212:215], v[20:23]
	v_mfma_f32_16x16x32_bf16 v[16:19], v[154:157], v[212:215], v[16:19]
	s_setprio 0
	s_setprio 1
	v_mfma_f32_16x16x32_bf16 v[44:47], v[158:161], v[174:177], 0
	v_mfma_f32_16x16x32_bf16 v[40:43], v[166:169], v[174:177], 0
	v_mfma_f32_16x16x32_bf16 v[28:31], v[158:161], v[182:185], 0
	v_mfma_f32_16x16x32_bf16 v[24:27], v[166:169], v[182:185], 0
	v_mfma_f32_16x16x32_bf16 v[12:15], v[158:161], v[200:203], 0
	v_mfma_f32_16x16x32_bf16 v[8:11], v[166:169], v[200:203], 0
	v_mfma_f32_16x16x32_bf16 v[4:7], v[158:161], v[208:211], 0
	v_mfma_f32_16x16x32_bf16 v[0:3], v[166:169], v[208:211], 0
	v_mfma_f32_16x16x32_bf16 v[44:47], v[162:165], v[178:181], v[44:47]
	v_mfma_f32_16x16x32_bf16 v[40:43], v[170:173], v[178:181], v[40:43]
	v_mfma_f32_16x16x32_bf16 v[28:31], v[162:165], v[196:199], v[28:31]
	v_mfma_f32_16x16x32_bf16 v[24:27], v[170:173], v[196:199], v[24:27]
	v_mfma_f32_16x16x32_bf16 v[12:15], v[162:165], v[204:207], v[12:15]
	v_mfma_f32_16x16x32_bf16 v[8:11], v[170:173], v[204:207], v[8:11]
	v_mfma_f32_16x16x32_bf16 v[4:7], v[162:165], v[212:215], v[4:7]
	v_mfma_f32_16x16x32_bf16 v[0:3], v[170:173], v[212:215], v[0:3]
	s_barrier
	s_setprio 0
	s_add_i32 s60, 0, 0x18000
	s_add_i32 s61, 0, 0x1c000
	v_add_u32_e32 v154, s60, v139
	v_add_u32_e32 v170, s61, v139
	ds_read_b128 v[142:145], v154
	ds_read_b128 v[146:149], v154 offset:1024
	ds_read_b128 v[150:153], v154 offset:2048
	ds_read_b128 v[154:157], v154 offset:3072
	ds_read_b128 v[158:161], v170
	ds_read_b128 v[162:165], v170 offset:1024
	ds_read_b128 v[166:169], v170 offset:2048
	ds_read_b128 v[170:173], v170 offset:3072
	s_add_u32 s34, s34, 0x80000
	s_addc_u32 s35, s35, 0
	s_mov_b32 m0, s41
	v_lshl_add_u64 v[222:223], s[34:35], 0, v[128:129]
	ds_read_b128 v[174:177], v141 offset:32768
	ds_read_b128 v[178:181], v141 offset:33792
	ds_read_b128 v[182:185], v141 offset:34816
	ds_read_b128 v[196:199], v141 offset:35840
	ds_read_b128 v[200:203], v141 offset:36864
	ds_read_b128 v[204:207], v141 offset:37888
	ds_read_b128 v[208:211], v141 offset:38912
	ds_read_b128 v[212:215], v141 offset:39936
	global_load_lds_dwordx4 v[222:223], off
	s_mov_b32 m0, s42
	v_lshl_add_u64 v[222:223], s[34:35], 0, v[130:131]
	global_load_lds_dwordx4 v[222:223], off
	s_waitcnt vmcnt(8) lgkmcnt(0)
	s_setprio 1
	s_barrier
	v_mfma_f32_16x16x32_bf16 v[124:127], v[142:145], v[174:177], v[124:127]
	v_mfma_f32_16x16x32_bf16 v[120:123], v[150:153], v[174:177], v[120:123]
	v_mfma_f32_16x16x32_bf16 v[116:119], v[142:145], v[182:185], v[116:119]
	v_mfma_f32_16x16x32_bf16 v[112:115], v[150:153], v[182:185], v[112:115]
	v_mfma_f32_16x16x32_bf16 v[100:103], v[142:145], v[200:203], v[100:103]
	v_mfma_f32_16x16x32_bf16 v[96:99], v[150:153], v[200:203], v[96:99]
	v_mfma_f32_16x16x32_bf16 v[84:87], v[142:145], v[208:211], v[84:87]
	v_mfma_f32_16x16x32_bf16 v[80:83], v[150:153], v[208:211], v[80:83]
	v_mfma_f32_16x16x32_bf16 v[124:127], v[146:149], v[178:181], v[124:127]
	v_mfma_f32_16x16x32_bf16 v[120:123], v[154:157], v[178:181], v[120:123]
	v_mfma_f32_16x16x32_bf16 v[116:119], v[146:149], v[196:199], v[116:119]
	v_mfma_f32_16x16x32_bf16 v[112:115], v[154:157], v[196:199], v[112:115]
	v_mfma_f32_16x16x32_bf16 v[100:103], v[146:149], v[204:207], v[100:103]
	v_mfma_f32_16x16x32_bf16 v[96:99], v[154:157], v[204:207], v[96:99]
	v_mfma_f32_16x16x32_bf16 v[84:87], v[146:149], v[212:215], v[84:87]
	v_mfma_f32_16x16x32_bf16 v[80:83], v[154:157], v[212:215], v[80:83]
	s_setprio 0
	s_setprio 1
	v_mfma_f32_16x16x32_bf16 v[108:111], v[158:161], v[174:177], v[108:111]
	v_mfma_f32_16x16x32_bf16 v[104:107], v[166:169], v[174:177], v[104:107]
	v_mfma_f32_16x16x32_bf16 v[92:95], v[158:161], v[182:185], v[92:95]
	v_mfma_f32_16x16x32_bf16 v[88:91], v[166:169], v[182:185], v[88:91]
	v_mfma_f32_16x16x32_bf16 v[76:79], v[158:161], v[200:203], v[76:79]
	v_mfma_f32_16x16x32_bf16 v[72:75], v[166:169], v[200:203], v[72:75]
	v_mfma_f32_16x16x32_bf16 v[68:71], v[158:161], v[208:211], v[68:71]
	v_mfma_f32_16x16x32_bf16 v[64:67], v[166:169], v[208:211], v[64:67]
	v_mfma_f32_16x16x32_bf16 v[108:111], v[162:165], v[178:181], v[108:111]
	v_mfma_f32_16x16x32_bf16 v[104:107], v[170:173], v[178:181], v[104:107]
	v_mfma_f32_16x16x32_bf16 v[92:95], v[162:165], v[196:199], v[92:95]
	v_mfma_f32_16x16x32_bf16 v[88:91], v[170:173], v[196:199], v[88:91]
	v_mfma_f32_16x16x32_bf16 v[76:79], v[162:165], v[204:207], v[76:79]
	v_mfma_f32_16x16x32_bf16 v[72:75], v[170:173], v[204:207], v[72:75]
	v_mfma_f32_16x16x32_bf16 v[68:71], v[162:165], v[212:215], v[68:71]
	v_mfma_f32_16x16x32_bf16 v[64:67], v[170:173], v[212:215], v[64:67]
	s_barrier
	s_setprio 0
	s_add_i32 s34, s60, s38
	v_lshl_add_u64 v[186:187], v[186:187], 0, s[58:59]
	s_mov_b32 m0, s34
	ds_read_b128 v[174:177], v141 offset:49152
	ds_read_b128 v[178:181], v141 offset:50176
	ds_read_b128 v[182:185], v141 offset:51200
	ds_read_b128 v[196:199], v141 offset:52224
	ds_read_b128 v[200:203], v141 offset:53248
	ds_read_b128 v[204:207], v141 offset:54272
	ds_read_b128 v[208:211], v141 offset:55296
	ds_read_b128 v[212:215], v141 offset:56320
	global_load_lds_dwordx4 v[186:187], off
	s_add_i32 m0, s34, 0x2000
	s_add_u32 s30, s30, 0x80080
	v_lshl_add_u64 v[186:187], v[216:217], 0, s[58:59]
	s_addc_u32 s31, s31, 0
	s_add_i32 s34, s61, s38
	global_load_lds_dwordx4 v[186:187], off
	s_mov_b32 m0, s34
	v_lshl_add_u64 v[186:187], s[30:31], 0, v[190:191]
	global_load_lds_dwordx4 v[186:187], off
	s_add_i32 m0, s34, 0x2000
	v_lshl_add_u64 v[186:187], s[30:31], 0, v[132:133]
	global_load_lds_dwordx4 v[186:187], off
	s_mov_b32 m0, s43
	v_lshl_add_u64 v[186:187], v[218:219], 0, s[58:59]
	global_load_lds_dwordx4 v[186:187], off
	s_mov_b32 m0, s47
	v_lshl_add_u64 v[186:187], v[220:221], 0, s[58:59]
	global_load_lds_dwordx4 v[186:187], off
	s_waitcnt vmcnt(8) lgkmcnt(0)
	s_setprio 1
	s_barrier
	v_mfma_f32_16x16x32_bf16 v[60:63], v[142:145], v[174:177], v[60:63]
	v_mfma_f32_16x16x32_bf16 v[56:59], v[150:153], v[174:177], v[56:59]
	v_mfma_f32_16x16x32_bf16 v[52:55], v[142:145], v[182:185], v[52:55]
	v_mfma_f32_16x16x32_bf16 v[48:51], v[150:153], v[182:185], v[48:51]
	v_mfma_f32_16x16x32_bf16 v[36:39], v[142:145], v[200:203], v[36:39]
	v_mfma_f32_16x16x32_bf16 v[32:35], v[150:153], v[200:203], v[32:35]
	v_mfma_f32_16x16x32_bf16 v[20:23], v[142:145], v[208:211], v[20:23]
	v_mfma_f32_16x16x32_bf16 v[16:19], v[150:153], v[208:211], v[16:19]
	v_mfma_f32_16x16x32_bf16 v[60:63], v[146:149], v[178:181], v[60:63]
	v_mfma_f32_16x16x32_bf16 v[56:59], v[154:157], v[178:181], v[56:59]
	v_mfma_f32_16x16x32_bf16 v[52:55], v[146:149], v[196:199], v[52:55]
	v_mfma_f32_16x16x32_bf16 v[48:51], v[154:157], v[196:199], v[48:51]
	v_mfma_f32_16x16x32_bf16 v[36:39], v[146:149], v[204:207], v[36:39]
	v_mfma_f32_16x16x32_bf16 v[32:35], v[154:157], v[204:207], v[32:35]
	v_mfma_f32_16x16x32_bf16 v[20:23], v[146:149], v[212:215], v[20:23]
	v_mfma_f32_16x16x32_bf16 v[16:19], v[154:157], v[212:215], v[16:19]
	s_setprio 0
	s_setprio 1
	v_mfma_f32_16x16x32_bf16 v[44:47], v[158:161], v[174:177], v[44:47]
	v_mfma_f32_16x16x32_bf16 v[40:43], v[166:169], v[174:177], v[40:43]
	v_mfma_f32_16x16x32_bf16 v[28:31], v[158:161], v[182:185], v[28:31]
	v_mfma_f32_16x16x32_bf16 v[24:27], v[166:169], v[182:185], v[24:27]
	v_mfma_f32_16x16x32_bf16 v[12:15], v[158:161], v[200:203], v[12:15]
	v_mfma_f32_16x16x32_bf16 v[8:11], v[166:169], v[200:203], v[8:11]
	v_mfma_f32_16x16x32_bf16 v[4:7], v[158:161], v[208:211], v[4:7]
	v_mfma_f32_16x16x32_bf16 v[0:3], v[166:169], v[208:211], v[0:3]
	v_mfma_f32_16x16x32_bf16 v[44:47], v[162:165], v[178:181], v[44:47]
	v_mfma_f32_16x16x32_bf16 v[40:43], v[170:173], v[178:181], v[40:43]
	v_mfma_f32_16x16x32_bf16 v[28:31], v[162:165], v[196:199], v[28:31]
	v_mfma_f32_16x16x32_bf16 v[24:27], v[170:173], v[196:199], v[24:27]
	v_mfma_f32_16x16x32_bf16 v[12:15], v[162:165], v[204:207], v[12:15]
	v_mfma_f32_16x16x32_bf16 v[8:11], v[170:173], v[204:207], v[8:11]
	v_mfma_f32_16x16x32_bf16 v[4:7], v[162:165], v[212:215], v[4:7]
	v_mfma_f32_16x16x32_bf16 v[0:3], v[170:173], v[212:215], v[0:3]
	s_barrier
	s_setprio 0
	s_add_i32 s57, s57, 2
	s_add_u32 s28, s28, 0x100
	s_addc_u32 s29, s29, 0
	s_add_u32 s55, s55, 0x100
	s_addc_u32 s56, s56, 0
	s_cmp_gt_u32 s57, 29
	s_cbranch_scc1 .Lpeel_done_6
	s_branch .LBB0_938
.Ltrip0_strict_6:
	s_add_u32 s30, s28, 0xfff80080
	s_addc_u32 s31, s29, -1
	s_add_i32 s60, 0, 0x10000
	s_cmp_eq_u32 s57, 28
	s_cselect_b32 s35, s11, s31
	s_cselect_b32 s34, s23, s30
	s_cselect_b32 s31, s21, s56
	s_cselect_b32 s30, s53, s55
	s_add_i32 s66, 0, 0x14000
	v_add_u32_e32 v154, s60, v139
	v_add_u32_e32 v170, s66, v139
	ds_read_b128 v[142:145], v154
	ds_read_b128 v[146:149], v154 offset:1024
	ds_read_b128 v[150:153], v154 offset:2048
	ds_read_b128 v[154:157], v154 offset:3072
	ds_read_b128 v[158:161], v170
	ds_read_b128 v[162:165], v170 offset:1024
	ds_read_b128 v[166:169], v170 offset:2048
	ds_read_b128 v[170:173], v170 offset:3072
	v_lshl_add_u64 v[186:187], s[28:29], 0, v[134:135]
	s_add_i32 m0, s13, 0xc000
	ds_read_b128 v[174:177], v141
	ds_read_b128 v[178:181], v141 offset:1024
	ds_read_b128 v[182:185], v141 offset:2048
	ds_read_b128 v[196:199], v141 offset:3072
	ds_read_b128 v[200:203], v141 offset:4096
	ds_read_b128 v[204:207], v141 offset:5120
	ds_read_b128 v[208:211], v141 offset:6144
	ds_read_b128 v[212:215], v141 offset:7168
	global_load_lds_dwordx4 v[186:187], off
	s_add_i32 m0, s13, 0xe000
	v_lshl_add_u64 v[186:187], s[28:29], 0, v[136:137]
	global_load_lds_dwordx4 v[186:187], off
	s_waitcnt vmcnt(8) lgkmcnt(0)
	s_setprio 1
	s_barrier
	v_mfma_f32_16x16x32_bf16 v[124:127], v[142:145], v[174:177], 0
	v_mfma_f32_16x16x32_bf16 v[120:123], v[150:153], v[174:177], 0
	v_mfma_f32_16x16x32_bf16 v[116:119], v[142:145], v[182:185], 0
	v_mfma_f32_16x16x32_bf16 v[112:115], v[150:153], v[182:185], 0
	v_mfma_f32_16x16x32_bf16 v[100:103], v[142:145], v[200:203], 0
	v_mfma_f32_16x16x32_bf16 v[96:99], v[150:153], v[200:203], 0
	v_mfma_f32_16x16x32_bf16 v[84:87], v[142:145], v[208:211], 0
	v_mfma_f32_16x16x32_bf16 v[80:83], v[150:153], v[208:211], 0
	v_mfma_f32_16x16x32_bf16 v[124:127], v[146:149], v[178:181], v[124:127]
	v_mfma_f32_16x16x32_bf16 v[120:123], v[154:157], v[178:181], v[120:123]
	v_mfma_f32_16x16x32_bf16 v[116:119], v[146:149], v[196:199], v[116:119]
	v_mfma_f32_16x16x32_bf16 v[112:115], v[154:157], v[196:199], v[112:115]
	v_mfma_f32_16x16x32_bf16 v[100:103], v[146:149], v[204:207], v[100:103]
	v_mfma_f32_16x16x32_bf16 v[96:99], v[154:157], v[204:207], v[96:99]
	v_mfma_f32_16x16x32_bf16 v[84:87], v[146:149], v[212:215], v[84:87]
	v_mfma_f32_16x16x32_bf16 v[80:83], v[154:157], v[212:215], v[80:83]
	s_setprio 0
	s_setprio 1
	v_mfma_f32_16x16x32_bf16 v[108:111], v[158:161], v[174:177], 0
	v_mfma_f32_16x16x32_bf16 v[104:107], v[166:169], v[174:177], 0
	v_mfma_f32_16x16x32_bf16 v[92:95], v[158:161], v[182:185], 0
	v_mfma_f32_16x16x32_bf16 v[88:91], v[166:169], v[182:185], 0
	v_mfma_f32_16x16x32_bf16 v[76:79], v[158:161], v[200:203], 0
	v_mfma_f32_16x16x32_bf16 v[72:75], v[166:169], v[200:203], 0
	v_mfma_f32_16x16x32_bf16 v[68:71], v[158:161], v[208:211], 0
	v_mfma_f32_16x16x32_bf16 v[64:67], v[166:169], v[208:211], 0
	v_mfma_f32_16x16x32_bf16 v[108:111], v[162:165], v[178:181], v[108:111]
	v_mfma_f32_16x16x32_bf16 v[104:107], v[170:173], v[178:181], v[104:107]
	v_mfma_f32_16x16x32_bf16 v[92:95], v[162:165], v[196:199], v[92:95]
	v_mfma_f32_16x16x32_bf16 v[88:91], v[170:173], v[196:199], v[88:91]
	v_mfma_f32_16x16x32_bf16 v[76:79], v[162:165], v[204:207], v[76:79]
	v_mfma_f32_16x16x32_bf16 v[72:75], v[170:173], v[204:207], v[72:75]
	v_mfma_f32_16x16x32_bf16 v[68:71], v[162:165], v[212:215], v[68:71]
	v_mfma_f32_16x16x32_bf16 v[64:67], v[170:173], v[212:215], v[64:67]
	s_barrier
	s_setprio 0
	s_add_i32 s60, s60, s38
	v_lshl_add_u64 v[186:187], s[30:31], 0, v[190:191]
	s_mov_b32 m0, s60
	ds_read_b128 v[174:177], v141 offset:16384
	ds_read_b128 v[178:181], v141 offset:17408
	ds_read_b128 v[182:185], v141 offset:18432
	ds_read_b128 v[196:199], v141 offset:19456
	ds_read_b128 v[200:203], v141 offset:20480
	ds_read_b128 v[204:207], v141 offset:21504
	ds_read_b128 v[208:211], v141 offset:22528
	ds_read_b128 v[212:215], v141 offset:23552
	global_load_lds_dwordx4 v[186:187], off
	s_add_i32 m0, s60, 0x2000
	s_add_u32 s60, s30, 0x80000
	v_lshl_add_u64 v[216:217], s[30:31], 0, v[132:133]
	s_addc_u32 s61, s31, 0
	s_add_i32 s66, s66, s38
	global_load_lds_dwordx4 v[216:217], off
	v_lshl_add_u64 v[218:219], s[60:61], 0, v[190:191]
	s_mov_b32 m0, s66
	v_lshl_add_u64 v[220:221], s[34:35], 0, v[130:131]
	global_load_lds_dwordx4 v[218:219], off
	s_add_i32 m0, s66, 0x2000
	v_lshl_add_u64 v[218:219], s[60:61], 0, v[132:133]
	global_load_lds_dwordx4 v[218:219], off
	s_mov_b32 m0, s13
	v_lshl_add_u64 v[218:219], s[34:35], 0, v[128:129]
	global_load_lds_dwordx4 v[218:219], off
	s_mov_b32 m0, s39
	s_nop 0
	global_load_lds_dwordx4 v[220:221], off
	s_waitcnt vmcnt(8) lgkmcnt(0)
	s_setprio 1
	s_barrier
	v_mfma_f32_16x16x32_bf16 v[60:63], v[142:145], v[174:177], 0
	v_mfma_f32_16x16x32_bf16 v[56:59], v[150:153], v[174:177], 0
	v_mfma_f32_16x16x32_bf16 v[52:55], v[142:145], v[182:185], 0
	v_mfma_f32_16x16x32_bf16 v[48:51], v[150:153], v[182:185], 0
	v_mfma_f32_16x16x32_bf16 v[36:39], v[142:145], v[200:203], 0
	v_mfma_f32_16x16x32_bf16 v[32:35], v[150:153], v[200:203], 0
	v_mfma_f32_16x16x32_bf16 v[20:23], v[142:145], v[208:211], 0
	v_mfma_f32_16x16x32_bf16 v[16:19], v[150:153], v[208:211], 0
	v_mfma_f32_16x16x32_bf16 v[60:63], v[146:149], v[178:181], v[60:63]
	v_mfma_f32_16x16x32_bf16 v[56:59], v[154:157], v[178:181], v[56:59]
	v_mfma_f32_16x16x32_bf16 v[52:55], v[146:149], v[196:199], v[52:55]
	v_mfma_f32_16x16x32_bf16 v[48:51], v[154:157], v[196:199], v[48:51]
	v_mfma_f32_16x16x32_bf16 v[36:39], v[146:149], v[204:207], v[36:39]
	v_mfma_f32_16x16x32_bf16 v[32:35], v[154:157], v[204:207], v[32:35]
	v_mfma_f32_16x16x32_bf16 v[20:23], v[146:149], v[212:215], v[20:23]
	v_mfma_f32_16x16x32_bf16 v[16:19], v[154:157], v[212:215], v[16:19]
	s_setprio 0
	s_setprio 1
	v_mfma_f32_16x16x32_bf16 v[44:47], v[158:161], v[174:177], 0
	v_mfma_f32_16x16x32_bf16 v[40:43], v[166:169], v[174:177], 0
	v_mfma_f32_16x16x32_bf16 v[28:31], v[158:161], v[182:185], 0
	v_mfma_f32_16x16x32_bf16 v[24:27], v[166:169], v[182:185], 0
	v_mfma_f32_16x16x32_bf16 v[12:15], v[158:161], v[200:203], 0
	v_mfma_f32_16x16x32_bf16 v[8:11], v[166:169], v[200:203], 0
	v_mfma_f32_16x16x32_bf16 v[4:7], v[158:161], v[208:211], 0
	v_mfma_f32_16x16x32_bf16 v[0:3], v[166:169], v[208:211], 0
	v_mfma_f32_16x16x32_bf16 v[44:47], v[162:165], v[178:181], v[44:47]
	v_mfma_f32_16x16x32_bf16 v[40:43], v[170:173], v[178:181], v[40:43]
	v_mfma_f32_16x16x32_bf16 v[28:31], v[162:165], v[196:199], v[28:31]
	v_mfma_f32_16x16x32_bf16 v[24:27], v[170:173], v[196:199], v[24:27]
	v_mfma_f32_16x16x32_bf16 v[12:15], v[162:165], v[204:207], v[12:15]
	v_mfma_f32_16x16x32_bf16 v[8:11], v[170:173], v[204:207], v[8:11]
	v_mfma_f32_16x16x32_bf16 v[4:7], v[162:165], v[212:215], v[4:7]
	v_mfma_f32_16x16x32_bf16 v[0:3], v[170:173], v[212:215], v[0:3]
	s_barrier
	s_setprio 0
	s_add_i32 s60, 0, 0x18000
	s_add_i32 s61, 0, 0x1c000
	v_add_u32_e32 v154, s60, v139
	v_add_u32_e32 v170, s61, v139
	ds_read_b128 v[142:145], v154
	ds_read_b128 v[146:149], v154 offset:1024
	ds_read_b128 v[150:153], v154 offset:2048
	ds_read_b128 v[154:157], v154 offset:3072
	ds_read_b128 v[158:161], v170
	ds_read_b128 v[162:165], v170 offset:1024
	ds_read_b128 v[166:169], v170 offset:2048
	ds_read_b128 v[170:173], v170 offset:3072
	s_add_u32 s34, s34, 0x80000
	s_addc_u32 s35, s35, 0
	s_mov_b32 m0, s41
	v_lshl_add_u64 v[222:223], s[34:35], 0, v[128:129]
	ds_read_b128 v[174:177], v141 offset:32768
	ds_read_b128 v[178:181], v141 offset:33792
	ds_read_b128 v[182:185], v141 offset:34816
	ds_read_b128 v[196:199], v141 offset:35840
	ds_read_b128 v[200:203], v141 offset:36864
	ds_read_b128 v[204:207], v141 offset:37888
	ds_read_b128 v[208:211], v141 offset:38912
	ds_read_b128 v[212:215], v141 offset:39936
	global_load_lds_dwordx4 v[222:223], off
	s_mov_b32 m0, s42
	v_lshl_add_u64 v[222:223], s[34:35], 0, v[130:131]
	global_load_lds_dwordx4 v[222:223], off
	s_waitcnt vmcnt(8) lgkmcnt(0)
	s_setprio 1
	s_barrier
	v_mfma_f32_16x16x32_bf16 v[124:127], v[142:145], v[174:177], v[124:127]
	v_mfma_f32_16x16x32_bf16 v[120:123], v[150:153], v[174:177], v[120:123]
	v_mfma_f32_16x16x32_bf16 v[116:119], v[142:145], v[182:185], v[116:119]
	v_mfma_f32_16x16x32_bf16 v[112:115], v[150:153], v[182:185], v[112:115]
	v_mfma_f32_16x16x32_bf16 v[100:103], v[142:145], v[200:203], v[100:103]
	v_mfma_f32_16x16x32_bf16 v[96:99], v[150:153], v[200:203], v[96:99]
	v_mfma_f32_16x16x32_bf16 v[84:87], v[142:145], v[208:211], v[84:87]
	v_mfma_f32_16x16x32_bf16 v[80:83], v[150:153], v[208:211], v[80:83]
	v_mfma_f32_16x16x32_bf16 v[124:127], v[146:149], v[178:181], v[124:127]
	v_mfma_f32_16x16x32_bf16 v[120:123], v[154:157], v[178:181], v[120:123]
	v_mfma_f32_16x16x32_bf16 v[116:119], v[146:149], v[196:199], v[116:119]
	v_mfma_f32_16x16x32_bf16 v[112:115], v[154:157], v[196:199], v[112:115]
	v_mfma_f32_16x16x32_bf16 v[100:103], v[146:149], v[204:207], v[100:103]
	v_mfma_f32_16x16x32_bf16 v[96:99], v[154:157], v[204:207], v[96:99]
	v_mfma_f32_16x16x32_bf16 v[84:87], v[146:149], v[212:215], v[84:87]
	v_mfma_f32_16x16x32_bf16 v[80:83], v[154:157], v[212:215], v[80:83]
	s_setprio 0
	s_setprio 1
	v_mfma_f32_16x16x32_bf16 v[108:111], v[158:161], v[174:177], v[108:111]
	v_mfma_f32_16x16x32_bf16 v[104:107], v[166:169], v[174:177], v[104:107]
	v_mfma_f32_16x16x32_bf16 v[92:95], v[158:161], v[182:185], v[92:95]
	v_mfma_f32_16x16x32_bf16 v[88:91], v[166:169], v[182:185], v[88:91]
	v_mfma_f32_16x16x32_bf16 v[76:79], v[158:161], v[200:203], v[76:79]
	v_mfma_f32_16x16x32_bf16 v[72:75], v[166:169], v[200:203], v[72:75]
	v_mfma_f32_16x16x32_bf16 v[68:71], v[158:161], v[208:211], v[68:71]
	v_mfma_f32_16x16x32_bf16 v[64:67], v[166:169], v[208:211], v[64:67]
	v_mfma_f32_16x16x32_bf16 v[108:111], v[162:165], v[178:181], v[108:111]
	v_mfma_f32_16x16x32_bf16 v[104:107], v[170:173], v[178:181], v[104:107]
	v_mfma_f32_16x16x32_bf16 v[92:95], v[162:165], v[196:199], v[92:95]
	v_mfma_f32_16x16x32_bf16 v[88:91], v[170:173], v[196:199], v[88:91]
	v_mfma_f32_16x16x32_bf16 v[76:79], v[162:165], v[204:207], v[76:79]
	v_mfma_f32_16x16x32_bf16 v[72:75], v[170:173], v[204:207], v[72:75]
	v_mfma_f32_16x16x32_bf16 v[68:71], v[162:165], v[212:215], v[68:71]
	v_mfma_f32_16x16x32_bf16 v[64:67], v[170:173], v[212:215], v[64:67]
	s_barrier
	s_setprio 0
	s_add_i32 s34, s60, s38
	v_lshl_add_u64 v[186:187], v[186:187], 0, s[58:59]
	s_mov_b32 m0, s34
	ds_read_b128 v[174:177], v141 offset:49152
	ds_read_b128 v[178:181], v141 offset:50176
	ds_read_b128 v[182:185], v141 offset:51200
	ds_read_b128 v[196:199], v141 offset:52224
	ds_read_b128 v[200:203], v141 offset:53248
	ds_read_b128 v[204:207], v141 offset:54272
	ds_read_b128 v[208:211], v141 offset:55296
	ds_read_b128 v[212:215], v141 offset:56320
	global_load_lds_dwordx4 v[186:187], off
	s_add_i32 m0, s34, 0x2000
	s_add_u32 s30, s30, 0x80080
	v_lshl_add_u64 v[186:187], v[216:217], 0, s[58:59]
	s_addc_u32 s31, s31, 0
	s_add_i32 s34, s61, s38
	global_load_lds_dwordx4 v[186:187], off
	s_mov_b32 m0, s34
	v_lshl_add_u64 v[186:187], s[30:31], 0, v[190:191]
	global_load_lds_dwordx4 v[186:187], off
	s_add_i32 m0, s34, 0x2000
	v_lshl_add_u64 v[186:187], s[30:31], 0, v[132:133]
	global_load_lds_dwordx4 v[186:187], off
	s_mov_b32 m0, s43
	v_lshl_add_u64 v[186:187], v[218:219], 0, s[58:59]
	global_load_lds_dwordx4 v[186:187], off
	s_mov_b32 m0, s47
	v_lshl_add_u64 v[186:187], v[220:221], 0, s[58:59]
	global_load_lds_dwordx4 v[186:187], off
	s_waitcnt vmcnt(8) lgkmcnt(0)
	s_setprio 1
	s_barrier
	v_mfma_f32_16x16x32_bf16 v[60:63], v[142:145], v[174:177], v[60:63]
	v_mfma_f32_16x16x32_bf16 v[56:59], v[150:153], v[174:177], v[56:59]
	v_mfma_f32_16x16x32_bf16 v[52:55], v[142:145], v[182:185], v[52:55]
	v_mfma_f32_16x16x32_bf16 v[48:51], v[150:153], v[182:185], v[48:51]
	v_mfma_f32_16x16x32_bf16 v[36:39], v[142:145], v[200:203], v[36:39]
	v_mfma_f32_16x16x32_bf16 v[32:35], v[150:153], v[200:203], v[32:35]
	v_mfma_f32_16x16x32_bf16 v[20:23], v[142:145], v[208:211], v[20:23]
	v_mfma_f32_16x16x32_bf16 v[16:19], v[150:153], v[208:211], v[16:19]
	v_mfma_f32_16x16x32_bf16 v[60:63], v[146:149], v[178:181], v[60:63]
	v_mfma_f32_16x16x32_bf16 v[56:59], v[154:157], v[178:181], v[56:59]
	v_mfma_f32_16x16x32_bf16 v[52:55], v[146:149], v[196:199], v[52:55]
	v_mfma_f32_16x16x32_bf16 v[48:51], v[154:157], v[196:199], v[48:51]
	v_mfma_f32_16x16x32_bf16 v[36:39], v[146:149], v[204:207], v[36:39]
	v_mfma_f32_16x16x32_bf16 v[32:35], v[154:157], v[204:207], v[32:35]
	v_mfma_f32_16x16x32_bf16 v[20:23], v[146:149], v[212:215], v[20:23]
	v_mfma_f32_16x16x32_bf16 v[16:19], v[154:157], v[212:215], v[16:19]
	s_setprio 0
	s_setprio 1
	v_mfma_f32_16x16x32_bf16 v[44:47], v[158:161], v[174:177], v[44:47]
	v_mfma_f32_16x16x32_bf16 v[40:43], v[166:169], v[174:177], v[40:43]
	v_mfma_f32_16x16x32_bf16 v[28:31], v[158:161], v[182:185], v[28:31]
	v_mfma_f32_16x16x32_bf16 v[24:27], v[166:169], v[182:185], v[24:27]
	v_mfma_f32_16x16x32_bf16 v[12:15], v[158:161], v[200:203], v[12:15]
	v_mfma_f32_16x16x32_bf16 v[8:11], v[166:169], v[200:203], v[8:11]
	v_mfma_f32_16x16x32_bf16 v[4:7], v[158:161], v[208:211], v[4:7]
	v_mfma_f32_16x16x32_bf16 v[0:3], v[166:169], v[208:211], v[0:3]
	v_mfma_f32_16x16x32_bf16 v[44:47], v[162:165], v[178:181], v[44:47]
	v_mfma_f32_16x16x32_bf16 v[40:43], v[170:173], v[178:181], v[40:43]
	v_mfma_f32_16x16x32_bf16 v[28:31], v[162:165], v[196:199], v[28:31]
	v_mfma_f32_16x16x32_bf16 v[24:27], v[170:173], v[196:199], v[24:27]
	v_mfma_f32_16x16x32_bf16 v[12:15], v[162:165], v[204:207], v[12:15]
	v_mfma_f32_16x16x32_bf16 v[8:11], v[170:173], v[204:207], v[8:11]
	v_mfma_f32_16x16x32_bf16 v[4:7], v[162:165], v[212:215], v[4:7]
	v_mfma_f32_16x16x32_bf16 v[0:3], v[170:173], v[212:215], v[0:3]
	s_barrier
	s_setprio 0
	s_add_i32 s57, s57, 2
	s_add_u32 s28, s28, 0x100
	s_addc_u32 s29, s29, 0
	s_add_u32 s55, s55, 0x100
	s_addc_u32 s56, s56, 0
	s_cmp_gt_u32 s57, 29
	s_cbranch_scc1 .Lpeel_done_6
.LBB0_938:
	s_add_u32 s30, s28, 0xfff80080
	s_addc_u32 s31, s29, -1
	s_add_i32 s60, 0, 0x10000
	s_cmp_eq_u32 s57, 28
	s_cselect_b32 s35, s11, s31
	s_cselect_b32 s34, s23, s30
	s_cselect_b32 s31, s21, s56
	s_cselect_b32 s30, s53, s55
	s_add_i32 s66, 0, 0x14000
	v_add_u32_e32 v154, s60, v139
	v_add_u32_e32 v170, s66, v139
	ds_read_b128 v[142:145], v154
	ds_read_b128 v[146:149], v154 offset:1024
	ds_read_b128 v[150:153], v154 offset:2048
	ds_read_b128 v[154:157], v154 offset:3072
	ds_read_b128 v[158:161], v170
	ds_read_b128 v[162:165], v170 offset:1024
	ds_read_b128 v[166:169], v170 offset:2048
	ds_read_b128 v[170:173], v170 offset:3072
	v_lshl_add_u64 v[186:187], s[28:29], 0, v[134:135]
	s_add_i32 m0, s13, 0xc000
	ds_read_b128 v[174:177], v141
	ds_read_b128 v[178:181], v141 offset:1024
	ds_read_b128 v[182:185], v141 offset:2048
	ds_read_b128 v[196:199], v141 offset:3072
	ds_read_b128 v[200:203], v141 offset:4096
	ds_read_b128 v[204:207], v141 offset:5120
	ds_read_b128 v[208:211], v141 offset:6144
	ds_read_b128 v[212:215], v141 offset:7168
	global_load_lds_dwordx4 v[186:187], off
	s_add_i32 m0, s13, 0xe000
	v_lshl_add_u64 v[186:187], s[28:29], 0, v[136:137]
	global_load_lds_dwordx4 v[186:187], off
	s_waitcnt vmcnt(8) lgkmcnt(0)
	s_setprio 1
	s_barrier
	v_mfma_f32_16x16x32_bf16 v[124:127], v[142:145], v[174:177], v[124:127]
	v_mfma_f32_16x16x32_bf16 v[120:123], v[150:153], v[174:177], v[120:123]
	v_mfma_f32_16x16x32_bf16 v[116:119], v[142:145], v[182:185], v[116:119]
	v_mfma_f32_16x16x32_bf16 v[112:115], v[150:153], v[182:185], v[112:115]
	v_mfma_f32_16x16x32_bf16 v[100:103], v[142:145], v[200:203], v[100:103]
	v_mfma_f32_16x16x32_bf16 v[96:99], v[150:153], v[200:203], v[96:99]
	v_mfma_f32_16x16x32_bf16 v[84:87], v[142:145], v[208:211], v[84:87]
	v_mfma_f32_16x16x32_bf16 v[80:83], v[150:153], v[208:211], v[80:83]
	v_mfma_f32_16x16x32_bf16 v[124:127], v[146:149], v[178:181], v[124:127]
	v_mfma_f32_16x16x32_bf16 v[120:123], v[154:157], v[178:181], v[120:123]
	v_mfma_f32_16x16x32_bf16 v[116:119], v[146:149], v[196:199], v[116:119]
	v_mfma_f32_16x16x32_bf16 v[112:115], v[154:157], v[196:199], v[112:115]
	v_mfma_f32_16x16x32_bf16 v[100:103], v[146:149], v[204:207], v[100:103]
	v_mfma_f32_16x16x32_bf16 v[96:99], v[154:157], v[204:207], v[96:99]
	v_mfma_f32_16x16x32_bf16 v[84:87], v[146:149], v[212:215], v[84:87]
	v_mfma_f32_16x16x32_bf16 v[80:83], v[154:157], v[212:215], v[80:83]
	s_setprio 0
	s_setprio 1
	v_mfma_f32_16x16x32_bf16 v[108:111], v[158:161], v[174:177], v[108:111]
	v_mfma_f32_16x16x32_bf16 v[104:107], v[166:169], v[174:177], v[104:107]
	v_mfma_f32_16x16x32_bf16 v[92:95], v[158:161], v[182:185], v[92:95]
	v_mfma_f32_16x16x32_bf16 v[88:91], v[166:169], v[182:185], v[88:91]
	v_mfma_f32_16x16x32_bf16 v[76:79], v[158:161], v[200:203], v[76:79]
	v_mfma_f32_16x16x32_bf16 v[72:75], v[166:169], v[200:203], v[72:75]
	v_mfma_f32_16x16x32_bf16 v[68:71], v[158:161], v[208:211], v[68:71]
	v_mfma_f32_16x16x32_bf16 v[64:67], v[166:169], v[208:211], v[64:67]
	v_mfma_f32_16x16x32_bf16 v[108:111], v[162:165], v[178:181], v[108:111]
	v_mfma_f32_16x16x32_bf16 v[104:107], v[170:173], v[178:181], v[104:107]
	v_mfma_f32_16x16x32_bf16 v[92:95], v[162:165], v[196:199], v[92:95]
	v_mfma_f32_16x16x32_bf16 v[88:91], v[170:173], v[196:199], v[88:91]
	v_mfma_f32_16x16x32_bf16 v[76:79], v[162:165], v[204:207], v[76:79]
	v_mfma_f32_16x16x32_bf16 v[72:75], v[170:173], v[204:207], v[72:75]
	v_mfma_f32_16x16x32_bf16 v[68:71], v[162:165], v[212:215], v[68:71]
	v_mfma_f32_16x16x32_bf16 v[64:67], v[170:173], v[212:215], v[64:67]
	s_setprio 0
	s_barrier
	s_add_i32 s60, s60, s38
	v_lshl_add_u64 v[186:187], s[30:31], 0, v[190:191]
	s_mov_b32 m0, s60
	ds_read_b128 v[174:177], v141 offset:16384
	ds_read_b128 v[178:181], v141 offset:17408
	ds_read_b128 v[182:185], v141 offset:18432
	ds_read_b128 v[196:199], v141 offset:19456
	ds_read_b128 v[200:203], v141 offset:20480
	ds_read_b128 v[204:207], v141 offset:21504
	ds_read_b128 v[208:211], v141 offset:22528
	ds_read_b128 v[212:215], v141 offset:23552
	global_load_lds_dwordx4 v[186:187], off
	s_add_i32 m0, s60, 0x2000
	s_add_u32 s60, s30, 0x80000
	v_lshl_add_u64 v[216:217], s[30:31], 0, v[132:133]
	s_addc_u32 s61, s31, 0
	s_add_i32 s66, s66, s38
	global_load_lds_dwordx4 v[216:217], off
	v_lshl_add_u64 v[218:219], s[60:61], 0, v[190:191]
	s_mov_b32 m0, s66
	v_lshl_add_u64 v[220:221], s[34:35], 0, v[130:131]
	global_load_lds_dwordx4 v[218:219], off
	s_add_i32 m0, s66, 0x2000
	v_lshl_add_u64 v[218:219], s[60:61], 0, v[132:133]
	global_load_lds_dwordx4 v[218:219], off
	s_mov_b32 m0, s13
	v_lshl_add_u64 v[218:219], s[34:35], 0, v[128:129]
	global_load_lds_dwordx4 v[218:219], off
	s_mov_b32 m0, s39
	s_nop 0
	global_load_lds_dwordx4 v[220:221], off
	s_waitcnt vmcnt(8) lgkmcnt(0)
	s_setprio 1
	s_barrier
	v_mfma_f32_16x16x32_bf16 v[60:63], v[142:145], v[174:177], v[60:63]
	v_mfma_f32_16x16x32_bf16 v[56:59], v[150:153], v[174:177], v[56:59]
	v_mfma_f32_16x16x32_bf16 v[52:55], v[142:145], v[182:185], v[52:55]
	v_mfma_f32_16x16x32_bf16 v[48:51], v[150:153], v[182:185], v[48:51]
	v_mfma_f32_16x16x32_bf16 v[36:39], v[142:145], v[200:203], v[36:39]
	v_mfma_f32_16x16x32_bf16 v[32:35], v[150:153], v[200:203], v[32:35]
	v_mfma_f32_16x16x32_bf16 v[20:23], v[142:145], v[208:211], v[20:23]
	v_mfma_f32_16x16x32_bf16 v[16:19], v[150:153], v[208:211], v[16:19]
	v_mfma_f32_16x16x32_bf16 v[60:63], v[146:149], v[178:181], v[60:63]
	v_mfma_f32_16x16x32_bf16 v[56:59], v[154:157], v[178:181], v[56:59]
	v_mfma_f32_16x16x32_bf16 v[52:55], v[146:149], v[196:199], v[52:55]
	v_mfma_f32_16x16x32_bf16 v[48:51], v[154:157], v[196:199], v[48:51]
	v_mfma_f32_16x16x32_bf16 v[36:39], v[146:149], v[204:207], v[36:39]
	v_mfma_f32_16x16x32_bf16 v[32:35], v[154:157], v[204:207], v[32:35]
	v_mfma_f32_16x16x32_bf16 v[20:23], v[146:149], v[212:215], v[20:23]
	v_mfma_f32_16x16x32_bf16 v[16:19], v[154:157], v[212:215], v[16:19]
	s_setprio 0
	s_setprio 1
	v_mfma_f32_16x16x32_bf16 v[44:47], v[158:161], v[174:177], v[44:47]
	v_mfma_f32_16x16x32_bf16 v[40:43], v[166:169], v[174:177], v[40:43]
	v_mfma_f32_16x16x32_bf16 v[28:31], v[158:161], v[182:185], v[28:31]
	v_mfma_f32_16x16x32_bf16 v[24:27], v[166:169], v[182:185], v[24:27]
	v_mfma_f32_16x16x32_bf16 v[12:15], v[158:161], v[200:203], v[12:15]
	v_mfma_f32_16x16x32_bf16 v[8:11], v[166:169], v[200:203], v[8:11]
	v_mfma_f32_16x16x32_bf16 v[4:7], v[158:161], v[208:211], v[4:7]
	v_mfma_f32_16x16x32_bf16 v[0:3], v[166:169], v[208:211], v[0:3]
	v_mfma_f32_16x16x32_bf16 v[44:47], v[162:165], v[178:181], v[44:47]
	v_mfma_f32_16x16x32_bf16 v[40:43], v[170:173], v[178:181], v[40:43]
	v_mfma_f32_16x16x32_bf16 v[28:31], v[162:165], v[196:199], v[28:31]
	v_mfma_f32_16x16x32_bf16 v[24:27], v[170:173], v[196:199], v[24:27]
	v_mfma_f32_16x16x32_bf16 v[12:15], v[162:165], v[204:207], v[12:15]
	v_mfma_f32_16x16x32_bf16 v[8:11], v[170:173], v[204:207], v[8:11]
	v_mfma_f32_16x16x32_bf16 v[4:7], v[162:165], v[212:215], v[4:7]
	v_mfma_f32_16x16x32_bf16 v[0:3], v[170:173], v[212:215], v[0:3]
	s_setprio 0
	s_barrier
	s_add_i32 s60, 0, 0x18000
	s_add_i32 s61, 0, 0x1c000
	v_add_u32_e32 v154, s60, v139
	v_add_u32_e32 v170, s61, v139
	ds_read_b128 v[142:145], v154
	ds_read_b128 v[146:149], v154 offset:1024
	ds_read_b128 v[150:153], v154 offset:2048
	ds_read_b128 v[154:157], v154 offset:3072
	ds_read_b128 v[158:161], v170
	ds_read_b128 v[162:165], v170 offset:1024
	ds_read_b128 v[166:169], v170 offset:2048
	ds_read_b128 v[170:173], v170 offset:3072
	s_add_u32 s34, s34, 0x80000
	s_addc_u32 s35, s35, 0
	s_mov_b32 m0, s41
	v_lshl_add_u64 v[222:223], s[34:35], 0, v[128:129]
	ds_read_b128 v[174:177], v141 offset:32768
	ds_read_b128 v[178:181], v141 offset:33792
	ds_read_b128 v[182:185], v141 offset:34816
	ds_read_b128 v[196:199], v141 offset:35840
	ds_read_b128 v[200:203], v141 offset:36864
	ds_read_b128 v[204:207], v141 offset:37888
	ds_read_b128 v[208:211], v141 offset:38912
	ds_read_b128 v[212:215], v141 offset:39936
	global_load_lds_dwordx4 v[222:223], off
	s_mov_b32 m0, s42
	v_lshl_add_u64 v[222:223], s[34:35], 0, v[130:131]
	global_load_lds_dwordx4 v[222:223], off
	s_waitcnt vmcnt(8) lgkmcnt(0)
	s_setprio 1
	s_barrier
	v_mfma_f32_16x16x32_bf16 v[124:127], v[142:145], v[174:177], v[124:127]
	v_mfma_f32_16x16x32_bf16 v[120:123], v[150:153], v[174:177], v[120:123]
	v_mfma_f32_16x16x32_bf16 v[116:119], v[142:145], v[182:185], v[116:119]
	v_mfma_f32_16x16x32_bf16 v[112:115], v[150:153], v[182:185], v[112:115]
	v_mfma_f32_16x16x32_bf16 v[100:103], v[142:145], v[200:203], v[100:103]
	v_mfma_f32_16x16x32_bf16 v[96:99], v[150:153], v[200:203], v[96:99]
	v_mfma_f32_16x16x32_bf16 v[84:87], v[142:145], v[208:211], v[84:87]
	v_mfma_f32_16x16x32_bf16 v[80:83], v[150:153], v[208:211], v[80:83]
	v_mfma_f32_16x16x32_bf16 v[124:127], v[146:149], v[178:181], v[124:127]
	v_mfma_f32_16x16x32_bf16 v[120:123], v[154:157], v[178:181], v[120:123]
	v_mfma_f32_16x16x32_bf16 v[116:119], v[146:149], v[196:199], v[116:119]
	v_mfma_f32_16x16x32_bf16 v[112:115], v[154:157], v[196:199], v[112:115]
	v_mfma_f32_16x16x32_bf16 v[100:103], v[146:149], v[204:207], v[100:103]
	v_mfma_f32_16x16x32_bf16 v[96:99], v[154:157], v[204:207], v[96:99]
	v_mfma_f32_16x16x32_bf16 v[84:87], v[146:149], v[212:215], v[84:87]
	v_mfma_f32_16x16x32_bf16 v[80:83], v[154:157], v[212:215], v[80:83]
	s_setprio 0
	s_setprio 1
	v_mfma_f32_16x16x32_bf16 v[108:111], v[158:161], v[174:177], v[108:111]
	v_mfma_f32_16x16x32_bf16 v[104:107], v[166:169], v[174:177], v[104:107]
	v_mfma_f32_16x16x32_bf16 v[92:95], v[158:161], v[182:185], v[92:95]
	v_mfma_f32_16x16x32_bf16 v[88:91], v[166:169], v[182:185], v[88:91]
	v_mfma_f32_16x16x32_bf16 v[76:79], v[158:161], v[200:203], v[76:79]
	v_mfma_f32_16x16x32_bf16 v[72:75], v[166:169], v[200:203], v[72:75]
	v_mfma_f32_16x16x32_bf16 v[68:71], v[158:161], v[208:211], v[68:71]
	v_mfma_f32_16x16x32_bf16 v[64:67], v[166:169], v[208:211], v[64:67]
	v_mfma_f32_16x16x32_bf16 v[108:111], v[162:165], v[178:181], v[108:111]
	v_mfma_f32_16x16x32_bf16 v[104:107], v[170:173], v[178:181], v[104:107]
	v_mfma_f32_16x16x32_bf16 v[92:95], v[162:165], v[196:199], v[92:95]
	v_mfma_f32_16x16x32_bf16 v[88:91], v[170:173], v[196:199], v[88:91]
	v_mfma_f32_16x16x32_bf16 v[76:79], v[162:165], v[204:207], v[76:79]
	v_mfma_f32_16x16x32_bf16 v[72:75], v[170:173], v[204:207], v[72:75]
	v_mfma_f32_16x16x32_bf16 v[68:71], v[162:165], v[212:215], v[68:71]
	v_mfma_f32_16x16x32_bf16 v[64:67], v[170:173], v[212:215], v[64:67]
	s_setprio 0
	s_barrier
	s_add_i32 s34, s60, s38
	v_lshl_add_u64 v[186:187], v[186:187], 0, s[58:59]
	s_mov_b32 m0, s34
	ds_read_b128 v[174:177], v141 offset:49152
	ds_read_b128 v[178:181], v141 offset:50176
	ds_read_b128 v[182:185], v141 offset:51200
	ds_read_b128 v[196:199], v141 offset:52224
	ds_read_b128 v[200:203], v141 offset:53248
	ds_read_b128 v[204:207], v141 offset:54272
	ds_read_b128 v[208:211], v141 offset:55296
	ds_read_b128 v[212:215], v141 offset:56320
	global_load_lds_dwordx4 v[186:187], off
	s_add_i32 m0, s34, 0x2000
	s_add_u32 s30, s30, 0x80080
	v_lshl_add_u64 v[186:187], v[216:217], 0, s[58:59]
	s_addc_u32 s31, s31, 0
	s_add_i32 s34, s61, s38
	global_load_lds_dwordx4 v[186:187], off
	s_mov_b32 m0, s34
	v_lshl_add_u64 v[186:187], s[30:31], 0, v[190:191]
	global_load_lds_dwordx4 v[186:187], off
	s_add_i32 m0, s34, 0x2000
	v_lshl_add_u64 v[186:187], s[30:31], 0, v[132:133]
	global_load_lds_dwordx4 v[186:187], off
	s_mov_b32 m0, s43
	v_lshl_add_u64 v[186:187], v[218:219], 0, s[58:59]
	global_load_lds_dwordx4 v[186:187], off
	s_mov_b32 m0, s47
	v_lshl_add_u64 v[186:187], v[220:221], 0, s[58:59]
	global_load_lds_dwordx4 v[186:187], off
	s_waitcnt vmcnt(8) lgkmcnt(0)
	s_setprio 1
	s_barrier
	v_mfma_f32_16x16x32_bf16 v[60:63], v[142:145], v[174:177], v[60:63]
	v_mfma_f32_16x16x32_bf16 v[56:59], v[150:153], v[174:177], v[56:59]
	v_mfma_f32_16x16x32_bf16 v[52:55], v[142:145], v[182:185], v[52:55]
	v_mfma_f32_16x16x32_bf16 v[48:51], v[150:153], v[182:185], v[48:51]
	v_mfma_f32_16x16x32_bf16 v[36:39], v[142:145], v[200:203], v[36:39]
	v_mfma_f32_16x16x32_bf16 v[32:35], v[150:153], v[200:203], v[32:35]
	v_mfma_f32_16x16x32_bf16 v[20:23], v[142:145], v[208:211], v[20:23]
	v_mfma_f32_16x16x32_bf16 v[16:19], v[150:153], v[208:211], v[16:19]
	v_mfma_f32_16x16x32_bf16 v[60:63], v[146:149], v[178:181], v[60:63]
	v_mfma_f32_16x16x32_bf16 v[56:59], v[154:157], v[178:181], v[56:59]
	v_mfma_f32_16x16x32_bf16 v[52:55], v[146:149], v[196:199], v[52:55]
	v_mfma_f32_16x16x32_bf16 v[48:51], v[154:157], v[196:199], v[48:51]
	v_mfma_f32_16x16x32_bf16 v[36:39], v[146:149], v[204:207], v[36:39]
	v_mfma_f32_16x16x32_bf16 v[32:35], v[154:157], v[204:207], v[32:35]
	v_mfma_f32_16x16x32_bf16 v[20:23], v[146:149], v[212:215], v[20:23]
	v_mfma_f32_16x16x32_bf16 v[16:19], v[154:157], v[212:215], v[16:19]
	s_setprio 0
	s_setprio 1
	v_mfma_f32_16x16x32_bf16 v[44:47], v[158:161], v[174:177], v[44:47]
	v_mfma_f32_16x16x32_bf16 v[40:43], v[166:169], v[174:177], v[40:43]
	v_mfma_f32_16x16x32_bf16 v[28:31], v[158:161], v[182:185], v[28:31]
	v_mfma_f32_16x16x32_bf16 v[24:27], v[166:169], v[182:185], v[24:27]
	v_mfma_f32_16x16x32_bf16 v[12:15], v[158:161], v[200:203], v[12:15]
	v_mfma_f32_16x16x32_bf16 v[8:11], v[166:169], v[200:203], v[8:11]
	v_mfma_f32_16x16x32_bf16 v[4:7], v[158:161], v[208:211], v[4:7]
	v_mfma_f32_16x16x32_bf16 v[0:3], v[166:169], v[208:211], v[0:3]
	v_mfma_f32_16x16x32_bf16 v[44:47], v[162:165], v[178:181], v[44:47]
	v_mfma_f32_16x16x32_bf16 v[40:43], v[170:173], v[178:181], v[40:43]
	v_mfma_f32_16x16x32_bf16 v[28:31], v[162:165], v[196:199], v[28:31]
	v_mfma_f32_16x16x32_bf16 v[24:27], v[170:173], v[196:199], v[24:27]
	v_mfma_f32_16x16x32_bf16 v[12:15], v[162:165], v[204:207], v[12:15]
	v_mfma_f32_16x16x32_bf16 v[8:11], v[170:173], v[204:207], v[8:11]
	v_mfma_f32_16x16x32_bf16 v[4:7], v[162:165], v[212:215], v[4:7]
	v_mfma_f32_16x16x32_bf16 v[0:3], v[170:173], v[212:215], v[0:3]
	s_setprio 0
	s_barrier
	s_add_i32 s57, s57, 2
	s_add_u32 s28, s28, 0x100
	s_addc_u32 s29, s29, 0
	s_add_u32 s55, s55, 0x100
	s_addc_u32 s56, s56, 0
	s_cmp_gt_u32 s57, 29
	s_cbranch_scc0 .LBB0_938

.LBB0_1104:
	s_ashr_i32 s61, s60, 31
	s_lshl_b64 s[52:53], s[60:61], 20
	v_readlane_b32 s0, v254, 17
	v_readlane_b32 s1, v254, 18
	s_add_u32 s88, s0, s52
	s_addc_u32 s89, s1, s53
	s_and_b64 s[52:53], s[8:9], exec
	s_cselect_b32 s13, s89, s11
	s_cselect_b32 s15, s88, s10
	s_ashr_i32 s57, s56, 31
	s_lshl_b64 s[52:53], s[56:57], 20
	v_readlane_b32 s0, v254, 36
	v_readlane_b32 s1, v254, 37
	s_add_u32 s90, s0, s52
	s_addc_u32 s91, s1, s53
	s_and_b64 s[52:53], s[8:9], exec
	s_cselect_b32 s57, s91, s17
	s_cselect_b32 s61, s90, s16
	s_add_u32 s66, s16, 0x100
	s_addc_u32 s67, s17, 0
	s_mov_b32 vcc_lo, -2
	v_readlane_b32 s0, v255, 49
	s_nop 3
	s_cmp_eq_u32 s0, 8
	v_writelane_b32 v255, 8, 49
	s_cbranch_scc0 .Ltrip0_strict_7
	s_add_u32 s16, s10, 0x100
	s_addc_u32 s17, s11, 0
	s_add_i32 vcc_hi, 0, 0x10000
	s_cmp_eq_u32 vcc_lo, 28
	s_cselect_b32 s69, s13, s17
	s_cselect_b32 s68, s15, s16
	s_cselect_b32 s53, s57, s67
	s_cselect_b32 s52, s61, s66
	s_add_i32 s0, 0, 0x14000
	v_add_u32_e32 v140, vcc_hi, v200
	v_add_u32_e32 v156, s0, v200
	ds_read_b128 v[128:131], v140
	ds_read_b128 v[132:135], v140 offset:1024
	ds_read_b128 v[136:139], v140 offset:2048
	ds_read_b128 v[140:143], v140 offset:3072
	ds_read_b128 v[144:147], v156
	ds_read_b128 v[148:151], v156 offset:1024
	ds_read_b128 v[152:155], v156 offset:2048
	ds_read_b128 v[156:159], v156 offset:3072
	v_lshl_add_u64 v[186:187], s[10:11], 0, v[182:183]
	s_add_i32 m0, s40, 0xc000
	ds_read_b128 v[160:163], v206
	ds_read_b128 v[164:167], v206 offset:1024
	ds_read_b128 v[168:171], v206 offset:2048
	ds_read_b128 v[172:175], v206 offset:3072
	ds_read_b128 v[196:199], v206 offset:4096
	ds_read_b128 v[208:211], v206 offset:5120
	ds_read_b128 v[212:215], v206 offset:6144
	ds_read_b128 v[216:219], v206 offset:7168
	global_load_lds_dwordx4 v[186:187], off
	s_add_i32 m0, s40, 0xe000
	v_lshl_add_u64 v[186:187], s[10:11], 0, v[184:185]
	global_load_lds_dwordx4 v[186:187], off
	s_waitcnt vmcnt(24) lgkmcnt(0)
	s_setprio 1
	s_barrier
	v_mfma_f32_16x16x32_bf16 v[120:123], v[128:131], v[160:163], 0
	v_mfma_f32_16x16x32_bf16 v[48:51], v[136:139], v[160:163], 0
	v_mfma_f32_16x16x32_bf16 v[124:127], v[128:131], v[168:171], 0
	v_mfma_f32_16x16x32_bf16 v[60:63], v[136:139], v[168:171], 0
	v_mfma_f32_16x16x32_bf16 v[112:115], v[128:131], v[196:199], 0
	v_mfma_f32_16x16x32_bf16 v[52:55], v[136:139], v[196:199], 0
	v_mfma_f32_16x16x32_bf16 v[108:111], v[128:131], v[212:215], 0
	v_mfma_f32_16x16x32_bf16 v[36:39], v[136:139], v[212:215], 0
	v_mfma_f32_16x16x32_bf16 v[120:123], v[132:135], v[164:167], v[120:123]
	v_mfma_f32_16x16x32_bf16 v[48:51], v[140:143], v[164:167], v[48:51]
	v_mfma_f32_16x16x32_bf16 v[124:127], v[132:135], v[172:175], v[124:127]
	v_mfma_f32_16x16x32_bf16 v[60:63], v[140:143], v[172:175], v[60:63]
	v_mfma_f32_16x16x32_bf16 v[112:115], v[132:135], v[208:211], v[112:115]
	v_mfma_f32_16x16x32_bf16 v[52:55], v[140:143], v[208:211], v[52:55]
	v_mfma_f32_16x16x32_bf16 v[108:111], v[132:135], v[216:219], v[108:111]
	v_mfma_f32_16x16x32_bf16 v[36:39], v[140:143], v[216:219], v[36:39]
	s_setprio 0
	s_setprio 1
	v_mfma_f32_16x16x32_bf16 v[100:103], v[144:147], v[160:163], 0
	v_mfma_f32_16x16x32_bf16 v[40:43], v[152:155], v[160:163], 0
	v_mfma_f32_16x16x32_bf16 v[116:119], v[144:147], v[168:171], 0
	v_mfma_f32_16x16x32_bf16 v[56:59], v[152:155], v[168:171], 0
	v_mfma_f32_16x16x32_bf16 v[104:107], v[144:147], v[196:199], 0
	v_mfma_f32_16x16x32_bf16 v[44:47], v[152:155], v[196:199], 0
	v_mfma_f32_16x16x32_bf16 v[96:99], v[144:147], v[212:215], 0
	v_mfma_f32_16x16x32_bf16 v[32:35], v[152:155], v[212:215], 0
	v_mfma_f32_16x16x32_bf16 v[100:103], v[148:151], v[164:167], v[100:103]
	v_mfma_f32_16x16x32_bf16 v[40:43], v[156:159], v[164:167], v[40:43]
	v_mfma_f32_16x16x32_bf16 v[116:119], v[148:151], v[172:175], v[116:119]
	v_mfma_f32_16x16x32_bf16 v[56:59], v[156:159], v[172:175], v[56:59]
	v_mfma_f32_16x16x32_bf16 v[104:107], v[148:151], v[208:211], v[104:107]
	v_mfma_f32_16x16x32_bf16 v[44:47], v[156:159], v[208:211], v[44:47]
	v_mfma_f32_16x16x32_bf16 v[96:99], v[148:151], v[216:219], v[96:99]
	v_mfma_f32_16x16x32_bf16 v[32:35], v[156:159], v[216:219], v[32:35]
	s_barrier
	s_setprio 0
	s_add_i32 s1, vcc_hi, s33
	v_lshl_add_u64 v[186:187], s[52:53], 0, v[190:191]
	s_mov_b32 m0, s1
	ds_read_b128 v[160:163], v206 offset:16384
	ds_read_b128 v[164:167], v206 offset:17408
	ds_read_b128 v[168:171], v206 offset:18432
	ds_read_b128 v[172:175], v206 offset:19456
	ds_read_b128 v[196:199], v206 offset:20480
	ds_read_b128 v[208:211], v206 offset:21504
	ds_read_b128 v[212:215], v206 offset:22528
	ds_read_b128 v[216:219], v206 offset:23552
	global_load_lds_dwordx4 v[186:187], off
	s_add_i32 m0, s1, 0x2000
	s_add_u32 s10, s52, 0x80000
	v_lshl_add_u64 v[220:221], s[52:53], 0, v[180:181]
	s_addc_u32 s11, s53, 0
	s_add_i32 s0, s0, s33
	global_load_lds_dwordx4 v[220:221], off
	v_lshl_add_u64 v[222:223], s[10:11], 0, v[190:191]
	s_mov_b32 m0, s0
	v_lshl_add_u64 v[224:225], s[68:69], 0, v[178:179]
	global_load_lds_dwordx4 v[222:223], off
	s_add_i32 m0, s0, 0x2000
	v_lshl_add_u64 v[222:223], s[10:11], 0, v[180:181]
	global_load_lds_dwordx4 v[222:223], off
	s_mov_b32 m0, s40
	v_lshl_add_u64 v[222:223], s[68:69], 0, v[176:177]
	global_load_lds_dwordx4 v[222:223], off
	s_mov_b32 m0, s41
	s_nop 0
	global_load_lds_dwordx4 v[224:225], off
	s_waitcnt vmcnt(24) lgkmcnt(0)
	s_setprio 1
	s_barrier
	v_mfma_f32_16x16x32_bf16 v[88:91], v[128:131], v[160:163], 0
	v_mfma_f32_16x16x32_bf16 v[20:23], v[136:139], v[160:163], 0
	v_mfma_f32_16x16x32_bf16 v[92:95], v[128:131], v[168:171], 0
	v_mfma_f32_16x16x32_bf16 v[28:31], v[136:139], v[168:171], 0
	v_mfma_f32_16x16x32_bf16 v[80:83], v[128:131], v[196:199], 0
	v_mfma_f32_16x16x32_bf16 v[16:19], v[136:139], v[196:199], 0
	v_mfma_f32_16x16x32_bf16 v[76:79], v[128:131], v[212:215], 0
	v_mfma_f32_16x16x32_bf16 v[12:15], v[136:139], v[212:215], 0
	v_mfma_f32_16x16x32_bf16 v[88:91], v[132:135], v[164:167], v[88:91]
	v_mfma_f32_16x16x32_bf16 v[20:23], v[140:143], v[164:167], v[20:23]
	v_mfma_f32_16x16x32_bf16 v[92:95], v[132:135], v[172:175], v[92:95]
	v_mfma_f32_16x16x32_bf16 v[28:31], v[140:143], v[172:175], v[28:31]
	v_mfma_f32_16x16x32_bf16 v[80:83], v[132:135], v[208:211], v[80:83]
	v_mfma_f32_16x16x32_bf16 v[16:19], v[140:143], v[208:211], v[16:19]
	v_mfma_f32_16x16x32_bf16 v[76:79], v[132:135], v[216:219], v[76:79]
	v_mfma_f32_16x16x32_bf16 v[12:15], v[140:143], v[216:219], v[12:15]
	s_setprio 0
	s_setprio 1
	v_mfma_f32_16x16x32_bf16 v[68:71], v[144:147], v[160:163], 0
	v_mfma_f32_16x16x32_bf16 v[4:7], v[152:155], v[160:163], 0
	v_mfma_f32_16x16x32_bf16 v[84:87], v[144:147], v[168:171], 0
	v_mfma_f32_16x16x32_bf16 v[24:27], v[152:155], v[168:171], 0
	v_mfma_f32_16x16x32_bf16 v[72:75], v[144:147], v[196:199], 0
	v_mfma_f32_16x16x32_bf16 v[8:11], v[152:155], v[196:199], 0
	v_mfma_f32_16x16x32_bf16 v[64:67], v[144:147], v[212:215], 0
	v_mfma_f32_16x16x32_bf16 v[0:3], v[152:155], v[212:215], 0
	v_mfma_f32_16x16x32_bf16 v[68:71], v[148:151], v[164:167], v[68:71]
	v_mfma_f32_16x16x32_bf16 v[4:7], v[156:159], v[164:167], v[4:7]
	v_mfma_f32_16x16x32_bf16 v[84:87], v[148:151], v[172:175], v[84:87]
	v_mfma_f32_16x16x32_bf16 v[24:27], v[156:159], v[172:175], v[24:27]
	v_mfma_f32_16x16x32_bf16 v[72:75], v[148:151], v[208:211], v[72:75]
	v_mfma_f32_16x16x32_bf16 v[8:11], v[156:159], v[208:211], v[8:11]
	v_mfma_f32_16x16x32_bf16 v[64:67], v[148:151], v[216:219], v[64:67]
	v_mfma_f32_16x16x32_bf16 v[0:3], v[156:159], v[216:219], v[0:3]
	s_barrier
	s_setprio 0
	s_add_i32 s0, 0, 0x18000
	s_add_i32 s1, 0, 0x1c000
	v_add_u32_e32 v140, s0, v200
	v_add_u32_e32 v156, s1, v200
	ds_read_b128 v[128:131], v140
	ds_read_b128 v[132:135], v140 offset:1024
	ds_read_b128 v[136:139], v140 offset:2048
	ds_read_b128 v[140:143], v140 offset:3072
	ds_read_b128 v[144:147], v156
	ds_read_b128 v[148:151], v156 offset:1024
	ds_read_b128 v[152:155], v156 offset:2048
	ds_read_b128 v[156:159], v156 offset:3072
	s_add_u32 s10, s68, 0x80000
	s_addc_u32 s11, s69, 0
	s_mov_b32 m0, s42
	v_lshl_add_u64 v[226:227], s[10:11], 0, v[176:177]
	ds_read_b128 v[160:163], v206 offset:32768
	ds_read_b128 v[164:167], v206 offset:33792
	ds_read_b128 v[168:171], v206 offset:34816
	ds_read_b128 v[172:175], v206 offset:35840
	ds_read_b128 v[196:199], v206 offset:36864
	ds_read_b128 v[208:211], v206 offset:37888
	ds_read_b128 v[212:215], v206 offset:38912
	ds_read_b128 v[216:219], v206 offset:39936
	global_load_lds_dwordx4 v[226:227], off
	s_mov_b32 m0, s43
	v_lshl_add_u64 v[226:227], s[10:11], 0, v[178:179]
	global_load_lds_dwordx4 v[226:227], off
	s_waitcnt vmcnt(8) lgkmcnt(0)
	s_setprio 1
	s_barrier
	v_mfma_f32_16x16x32_bf16 v[120:123], v[128:131], v[160:163], v[120:123]
	v_mfma_f32_16x16x32_bf16 v[48:51], v[136:139], v[160:163], v[48:51]
	v_mfma_f32_16x16x32_bf16 v[124:127], v[128:131], v[168:171], v[124:127]
	v_mfma_f32_16x16x32_bf16 v[60:63], v[136:139], v[168:171], v[60:63]
	v_mfma_f32_16x16x32_bf16 v[112:115], v[128:131], v[196:199], v[112:115]
	v_mfma_f32_16x16x32_bf16 v[52:55], v[136:139], v[196:199], v[52:55]
	v_mfma_f32_16x16x32_bf16 v[108:111], v[128:131], v[212:215], v[108:111]
	v_mfma_f32_16x16x32_bf16 v[36:39], v[136:139], v[212:215], v[36:39]
	v_mfma_f32_16x16x32_bf16 v[120:123], v[132:135], v[164:167], v[120:123]
	v_mfma_f32_16x16x32_bf16 v[48:51], v[140:143], v[164:167], v[48:51]
	v_mfma_f32_16x16x32_bf16 v[124:127], v[132:135], v[172:175], v[124:127]
	v_mfma_f32_16x16x32_bf16 v[60:63], v[140:143], v[172:175], v[60:63]
	v_mfma_f32_16x16x32_bf16 v[112:115], v[132:135], v[208:211], v[112:115]
	v_mfma_f32_16x16x32_bf16 v[52:55], v[140:143], v[208:211], v[52:55]
	v_mfma_f32_16x16x32_bf16 v[108:111], v[132:135], v[216:219], v[108:111]
	v_mfma_f32_16x16x32_bf16 v[36:39], v[140:143], v[216:219], v[36:39]
	s_setprio 0
	s_setprio 1
	v_mfma_f32_16x16x32_bf16 v[100:103], v[144:147], v[160:163], v[100:103]
	v_mfma_f32_16x16x32_bf16 v[40:43], v[152:155], v[160:163], v[40:43]
	v_mfma_f32_16x16x32_bf16 v[116:119], v[144:147], v[168:171], v[116:119]
	v_mfma_f32_16x16x32_bf16 v[56:59], v[152:155], v[168:171], v[56:59]
	v_mfma_f32_16x16x32_bf16 v[104:107], v[144:147], v[196:199], v[104:107]
	v_mfma_f32_16x16x32_bf16 v[44:47], v[152:155], v[196:199], v[44:47]
	v_mfma_f32_16x16x32_bf16 v[96:99], v[144:147], v[212:215], v[96:99]
	v_mfma_f32_16x16x32_bf16 v[32:35], v[152:155], v[212:215], v[32:35]
	v_mfma_f32_16x16x32_bf16 v[100:103], v[148:151], v[164:167], v[100:103]
	v_mfma_f32_16x16x32_bf16 v[40:43], v[156:159], v[164:167], v[40:43]
	v_mfma_f32_16x16x32_bf16 v[116:119], v[148:151], v[172:175], v[116:119]
	v_mfma_f32_16x16x32_bf16 v[56:59], v[156:159], v[172:175], v[56:59]
	v_mfma_f32_16x16x32_bf16 v[104:107], v[148:151], v[208:211], v[104:107]
	v_mfma_f32_16x16x32_bf16 v[44:47], v[156:159], v[208:211], v[44:47]
	v_mfma_f32_16x16x32_bf16 v[96:99], v[148:151], v[216:219], v[96:99]
	v_mfma_f32_16x16x32_bf16 v[32:35], v[156:159], v[216:219], v[32:35]
	s_barrier
	s_setprio 0
	s_add_i32 s0, s0, s33
	v_lshl_add_u64 v[186:187], v[186:187], 0, s[58:59]
	s_mov_b32 m0, s0
	ds_read_b128 v[160:163], v206 offset:49152
	ds_read_b128 v[164:167], v206 offset:50176
	ds_read_b128 v[168:171], v206 offset:51200
	ds_read_b128 v[172:175], v206 offset:52224
	ds_read_b128 v[196:199], v206 offset:53248
	ds_read_b128 v[208:211], v206 offset:54272
	ds_read_b128 v[212:215], v206 offset:55296
	ds_read_b128 v[216:219], v206 offset:56320
	global_load_lds_dwordx4 v[186:187], off
	s_add_i32 m0, s0, 0x2000
	s_add_u32 s10, s52, 0x80080
	v_lshl_add_u64 v[186:187], v[220:221], 0, s[58:59]
	s_addc_u32 s11, s53, 0
	s_add_i32 s0, s1, s33
	global_load_lds_dwordx4 v[186:187], off
	s_mov_b32 m0, s0
	v_lshl_add_u64 v[186:187], s[10:11], 0, v[190:191]
	global_load_lds_dwordx4 v[186:187], off
	s_add_i32 m0, s0, 0x2000
	v_lshl_add_u64 v[186:187], s[10:11], 0, v[180:181]
	global_load_lds_dwordx4 v[186:187], off
	s_mov_b32 m0, s55
	v_lshl_add_u64 v[186:187], v[222:223], 0, s[58:59]
	global_load_lds_dwordx4 v[186:187], off
	s_mov_b32 m0, s77
	v_lshl_add_u64 v[186:187], v[224:225], 0, s[58:59]
	global_load_lds_dwordx4 v[186:187], off
	s_waitcnt vmcnt(8) lgkmcnt(0)
	s_setprio 1
	s_barrier
	v_mfma_f32_16x16x32_bf16 v[88:91], v[128:131], v[160:163], v[88:91]
	v_mfma_f32_16x16x32_bf16 v[20:23], v[136:139], v[160:163], v[20:23]
	v_mfma_f32_16x16x32_bf16 v[92:95], v[128:131], v[168:171], v[92:95]
	v_mfma_f32_16x16x32_bf16 v[28:31], v[136:139], v[168:171], v[28:31]
	v_mfma_f32_16x16x32_bf16 v[80:83], v[128:131], v[196:199], v[80:83]
	v_mfma_f32_16x16x32_bf16 v[16:19], v[136:139], v[196:199], v[16:19]
	v_mfma_f32_16x16x32_bf16 v[76:79], v[128:131], v[212:215], v[76:79]
	v_mfma_f32_16x16x32_bf16 v[12:15], v[136:139], v[212:215], v[12:15]
	v_mfma_f32_16x16x32_bf16 v[88:91], v[132:135], v[164:167], v[88:91]
	v_mfma_f32_16x16x32_bf16 v[20:23], v[140:143], v[164:167], v[20:23]
	v_mfma_f32_16x16x32_bf16 v[92:95], v[132:135], v[172:175], v[92:95]
	v_mfma_f32_16x16x32_bf16 v[28:31], v[140:143], v[172:175], v[28:31]
	v_mfma_f32_16x16x32_bf16 v[80:83], v[132:135], v[208:211], v[80:83]
	v_mfma_f32_16x16x32_bf16 v[16:19], v[140:143], v[208:211], v[16:19]
	v_mfma_f32_16x16x32_bf16 v[76:79], v[132:135], v[216:219], v[76:79]
	v_mfma_f32_16x16x32_bf16 v[12:15], v[140:143], v[216:219], v[12:15]
	s_setprio 0
	s_setprio 1
	v_mfma_f32_16x16x32_bf16 v[68:71], v[144:147], v[160:163], v[68:71]
	v_mfma_f32_16x16x32_bf16 v[4:7], v[152:155], v[160:163], v[4:7]
	v_mfma_f32_16x16x32_bf16 v[84:87], v[144:147], v[168:171], v[84:87]
	v_mfma_f32_16x16x32_bf16 v[24:27], v[152:155], v[168:171], v[24:27]
	v_mfma_f32_16x16x32_bf16 v[72:75], v[144:147], v[196:199], v[72:75]
	v_mfma_f32_16x16x32_bf16 v[8:11], v[152:155], v[196:199], v[8:11]
	v_mfma_f32_16x16x32_bf16 v[64:67], v[144:147], v[212:215], v[64:67]
	v_mfma_f32_16x16x32_bf16 v[0:3], v[152:155], v[212:215], v[0:3]
	v_mfma_f32_16x16x32_bf16 v[68:71], v[148:151], v[164:167], v[68:71]
	v_mfma_f32_16x16x32_bf16 v[4:7], v[156:159], v[164:167], v[4:7]
	v_mfma_f32_16x16x32_bf16 v[84:87], v[148:151], v[172:175], v[84:87]
	v_mfma_f32_16x16x32_bf16 v[24:27], v[156:159], v[172:175], v[24:27]
	v_mfma_f32_16x16x32_bf16 v[72:75], v[148:151], v[208:211], v[72:75]
	v_mfma_f32_16x16x32_bf16 v[8:11], v[156:159], v[208:211], v[8:11]
	v_mfma_f32_16x16x32_bf16 v[64:67], v[148:151], v[216:219], v[64:67]
	v_mfma_f32_16x16x32_bf16 v[0:3], v[156:159], v[216:219], v[0:3]
	s_barrier
	s_setprio 0
	s_add_i32 vcc_lo, vcc_lo, 2
	s_add_u32 s66, s66, 0x100
	s_addc_u32 s67, s67, 0
	s_cmp_gt_u32 vcc_lo, 29
	s_mov_b64 s[10:11], s[16:17]
	s_cbranch_scc1 .Lpeel_done_7
	s_branch .LBB0_1105
.Ltrip0_strict_7:
	s_add_u32 s16, s10, 0x100
	s_addc_u32 s17, s11, 0
	s_add_i32 vcc_hi, 0, 0x10000
	s_cmp_eq_u32 vcc_lo, 28
	s_cselect_b32 s69, s13, s17
	s_cselect_b32 s68, s15, s16
	s_cselect_b32 s53, s57, s67
	s_cselect_b32 s52, s61, s66
	s_add_i32 s0, 0, 0x14000
	v_add_u32_e32 v140, vcc_hi, v200
	v_add_u32_e32 v156, s0, v200
	ds_read_b128 v[128:131], v140
	ds_read_b128 v[132:135], v140 offset:1024
	ds_read_b128 v[136:139], v140 offset:2048
	ds_read_b128 v[140:143], v140 offset:3072
	ds_read_b128 v[144:147], v156
	ds_read_b128 v[148:151], v156 offset:1024
	ds_read_b128 v[152:155], v156 offset:2048
	ds_read_b128 v[156:159], v156 offset:3072
	v_lshl_add_u64 v[186:187], s[10:11], 0, v[182:183]
	s_add_i32 m0, s40, 0xc000
	ds_read_b128 v[160:163], v206
	ds_read_b128 v[164:167], v206 offset:1024
	ds_read_b128 v[168:171], v206 offset:2048
	ds_read_b128 v[172:175], v206 offset:3072
	ds_read_b128 v[196:199], v206 offset:4096
	ds_read_b128 v[208:211], v206 offset:5120
	ds_read_b128 v[212:215], v206 offset:6144
	ds_read_b128 v[216:219], v206 offset:7168
	global_load_lds_dwordx4 v[186:187], off
	s_add_i32 m0, s40, 0xe000
	v_lshl_add_u64 v[186:187], s[10:11], 0, v[184:185]
	global_load_lds_dwordx4 v[186:187], off
	s_waitcnt vmcnt(8) lgkmcnt(0)
	s_setprio 1
	s_barrier
	v_mfma_f32_16x16x32_bf16 v[120:123], v[128:131], v[160:163], 0
	v_mfma_f32_16x16x32_bf16 v[48:51], v[136:139], v[160:163], 0
	v_mfma_f32_16x16x32_bf16 v[124:127], v[128:131], v[168:171], 0
	v_mfma_f32_16x16x32_bf16 v[60:63], v[136:139], v[168:171], 0
	v_mfma_f32_16x16x32_bf16 v[112:115], v[128:131], v[196:199], 0
	v_mfma_f32_16x16x32_bf16 v[52:55], v[136:139], v[196:199], 0
	v_mfma_f32_16x16x32_bf16 v[108:111], v[128:131], v[212:215], 0
	v_mfma_f32_16x16x32_bf16 v[36:39], v[136:139], v[212:215], 0
	v_mfma_f32_16x16x32_bf16 v[120:123], v[132:135], v[164:167], v[120:123]
	v_mfma_f32_16x16x32_bf16 v[48:51], v[140:143], v[164:167], v[48:51]
	v_mfma_f32_16x16x32_bf16 v[124:127], v[132:135], v[172:175], v[124:127]
	v_mfma_f32_16x16x32_bf16 v[60:63], v[140:143], v[172:175], v[60:63]
	v_mfma_f32_16x16x32_bf16 v[112:115], v[132:135], v[208:211], v[112:115]
	v_mfma_f32_16x16x32_bf16 v[52:55], v[140:143], v[208:211], v[52:55]
	v_mfma_f32_16x16x32_bf16 v[108:111], v[132:135], v[216:219], v[108:111]
	v_mfma_f32_16x16x32_bf16 v[36:39], v[140:143], v[216:219], v[36:39]
	s_setprio 0
	s_setprio 1
	v_mfma_f32_16x16x32_bf16 v[100:103], v[144:147], v[160:163], 0
	v_mfma_f32_16x16x32_bf16 v[40:43], v[152:155], v[160:163], 0
	v_mfma_f32_16x16x32_bf16 v[116:119], v[144:147], v[168:171], 0
	v_mfma_f32_16x16x32_bf16 v[56:59], v[152:155], v[168:171], 0
	v_mfma_f32_16x16x32_bf16 v[104:107], v[144:147], v[196:199], 0
	v_mfma_f32_16x16x32_bf16 v[44:47], v[152:155], v[196:199], 0
	v_mfma_f32_16x16x32_bf16 v[96:99], v[144:147], v[212:215], 0
	v_mfma_f32_16x16x32_bf16 v[32:35], v[152:155], v[212:215], 0
	v_mfma_f32_16x16x32_bf16 v[100:103], v[148:151], v[164:167], v[100:103]
	v_mfma_f32_16x16x32_bf16 v[40:43], v[156:159], v[164:167], v[40:43]
	v_mfma_f32_16x16x32_bf16 v[116:119], v[148:151], v[172:175], v[116:119]
	v_mfma_f32_16x16x32_bf16 v[56:59], v[156:159], v[172:175], v[56:59]
	v_mfma_f32_16x16x32_bf16 v[104:107], v[148:151], v[208:211], v[104:107]
	v_mfma_f32_16x16x32_bf16 v[44:47], v[156:159], v[208:211], v[44:47]
	v_mfma_f32_16x16x32_bf16 v[96:99], v[148:151], v[216:219], v[96:99]
	v_mfma_f32_16x16x32_bf16 v[32:35], v[156:159], v[216:219], v[32:35]
	s_barrier
	s_setprio 0
	s_add_i32 s1, vcc_hi, s33
	v_lshl_add_u64 v[186:187], s[52:53], 0, v[190:191]
	s_mov_b32 m0, s1
	ds_read_b128 v[160:163], v206 offset:16384
	ds_read_b128 v[164:167], v206 offset:17408
	ds_read_b128 v[168:171], v206 offset:18432
	ds_read_b128 v[172:175], v206 offset:19456
	ds_read_b128 v[196:199], v206 offset:20480
	ds_read_b128 v[208:211], v206 offset:21504
	ds_read_b128 v[212:215], v206 offset:22528
	ds_read_b128 v[216:219], v206 offset:23552
	global_load_lds_dwordx4 v[186:187], off
	s_add_i32 m0, s1, 0x2000
	s_add_u32 s10, s52, 0x80000
	v_lshl_add_u64 v[220:221], s[52:53], 0, v[180:181]
	s_addc_u32 s11, s53, 0
	s_add_i32 s0, s0, s33
	global_load_lds_dwordx4 v[220:221], off
	v_lshl_add_u64 v[222:223], s[10:11], 0, v[190:191]
	s_mov_b32 m0, s0
	v_lshl_add_u64 v[224:225], s[68:69], 0, v[178:179]
	global_load_lds_dwordx4 v[222:223], off
	s_add_i32 m0, s0, 0x2000
	v_lshl_add_u64 v[222:223], s[10:11], 0, v[180:181]
	global_load_lds_dwordx4 v[222:223], off
	s_mov_b32 m0, s40
	v_lshl_add_u64 v[222:223], s[68:69], 0, v[176:177]
	global_load_lds_dwordx4 v[222:223], off
	s_mov_b32 m0, s41
	s_nop 0
	global_load_lds_dwordx4 v[224:225], off
	s_waitcnt vmcnt(8) lgkmcnt(0)
	s_setprio 1
	s_barrier
	v_mfma_f32_16x16x32_bf16 v[88:91], v[128:131], v[160:163], 0
	v_mfma_f32_16x16x32_bf16 v[20:23], v[136:139], v[160:163], 0
	v_mfma_f32_16x16x32_bf16 v[92:95], v[128:131], v[168:171], 0
	v_mfma_f32_16x16x32_bf16 v[28:31], v[136:139], v[168:171], 0
	v_mfma_f32_16x16x32_bf16 v[80:83], v[128:131], v[196:199], 0
	v_mfma_f32_16x16x32_bf16 v[16:19], v[136:139], v[196:199], 0
	v_mfma_f32_16x16x32_bf16 v[76:79], v[128:131], v[212:215], 0
	v_mfma_f32_16x16x32_bf16 v[12:15], v[136:139], v[212:215], 0
	v_mfma_f32_16x16x32_bf16 v[88:91], v[132:135], v[164:167], v[88:91]
	v_mfma_f32_16x16x32_bf16 v[20:23], v[140:143], v[164:167], v[20:23]
	v_mfma_f32_16x16x32_bf16 v[92:95], v[132:135], v[172:175], v[92:95]
	v_mfma_f32_16x16x32_bf16 v[28:31], v[140:143], v[172:175], v[28:31]
	v_mfma_f32_16x16x32_bf16 v[80:83], v[132:135], v[208:211], v[80:83]
	v_mfma_f32_16x16x32_bf16 v[16:19], v[140:143], v[208:211], v[16:19]
	v_mfma_f32_16x16x32_bf16 v[76:79], v[132:135], v[216:219], v[76:79]
	v_mfma_f32_16x16x32_bf16 v[12:15], v[140:143], v[216:219], v[12:15]
	s_setprio 0
	s_setprio 1
	v_mfma_f32_16x16x32_bf16 v[68:71], v[144:147], v[160:163], 0
	v_mfma_f32_16x16x32_bf16 v[4:7], v[152:155], v[160:163], 0
	v_mfma_f32_16x16x32_bf16 v[84:87], v[144:147], v[168:171], 0
	v_mfma_f32_16x16x32_bf16 v[24:27], v[152:155], v[168:171], 0
	v_mfma_f32_16x16x32_bf16 v[72:75], v[144:147], v[196:199], 0
	v_mfma_f32_16x16x32_bf16 v[8:11], v[152:155], v[196:199], 0
	v_mfma_f32_16x16x32_bf16 v[64:67], v[144:147], v[212:215], 0
	v_mfma_f32_16x16x32_bf16 v[0:3], v[152:155], v[212:215], 0
	v_mfma_f32_16x16x32_bf16 v[68:71], v[148:151], v[164:167], v[68:71]
	v_mfma_f32_16x16x32_bf16 v[4:7], v[156:159], v[164:167], v[4:7]
	v_mfma_f32_16x16x32_bf16 v[84:87], v[148:151], v[172:175], v[84:87]
	v_mfma_f32_16x16x32_bf16 v[24:27], v[156:159], v[172:175], v[24:27]
	v_mfma_f32_16x16x32_bf16 v[72:75], v[148:151], v[208:211], v[72:75]
	v_mfma_f32_16x16x32_bf16 v[8:11], v[156:159], v[208:211], v[8:11]
	v_mfma_f32_16x16x32_bf16 v[64:67], v[148:151], v[216:219], v[64:67]
	v_mfma_f32_16x16x32_bf16 v[0:3], v[156:159], v[216:219], v[0:3]
	s_barrier
	s_setprio 0
	s_add_i32 s0, 0, 0x18000
	s_add_i32 s1, 0, 0x1c000
	v_add_u32_e32 v140, s0, v200
	v_add_u32_e32 v156, s1, v200
	ds_read_b128 v[128:131], v140
	ds_read_b128 v[132:135], v140 offset:1024
	ds_read_b128 v[136:139], v140 offset:2048
	ds_read_b128 v[140:143], v140 offset:3072
	ds_read_b128 v[144:147], v156
	ds_read_b128 v[148:151], v156 offset:1024
	ds_read_b128 v[152:155], v156 offset:2048
	ds_read_b128 v[156:159], v156 offset:3072
	s_add_u32 s10, s68, 0x80000
	s_addc_u32 s11, s69, 0
	s_mov_b32 m0, s42
	v_lshl_add_u64 v[226:227], s[10:11], 0, v[176:177]
	ds_read_b128 v[160:163], v206 offset:32768
	ds_read_b128 v[164:167], v206 offset:33792
	ds_read_b128 v[168:171], v206 offset:34816
	ds_read_b128 v[172:175], v206 offset:35840
	ds_read_b128 v[196:199], v206 offset:36864
	ds_read_b128 v[208:211], v206 offset:37888
	ds_read_b128 v[212:215], v206 offset:38912
	ds_read_b128 v[216:219], v206 offset:39936
	global_load_lds_dwordx4 v[226:227], off
	s_mov_b32 m0, s43
	v_lshl_add_u64 v[226:227], s[10:11], 0, v[178:179]
	global_load_lds_dwordx4 v[226:227], off
	s_waitcnt vmcnt(8) lgkmcnt(0)
	s_setprio 1
	s_barrier
	v_mfma_f32_16x16x32_bf16 v[120:123], v[128:131], v[160:163], v[120:123]
	v_mfma_f32_16x16x32_bf16 v[48:51], v[136:139], v[160:163], v[48:51]
	v_mfma_f32_16x16x32_bf16 v[124:127], v[128:131], v[168:171], v[124:127]
	v_mfma_f32_16x16x32_bf16 v[60:63], v[136:139], v[168:171], v[60:63]
	v_mfma_f32_16x16x32_bf16 v[112:115], v[128:131], v[196:199], v[112:115]
	v_mfma_f32_16x16x32_bf16 v[52:55], v[136:139], v[196:199], v[52:55]
	v_mfma_f32_16x16x32_bf16 v[108:111], v[128:131], v[212:215], v[108:111]
	v_mfma_f32_16x16x32_bf16 v[36:39], v[136:139], v[212:215], v[36:39]
	v_mfma_f32_16x16x32_bf16 v[120:123], v[132:135], v[164:167], v[120:123]
	v_mfma_f32_16x16x32_bf16 v[48:51], v[140:143], v[164:167], v[48:51]
	v_mfma_f32_16x16x32_bf16 v[124:127], v[132:135], v[172:175], v[124:127]
	v_mfma_f32_16x16x32_bf16 v[60:63], v[140:143], v[172:175], v[60:63]
	v_mfma_f32_16x16x32_bf16 v[112:115], v[132:135], v[208:211], v[112:115]
	v_mfma_f32_16x16x32_bf16 v[52:55], v[140:143], v[208:211], v[52:55]
	v_mfma_f32_16x16x32_bf16 v[108:111], v[132:135], v[216:219], v[108:111]
	v_mfma_f32_16x16x32_bf16 v[36:39], v[140:143], v[216:219], v[36:39]
	s_setprio 0
	s_setprio 1
	v_mfma_f32_16x16x32_bf16 v[100:103], v[144:147], v[160:163], v[100:103]
	v_mfma_f32_16x16x32_bf16 v[40:43], v[152:155], v[160:163], v[40:43]
	v_mfma_f32_16x16x32_bf16 v[116:119], v[144:147], v[168:171], v[116:119]
	v_mfma_f32_16x16x32_bf16 v[56:59], v[152:155], v[168:171], v[56:59]
	v_mfma_f32_16x16x32_bf16 v[104:107], v[144:147], v[196:199], v[104:107]
	v_mfma_f32_16x16x32_bf16 v[44:47], v[152:155], v[196:199], v[44:47]
	v_mfma_f32_16x16x32_bf16 v[96:99], v[144:147], v[212:215], v[96:99]
	v_mfma_f32_16x16x32_bf16 v[32:35], v[152:155], v[212:215], v[32:35]
	v_mfma_f32_16x16x32_bf16 v[100:103], v[148:151], v[164:167], v[100:103]
	v_mfma_f32_16x16x32_bf16 v[40:43], v[156:159], v[164:167], v[40:43]
	v_mfma_f32_16x16x32_bf16 v[116:119], v[148:151], v[172:175], v[116:119]
	v_mfma_f32_16x16x32_bf16 v[56:59], v[156:159], v[172:175], v[56:59]
	v_mfma_f32_16x16x32_bf16 v[104:107], v[148:151], v[208:211], v[104:107]
	v_mfma_f32_16x16x32_bf16 v[44:47], v[156:159], v[208:211], v[44:47]
	v_mfma_f32_16x16x32_bf16 v[96:99], v[148:151], v[216:219], v[96:99]
	v_mfma_f32_16x16x32_bf16 v[32:35], v[156:159], v[216:219], v[32:35]
	s_barrier
	s_setprio 0
	s_add_i32 s0, s0, s33
	v_lshl_add_u64 v[186:187], v[186:187], 0, s[58:59]
	s_mov_b32 m0, s0
	ds_read_b128 v[160:163], v206 offset:49152
	ds_read_b128 v[164:167], v206 offset:50176
	ds_read_b128 v[168:171], v206 offset:51200
	ds_read_b128 v[172:175], v206 offset:52224
	ds_read_b128 v[196:199], v206 offset:53248
	ds_read_b128 v[208:211], v206 offset:54272
	ds_read_b128 v[212:215], v206 offset:55296
	ds_read_b128 v[216:219], v206 offset:56320
	global_load_lds_dwordx4 v[186:187], off
	s_add_i32 m0, s0, 0x2000
	s_add_u32 s10, s52, 0x80080
	v_lshl_add_u64 v[186:187], v[220:221], 0, s[58:59]
	s_addc_u32 s11, s53, 0
	s_add_i32 s0, s1, s33
	global_load_lds_dwordx4 v[186:187], off
	s_mov_b32 m0, s0
	v_lshl_add_u64 v[186:187], s[10:11], 0, v[190:191]
	global_load_lds_dwordx4 v[186:187], off
	s_add_i32 m0, s0, 0x2000
	v_lshl_add_u64 v[186:187], s[10:11], 0, v[180:181]
	global_load_lds_dwordx4 v[186:187], off
	s_mov_b32 m0, s55
	v_lshl_add_u64 v[186:187], v[222:223], 0, s[58:59]
	global_load_lds_dwordx4 v[186:187], off
	s_mov_b32 m0, s77
	v_lshl_add_u64 v[186:187], v[224:225], 0, s[58:59]
	global_load_lds_dwordx4 v[186:187], off
	s_waitcnt vmcnt(8) lgkmcnt(0)
	s_setprio 1
	s_barrier
	v_mfma_f32_16x16x32_bf16 v[88:91], v[128:131], v[160:163], v[88:91]
	v_mfma_f32_16x16x32_bf16 v[20:23], v[136:139], v[160:163], v[20:23]
	v_mfma_f32_16x16x32_bf16 v[92:95], v[128:131], v[168:171], v[92:95]
	v_mfma_f32_16x16x32_bf16 v[28:31], v[136:139], v[168:171], v[28:31]
	v_mfma_f32_16x16x32_bf16 v[80:83], v[128:131], v[196:199], v[80:83]
	v_mfma_f32_16x16x32_bf16 v[16:19], v[136:139], v[196:199], v[16:19]
	v_mfma_f32_16x16x32_bf16 v[76:79], v[128:131], v[212:215], v[76:79]
	v_mfma_f32_16x16x32_bf16 v[12:15], v[136:139], v[212:215], v[12:15]
	v_mfma_f32_16x16x32_bf16 v[88:91], v[132:135], v[164:167], v[88:91]
	v_mfma_f32_16x16x32_bf16 v[20:23], v[140:143], v[164:167], v[20:23]
	v_mfma_f32_16x16x32_bf16 v[92:95], v[132:135], v[172:175], v[92:95]
	v_mfma_f32_16x16x32_bf16 v[28:31], v[140:143], v[172:175], v[28:31]
	v_mfma_f32_16x16x32_bf16 v[80:83], v[132:135], v[208:211], v[80:83]
	v_mfma_f32_16x16x32_bf16 v[16:19], v[140:143], v[208:211], v[16:19]
	v_mfma_f32_16x16x32_bf16 v[76:79], v[132:135], v[216:219], v[76:79]
	v_mfma_f32_16x16x32_bf16 v[12:15], v[140:143], v[216:219], v[12:15]
	s_setprio 0
	s_setprio 1
	v_mfma_f32_16x16x32_bf16 v[68:71], v[144:147], v[160:163], v[68:71]
	v_mfma_f32_16x16x32_bf16 v[4:7], v[152:155], v[160:163], v[4:7]
	v_mfma_f32_16x16x32_bf16 v[84:87], v[144:147], v[168:171], v[84:87]
	v_mfma_f32_16x16x32_bf16 v[24:27], v[152:155], v[168:171], v[24:27]
	v_mfma_f32_16x16x32_bf16 v[72:75], v[144:147], v[196:199], v[72:75]
	v_mfma_f32_16x16x32_bf16 v[8:11], v[152:155], v[196:199], v[8:11]
	v_mfma_f32_16x16x32_bf16 v[64:67], v[144:147], v[212:215], v[64:67]
	v_mfma_f32_16x16x32_bf16 v[0:3], v[152:155], v[212:215], v[0:3]
	v_mfma_f32_16x16x32_bf16 v[68:71], v[148:151], v[164:167], v[68:71]
	v_mfma_f32_16x16x32_bf16 v[4:7], v[156:159], v[164:167], v[4:7]
	v_mfma_f32_16x16x32_bf16 v[84:87], v[148:151], v[172:175], v[84:87]
	v_mfma_f32_16x16x32_bf16 v[24:27], v[156:159], v[172:175], v[24:27]
	v_mfma_f32_16x16x32_bf16 v[72:75], v[148:151], v[208:211], v[72:75]
	v_mfma_f32_16x16x32_bf16 v[8:11], v[156:159], v[208:211], v[8:11]
	v_mfma_f32_16x16x32_bf16 v[64:67], v[148:151], v[216:219], v[64:67]
	v_mfma_f32_16x16x32_bf16 v[0:3], v[156:159], v[216:219], v[0:3]
	s_barrier
	s_setprio 0
	s_add_i32 vcc_lo, vcc_lo, 2
	s_add_u32 s66, s66, 0x100
	s_addc_u32 s67, s67, 0
	s_cmp_gt_u32 vcc_lo, 29
	s_mov_b64 s[10:11], s[16:17]
	s_cbranch_scc1 .Lpeel_done_7
.LBB0_1105:
	s_add_u32 s16, s10, 0x100
	s_addc_u32 s17, s11, 0
	s_add_i32 vcc_hi, 0, 0x10000
	s_cmp_eq_u32 vcc_lo, 28
	s_cselect_b32 s69, s13, s17
	s_cselect_b32 s68, s15, s16
	s_cselect_b32 s53, s57, s67
	s_cselect_b32 s52, s61, s66
	s_add_i32 s0, 0, 0x14000
	v_add_u32_e32 v140, vcc_hi, v200
	v_add_u32_e32 v156, s0, v200
	ds_read_b128 v[128:131], v140
	ds_read_b128 v[132:135], v140 offset:1024
	ds_read_b128 v[136:139], v140 offset:2048
	ds_read_b128 v[140:143], v140 offset:3072
	ds_read_b128 v[144:147], v156
	ds_read_b128 v[148:151], v156 offset:1024
	ds_read_b128 v[152:155], v156 offset:2048
	ds_read_b128 v[156:159], v156 offset:3072
	v_lshl_add_u64 v[186:187], s[10:11], 0, v[182:183]
	s_add_i32 m0, s40, 0xc000
	ds_read_b128 v[160:163], v206
	ds_read_b128 v[164:167], v206 offset:1024
	ds_read_b128 v[168:171], v206 offset:2048
	ds_read_b128 v[172:175], v206 offset:3072
	ds_read_b128 v[196:199], v206 offset:4096
	ds_read_b128 v[208:211], v206 offset:5120
	ds_read_b128 v[212:215], v206 offset:6144
	ds_read_b128 v[216:219], v206 offset:7168
	global_load_lds_dwordx4 v[186:187], off
	s_add_i32 m0, s40, 0xe000
	v_lshl_add_u64 v[186:187], s[10:11], 0, v[184:185]
	global_load_lds_dwordx4 v[186:187], off
	s_waitcnt vmcnt(8) lgkmcnt(0)
	s_setprio 1
	s_barrier
	v_mfma_f32_16x16x32_bf16 v[120:123], v[128:131], v[160:163], v[120:123]
	v_mfma_f32_16x16x32_bf16 v[48:51], v[136:139], v[160:163], v[48:51]
	v_mfma_f32_16x16x32_bf16 v[124:127], v[128:131], v[168:171], v[124:127]
	v_mfma_f32_16x16x32_bf16 v[60:63], v[136:139], v[168:171], v[60:63]
	v_mfma_f32_16x16x32_bf16 v[112:115], v[128:131], v[196:199], v[112:115]
	v_mfma_f32_16x16x32_bf16 v[52:55], v[136:139], v[196:199], v[52:55]
	v_mfma_f32_16x16x32_bf16 v[108:111], v[128:131], v[212:215], v[108:111]
	v_mfma_f32_16x16x32_bf16 v[36:39], v[136:139], v[212:215], v[36:39]
	v_mfma_f32_16x16x32_bf16 v[120:123], v[132:135], v[164:167], v[120:123]
	v_mfma_f32_16x16x32_bf16 v[48:51], v[140:143], v[164:167], v[48:51]
	v_mfma_f32_16x16x32_bf16 v[124:127], v[132:135], v[172:175], v[124:127]
	v_mfma_f32_16x16x32_bf16 v[60:63], v[140:143], v[172:175], v[60:63]
	v_mfma_f32_16x16x32_bf16 v[112:115], v[132:135], v[208:211], v[112:115]
	v_mfma_f32_16x16x32_bf16 v[52:55], v[140:143], v[208:211], v[52:55]
	v_mfma_f32_16x16x32_bf16 v[108:111], v[132:135], v[216:219], v[108:111]
	v_mfma_f32_16x16x32_bf16 v[36:39], v[140:143], v[216:219], v[36:39]
	s_setprio 0
	s_setprio 1
	v_mfma_f32_16x16x32_bf16 v[100:103], v[144:147], v[160:163], v[100:103]
	v_mfma_f32_16x16x32_bf16 v[40:43], v[152:155], v[160:163], v[40:43]
	v_mfma_f32_16x16x32_bf16 v[116:119], v[144:147], v[168:171], v[116:119]
	v_mfma_f32_16x16x32_bf16 v[56:59], v[152:155], v[168:171], v[56:59]
	v_mfma_f32_16x16x32_bf16 v[104:107], v[144:147], v[196:199], v[104:107]
	v_mfma_f32_16x16x32_bf16 v[44:47], v[152:155], v[196:199], v[44:47]
	v_mfma_f32_16x16x32_bf16 v[96:99], v[144:147], v[212:215], v[96:99]
	v_mfma_f32_16x16x32_bf16 v[32:35], v[152:155], v[212:215], v[32:35]
	v_mfma_f32_16x16x32_bf16 v[100:103], v[148:151], v[164:167], v[100:103]
	v_mfma_f32_16x16x32_bf16 v[40:43], v[156:159], v[164:167], v[40:43]
	v_mfma_f32_16x16x32_bf16 v[116:119], v[148:151], v[172:175], v[116:119]
	v_mfma_f32_16x16x32_bf16 v[56:59], v[156:159], v[172:175], v[56:59]
	v_mfma_f32_16x16x32_bf16 v[104:107], v[148:151], v[208:211], v[104:107]
	v_mfma_f32_16x16x32_bf16 v[44:47], v[156:159], v[208:211], v[44:47]
	v_mfma_f32_16x16x32_bf16 v[96:99], v[148:151], v[216:219], v[96:99]
	v_mfma_f32_16x16x32_bf16 v[32:35], v[156:159], v[216:219], v[32:35]
	s_setprio 0
	s_barrier
	s_add_i32 s1, vcc_hi, s33
	v_lshl_add_u64 v[186:187], s[52:53], 0, v[190:191]
	s_mov_b32 m0, s1
	ds_read_b128 v[160:163], v206 offset:16384
	ds_read_b128 v[164:167], v206 offset:17408
	ds_read_b128 v[168:171], v206 offset:18432
	ds_read_b128 v[172:175], v206 offset:19456
	ds_read_b128 v[196:199], v206 offset:20480
	ds_read_b128 v[208:211], v206 offset:21504
	ds_read_b128 v[212:215], v206 offset:22528
	ds_read_b128 v[216:219], v206 offset:23552
	global_load_lds_dwordx4 v[186:187], off
	s_add_i32 m0, s1, 0x2000
	s_add_u32 s10, s52, 0x80000
	v_lshl_add_u64 v[220:221], s[52:53], 0, v[180:181]
	s_addc_u32 s11, s53, 0
	s_add_i32 s0, s0, s33
	global_load_lds_dwordx4 v[220:221], off
	v_lshl_add_u64 v[222:223], s[10:11], 0, v[190:191]
	s_mov_b32 m0, s0
	v_lshl_add_u64 v[224:225], s[68:69], 0, v[178:179]
	global_load_lds_dwordx4 v[222:223], off
	s_add_i32 m0, s0, 0x2000
	v_lshl_add_u64 v[222:223], s[10:11], 0, v[180:181]
	global_load_lds_dwordx4 v[222:223], off
	s_mov_b32 m0, s40
	v_lshl_add_u64 v[222:223], s[68:69], 0, v[176:177]
	global_load_lds_dwordx4 v[222:223], off
	s_mov_b32 m0, s41
	s_nop 0
	global_load_lds_dwordx4 v[224:225], off
	s_waitcnt vmcnt(8) lgkmcnt(0)
	s_setprio 1
	s_barrier
	v_mfma_f32_16x16x32_bf16 v[88:91], v[128:131], v[160:163], v[88:91]
	v_mfma_f32_16x16x32_bf16 v[20:23], v[136:139], v[160:163], v[20:23]
	v_mfma_f32_16x16x32_bf16 v[92:95], v[128:131], v[168:171], v[92:95]
	v_mfma_f32_16x16x32_bf16 v[28:31], v[136:139], v[168:171], v[28:31]
	v_mfma_f32_16x16x32_bf16 v[80:83], v[128:131], v[196:199], v[80:83]
	v_mfma_f32_16x16x32_bf16 v[16:19], v[136:139], v[196:199], v[16:19]
	v_mfma_f32_16x16x32_bf16 v[76:79], v[128:131], v[212:215], v[76:79]
	v_mfma_f32_16x16x32_bf16 v[12:15], v[136:139], v[212:215], v[12:15]
	v_mfma_f32_16x16x32_bf16 v[88:91], v[132:135], v[164:167], v[88:91]
	v_mfma_f32_16x16x32_bf16 v[20:23], v[140:143], v[164:167], v[20:23]
	v_mfma_f32_16x16x32_bf16 v[92:95], v[132:135], v[172:175], v[92:95]
	v_mfma_f32_16x16x32_bf16 v[28:31], v[140:143], v[172:175], v[28:31]
	v_mfma_f32_16x16x32_bf16 v[80:83], v[132:135], v[208:211], v[80:83]
	v_mfma_f32_16x16x32_bf16 v[16:19], v[140:143], v[208:211], v[16:19]
	v_mfma_f32_16x16x32_bf16 v[76:79], v[132:135], v[216:219], v[76:79]
	v_mfma_f32_16x16x32_bf16 v[12:15], v[140:143], v[216:219], v[12:15]
	s_setprio 0
	s_setprio 1
	v_mfma_f32_16x16x32_bf16 v[68:71], v[144:147], v[160:163], v[68:71]
	v_mfma_f32_16x16x32_bf16 v[4:7], v[152:155], v[160:163], v[4:7]
	v_mfma_f32_16x16x32_bf16 v[84:87], v[144:147], v[168:171], v[84:87]
	v_mfma_f32_16x16x32_bf16 v[24:27], v[152:155], v[168:171], v[24:27]
	v_mfma_f32_16x16x32_bf16 v[72:75], v[144:147], v[196:199], v[72:75]
	v_mfma_f32_16x16x32_bf16 v[8:11], v[152:155], v[196:199], v[8:11]
	v_mfma_f32_16x16x32_bf16 v[64:67], v[144:147], v[212:215], v[64:67]
	v_mfma_f32_16x16x32_bf16 v[0:3], v[152:155], v[212:215], v[0:3]
	v_mfma_f32_16x16x32_bf16 v[68:71], v[148:151], v[164:167], v[68:71]
	v_mfma_f32_16x16x32_bf16 v[4:7], v[156:159], v[164:167], v[4:7]
	v_mfma_f32_16x16x32_bf16 v[84:87], v[148:151], v[172:175], v[84:87]
	v_mfma_f32_16x16x32_bf16 v[24:27], v[156:159], v[172:175], v[24:27]
	v_mfma_f32_16x16x32_bf16 v[72:75], v[148:151], v[208:211], v[72:75]
	v_mfma_f32_16x16x32_bf16 v[8:11], v[156:159], v[208:211], v[8:11]
	v_mfma_f32_16x16x32_bf16 v[64:67], v[148:151], v[216:219], v[64:67]
	v_mfma_f32_16x16x32_bf16 v[0:3], v[156:159], v[216:219], v[0:3]
	s_setprio 0
	s_barrier
	s_add_i32 s0, 0, 0x18000
	s_add_i32 s1, 0, 0x1c000
	v_add_u32_e32 v140, s0, v200
	v_add_u32_e32 v156, s1, v200
	ds_read_b128 v[128:131], v140
	ds_read_b128 v[132:135], v140 offset:1024
	ds_read_b128 v[136:139], v140 offset:2048
	ds_read_b128 v[140:143], v140 offset:3072
	ds_read_b128 v[144:147], v156
	ds_read_b128 v[148:151], v156 offset:1024
	ds_read_b128 v[152:155], v156 offset:2048
	ds_read_b128 v[156:159], v156 offset:3072
	s_add_u32 s10, s68, 0x80000
	s_addc_u32 s11, s69, 0
	s_mov_b32 m0, s42
	v_lshl_add_u64 v[226:227], s[10:11], 0, v[176:177]
	ds_read_b128 v[160:163], v206 offset:32768
	ds_read_b128 v[164:167], v206 offset:33792
	ds_read_b128 v[168:171], v206 offset:34816
	ds_read_b128 v[172:175], v206 offset:35840
	ds_read_b128 v[196:199], v206 offset:36864
	ds_read_b128 v[208:211], v206 offset:37888
	ds_read_b128 v[212:215], v206 offset:38912
	ds_read_b128 v[216:219], v206 offset:39936
	global_load_lds_dwordx4 v[226:227], off
	s_mov_b32 m0, s43
	v_lshl_add_u64 v[226:227], s[10:11], 0, v[178:179]
	global_load_lds_dwordx4 v[226:227], off
	s_waitcnt vmcnt(8) lgkmcnt(0)
	s_setprio 1
	s_barrier
	v_mfma_f32_16x16x32_bf16 v[120:123], v[128:131], v[160:163], v[120:123]
	v_mfma_f32_16x16x32_bf16 v[48:51], v[136:139], v[160:163], v[48:51]
	v_mfma_f32_16x16x32_bf16 v[124:127], v[128:131], v[168:171], v[124:127]
	v_mfma_f32_16x16x32_bf16 v[60:63], v[136:139], v[168:171], v[60:63]
	v_mfma_f32_16x16x32_bf16 v[112:115], v[128:131], v[196:199], v[112:115]
	v_mfma_f32_16x16x32_bf16 v[52:55], v[136:139], v[196:199], v[52:55]
	v_mfma_f32_16x16x32_bf16 v[108:111], v[128:131], v[212:215], v[108:111]
	v_mfma_f32_16x16x32_bf16 v[36:39], v[136:139], v[212:215], v[36:39]
	v_mfma_f32_16x16x32_bf16 v[120:123], v[132:135], v[164:167], v[120:123]
	v_mfma_f32_16x16x32_bf16 v[48:51], v[140:143], v[164:167], v[48:51]
	v_mfma_f32_16x16x32_bf16 v[124:127], v[132:135], v[172:175], v[124:127]
	v_mfma_f32_16x16x32_bf16 v[60:63], v[140:143], v[172:175], v[60:63]
	v_mfma_f32_16x16x32_bf16 v[112:115], v[132:135], v[208:211], v[112:115]
	v_mfma_f32_16x16x32_bf16 v[52:55], v[140:143], v[208:211], v[52:55]
	v_mfma_f32_16x16x32_bf16 v[108:111], v[132:135], v[216:219], v[108:111]
	v_mfma_f32_16x16x32_bf16 v[36:39], v[140:143], v[216:219], v[36:39]
	s_setprio 0
	s_setprio 1
	v_mfma_f32_16x16x32_bf16 v[100:103], v[144:147], v[160:163], v[100:103]
	v_mfma_f32_16x16x32_bf16 v[40:43], v[152:155], v[160:163], v[40:43]
	v_mfma_f32_16x16x32_bf16 v[116:119], v[144:147], v[168:171], v[116:119]
	v_mfma_f32_16x16x32_bf16 v[56:59], v[152:155], v[168:171], v[56:59]
	v_mfma_f32_16x16x32_bf16 v[104:107], v[144:147], v[196:199], v[104:107]
	v_mfma_f32_16x16x32_bf16 v[44:47], v[152:155], v[196:199], v[44:47]
	v_mfma_f32_16x16x32_bf16 v[96:99], v[144:147], v[212:215], v[96:99]
	v_mfma_f32_16x16x32_bf16 v[32:35], v[152:155], v[212:215], v[32:35]
	v_mfma_f32_16x16x32_bf16 v[100:103], v[148:151], v[164:167], v[100:103]
	v_mfma_f32_16x16x32_bf16 v[40:43], v[156:159], v[164:167], v[40:43]
	v_mfma_f32_16x16x32_bf16 v[116:119], v[148:151], v[172:175], v[116:119]
	v_mfma_f32_16x16x32_bf16 v[56:59], v[156:159], v[172:175], v[56:59]
	v_mfma_f32_16x16x32_bf16 v[104:107], v[148:151], v[208:211], v[104:107]
	v_mfma_f32_16x16x32_bf16 v[44:47], v[156:159], v[208:211], v[44:47]
	v_mfma_f32_16x16x32_bf16 v[96:99], v[148:151], v[216:219], v[96:99]
	v_mfma_f32_16x16x32_bf16 v[32:35], v[156:159], v[216:219], v[32:35]
	s_setprio 0
	s_barrier
	s_add_i32 s0, s0, s33
	v_lshl_add_u64 v[186:187], v[186:187], 0, s[58:59]
	s_mov_b32 m0, s0
	ds_read_b128 v[160:163], v206 offset:49152
	ds_read_b128 v[164:167], v206 offset:50176
	ds_read_b128 v[168:171], v206 offset:51200
	ds_read_b128 v[172:175], v206 offset:52224
	ds_read_b128 v[196:199], v206 offset:53248
	ds_read_b128 v[208:211], v206 offset:54272
	ds_read_b128 v[212:215], v206 offset:55296
	ds_read_b128 v[216:219], v206 offset:56320
	global_load_lds_dwordx4 v[186:187], off
	s_add_i32 m0, s0, 0x2000
	s_add_u32 s10, s52, 0x80080
	v_lshl_add_u64 v[186:187], v[220:221], 0, s[58:59]
	s_addc_u32 s11, s53, 0
	s_add_i32 s0, s1, s33
	global_load_lds_dwordx4 v[186:187], off
	s_mov_b32 m0, s0
	v_lshl_add_u64 v[186:187], s[10:11], 0, v[190:191]
	global_load_lds_dwordx4 v[186:187], off
	s_add_i32 m0, s0, 0x2000
	v_lshl_add_u64 v[186:187], s[10:11], 0, v[180:181]
	global_load_lds_dwordx4 v[186:187], off
	s_mov_b32 m0, s55
	v_lshl_add_u64 v[186:187], v[222:223], 0, s[58:59]
	global_load_lds_dwordx4 v[186:187], off
	s_mov_b32 m0, s77
	v_lshl_add_u64 v[186:187], v[224:225], 0, s[58:59]
	global_load_lds_dwordx4 v[186:187], off
	s_waitcnt vmcnt(8) lgkmcnt(0)
	s_setprio 1
	s_barrier
	v_mfma_f32_16x16x32_bf16 v[88:91], v[128:131], v[160:163], v[88:91]
	v_mfma_f32_16x16x32_bf16 v[20:23], v[136:139], v[160:163], v[20:23]
	v_mfma_f32_16x16x32_bf16 v[92:95], v[128:131], v[168:171], v[92:95]
	v_mfma_f32_16x16x32_bf16 v[28:31], v[136:139], v[168:171], v[28:31]
	v_mfma_f32_16x16x32_bf16 v[80:83], v[128:131], v[196:199], v[80:83]
	v_mfma_f32_16x16x32_bf16 v[16:19], v[136:139], v[196:199], v[16:19]
	v_mfma_f32_16x16x32_bf16 v[76:79], v[128:131], v[212:215], v[76:79]
	v_mfma_f32_16x16x32_bf16 v[12:15], v[136:139], v[212:215], v[12:15]
	v_mfma_f32_16x16x32_bf16 v[88:91], v[132:135], v[164:167], v[88:91]
	v_mfma_f32_16x16x32_bf16 v[20:23], v[140:143], v[164:167], v[20:23]
	v_mfma_f32_16x16x32_bf16 v[92:95], v[132:135], v[172:175], v[92:95]
	v_mfma_f32_16x16x32_bf16 v[28:31], v[140:143], v[172:175], v[28:31]
	v_mfma_f32_16x16x32_bf16 v[80:83], v[132:135], v[208:211], v[80:83]
	v_mfma_f32_16x16x32_bf16 v[16:19], v[140:143], v[208:211], v[16:19]
	v_mfma_f32_16x16x32_bf16 v[76:79], v[132:135], v[216:219], v[76:79]
	v_mfma_f32_16x16x32_bf16 v[12:15], v[140:143], v[216:219], v[12:15]
	s_setprio 0
	s_setprio 1
	v_mfma_f32_16x16x32_bf16 v[68:71], v[144:147], v[160:163], v[68:71]
	v_mfma_f32_16x16x32_bf16 v[4:7], v[152:155], v[160:163], v[4:7]
	v_mfma_f32_16x16x32_bf16 v[84:87], v[144:147], v[168:171], v[84:87]
	v_mfma_f32_16x16x32_bf16 v[24:27], v[152:155], v[168:171], v[24:27]
	v_mfma_f32_16x16x32_bf16 v[72:75], v[144:147], v[196:199], v[72:75]
	v_mfma_f32_16x16x32_bf16 v[8:11], v[152:155], v[196:199], v[8:11]
	v_mfma_f32_16x16x32_bf16 v[64:67], v[144:147], v[212:215], v[64:67]
	v_mfma_f32_16x16x32_bf16 v[0:3], v[152:155], v[212:215], v[0:3]
	v_mfma_f32_16x16x32_bf16 v[68:71], v[148:151], v[164:167], v[68:71]
	v_mfma_f32_16x16x32_bf16 v[4:7], v[156:159], v[164:167], v[4:7]
	v_mfma_f32_16x16x32_bf16 v[84:87], v[148:151], v[172:175], v[84:87]
	v_mfma_f32_16x16x32_bf16 v[24:27], v[156:159], v[172:175], v[24:27]
	v_mfma_f32_16x16x32_bf16 v[72:75], v[148:151], v[208:211], v[72:75]
	v_mfma_f32_16x16x32_bf16 v[8:11], v[156:159], v[208:211], v[8:11]
	v_mfma_f32_16x16x32_bf16 v[64:67], v[148:151], v[216:219], v[64:67]
	v_mfma_f32_16x16x32_bf16 v[0:3], v[156:159], v[216:219], v[0:3]
	s_setprio 0
	s_barrier
	s_add_i32 vcc_lo, vcc_lo, 2
	s_add_u32 s66, s66, 0x100
	s_addc_u32 s67, s67, 0
	s_cmp_gt_u32 vcc_lo, 29
	s_mov_b64 s[10:11], s[16:17]
	s_cbranch_scc0 .LBB0_1105

.LBB0_1349:
	s_add_u32 s47, s20, 0x100
	s_addc_u32 s52, s21, 0
	s_mov_b32 s53, -2
	v_readlane_b32 s0, v255, 49
	s_nop 3
	s_cmp_eq_u32 s0, 9
	v_writelane_b32 v255, 9, 49
	s_cbranch_scc0 .Ltrip0_strict_8
	s_add_u32 s20, s16, 0x100
	s_addc_u32 s21, s17, 0
	s_add_i32 s0, 0, 0x10000
	s_cmpk_eq_i32 s53, 0x54
	s_cselect_b32 s25, s13, s21
	s_cselect_b32 s24, s12, s20
	s_cselect_b32 s23, s15, s52
	s_cselect_b32 s22, s14, s47
	s_add_i32 s1, 0, 0x14000
	v_add_u32_e32 v154, s0, v139
	v_add_u32_e32 v170, s1, v139
	ds_read_b128 v[142:145], v154
	ds_read_b128 v[146:149], v154 offset:1024
	ds_read_b128 v[150:153], v154 offset:2048
	ds_read_b128 v[154:157], v154 offset:3072
	ds_read_b128 v[158:161], v170
	ds_read_b128 v[162:165], v170 offset:1024
	ds_read_b128 v[166:169], v170 offset:2048
	ds_read_b128 v[170:173], v170 offset:3072
	v_lshl_add_u64 v[186:187], s[16:17], 0, v[134:135]
	s_add_i32 m0, s29, 0xc000
	ds_read_b128 v[174:177], v141
	ds_read_b128 v[178:181], v141 offset:1024
	ds_read_b128 v[182:185], v141 offset:2048
	ds_read_b128 v[196:199], v141 offset:3072
	ds_read_b128 v[200:203], v141 offset:4096
	ds_read_b128 v[204:207], v141 offset:5120
	ds_read_b128 v[208:211], v141 offset:6144
	ds_read_b128 v[212:215], v141 offset:7168
	global_load_lds_dwordx4 v[186:187], off
	s_add_i32 m0, s29, 0xe000
	v_lshl_add_u64 v[186:187], s[16:17], 0, v[136:137]
	global_load_lds_dwordx4 v[186:187], off
	s_waitcnt vmcnt(24) lgkmcnt(0)
	s_setprio 1
	s_barrier
	v_mfma_f32_16x16x32_bf16 v[124:127], v[142:145], v[174:177], 0
	v_mfma_f32_16x16x32_bf16 v[120:123], v[150:153], v[174:177], 0
	v_mfma_f32_16x16x32_bf16 v[116:119], v[142:145], v[182:185], 0
	v_mfma_f32_16x16x32_bf16 v[112:115], v[150:153], v[182:185], 0
	v_mfma_f32_16x16x32_bf16 v[100:103], v[142:145], v[200:203], 0
	v_mfma_f32_16x16x32_bf16 v[96:99], v[150:153], v[200:203], 0
	v_mfma_f32_16x16x32_bf16 v[84:87], v[142:145], v[208:211], 0
	v_mfma_f32_16x16x32_bf16 v[80:83], v[150:153], v[208:211], 0
	v_mfma_f32_16x16x32_bf16 v[124:127], v[146:149], v[178:181], v[124:127]
	v_mfma_f32_16x16x32_bf16 v[120:123], v[154:157], v[178:181], v[120:123]
	v_mfma_f32_16x16x32_bf16 v[116:119], v[146:149], v[196:199], v[116:119]
	v_mfma_f32_16x16x32_bf16 v[112:115], v[154:157], v[196:199], v[112:115]
	v_mfma_f32_16x16x32_bf16 v[100:103], v[146:149], v[204:207], v[100:103]
	v_mfma_f32_16x16x32_bf16 v[96:99], v[154:157], v[204:207], v[96:99]
	v_mfma_f32_16x16x32_bf16 v[84:87], v[146:149], v[212:215], v[84:87]
	v_mfma_f32_16x16x32_bf16 v[80:83], v[154:157], v[212:215], v[80:83]
	s_setprio 0
	s_setprio 1
	v_mfma_f32_16x16x32_bf16 v[108:111], v[158:161], v[174:177], 0
	v_mfma_f32_16x16x32_bf16 v[104:107], v[166:169], v[174:177], 0
	v_mfma_f32_16x16x32_bf16 v[92:95], v[158:161], v[182:185], 0
	v_mfma_f32_16x16x32_bf16 v[88:91], v[166:169], v[182:185], 0
	v_mfma_f32_16x16x32_bf16 v[76:79], v[158:161], v[200:203], 0
	v_mfma_f32_16x16x32_bf16 v[72:75], v[166:169], v[200:203], 0
	v_mfma_f32_16x16x32_bf16 v[68:71], v[158:161], v[208:211], 0
	v_mfma_f32_16x16x32_bf16 v[64:67], v[166:169], v[208:211], 0
	v_mfma_f32_16x16x32_bf16 v[108:111], v[162:165], v[178:181], v[108:111]
	v_mfma_f32_16x16x32_bf16 v[104:107], v[170:173], v[178:181], v[104:107]
	v_mfma_f32_16x16x32_bf16 v[92:95], v[162:165], v[196:199], v[92:95]
	v_mfma_f32_16x16x32_bf16 v[88:91], v[170:173], v[196:199], v[88:91]
	v_mfma_f32_16x16x32_bf16 v[76:79], v[162:165], v[204:207], v[76:79]
	v_mfma_f32_16x16x32_bf16 v[72:75], v[170:173], v[204:207], v[72:75]
	v_mfma_f32_16x16x32_bf16 v[68:71], v[162:165], v[212:215], v[68:71]
	v_mfma_f32_16x16x32_bf16 v[64:67], v[170:173], v[212:215], v[64:67]
	s_barrier
	s_setprio 0
	s_add_i32 s0, s0, s28
	v_lshl_add_u64 v[186:187], s[22:23], 0, v[190:191]
	s_mov_b32 m0, s0
	ds_read_b128 v[174:177], v141 offset:16384
	ds_read_b128 v[178:181], v141 offset:17408
	ds_read_b128 v[182:185], v141 offset:18432
	ds_read_b128 v[196:199], v141 offset:19456
	ds_read_b128 v[200:203], v141 offset:20480
	ds_read_b128 v[204:207], v141 offset:21504
	ds_read_b128 v[208:211], v141 offset:22528
	ds_read_b128 v[212:215], v141 offset:23552
	global_load_lds_dwordx4 v[186:187], off
	s_add_i32 m0, s0, 0x2000
	s_add_u32 s16, s22, 0x160000
	v_lshl_add_u64 v[216:217], s[22:23], 0, v[132:133]
	s_addc_u32 s17, s23, 0
	s_add_i32 s0, s1, s28
	global_load_lds_dwordx4 v[216:217], off
	v_lshl_add_u64 v[218:219], s[16:17], 0, v[190:191]
	s_mov_b32 m0, s0
	v_lshl_add_u64 v[220:221], s[24:25], 0, v[130:131]
	global_load_lds_dwordx4 v[218:219], off
	s_add_i32 m0, s0, 0x2000
	v_lshl_add_u64 v[218:219], s[16:17], 0, v[132:133]
	global_load_lds_dwordx4 v[218:219], off
	s_mov_b32 m0, s29
	v_lshl_add_u64 v[218:219], s[24:25], 0, v[128:129]
	global_load_lds_dwordx4 v[218:219], off
	s_mov_b32 m0, s30
	s_nop 0
	global_load_lds_dwordx4 v[220:221], off
	s_waitcnt vmcnt(24) lgkmcnt(0)
	s_setprio 1
	s_barrier
	v_mfma_f32_16x16x32_bf16 v[60:63], v[142:145], v[174:177], 0
	v_mfma_f32_16x16x32_bf16 v[56:59], v[150:153], v[174:177], 0
	v_mfma_f32_16x16x32_bf16 v[52:55], v[142:145], v[182:185], 0
	v_mfma_f32_16x16x32_bf16 v[48:51], v[150:153], v[182:185], 0
	v_mfma_f32_16x16x32_bf16 v[36:39], v[142:145], v[200:203], 0
	v_mfma_f32_16x16x32_bf16 v[32:35], v[150:153], v[200:203], 0
	v_mfma_f32_16x16x32_bf16 v[20:23], v[142:145], v[208:211], 0
	v_mfma_f32_16x16x32_bf16 v[16:19], v[150:153], v[208:211], 0
	v_mfma_f32_16x16x32_bf16 v[60:63], v[146:149], v[178:181], v[60:63]
	v_mfma_f32_16x16x32_bf16 v[56:59], v[154:157], v[178:181], v[56:59]
	v_mfma_f32_16x16x32_bf16 v[52:55], v[146:149], v[196:199], v[52:55]
	v_mfma_f32_16x16x32_bf16 v[48:51], v[154:157], v[196:199], v[48:51]
	v_mfma_f32_16x16x32_bf16 v[36:39], v[146:149], v[204:207], v[36:39]
	v_mfma_f32_16x16x32_bf16 v[32:35], v[154:157], v[204:207], v[32:35]
	v_mfma_f32_16x16x32_bf16 v[20:23], v[146:149], v[212:215], v[20:23]
	v_mfma_f32_16x16x32_bf16 v[16:19], v[154:157], v[212:215], v[16:19]
	s_setprio 0
	s_setprio 1
	v_mfma_f32_16x16x32_bf16 v[44:47], v[158:161], v[174:177], 0
	v_mfma_f32_16x16x32_bf16 v[40:43], v[166:169], v[174:177], 0
	v_mfma_f32_16x16x32_bf16 v[28:31], v[158:161], v[182:185], 0
	v_mfma_f32_16x16x32_bf16 v[24:27], v[166:169], v[182:185], 0
	v_mfma_f32_16x16x32_bf16 v[12:15], v[158:161], v[200:203], 0
	v_mfma_f32_16x16x32_bf16 v[8:11], v[166:169], v[200:203], 0
	v_mfma_f32_16x16x32_bf16 v[4:7], v[158:161], v[208:211], 0
	v_mfma_f32_16x16x32_bf16 v[0:3], v[166:169], v[208:211], 0
	v_mfma_f32_16x16x32_bf16 v[44:47], v[162:165], v[178:181], v[44:47]
	v_mfma_f32_16x16x32_bf16 v[40:43], v[170:173], v[178:181], v[40:43]
	v_mfma_f32_16x16x32_bf16 v[28:31], v[162:165], v[196:199], v[28:31]
	v_mfma_f32_16x16x32_bf16 v[24:27], v[170:173], v[196:199], v[24:27]
	v_mfma_f32_16x16x32_bf16 v[12:15], v[162:165], v[204:207], v[12:15]
	v_mfma_f32_16x16x32_bf16 v[8:11], v[170:173], v[204:207], v[8:11]
	v_mfma_f32_16x16x32_bf16 v[4:7], v[162:165], v[212:215], v[4:7]
	v_mfma_f32_16x16x32_bf16 v[0:3], v[170:173], v[212:215], v[0:3]
	s_barrier
	s_setprio 0
	s_add_i32 s0, 0, 0x18000
	s_add_i32 s1, 0, 0x1c000
	v_add_u32_e32 v154, s0, v139
	v_add_u32_e32 v170, s1, v139
	ds_read_b128 v[142:145], v154
	ds_read_b128 v[146:149], v154 offset:1024
	ds_read_b128 v[150:153], v154 offset:2048
	ds_read_b128 v[154:157], v154 offset:3072
	ds_read_b128 v[158:161], v170
	ds_read_b128 v[162:165], v170 offset:1024
	ds_read_b128 v[166:169], v170 offset:2048
	ds_read_b128 v[170:173], v170 offset:3072
	s_add_u32 s16, s24, 0x160000
	s_addc_u32 s17, s25, 0
	s_mov_b32 m0, s31
	v_lshl_add_u64 v[222:223], s[16:17], 0, v[128:129]
	ds_read_b128 v[174:177], v141 offset:32768
	ds_read_b128 v[178:181], v141 offset:33792
	ds_read_b128 v[182:185], v141 offset:34816
	ds_read_b128 v[196:199], v141 offset:35840
	ds_read_b128 v[200:203], v141 offset:36864
	ds_read_b128 v[204:207], v141 offset:37888
	ds_read_b128 v[208:211], v141 offset:38912
	ds_read_b128 v[212:215], v141 offset:39936
	global_load_lds_dwordx4 v[222:223], off
	s_mov_b32 m0, s33
	v_lshl_add_u64 v[222:223], s[16:17], 0, v[130:131]
	global_load_lds_dwordx4 v[222:223], off
	s_waitcnt vmcnt(8) lgkmcnt(0)
	s_setprio 1
	s_barrier
	v_mfma_f32_16x16x32_bf16 v[124:127], v[142:145], v[174:177], v[124:127]
	v_mfma_f32_16x16x32_bf16 v[120:123], v[150:153], v[174:177], v[120:123]
	v_mfma_f32_16x16x32_bf16 v[116:119], v[142:145], v[182:185], v[116:119]
	v_mfma_f32_16x16x32_bf16 v[112:115], v[150:153], v[182:185], v[112:115]
	v_mfma_f32_16x16x32_bf16 v[100:103], v[142:145], v[200:203], v[100:103]
	v_mfma_f32_16x16x32_bf16 v[96:99], v[150:153], v[200:203], v[96:99]
	v_mfma_f32_16x16x32_bf16 v[84:87], v[142:145], v[208:211], v[84:87]
	v_mfma_f32_16x16x32_bf16 v[80:83], v[150:153], v[208:211], v[80:83]
	v_mfma_f32_16x16x32_bf16 v[124:127], v[146:149], v[178:181], v[124:127]
	v_mfma_f32_16x16x32_bf16 v[120:123], v[154:157], v[178:181], v[120:123]
	v_mfma_f32_16x16x32_bf16 v[116:119], v[146:149], v[196:199], v[116:119]
	v_mfma_f32_16x16x32_bf16 v[112:115], v[154:157], v[196:199], v[112:115]
	v_mfma_f32_16x16x32_bf16 v[100:103], v[146:149], v[204:207], v[100:103]
	v_mfma_f32_16x16x32_bf16 v[96:99], v[154:157], v[204:207], v[96:99]
	v_mfma_f32_16x16x32_bf16 v[84:87], v[146:149], v[212:215], v[84:87]
	v_mfma_f32_16x16x32_bf16 v[80:83], v[154:157], v[212:215], v[80:83]
	s_setprio 0
	s_setprio 1
	v_mfma_f32_16x16x32_bf16 v[108:111], v[158:161], v[174:177], v[108:111]
	v_mfma_f32_16x16x32_bf16 v[104:107], v[166:169], v[174:177], v[104:107]
	v_mfma_f32_16x16x32_bf16 v[92:95], v[158:161], v[182:185], v[92:95]
	v_mfma_f32_16x16x32_bf16 v[88:91], v[166:169], v[182:185], v[88:91]
	v_mfma_f32_16x16x32_bf16 v[76:79], v[158:161], v[200:203], v[76:79]
	v_mfma_f32_16x16x32_bf16 v[72:75], v[166:169], v[200:203], v[72:75]
	v_mfma_f32_16x16x32_bf16 v[68:71], v[158:161], v[208:211], v[68:71]
	v_mfma_f32_16x16x32_bf16 v[64:67], v[166:169], v[208:211], v[64:67]
	v_mfma_f32_16x16x32_bf16 v[108:111], v[162:165], v[178:181], v[108:111]
	v_mfma_f32_16x16x32_bf16 v[104:107], v[170:173], v[178:181], v[104:107]
	v_mfma_f32_16x16x32_bf16 v[92:95], v[162:165], v[196:199], v[92:95]
	v_mfma_f32_16x16x32_bf16 v[88:91], v[170:173], v[196:199], v[88:91]
	v_mfma_f32_16x16x32_bf16 v[76:79], v[162:165], v[204:207], v[76:79]
	v_mfma_f32_16x16x32_bf16 v[72:75], v[170:173], v[204:207], v[72:75]
	v_mfma_f32_16x16x32_bf16 v[68:71], v[162:165], v[212:215], v[68:71]
	v_mfma_f32_16x16x32_bf16 v[64:67], v[170:173], v[212:215], v[64:67]
	s_barrier
	s_setprio 0
	s_add_i32 s0, s0, s28
	v_lshl_add_u64 v[186:187], v[186:187], 0, s[58:59]
	s_mov_b32 m0, s0
	ds_read_b128 v[174:177], v141 offset:49152
	ds_read_b128 v[178:181], v141 offset:50176
	ds_read_b128 v[182:185], v141 offset:51200
	ds_read_b128 v[196:199], v141 offset:52224
	ds_read_b128 v[200:203], v141 offset:53248
	ds_read_b128 v[204:207], v141 offset:54272
	ds_read_b128 v[208:211], v141 offset:55296
	ds_read_b128 v[212:215], v141 offset:56320
	global_load_lds_dwordx4 v[186:187], off
	s_add_i32 m0, s0, 0x2000
	s_add_u32 s16, s22, 0x160080
	v_lshl_add_u64 v[186:187], v[216:217], 0, s[58:59]
	s_addc_u32 s17, s23, 0
	s_add_i32 s0, s1, s28
	global_load_lds_dwordx4 v[186:187], off
	s_mov_b32 m0, s0
	v_lshl_add_u64 v[186:187], s[16:17], 0, v[190:191]
	global_load_lds_dwordx4 v[186:187], off
	s_add_i32 m0, s0, 0x2000
	v_lshl_add_u64 v[186:187], s[16:17], 0, v[132:133]
	global_load_lds_dwordx4 v[186:187], off
	s_mov_b32 m0, s37
	v_lshl_add_u64 v[186:187], v[218:219], 0, s[58:59]
	global_load_lds_dwordx4 v[186:187], off
	s_mov_b32 m0, s38
	v_lshl_add_u64 v[186:187], v[220:221], 0, s[58:59]
	global_load_lds_dwordx4 v[186:187], off
	s_waitcnt vmcnt(8) lgkmcnt(0)
	s_setprio 1
	s_barrier
	v_mfma_f32_16x16x32_bf16 v[60:63], v[142:145], v[174:177], v[60:63]
	v_mfma_f32_16x16x32_bf16 v[56:59], v[150:153], v[174:177], v[56:59]
	v_mfma_f32_16x16x32_bf16 v[52:55], v[142:145], v[182:185], v[52:55]
	v_mfma_f32_16x16x32_bf16 v[48:51], v[150:153], v[182:185], v[48:51]
	v_mfma_f32_16x16x32_bf16 v[36:39], v[142:145], v[200:203], v[36:39]
	v_mfma_f32_16x16x32_bf16 v[32:35], v[150:153], v[200:203], v[32:35]
	v_mfma_f32_16x16x32_bf16 v[20:23], v[142:145], v[208:211], v[20:23]
	v_mfma_f32_16x16x32_bf16 v[16:19], v[150:153], v[208:211], v[16:19]
	v_mfma_f32_16x16x32_bf16 v[60:63], v[146:149], v[178:181], v[60:63]
	v_mfma_f32_16x16x32_bf16 v[56:59], v[154:157], v[178:181], v[56:59]
	v_mfma_f32_16x16x32_bf16 v[52:55], v[146:149], v[196:199], v[52:55]
	v_mfma_f32_16x16x32_bf16 v[48:51], v[154:157], v[196:199], v[48:51]
	v_mfma_f32_16x16x32_bf16 v[36:39], v[146:149], v[204:207], v[36:39]
	v_mfma_f32_16x16x32_bf16 v[32:35], v[154:157], v[204:207], v[32:35]
	v_mfma_f32_16x16x32_bf16 v[20:23], v[146:149], v[212:215], v[20:23]
	v_mfma_f32_16x16x32_bf16 v[16:19], v[154:157], v[212:215], v[16:19]
	s_setprio 0
	s_setprio 1
	v_mfma_f32_16x16x32_bf16 v[44:47], v[158:161], v[174:177], v[44:47]
	v_mfma_f32_16x16x32_bf16 v[40:43], v[166:169], v[174:177], v[40:43]
	v_mfma_f32_16x16x32_bf16 v[28:31], v[158:161], v[182:185], v[28:31]
	v_mfma_f32_16x16x32_bf16 v[24:27], v[166:169], v[182:185], v[24:27]
	v_mfma_f32_16x16x32_bf16 v[12:15], v[158:161], v[200:203], v[12:15]
	v_mfma_f32_16x16x32_bf16 v[8:11], v[166:169], v[200:203], v[8:11]
	v_mfma_f32_16x16x32_bf16 v[4:7], v[158:161], v[208:211], v[4:7]
	v_mfma_f32_16x16x32_bf16 v[0:3], v[166:169], v[208:211], v[0:3]
	v_mfma_f32_16x16x32_bf16 v[44:47], v[162:165], v[178:181], v[44:47]
	v_mfma_f32_16x16x32_bf16 v[40:43], v[170:173], v[178:181], v[40:43]
	v_mfma_f32_16x16x32_bf16 v[28:31], v[162:165], v[196:199], v[28:31]
	v_mfma_f32_16x16x32_bf16 v[24:27], v[170:173], v[196:199], v[24:27]
	v_mfma_f32_16x16x32_bf16 v[12:15], v[162:165], v[204:207], v[12:15]
	v_mfma_f32_16x16x32_bf16 v[8:11], v[170:173], v[204:207], v[8:11]
	v_mfma_f32_16x16x32_bf16 v[4:7], v[162:165], v[212:215], v[4:7]
	v_mfma_f32_16x16x32_bf16 v[0:3], v[170:173], v[212:215], v[0:3]
	s_barrier
	s_setprio 0
	s_add_i32 s53, s53, 2
	s_add_u32 s47, s47, 0x100
	s_addc_u32 s52, s52, 0
	s_cmpk_gt_u32 s53, 0x55
	s_mov_b64 s[16:17], s[20:21]
	s_cbranch_scc1 .Lpeel_done_8
	s_branch .LBB0_1350
.Ltrip0_strict_8:
	s_add_u32 s20, s16, 0x100
	s_addc_u32 s21, s17, 0
	s_add_i32 s0, 0, 0x10000
	s_cmpk_eq_i32 s53, 0x54
	s_cselect_b32 s25, s13, s21
	s_cselect_b32 s24, s12, s20
	s_cselect_b32 s23, s15, s52
	s_cselect_b32 s22, s14, s47
	s_add_i32 s1, 0, 0x14000
	v_add_u32_e32 v154, s0, v139
	v_add_u32_e32 v170, s1, v139
	ds_read_b128 v[142:145], v154
	ds_read_b128 v[146:149], v154 offset:1024
	ds_read_b128 v[150:153], v154 offset:2048
	ds_read_b128 v[154:157], v154 offset:3072
	ds_read_b128 v[158:161], v170
	ds_read_b128 v[162:165], v170 offset:1024
	ds_read_b128 v[166:169], v170 offset:2048
	ds_read_b128 v[170:173], v170 offset:3072
	v_lshl_add_u64 v[186:187], s[16:17], 0, v[134:135]
	s_add_i32 m0, s29, 0xc000
	ds_read_b128 v[174:177], v141
	ds_read_b128 v[178:181], v141 offset:1024
	ds_read_b128 v[182:185], v141 offset:2048
	ds_read_b128 v[196:199], v141 offset:3072
	ds_read_b128 v[200:203], v141 offset:4096
	ds_read_b128 v[204:207], v141 offset:5120
	ds_read_b128 v[208:211], v141 offset:6144
	ds_read_b128 v[212:215], v141 offset:7168
	global_load_lds_dwordx4 v[186:187], off
	s_add_i32 m0, s29, 0xe000
	v_lshl_add_u64 v[186:187], s[16:17], 0, v[136:137]
	global_load_lds_dwordx4 v[186:187], off
	s_waitcnt vmcnt(8) lgkmcnt(0)
	s_setprio 1
	s_barrier
	v_mfma_f32_16x16x32_bf16 v[124:127], v[142:145], v[174:177], 0
	v_mfma_f32_16x16x32_bf16 v[120:123], v[150:153], v[174:177], 0
	v_mfma_f32_16x16x32_bf16 v[116:119], v[142:145], v[182:185], 0
	v_mfma_f32_16x16x32_bf16 v[112:115], v[150:153], v[182:185], 0
	v_mfma_f32_16x16x32_bf16 v[100:103], v[142:145], v[200:203], 0
	v_mfma_f32_16x16x32_bf16 v[96:99], v[150:153], v[200:203], 0
	v_mfma_f32_16x16x32_bf16 v[84:87], v[142:145], v[208:211], 0
	v_mfma_f32_16x16x32_bf16 v[80:83], v[150:153], v[208:211], 0
	v_mfma_f32_16x16x32_bf16 v[124:127], v[146:149], v[178:181], v[124:127]
	v_mfma_f32_16x16x32_bf16 v[120:123], v[154:157], v[178:181], v[120:123]
	v_mfma_f32_16x16x32_bf16 v[116:119], v[146:149], v[196:199], v[116:119]
	v_mfma_f32_16x16x32_bf16 v[112:115], v[154:157], v[196:199], v[112:115]
	v_mfma_f32_16x16x32_bf16 v[100:103], v[146:149], v[204:207], v[100:103]
	v_mfma_f32_16x16x32_bf16 v[96:99], v[154:157], v[204:207], v[96:99]
	v_mfma_f32_16x16x32_bf16 v[84:87], v[146:149], v[212:215], v[84:87]
	v_mfma_f32_16x16x32_bf16 v[80:83], v[154:157], v[212:215], v[80:83]
	s_setprio 0
	s_setprio 1
	v_mfma_f32_16x16x32_bf16 v[108:111], v[158:161], v[174:177], 0
	v_mfma_f32_16x16x32_bf16 v[104:107], v[166:169], v[174:177], 0
	v_mfma_f32_16x16x32_bf16 v[92:95], v[158:161], v[182:185], 0
	v_mfma_f32_16x16x32_bf16 v[88:91], v[166:169], v[182:185], 0
	v_mfma_f32_16x16x32_bf16 v[76:79], v[158:161], v[200:203], 0
	v_mfma_f32_16x16x32_bf16 v[72:75], v[166:169], v[200:203], 0
	v_mfma_f32_16x16x32_bf16 v[68:71], v[158:161], v[208:211], 0
	v_mfma_f32_16x16x32_bf16 v[64:67], v[166:169], v[208:211], 0
	v_mfma_f32_16x16x32_bf16 v[108:111], v[162:165], v[178:181], v[108:111]
	v_mfma_f32_16x16x32_bf16 v[104:107], v[170:173], v[178:181], v[104:107]
	v_mfma_f32_16x16x32_bf16 v[92:95], v[162:165], v[196:199], v[92:95]
	v_mfma_f32_16x16x32_bf16 v[88:91], v[170:173], v[196:199], v[88:91]
	v_mfma_f32_16x16x32_bf16 v[76:79], v[162:165], v[204:207], v[76:79]
	v_mfma_f32_16x16x32_bf16 v[72:75], v[170:173], v[204:207], v[72:75]
	v_mfma_f32_16x16x32_bf16 v[68:71], v[162:165], v[212:215], v[68:71]
	v_mfma_f32_16x16x32_bf16 v[64:67], v[170:173], v[212:215], v[64:67]
	s_barrier
	s_setprio 0
	s_add_i32 s0, s0, s28
	v_lshl_add_u64 v[186:187], s[22:23], 0, v[190:191]
	s_mov_b32 m0, s0
	ds_read_b128 v[174:177], v141 offset:16384
	ds_read_b128 v[178:181], v141 offset:17408
	ds_read_b128 v[182:185], v141 offset:18432
	ds_read_b128 v[196:199], v141 offset:19456
	ds_read_b128 v[200:203], v141 offset:20480
	ds_read_b128 v[204:207], v141 offset:21504
	ds_read_b128 v[208:211], v141 offset:22528
	ds_read_b128 v[212:215], v141 offset:23552
	global_load_lds_dwordx4 v[186:187], off
	s_add_i32 m0, s0, 0x2000
	s_add_u32 s16, s22, 0x160000
	v_lshl_add_u64 v[216:217], s[22:23], 0, v[132:133]
	s_addc_u32 s17, s23, 0
	s_add_i32 s0, s1, s28
	global_load_lds_dwordx4 v[216:217], off
	v_lshl_add_u64 v[218:219], s[16:17], 0, v[190:191]
	s_mov_b32 m0, s0
	v_lshl_add_u64 v[220:221], s[24:25], 0, v[130:131]
	global_load_lds_dwordx4 v[218:219], off
	s_add_i32 m0, s0, 0x2000
	v_lshl_add_u64 v[218:219], s[16:17], 0, v[132:133]
	global_load_lds_dwordx4 v[218:219], off
	s_mov_b32 m0, s29
	v_lshl_add_u64 v[218:219], s[24:25], 0, v[128:129]
	global_load_lds_dwordx4 v[218:219], off
	s_mov_b32 m0, s30
	s_nop 0
	global_load_lds_dwordx4 v[220:221], off
	s_waitcnt vmcnt(8) lgkmcnt(0)
	s_setprio 1
	s_barrier
	v_mfma_f32_16x16x32_bf16 v[60:63], v[142:145], v[174:177], 0
	v_mfma_f32_16x16x32_bf16 v[56:59], v[150:153], v[174:177], 0
	v_mfma_f32_16x16x32_bf16 v[52:55], v[142:145], v[182:185], 0
	v_mfma_f32_16x16x32_bf16 v[48:51], v[150:153], v[182:185], 0
	v_mfma_f32_16x16x32_bf16 v[36:39], v[142:145], v[200:203], 0
	v_mfma_f32_16x16x32_bf16 v[32:35], v[150:153], v[200:203], 0
	v_mfma_f32_16x16x32_bf16 v[20:23], v[142:145], v[208:211], 0
	v_mfma_f32_16x16x32_bf16 v[16:19], v[150:153], v[208:211], 0
	v_mfma_f32_16x16x32_bf16 v[60:63], v[146:149], v[178:181], v[60:63]
	v_mfma_f32_16x16x32_bf16 v[56:59], v[154:157], v[178:181], v[56:59]
	v_mfma_f32_16x16x32_bf16 v[52:55], v[146:149], v[196:199], v[52:55]
	v_mfma_f32_16x16x32_bf16 v[48:51], v[154:157], v[196:199], v[48:51]
	v_mfma_f32_16x16x32_bf16 v[36:39], v[146:149], v[204:207], v[36:39]
	v_mfma_f32_16x16x32_bf16 v[32:35], v[154:157], v[204:207], v[32:35]
	v_mfma_f32_16x16x32_bf16 v[20:23], v[146:149], v[212:215], v[20:23]
	v_mfma_f32_16x16x32_bf16 v[16:19], v[154:157], v[212:215], v[16:19]
	s_setprio 0
	s_setprio 1
	v_mfma_f32_16x16x32_bf16 v[44:47], v[158:161], v[174:177], 0
	v_mfma_f32_16x16x32_bf16 v[40:43], v[166:169], v[174:177], 0
	v_mfma_f32_16x16x32_bf16 v[28:31], v[158:161], v[182:185], 0
	v_mfma_f32_16x16x32_bf16 v[24:27], v[166:169], v[182:185], 0
	v_mfma_f32_16x16x32_bf16 v[12:15], v[158:161], v[200:203], 0
	v_mfma_f32_16x16x32_bf16 v[8:11], v[166:169], v[200:203], 0
	v_mfma_f32_16x16x32_bf16 v[4:7], v[158:161], v[208:211], 0
	v_mfma_f32_16x16x32_bf16 v[0:3], v[166:169], v[208:211], 0
	v_mfma_f32_16x16x32_bf16 v[44:47], v[162:165], v[178:181], v[44:47]
	v_mfma_f32_16x16x32_bf16 v[40:43], v[170:173], v[178:181], v[40:43]
	v_mfma_f32_16x16x32_bf16 v[28:31], v[162:165], v[196:199], v[28:31]
	v_mfma_f32_16x16x32_bf16 v[24:27], v[170:173], v[196:199], v[24:27]
	v_mfma_f32_16x16x32_bf16 v[12:15], v[162:165], v[204:207], v[12:15]
	v_mfma_f32_16x16x32_bf16 v[8:11], v[170:173], v[204:207], v[8:11]
	v_mfma_f32_16x16x32_bf16 v[4:7], v[162:165], v[212:215], v[4:7]
	v_mfma_f32_16x16x32_bf16 v[0:3], v[170:173], v[212:215], v[0:3]
	s_barrier
	s_setprio 0
	s_add_i32 s0, 0, 0x18000
	s_add_i32 s1, 0, 0x1c000
	v_add_u32_e32 v154, s0, v139
	v_add_u32_e32 v170, s1, v139
	ds_read_b128 v[142:145], v154
	ds_read_b128 v[146:149], v154 offset:1024
	ds_read_b128 v[150:153], v154 offset:2048
	ds_read_b128 v[154:157], v154 offset:3072
	ds_read_b128 v[158:161], v170
	ds_read_b128 v[162:165], v170 offset:1024
	ds_read_b128 v[166:169], v170 offset:2048
	ds_read_b128 v[170:173], v170 offset:3072
	s_add_u32 s16, s24, 0x160000
	s_addc_u32 s17, s25, 0
	s_mov_b32 m0, s31
	v_lshl_add_u64 v[222:223], s[16:17], 0, v[128:129]
	ds_read_b128 v[174:177], v141 offset:32768
	ds_read_b128 v[178:181], v141 offset:33792
	ds_read_b128 v[182:185], v141 offset:34816
	ds_read_b128 v[196:199], v141 offset:35840
	ds_read_b128 v[200:203], v141 offset:36864
	ds_read_b128 v[204:207], v141 offset:37888
	ds_read_b128 v[208:211], v141 offset:38912
	ds_read_b128 v[212:215], v141 offset:39936
	global_load_lds_dwordx4 v[222:223], off
	s_mov_b32 m0, s33
	v_lshl_add_u64 v[222:223], s[16:17], 0, v[130:131]
	global_load_lds_dwordx4 v[222:223], off
	s_waitcnt vmcnt(8) lgkmcnt(0)
	s_setprio 1
	s_barrier
	v_mfma_f32_16x16x32_bf16 v[124:127], v[142:145], v[174:177], v[124:127]
	v_mfma_f32_16x16x32_bf16 v[120:123], v[150:153], v[174:177], v[120:123]
	v_mfma_f32_16x16x32_bf16 v[116:119], v[142:145], v[182:185], v[116:119]
	v_mfma_f32_16x16x32_bf16 v[112:115], v[150:153], v[182:185], v[112:115]
	v_mfma_f32_16x16x32_bf16 v[100:103], v[142:145], v[200:203], v[100:103]
	v_mfma_f32_16x16x32_bf16 v[96:99], v[150:153], v[200:203], v[96:99]
	v_mfma_f32_16x16x32_bf16 v[84:87], v[142:145], v[208:211], v[84:87]
	v_mfma_f32_16x16x32_bf16 v[80:83], v[150:153], v[208:211], v[80:83]
	v_mfma_f32_16x16x32_bf16 v[124:127], v[146:149], v[178:181], v[124:127]
	v_mfma_f32_16x16x32_bf16 v[120:123], v[154:157], v[178:181], v[120:123]
	v_mfma_f32_16x16x32_bf16 v[116:119], v[146:149], v[196:199], v[116:119]
	v_mfma_f32_16x16x32_bf16 v[112:115], v[154:157], v[196:199], v[112:115]
	v_mfma_f32_16x16x32_bf16 v[100:103], v[146:149], v[204:207], v[100:103]
	v_mfma_f32_16x16x32_bf16 v[96:99], v[154:157], v[204:207], v[96:99]
	v_mfma_f32_16x16x32_bf16 v[84:87], v[146:149], v[212:215], v[84:87]
	v_mfma_f32_16x16x32_bf16 v[80:83], v[154:157], v[212:215], v[80:83]
	s_setprio 0
	s_setprio 1
	v_mfma_f32_16x16x32_bf16 v[108:111], v[158:161], v[174:177], v[108:111]
	v_mfma_f32_16x16x32_bf16 v[104:107], v[166:169], v[174:177], v[104:107]
	v_mfma_f32_16x16x32_bf16 v[92:95], v[158:161], v[182:185], v[92:95]
	v_mfma_f32_16x16x32_bf16 v[88:91], v[166:169], v[182:185], v[88:91]
	v_mfma_f32_16x16x32_bf16 v[76:79], v[158:161], v[200:203], v[76:79]
	v_mfma_f32_16x16x32_bf16 v[72:75], v[166:169], v[200:203], v[72:75]
	v_mfma_f32_16x16x32_bf16 v[68:71], v[158:161], v[208:211], v[68:71]
	v_mfma_f32_16x16x32_bf16 v[64:67], v[166:169], v[208:211], v[64:67]
	v_mfma_f32_16x16x32_bf16 v[108:111], v[162:165], v[178:181], v[108:111]
	v_mfma_f32_16x16x32_bf16 v[104:107], v[170:173], v[178:181], v[104:107]
	v_mfma_f32_16x16x32_bf16 v[92:95], v[162:165], v[196:199], v[92:95]
	v_mfma_f32_16x16x32_bf16 v[88:91], v[170:173], v[196:199], v[88:91]
	v_mfma_f32_16x16x32_bf16 v[76:79], v[162:165], v[204:207], v[76:79]
	v_mfma_f32_16x16x32_bf16 v[72:75], v[170:173], v[204:207], v[72:75]
	v_mfma_f32_16x16x32_bf16 v[68:71], v[162:165], v[212:215], v[68:71]
	v_mfma_f32_16x16x32_bf16 v[64:67], v[170:173], v[212:215], v[64:67]
	s_barrier
	s_setprio 0
	s_add_i32 s0, s0, s28
	v_lshl_add_u64 v[186:187], v[186:187], 0, s[58:59]
	s_mov_b32 m0, s0
	ds_read_b128 v[174:177], v141 offset:49152
	ds_read_b128 v[178:181], v141 offset:50176
	ds_read_b128 v[182:185], v141 offset:51200
	ds_read_b128 v[196:199], v141 offset:52224
	ds_read_b128 v[200:203], v141 offset:53248
	ds_read_b128 v[204:207], v141 offset:54272
	ds_read_b128 v[208:211], v141 offset:55296
	ds_read_b128 v[212:215], v141 offset:56320
	global_load_lds_dwordx4 v[186:187], off
	s_add_i32 m0, s0, 0x2000
	s_add_u32 s16, s22, 0x160080
	v_lshl_add_u64 v[186:187], v[216:217], 0, s[58:59]
	s_addc_u32 s17, s23, 0
	s_add_i32 s0, s1, s28
	global_load_lds_dwordx4 v[186:187], off
	s_mov_b32 m0, s0
	v_lshl_add_u64 v[186:187], s[16:17], 0, v[190:191]
	global_load_lds_dwordx4 v[186:187], off
	s_add_i32 m0, s0, 0x2000
	v_lshl_add_u64 v[186:187], s[16:17], 0, v[132:133]
	global_load_lds_dwordx4 v[186:187], off
	s_mov_b32 m0, s37
	v_lshl_add_u64 v[186:187], v[218:219], 0, s[58:59]
	global_load_lds_dwordx4 v[186:187], off
	s_mov_b32 m0, s38
	v_lshl_add_u64 v[186:187], v[220:221], 0, s[58:59]
	global_load_lds_dwordx4 v[186:187], off
	s_waitcnt vmcnt(8) lgkmcnt(0)
	s_setprio 1
	s_barrier
	v_mfma_f32_16x16x32_bf16 v[60:63], v[142:145], v[174:177], v[60:63]
	v_mfma_f32_16x16x32_bf16 v[56:59], v[150:153], v[174:177], v[56:59]
	v_mfma_f32_16x16x32_bf16 v[52:55], v[142:145], v[182:185], v[52:55]
	v_mfma_f32_16x16x32_bf16 v[48:51], v[150:153], v[182:185], v[48:51]
	v_mfma_f32_16x16x32_bf16 v[36:39], v[142:145], v[200:203], v[36:39]
	v_mfma_f32_16x16x32_bf16 v[32:35], v[150:153], v[200:203], v[32:35]
	v_mfma_f32_16x16x32_bf16 v[20:23], v[142:145], v[208:211], v[20:23]
	v_mfma_f32_16x16x32_bf16 v[16:19], v[150:153], v[208:211], v[16:19]
	v_mfma_f32_16x16x32_bf16 v[60:63], v[146:149], v[178:181], v[60:63]
	v_mfma_f32_16x16x32_bf16 v[56:59], v[154:157], v[178:181], v[56:59]
	v_mfma_f32_16x16x32_bf16 v[52:55], v[146:149], v[196:199], v[52:55]
	v_mfma_f32_16x16x32_bf16 v[48:51], v[154:157], v[196:199], v[48:51]
	v_mfma_f32_16x16x32_bf16 v[36:39], v[146:149], v[204:207], v[36:39]
	v_mfma_f32_16x16x32_bf16 v[32:35], v[154:157], v[204:207], v[32:35]
	v_mfma_f32_16x16x32_bf16 v[20:23], v[146:149], v[212:215], v[20:23]
	v_mfma_f32_16x16x32_bf16 v[16:19], v[154:157], v[212:215], v[16:19]
	s_setprio 0
	s_setprio 1
	v_mfma_f32_16x16x32_bf16 v[44:47], v[158:161], v[174:177], v[44:47]
	v_mfma_f32_16x16x32_bf16 v[40:43], v[166:169], v[174:177], v[40:43]
	v_mfma_f32_16x16x32_bf16 v[28:31], v[158:161], v[182:185], v[28:31]
	v_mfma_f32_16x16x32_bf16 v[24:27], v[166:169], v[182:185], v[24:27]
	v_mfma_f32_16x16x32_bf16 v[12:15], v[158:161], v[200:203], v[12:15]
	v_mfma_f32_16x16x32_bf16 v[8:11], v[166:169], v[200:203], v[8:11]
	v_mfma_f32_16x16x32_bf16 v[4:7], v[158:161], v[208:211], v[4:7]
	v_mfma_f32_16x16x32_bf16 v[0:3], v[166:169], v[208:211], v[0:3]
	v_mfma_f32_16x16x32_bf16 v[44:47], v[162:165], v[178:181], v[44:47]
	v_mfma_f32_16x16x32_bf16 v[40:43], v[170:173], v[178:181], v[40:43]
	v_mfma_f32_16x16x32_bf16 v[28:31], v[162:165], v[196:199], v[28:31]
	v_mfma_f32_16x16x32_bf16 v[24:27], v[170:173], v[196:199], v[24:27]
	v_mfma_f32_16x16x32_bf16 v[12:15], v[162:165], v[204:207], v[12:15]
	v_mfma_f32_16x16x32_bf16 v[8:11], v[170:173], v[204:207], v[8:11]
	v_mfma_f32_16x16x32_bf16 v[4:7], v[162:165], v[212:215], v[4:7]
	v_mfma_f32_16x16x32_bf16 v[0:3], v[170:173], v[212:215], v[0:3]
	s_barrier
	s_setprio 0
	s_add_i32 s53, s53, 2
	s_add_u32 s47, s47, 0x100
	s_addc_u32 s52, s52, 0
	s_cmpk_gt_u32 s53, 0x55
	s_mov_b64 s[16:17], s[20:21]
	s_cbranch_scc1 .Lpeel_done_8
.LBB0_1350:
	s_add_u32 s20, s16, 0x100
	s_addc_u32 s21, s17, 0
	s_add_i32 s0, 0, 0x10000
	s_cmpk_eq_i32 s53, 0x54
	s_cselect_b32 s25, s13, s21
	s_cselect_b32 s24, s12, s20
	s_cselect_b32 s23, s15, s52
	s_cselect_b32 s22, s14, s47
	s_add_i32 s1, 0, 0x14000
	v_add_u32_e32 v154, s0, v139
	v_add_u32_e32 v170, s1, v139
	ds_read_b128 v[142:145], v154
	ds_read_b128 v[146:149], v154 offset:1024
	ds_read_b128 v[150:153], v154 offset:2048
	ds_read_b128 v[154:157], v154 offset:3072
	ds_read_b128 v[158:161], v170
	ds_read_b128 v[162:165], v170 offset:1024
	ds_read_b128 v[166:169], v170 offset:2048
	ds_read_b128 v[170:173], v170 offset:3072
	v_lshl_add_u64 v[186:187], s[16:17], 0, v[134:135]
	s_add_i32 m0, s29, 0xc000
	ds_read_b128 v[174:177], v141
	ds_read_b128 v[178:181], v141 offset:1024
	ds_read_b128 v[182:185], v141 offset:2048
	ds_read_b128 v[196:199], v141 offset:3072
	ds_read_b128 v[200:203], v141 offset:4096
	ds_read_b128 v[204:207], v141 offset:5120
	ds_read_b128 v[208:211], v141 offset:6144
	ds_read_b128 v[212:215], v141 offset:7168
	global_load_lds_dwordx4 v[186:187], off
	s_add_i32 m0, s29, 0xe000
	v_lshl_add_u64 v[186:187], s[16:17], 0, v[136:137]
	global_load_lds_dwordx4 v[186:187], off
	s_waitcnt vmcnt(8) lgkmcnt(0)
	s_setprio 1
	s_barrier
	v_mfma_f32_16x16x32_bf16 v[124:127], v[142:145], v[174:177], v[124:127]
	v_mfma_f32_16x16x32_bf16 v[120:123], v[150:153], v[174:177], v[120:123]
	v_mfma_f32_16x16x32_bf16 v[116:119], v[142:145], v[182:185], v[116:119]
	v_mfma_f32_16x16x32_bf16 v[112:115], v[150:153], v[182:185], v[112:115]
	v_mfma_f32_16x16x32_bf16 v[100:103], v[142:145], v[200:203], v[100:103]
	v_mfma_f32_16x16x32_bf16 v[96:99], v[150:153], v[200:203], v[96:99]
	v_mfma_f32_16x16x32_bf16 v[84:87], v[142:145], v[208:211], v[84:87]
	v_mfma_f32_16x16x32_bf16 v[80:83], v[150:153], v[208:211], v[80:83]
	v_mfma_f32_16x16x32_bf16 v[124:127], v[146:149], v[178:181], v[124:127]
	v_mfma_f32_16x16x32_bf16 v[120:123], v[154:157], v[178:181], v[120:123]
	v_mfma_f32_16x16x32_bf16 v[116:119], v[146:149], v[196:199], v[116:119]
	v_mfma_f32_16x16x32_bf16 v[112:115], v[154:157], v[196:199], v[112:115]
	v_mfma_f32_16x16x32_bf16 v[100:103], v[146:149], v[204:207], v[100:103]
	v_mfma_f32_16x16x32_bf16 v[96:99], v[154:157], v[204:207], v[96:99]
	v_mfma_f32_16x16x32_bf16 v[84:87], v[146:149], v[212:215], v[84:87]
	v_mfma_f32_16x16x32_bf16 v[80:83], v[154:157], v[212:215], v[80:83]
	s_setprio 0
	s_setprio 1
	v_mfma_f32_16x16x32_bf16 v[108:111], v[158:161], v[174:177], v[108:111]
	v_mfma_f32_16x16x32_bf16 v[104:107], v[166:169], v[174:177], v[104:107]
	v_mfma_f32_16x16x32_bf16 v[92:95], v[158:161], v[182:185], v[92:95]
	v_mfma_f32_16x16x32_bf16 v[88:91], v[166:169], v[182:185], v[88:91]
	v_mfma_f32_16x16x32_bf16 v[76:79], v[158:161], v[200:203], v[76:79]
	v_mfma_f32_16x16x32_bf16 v[72:75], v[166:169], v[200:203], v[72:75]
	v_mfma_f32_16x16x32_bf16 v[68:71], v[158:161], v[208:211], v[68:71]
	v_mfma_f32_16x16x32_bf16 v[64:67], v[166:169], v[208:211], v[64:67]
	v_mfma_f32_16x16x32_bf16 v[108:111], v[162:165], v[178:181], v[108:111]
	v_mfma_f32_16x16x32_bf16 v[104:107], v[170:173], v[178:181], v[104:107]
	v_mfma_f32_16x16x32_bf16 v[92:95], v[162:165], v[196:199], v[92:95]
	v_mfma_f32_16x16x32_bf16 v[88:91], v[170:173], v[196:199], v[88:91]
	v_mfma_f32_16x16x32_bf16 v[76:79], v[162:165], v[204:207], v[76:79]
	v_mfma_f32_16x16x32_bf16 v[72:75], v[170:173], v[204:207], v[72:75]
	v_mfma_f32_16x16x32_bf16 v[68:71], v[162:165], v[212:215], v[68:71]
	v_mfma_f32_16x16x32_bf16 v[64:67], v[170:173], v[212:215], v[64:67]
	s_setprio 0
	s_barrier
	s_add_i32 s0, s0, s28
	v_lshl_add_u64 v[186:187], s[22:23], 0, v[190:191]
	s_mov_b32 m0, s0
	ds_read_b128 v[174:177], v141 offset:16384
	ds_read_b128 v[178:181], v141 offset:17408
	ds_read_b128 v[182:185], v141 offset:18432
	ds_read_b128 v[196:199], v141 offset:19456
	ds_read_b128 v[200:203], v141 offset:20480
	ds_read_b128 v[204:207], v141 offset:21504
	ds_read_b128 v[208:211], v141 offset:22528
	ds_read_b128 v[212:215], v141 offset:23552
	global_load_lds_dwordx4 v[186:187], off
	s_add_i32 m0, s0, 0x2000
	s_add_u32 s16, s22, 0x160000
	v_lshl_add_u64 v[216:217], s[22:23], 0, v[132:133]
	s_addc_u32 s17, s23, 0
	s_add_i32 s0, s1, s28
	global_load_lds_dwordx4 v[216:217], off
	v_lshl_add_u64 v[218:219], s[16:17], 0, v[190:191]
	s_mov_b32 m0, s0
	v_lshl_add_u64 v[220:221], s[24:25], 0, v[130:131]
	global_load_lds_dwordx4 v[218:219], off
	s_add_i32 m0, s0, 0x2000
	v_lshl_add_u64 v[218:219], s[16:17], 0, v[132:133]
	global_load_lds_dwordx4 v[218:219], off
	s_mov_b32 m0, s29
	v_lshl_add_u64 v[218:219], s[24:25], 0, v[128:129]
	global_load_lds_dwordx4 v[218:219], off
	s_mov_b32 m0, s30
	s_nop 0
	global_load_lds_dwordx4 v[220:221], off
	s_waitcnt vmcnt(8) lgkmcnt(0)
	s_setprio 1
	s_barrier
	v_mfma_f32_16x16x32_bf16 v[60:63], v[142:145], v[174:177], v[60:63]
	v_mfma_f32_16x16x32_bf16 v[56:59], v[150:153], v[174:177], v[56:59]
	v_mfma_f32_16x16x32_bf16 v[52:55], v[142:145], v[182:185], v[52:55]
	v_mfma_f32_16x16x32_bf16 v[48:51], v[150:153], v[182:185], v[48:51]
	v_mfma_f32_16x16x32_bf16 v[36:39], v[142:145], v[200:203], v[36:39]
	v_mfma_f32_16x16x32_bf16 v[32:35], v[150:153], v[200:203], v[32:35]
	v_mfma_f32_16x16x32_bf16 v[20:23], v[142:145], v[208:211], v[20:23]
	v_mfma_f32_16x16x32_bf16 v[16:19], v[150:153], v[208:211], v[16:19]
	v_mfma_f32_16x16x32_bf16 v[60:63], v[146:149], v[178:181], v[60:63]
	v_mfma_f32_16x16x32_bf16 v[56:59], v[154:157], v[178:181], v[56:59]
	v_mfma_f32_16x16x32_bf16 v[52:55], v[146:149], v[196:199], v[52:55]
	v_mfma_f32_16x16x32_bf16 v[48:51], v[154:157], v[196:199], v[48:51]
	v_mfma_f32_16x16x32_bf16 v[36:39], v[146:149], v[204:207], v[36:39]
	v_mfma_f32_16x16x32_bf16 v[32:35], v[154:157], v[204:207], v[32:35]
	v_mfma_f32_16x16x32_bf16 v[20:23], v[146:149], v[212:215], v[20:23]
	v_mfma_f32_16x16x32_bf16 v[16:19], v[154:157], v[212:215], v[16:19]
	s_setprio 0
	s_setprio 1
	v_mfma_f32_16x16x32_bf16 v[44:47], v[158:161], v[174:177], v[44:47]
	v_mfma_f32_16x16x32_bf16 v[40:43], v[166:169], v[174:177], v[40:43]
	v_mfma_f32_16x16x32_bf16 v[28:31], v[158:161], v[182:185], v[28:31]
	v_mfma_f32_16x16x32_bf16 v[24:27], v[166:169], v[182:185], v[24:27]
	v_mfma_f32_16x16x32_bf16 v[12:15], v[158:161], v[200:203], v[12:15]
	v_mfma_f32_16x16x32_bf16 v[8:11], v[166:169], v[200:203], v[8:11]
	v_mfma_f32_16x16x32_bf16 v[4:7], v[158:161], v[208:211], v[4:7]
	v_mfma_f32_16x16x32_bf16 v[0:3], v[166:169], v[208:211], v[0:3]
	v_mfma_f32_16x16x32_bf16 v[44:47], v[162:165], v[178:181], v[44:47]
	v_mfma_f32_16x16x32_bf16 v[40:43], v[170:173], v[178:181], v[40:43]
	v_mfma_f32_16x16x32_bf16 v[28:31], v[162:165], v[196:199], v[28:31]
	v_mfma_f32_16x16x32_bf16 v[24:27], v[170:173], v[196:199], v[24:27]
	v_mfma_f32_16x16x32_bf16 v[12:15], v[162:165], v[204:207], v[12:15]
	v_mfma_f32_16x16x32_bf16 v[8:11], v[170:173], v[204:207], v[8:11]
	v_mfma_f32_16x16x32_bf16 v[4:7], v[162:165], v[212:215], v[4:7]
	v_mfma_f32_16x16x32_bf16 v[0:3], v[170:173], v[212:215], v[0:3]
	s_setprio 0
	s_barrier
	s_add_i32 s0, 0, 0x18000
	s_add_i32 s1, 0, 0x1c000
	v_add_u32_e32 v154, s0, v139
	v_add_u32_e32 v170, s1, v139
	ds_read_b128 v[142:145], v154
	ds_read_b128 v[146:149], v154 offset:1024
	ds_read_b128 v[150:153], v154 offset:2048
	ds_read_b128 v[154:157], v154 offset:3072
	ds_read_b128 v[158:161], v170
	ds_read_b128 v[162:165], v170 offset:1024
	ds_read_b128 v[166:169], v170 offset:2048
	ds_read_b128 v[170:173], v170 offset:3072
	s_add_u32 s16, s24, 0x160000
	s_addc_u32 s17, s25, 0
	s_mov_b32 m0, s31
	v_lshl_add_u64 v[222:223], s[16:17], 0, v[128:129]
	ds_read_b128 v[174:177], v141 offset:32768
	ds_read_b128 v[178:181], v141 offset:33792
	ds_read_b128 v[182:185], v141 offset:34816
	ds_read_b128 v[196:199], v141 offset:35840
	ds_read_b128 v[200:203], v141 offset:36864
	ds_read_b128 v[204:207], v141 offset:37888
	ds_read_b128 v[208:211], v141 offset:38912
	ds_read_b128 v[212:215], v141 offset:39936
	global_load_lds_dwordx4 v[222:223], off
	s_mov_b32 m0, s33
	v_lshl_add_u64 v[222:223], s[16:17], 0, v[130:131]
	global_load_lds_dwordx4 v[222:223], off
	s_waitcnt vmcnt(8) lgkmcnt(0)
	s_setprio 1
	s_barrier
	v_mfma_f32_16x16x32_bf16 v[124:127], v[142:145], v[174:177], v[124:127]
	v_mfma_f32_16x16x32_bf16 v[120:123], v[150:153], v[174:177], v[120:123]
	v_mfma_f32_16x16x32_bf16 v[116:119], v[142:145], v[182:185], v[116:119]
	v_mfma_f32_16x16x32_bf16 v[112:115], v[150:153], v[182:185], v[112:115]
	v_mfma_f32_16x16x32_bf16 v[100:103], v[142:145], v[200:203], v[100:103]
	v_mfma_f32_16x16x32_bf16 v[96:99], v[150:153], v[200:203], v[96:99]
	v_mfma_f32_16x16x32_bf16 v[84:87], v[142:145], v[208:211], v[84:87]
	v_mfma_f32_16x16x32_bf16 v[80:83], v[150:153], v[208:211], v[80:83]
	v_mfma_f32_16x16x32_bf16 v[124:127], v[146:149], v[178:181], v[124:127]
	v_mfma_f32_16x16x32_bf16 v[120:123], v[154:157], v[178:181], v[120:123]
	v_mfma_f32_16x16x32_bf16 v[116:119], v[146:149], v[196:199], v[116:119]
	v_mfma_f32_16x16x32_bf16 v[112:115], v[154:157], v[196:199], v[112:115]
	v_mfma_f32_16x16x32_bf16 v[100:103], v[146:149], v[204:207], v[100:103]
	v_mfma_f32_16x16x32_bf16 v[96:99], v[154:157], v[204:207], v[96:99]
	v_mfma_f32_16x16x32_bf16 v[84:87], v[146:149], v[212:215], v[84:87]
	v_mfma_f32_16x16x32_bf16 v[80:83], v[154:157], v[212:215], v[80:83]
	s_setprio 0
	s_setprio 1
	v_mfma_f32_16x16x32_bf16 v[108:111], v[158:161], v[174:177], v[108:111]
	v_mfma_f32_16x16x32_bf16 v[104:107], v[166:169], v[174:177], v[104:107]
	v_mfma_f32_16x16x32_bf16 v[92:95], v[158:161], v[182:185], v[92:95]
	v_mfma_f32_16x16x32_bf16 v[88:91], v[166:169], v[182:185], v[88:91]
	v_mfma_f32_16x16x32_bf16 v[76:79], v[158:161], v[200:203], v[76:79]
	v_mfma_f32_16x16x32_bf16 v[72:75], v[166:169], v[200:203], v[72:75]
	v_mfma_f32_16x16x32_bf16 v[68:71], v[158:161], v[208:211], v[68:71]
	v_mfma_f32_16x16x32_bf16 v[64:67], v[166:169], v[208:211], v[64:67]
	v_mfma_f32_16x16x32_bf16 v[108:111], v[162:165], v[178:181], v[108:111]
	v_mfma_f32_16x16x32_bf16 v[104:107], v[170:173], v[178:181], v[104:107]
	v_mfma_f32_16x16x32_bf16 v[92:95], v[162:165], v[196:199], v[92:95]
	v_mfma_f32_16x16x32_bf16 v[88:91], v[170:173], v[196:199], v[88:91]
	v_mfma_f32_16x16x32_bf16 v[76:79], v[162:165], v[204:207], v[76:79]
	v_mfma_f32_16x16x32_bf16 v[72:75], v[170:173], v[204:207], v[72:75]
	v_mfma_f32_16x16x32_bf16 v[68:71], v[162:165], v[212:215], v[68:71]
	v_mfma_f32_16x16x32_bf16 v[64:67], v[170:173], v[212:215], v[64:67]
	s_setprio 0
	s_barrier
	s_add_i32 s0, s0, s28
	v_lshl_add_u64 v[186:187], v[186:187], 0, s[58:59]
	s_mov_b32 m0, s0
	ds_read_b128 v[174:177], v141 offset:49152
	ds_read_b128 v[178:181], v141 offset:50176
	ds_read_b128 v[182:185], v141 offset:51200
	ds_read_b128 v[196:199], v141 offset:52224
	ds_read_b128 v[200:203], v141 offset:53248
	ds_read_b128 v[204:207], v141 offset:54272
	ds_read_b128 v[208:211], v141 offset:55296
	ds_read_b128 v[212:215], v141 offset:56320
	global_load_lds_dwordx4 v[186:187], off
	s_add_i32 m0, s0, 0x2000
	s_add_u32 s16, s22, 0x160080
	v_lshl_add_u64 v[186:187], v[216:217], 0, s[58:59]
	s_addc_u32 s17, s23, 0
	s_add_i32 s0, s1, s28
	global_load_lds_dwordx4 v[186:187], off
	s_mov_b32 m0, s0
	v_lshl_add_u64 v[186:187], s[16:17], 0, v[190:191]
	global_load_lds_dwordx4 v[186:187], off
	s_add_i32 m0, s0, 0x2000
	v_lshl_add_u64 v[186:187], s[16:17], 0, v[132:133]
	global_load_lds_dwordx4 v[186:187], off
	s_mov_b32 m0, s37
	v_lshl_add_u64 v[186:187], v[218:219], 0, s[58:59]
	global_load_lds_dwordx4 v[186:187], off
	s_mov_b32 m0, s38
	v_lshl_add_u64 v[186:187], v[220:221], 0, s[58:59]
	global_load_lds_dwordx4 v[186:187], off
	s_waitcnt vmcnt(8) lgkmcnt(0)
	s_setprio 1
	s_barrier
	v_mfma_f32_16x16x32_bf16 v[60:63], v[142:145], v[174:177], v[60:63]
	v_mfma_f32_16x16x32_bf16 v[56:59], v[150:153], v[174:177], v[56:59]
	v_mfma_f32_16x16x32_bf16 v[52:55], v[142:145], v[182:185], v[52:55]
	v_mfma_f32_16x16x32_bf16 v[48:51], v[150:153], v[182:185], v[48:51]
	v_mfma_f32_16x16x32_bf16 v[36:39], v[142:145], v[200:203], v[36:39]
	v_mfma_f32_16x16x32_bf16 v[32:35], v[150:153], v[200:203], v[32:35]
	v_mfma_f32_16x16x32_bf16 v[20:23], v[142:145], v[208:211], v[20:23]
	v_mfma_f32_16x16x32_bf16 v[16:19], v[150:153], v[208:211], v[16:19]
	v_mfma_f32_16x16x32_bf16 v[60:63], v[146:149], v[178:181], v[60:63]
	v_mfma_f32_16x16x32_bf16 v[56:59], v[154:157], v[178:181], v[56:59]
	v_mfma_f32_16x16x32_bf16 v[52:55], v[146:149], v[196:199], v[52:55]
	v_mfma_f32_16x16x32_bf16 v[48:51], v[154:157], v[196:199], v[48:51]
	v_mfma_f32_16x16x32_bf16 v[36:39], v[146:149], v[204:207], v[36:39]
	v_mfma_f32_16x16x32_bf16 v[32:35], v[154:157], v[204:207], v[32:35]
	v_mfma_f32_16x16x32_bf16 v[20:23], v[146:149], v[212:215], v[20:23]
	v_mfma_f32_16x16x32_bf16 v[16:19], v[154:157], v[212:215], v[16:19]
	s_setprio 0
	s_setprio 1
	v_mfma_f32_16x16x32_bf16 v[44:47], v[158:161], v[174:177], v[44:47]
	v_mfma_f32_16x16x32_bf16 v[40:43], v[166:169], v[174:177], v[40:43]
	v_mfma_f32_16x16x32_bf16 v[28:31], v[158:161], v[182:185], v[28:31]
	v_mfma_f32_16x16x32_bf16 v[24:27], v[166:169], v[182:185], v[24:27]
	v_mfma_f32_16x16x32_bf16 v[12:15], v[158:161], v[200:203], v[12:15]
	v_mfma_f32_16x16x32_bf16 v[8:11], v[166:169], v[200:203], v[8:11]
	v_mfma_f32_16x16x32_bf16 v[4:7], v[158:161], v[208:211], v[4:7]
	v_mfma_f32_16x16x32_bf16 v[0:3], v[166:169], v[208:211], v[0:3]
	v_mfma_f32_16x16x32_bf16 v[44:47], v[162:165], v[178:181], v[44:47]
	v_mfma_f32_16x16x32_bf16 v[40:43], v[170:173], v[178:181], v[40:43]
	v_mfma_f32_16x16x32_bf16 v[28:31], v[162:165], v[196:199], v[28:31]
	v_mfma_f32_16x16x32_bf16 v[24:27], v[170:173], v[196:199], v[24:27]
	v_mfma_f32_16x16x32_bf16 v[12:15], v[162:165], v[204:207], v[12:15]
	v_mfma_f32_16x16x32_bf16 v[8:11], v[170:173], v[204:207], v[8:11]
	v_mfma_f32_16x16x32_bf16 v[4:7], v[162:165], v[212:215], v[4:7]
	v_mfma_f32_16x16x32_bf16 v[0:3], v[170:173], v[212:215], v[0:3]
	s_setprio 0
	s_barrier
	s_add_i32 s53, s53, 2
	s_add_u32 s47, s47, 0x100
	s_addc_u32 s52, s52, 0
	s_cmpk_gt_u32 s53, 0x55
	s_mov_b64 s[16:17], s[20:21]
	s_cbranch_scc0 .LBB0_1350
